# K-loop back edges rotated in front of the loop-back barrier (on v8: no setprio flips)
# baseline (speedup 1.0000x reference)
.LBB0_231:
	s_ashr_i32 s19, s18, 31
	ds_read_b128 v[0:3], v152
	ds_read_b128 v[4:7], v152 offset:1024
	ds_read_b128 v[8:11], v152 offset:2048
	ds_read_b128 v[12:15], v152 offset:3072
	s_lshl_b64 s[20:21], s[18:19], 19
	s_add_u32 s20, s10, s20
	s_addc_u32 s21, s11, s21
	s_ashr_i32 s17, s16, 31
	s_lshl_b64 s[22:23], s[16:17], 19
	s_add_u32 s22, s39, s22
	s_addc_u32 s23, s40, s23
	s_add_u32 s34, s26, 0x40080
	s_addc_u32 s35, s27, 0
	s_mov_b32 m0, s47
	v_lshl_add_u64 v[48:49], s[34:35], 0, v[136:137]
	ds_read_b128 v[16:19], v153
	ds_read_b128 v[20:23], v153 offset:1024
	ds_read_b128 v[24:27], v153 offset:2048
	ds_read_b128 v[28:31], v153 offset:3072
	ds_read_b128 v[32:35], v153 offset:4096
	ds_read_b128 v[36:39], v153 offset:5120
	ds_read_b128 v[40:43], v153 offset:6144
	ds_read_b128 v[44:47], v153 offset:7168
	global_load_lds_dwordx4 v[48:49], off
	s_mov_b32 m0, s48
	v_lshl_add_u64 v[48:49], s[34:35], 0, v[132:133]
	global_load_lds_dwordx4 v[48:49], off
	s_waitcnt lgkmcnt(8)
	s_barrier
	s_waitcnt lgkmcnt(0)
	v_mfma_f32_16x16x32_bf16 v[48:51], v[0:3], v[16:19], 0
	v_mfma_f32_16x16x32_bf16 v[52:55], v[8:11], v[16:19], 0
	v_mfma_f32_16x16x32_bf16 v[56:59], v[0:3], v[24:27], 0
	v_mfma_f32_16x16x32_bf16 v[60:63], v[8:11], v[24:27], 0
	v_mfma_f32_16x16x32_bf16 v[64:67], v[0:3], v[32:35], 0
	v_mfma_f32_16x16x32_bf16 v[68:71], v[8:11], v[32:35], 0
	v_mfma_f32_16x16x32_bf16 v[72:75], v[0:3], v[40:43], 0
	v_mfma_f32_16x16x32_bf16 v[76:79], v[8:11], v[40:43], 0
	v_mfma_f32_16x16x32_bf16 v[48:51], v[4:7], v[20:23], v[48:51]
	v_mfma_f32_16x16x32_bf16 v[52:55], v[12:15], v[20:23], v[52:55]
	v_mfma_f32_16x16x32_bf16 v[56:59], v[4:7], v[28:31], v[56:59]
	v_mfma_f32_16x16x32_bf16 v[60:63], v[12:15], v[28:31], v[60:63]
	v_mfma_f32_16x16x32_bf16 v[64:67], v[4:7], v[36:39], v[64:67]
	v_mfma_f32_16x16x32_bf16 v[68:71], v[12:15], v[36:39], v[68:71]
	v_mfma_f32_16x16x32_bf16 v[72:75], v[4:7], v[44:47], v[72:75]
	v_mfma_f32_16x16x32_bf16 v[76:79], v[12:15], v[44:47], v[76:79]
	s_barrier
	v_lshl_add_u64 v[218:219], s[28:29], 0, v[134:135]
	s_mov_b32 m0, s49
	v_lshl_add_u64 v[96:97], v[218:219], 0, s[8:9]
	v_lshl_add_u64 v[238:239], s[28:29], 0, v[130:131]
	ds_read_b128 v[80:83], v154
	ds_read_b128 v[84:87], v154 offset:1024
	ds_read_b128 v[88:91], v154 offset:2048
	ds_read_b128 v[92:95], v154 offset:3072
	global_load_lds_dwordx4 v[96:97], off
	s_mov_b32 m0, s50
	v_lshl_add_u64 v[96:97], v[238:239], 0, s[8:9]
	global_load_lds_dwordx4 v[96:97], off
	s_barrier
	s_waitcnt lgkmcnt(0)
	v_mfma_f32_16x16x32_bf16 v[96:99], v[80:83], v[16:19], 0
	v_mfma_f32_16x16x32_bf16 v[16:19], v[88:91], v[16:19], 0
	v_mfma_f32_16x16x32_bf16 v[100:103], v[80:83], v[24:27], 0
	v_mfma_f32_16x16x32_bf16 v[24:27], v[88:91], v[24:27], 0
	v_mfma_f32_16x16x32_bf16 v[104:107], v[80:83], v[32:35], 0
	v_mfma_f32_16x16x32_bf16 v[32:35], v[88:91], v[32:35], 0
	v_mfma_f32_16x16x32_bf16 v[108:111], v[80:83], v[40:43], 0
	v_mfma_f32_16x16x32_bf16 v[40:43], v[88:91], v[40:43], 0
	v_mfma_f32_16x16x32_bf16 v[116:119], v[84:87], v[20:23], v[96:99]
	v_mfma_f32_16x16x32_bf16 v[16:19], v[92:95], v[20:23], v[16:19]
	v_mfma_f32_16x16x32_bf16 v[20:23], v[84:87], v[28:31], v[100:103]
	v_mfma_f32_16x16x32_bf16 v[24:27], v[92:95], v[28:31], v[24:27]
	v_mfma_f32_16x16x32_bf16 v[28:31], v[84:87], v[36:39], v[104:107]
	v_mfma_f32_16x16x32_bf16 v[32:35], v[92:95], v[36:39], v[32:35]
	v_mfma_f32_16x16x32_bf16 v[36:39], v[84:87], v[44:47], v[108:111]
	v_mfma_f32_16x16x32_bf16 v[40:43], v[92:95], v[44:47], v[40:43]
	v_lshl_add_u64 v[246:247], s[26:27], 0, v[136:137]
	s_mov_b32 m0, s25
	v_lshl_add_u64 v[142:143], v[246:247], 0, s[8:9]
	v_lshl_add_u64 v[248:249], s[26:27], 0, v[132:133]
	s_barrier
	ds_read_b128 v[44:47], v153 offset:16384
	ds_read_b128 v[96:99], v153 offset:17408
	ds_read_b128 v[100:103], v153 offset:18432
	ds_read_b128 v[104:107], v153 offset:19456
	ds_read_b128 v[108:111], v153 offset:20480
	ds_read_b128 v[112:115], v153 offset:21504
	ds_read_b128 v[120:123], v153 offset:22528
	ds_read_b128 v[124:127], v153 offset:23552
	global_load_lds_dwordx4 v[142:143], off
	s_mov_b32 m0, s41
	v_lshl_add_u64 v[142:143], v[248:249], 0, s[8:9]
	global_load_lds_dwordx4 v[142:143], off
	s_barrier
	s_waitcnt lgkmcnt(0)
	v_mfma_f32_16x16x32_bf16 v[142:145], v[0:3], v[44:47], 0
	v_mfma_f32_16x16x32_bf16 v[158:161], v[8:11], v[44:47], 0
	v_mfma_f32_16x16x32_bf16 v[162:165], v[0:3], v[100:103], 0
	v_mfma_f32_16x16x32_bf16 v[166:169], v[8:11], v[100:103], 0
	v_mfma_f32_16x16x32_bf16 v[170:173], v[0:3], v[108:111], 0
	v_mfma_f32_16x16x32_bf16 v[174:177], v[8:11], v[108:111], 0
	v_mfma_f32_16x16x32_bf16 v[0:3], v[0:3], v[120:123], 0
	v_mfma_f32_16x16x32_bf16 v[8:11], v[8:11], v[120:123], 0
	v_mfma_f32_16x16x32_bf16 v[142:145], v[4:7], v[96:99], v[142:145]
	v_mfma_f32_16x16x32_bf16 v[162:165], v[4:7], v[104:107], v[162:165]
	v_mfma_f32_16x16x32_bf16 v[170:173], v[4:7], v[112:115], v[170:173]
	v_mfma_f32_16x16x32_bf16 v[0:3], v[4:7], v[124:127], v[0:3]
	v_mfma_f32_16x16x32_bf16 v[4:7], v[12:15], v[124:127], v[8:11]
	v_mfma_f32_16x16x32_bf16 v[158:161], v[12:15], v[96:99], v[158:161]
	v_mfma_f32_16x16x32_bf16 v[166:169], v[12:15], v[104:107], v[166:169]
	v_mfma_f32_16x16x32_bf16 v[174:177], v[12:15], v[112:115], v[174:177]
	s_barrier
	s_add_u32 s34, s28, 0x40100
	s_addc_u32 s35, s29, 0
	s_mov_b32 m0, s55
	v_lshl_add_u64 v[8:9], s[34:35], 0, v[134:135]
	global_load_lds_dwordx4 v[8:9], off
	s_mov_b32 m0, s56
	v_lshl_add_u64 v[8:9], s[34:35], 0, v[130:131]
	global_load_lds_dwordx4 v[8:9], off
	s_waitcnt vmcnt(6)
	s_barrier
	v_mfma_f32_16x16x32_bf16 v[8:11], v[80:83], v[44:47], 0
	v_mfma_f32_16x16x32_bf16 v[12:15], v[88:91], v[44:47], 0
	v_mfma_f32_16x16x32_bf16 v[44:47], v[80:83], v[100:103], 0
	v_mfma_f32_16x16x32_bf16 v[100:103], v[88:91], v[100:103], 0
	v_mfma_f32_16x16x32_bf16 v[178:181], v[80:83], v[108:111], 0
	v_mfma_f32_16x16x32_bf16 v[108:111], v[88:91], v[108:111], 0
	v_mfma_f32_16x16x32_bf16 v[80:83], v[80:83], v[120:123], 0
	v_mfma_f32_16x16x32_bf16 v[88:91], v[88:91], v[120:123], 0
	v_mfma_f32_16x16x32_bf16 v[12:15], v[92:95], v[96:99], v[12:15]
	v_mfma_f32_16x16x32_bf16 v[44:47], v[84:87], v[104:107], v[44:47]
	v_mfma_f32_16x16x32_bf16 v[182:185], v[84:87], v[96:99], v[8:11]
	v_mfma_f32_16x16x32_bf16 v[186:189], v[92:95], v[104:107], v[100:103]
	v_mfma_f32_16x16x32_bf16 v[178:181], v[84:87], v[112:115], v[178:181]
	v_mfma_f32_16x16x32_bf16 v[190:193], v[92:95], v[112:115], v[108:111]
	v_mfma_f32_16x16x32_bf16 v[194:197], v[84:87], v[124:127], v[80:83]
	v_mfma_f32_16x16x32_bf16 v[198:201], v[92:95], v[124:127], v[88:91]
	s_barrier
	ds_read_b128 v[8:11], v155
	ds_read_b128 v[202:205], v155 offset:1024
	ds_read_b128 v[206:209], v155 offset:2048
	ds_read_b128 v[210:213], v155 offset:3072
	s_add_u32 s34, s26, 0x40100
	s_addc_u32 s35, s27, 0
	s_mov_b32 m0, s42
	v_lshl_add_u64 v[80:81], s[34:35], 0, v[136:137]
	ds_read_b128 v[84:87], v153 offset:32768
	ds_read_b128 v[92:95], v153 offset:33792
	ds_read_b128 v[100:103], v153 offset:34816
	ds_read_b128 v[214:217], v153 offset:35840
	ds_read_b128 v[108:111], v153 offset:36864
	ds_read_b128 v[222:225], v153 offset:37888
	ds_read_b128 v[124:127], v153 offset:38912
	ds_read_b128 v[226:229], v153 offset:39936
	global_load_lds_dwordx4 v[80:81], off
	s_mov_b32 m0, s43
	v_lshl_add_u64 v[80:81], s[34:35], 0, v[132:133]
	global_load_lds_dwordx4 v[80:81], off
	s_waitcnt lgkmcnt(8)
	s_barrier
	s_waitcnt lgkmcnt(0)
	v_mfma_f32_16x16x32_bf16 v[48:51], v[8:11], v[84:87], v[48:51]
	v_mfma_f32_16x16x32_bf16 v[52:55], v[206:209], v[84:87], v[52:55]
	v_mfma_f32_16x16x32_bf16 v[56:59], v[8:11], v[100:103], v[56:59]
	v_mfma_f32_16x16x32_bf16 v[60:63], v[206:209], v[100:103], v[60:63]
	v_mfma_f32_16x16x32_bf16 v[64:67], v[8:11], v[108:111], v[64:67]
	v_mfma_f32_16x16x32_bf16 v[68:71], v[206:209], v[108:111], v[68:71]
	v_mfma_f32_16x16x32_bf16 v[72:75], v[8:11], v[124:127], v[72:75]
	v_mfma_f32_16x16x32_bf16 v[76:79], v[206:209], v[124:127], v[76:79]
	v_mfma_f32_16x16x32_bf16 v[120:123], v[202:205], v[92:95], v[48:51]
	v_mfma_f32_16x16x32_bf16 v[112:115], v[210:213], v[92:95], v[52:55]
	v_mfma_f32_16x16x32_bf16 v[104:107], v[202:205], v[214:217], v[56:59]
	v_mfma_f32_16x16x32_bf16 v[96:99], v[210:213], v[214:217], v[60:63]
	v_mfma_f32_16x16x32_bf16 v[88:91], v[202:205], v[222:225], v[64:67]
	v_mfma_f32_16x16x32_bf16 v[80:83], v[210:213], v[222:225], v[68:71]
	v_mfma_f32_16x16x32_bf16 v[72:75], v[202:205], v[226:229], v[72:75]
	v_mfma_f32_16x16x32_bf16 v[60:63], v[210:213], v[226:229], v[76:79]
	s_barrier
	s_mov_b32 m0, s57
	v_lshl_add_u64 v[48:49], v[218:219], 0, s[12:13]
	ds_read_b128 v[52:55], v156
	ds_read_b128 v[230:233], v156 offset:1024
	ds_read_b128 v[68:71], v156 offset:2048
	ds_read_b128 v[234:237], v156 offset:3072
	global_load_lds_dwordx4 v[48:49], off
	s_mov_b32 m0, s58
	v_lshl_add_u64 v[48:49], v[238:239], 0, s[12:13]
	global_load_lds_dwordx4 v[48:49], off
	s_barrier
	s_waitcnt lgkmcnt(0)
	v_mfma_f32_16x16x32_bf16 v[48:51], v[52:55], v[84:87], v[116:119]
	v_mfma_f32_16x16x32_bf16 v[16:19], v[68:71], v[84:87], v[16:19]
	v_mfma_f32_16x16x32_bf16 v[20:23], v[52:55], v[100:103], v[20:23]
	v_mfma_f32_16x16x32_bf16 v[24:27], v[68:71], v[100:103], v[24:27]
	v_mfma_f32_16x16x32_bf16 v[28:31], v[52:55], v[108:111], v[28:31]
	v_mfma_f32_16x16x32_bf16 v[32:35], v[68:71], v[108:111], v[32:35]
	v_mfma_f32_16x16x32_bf16 v[36:39], v[52:55], v[124:127], v[36:39]
	v_mfma_f32_16x16x32_bf16 v[40:43], v[68:71], v[124:127], v[40:43]
	v_mfma_f32_16x16x32_bf16 v[124:127], v[230:233], v[92:95], v[48:51]
	v_mfma_f32_16x16x32_bf16 v[116:119], v[234:237], v[92:95], v[16:19]
	v_mfma_f32_16x16x32_bf16 v[108:111], v[230:233], v[214:217], v[20:23]
	v_mfma_f32_16x16x32_bf16 v[100:103], v[234:237], v[214:217], v[24:27]
	v_mfma_f32_16x16x32_bf16 v[92:95], v[230:233], v[222:225], v[28:31]
	v_mfma_f32_16x16x32_bf16 v[84:87], v[234:237], v[222:225], v[32:35]
	v_mfma_f32_16x16x32_bf16 v[76:79], v[230:233], v[226:229], v[36:39]
	v_mfma_f32_16x16x32_bf16 v[64:67], v[234:237], v[226:229], v[40:43]
	s_mov_b32 m0, s44
	v_lshl_add_u64 v[16:17], v[246:247], 0, s[12:13]
	s_barrier
	ds_read_b128 v[20:23], v153 offset:49152
	ds_read_b128 v[28:31], v153 offset:50176
	ds_read_b128 v[36:39], v153 offset:51200
	ds_read_b128 v[214:217], v153 offset:52224
	ds_read_b128 v[222:225], v153 offset:53248
	ds_read_b128 v[226:229], v153 offset:54272
	ds_read_b128 v[238:241], v153 offset:55296
	ds_read_b128 v[242:245], v153 offset:56320
	global_load_lds_dwordx4 v[16:17], off
	s_mov_b32 m0, s45
	v_lshl_add_u64 v[16:17], v[248:249], 0, s[12:13]
	global_load_lds_dwordx4 v[16:17], off
	s_barrier
	s_waitcnt lgkmcnt(0)
	v_mfma_f32_16x16x32_bf16 v[16:19], v[8:11], v[20:23], v[142:145]
	v_mfma_f32_16x16x32_bf16 v[24:27], v[206:209], v[20:23], v[158:161]
	v_mfma_f32_16x16x32_bf16 v[32:35], v[8:11], v[36:39], v[162:165]
	v_mfma_f32_16x16x32_bf16 v[142:145], v[206:209], v[36:39], v[166:169]
	v_mfma_f32_16x16x32_bf16 v[158:161], v[8:11], v[222:225], v[170:173]
	v_mfma_f32_16x16x32_bf16 v[162:165], v[206:209], v[222:225], v[174:177]
	v_mfma_f32_16x16x32_bf16 v[0:3], v[8:11], v[238:241], v[0:3]
	v_mfma_f32_16x16x32_bf16 v[4:7], v[206:209], v[238:241], v[4:7]
	v_mfma_f32_16x16x32_bf16 v[56:59], v[202:205], v[28:31], v[16:19]
	v_mfma_f32_16x16x32_bf16 v[48:51], v[210:213], v[28:31], v[24:27]
	v_mfma_f32_16x16x32_bf16 v[40:43], v[202:205], v[214:217], v[32:35]
	v_mfma_f32_16x16x32_bf16 v[32:35], v[210:213], v[214:217], v[142:145]
	v_mfma_f32_16x16x32_bf16 v[24:27], v[202:205], v[226:229], v[158:161]
	v_mfma_f32_16x16x32_bf16 v[16:19], v[210:213], v[226:229], v[162:165]
	v_mfma_f32_16x16x32_bf16 v[8:11], v[202:205], v[242:245], v[0:3]
	v_mfma_f32_16x16x32_bf16 v[0:3], v[210:213], v[242:245], v[4:7]
	s_barrier
	s_add_u32 s34, s28, 0x40180
	s_addc_u32 s35, s29, 0
	s_mov_b32 m0, s59
	v_lshl_add_u64 v[4:5], s[34:35], 0, v[134:135]
	s_add_i32 s17, s59, 0x2000
	global_load_lds_dwordx4 v[4:5], off
	v_lshl_add_u64 v[4:5], s[34:35], 0, v[130:131]
	s_mov_b32 m0, s17
	s_mov_b64 s[34:35], 0x40180
	global_load_lds_dwordx4 v[4:5], off
	s_waitcnt vmcnt(6)
	s_barrier
	v_mfma_f32_16x16x32_bf16 v[4:7], v[52:55], v[20:23], v[182:185]
	v_mfma_f32_16x16x32_bf16 v[12:15], v[68:71], v[20:23], v[12:15]
	v_mfma_f32_16x16x32_bf16 v[20:23], v[52:55], v[36:39], v[44:47]
	v_mfma_f32_16x16x32_bf16 v[36:39], v[68:71], v[36:39], v[186:189]
	v_mfma_f32_16x16x32_bf16 v[142:145], v[52:55], v[222:225], v[178:181]
	v_mfma_f32_16x16x32_bf16 v[158:161], v[68:71], v[222:225], v[190:193]
	v_mfma_f32_16x16x32_bf16 v[162:165], v[52:55], v[238:241], v[194:197]
	v_mfma_f32_16x16x32_bf16 v[166:169], v[68:71], v[238:241], v[198:201]
	v_mfma_f32_16x16x32_bf16 v[68:71], v[230:233], v[28:31], v[4:7]
	v_mfma_f32_16x16x32_bf16 v[52:55], v[234:237], v[28:31], v[12:15]
	v_mfma_f32_16x16x32_bf16 v[44:47], v[230:233], v[214:217], v[20:23]
	v_mfma_f32_16x16x32_bf16 v[36:39], v[234:237], v[214:217], v[36:39]
	v_mfma_f32_16x16x32_bf16 v[28:31], v[230:233], v[226:229], v[142:145]
	v_mfma_f32_16x16x32_bf16 v[20:23], v[234:237], v[226:229], v[158:161]
	v_mfma_f32_16x16x32_bf16 v[12:15], v[230:233], v[242:245], v[162:165]
	v_mfma_f32_16x16x32_bf16 v[4:7], v[234:237], v[242:245], v[166:169]
	v_lshl_add_u64 v[142:143], s[26:27], 0, v[138:139]
	v_lshl_add_u64 v[144:145], s[26:27], 0, v[140:141]
	s_mov_b32 s19, 0
.Lrot_232:
	s_barrier
.LBB0_232:
	ds_read_b128 v[158:161], v152
	ds_read_b128 v[162:165], v152 offset:1024
	ds_read_b128 v[166:169], v152 offset:2048
	ds_read_b128 v[170:173], v152 offset:3072
	s_mov_b32 m0, s47
	v_lshl_add_u64 v[206:207], v[142:143], 0, s[34:35]
	ds_read_b128 v[174:177], v153
	ds_read_b128 v[178:181], v153 offset:1024
	ds_read_b128 v[182:185], v153 offset:2048
	ds_read_b128 v[186:189], v153 offset:3072
	ds_read_b128 v[190:193], v153 offset:4096
	ds_read_b128 v[194:197], v153 offset:5120
	ds_read_b128 v[198:201], v153 offset:6144
	ds_read_b128 v[202:205], v153 offset:7168
	global_load_lds_dwordx4 v[206:207], off
	s_mov_b32 m0, s48
	v_lshl_add_u64 v[206:207], v[144:145], 0, s[34:35]
	global_load_lds_dwordx4 v[206:207], off
	s_waitcnt lgkmcnt(8)
	s_barrier
	s_waitcnt lgkmcnt(0)
	v_mfma_f32_16x16x32_bf16 v[120:123], v[158:161], v[174:177], v[120:123]
	s_add_i32 s61, s34, 0xfffc0080
	v_mfma_f32_16x16x32_bf16 v[112:115], v[166:169], v[174:177], v[112:115]
	s_cmp_eq_u32 s19, 12
	v_mfma_f32_16x16x32_bf16 v[104:107], v[158:161], v[182:185], v[104:107]
	s_cselect_b64 s[36:37], -1, 0
	v_mfma_f32_16x16x32_bf16 v[96:99], v[166:169], v[182:185], v[96:99]
	s_and_b64 s[62:63], s[36:37], exec
	v_mfma_f32_16x16x32_bf16 v[88:91], v[158:161], v[190:193], v[88:91]
	s_cselect_b32 s61, 0, s61
	v_mfma_f32_16x16x32_bf16 v[80:83], v[166:169], v[190:193], v[80:83]
	s_and_b64 s[36:37], s[30:31], s[36:37]
	v_mfma_f32_16x16x32_bf16 v[72:75], v[158:161], v[198:201], v[72:75]
	s_and_b64 s[36:37], s[36:37], exec
	v_mfma_f32_16x16x32_bf16 v[60:63], v[166:169], v[198:201], v[60:63]
	s_cselect_b32 s63, s21, s27
	v_mfma_f32_16x16x32_bf16 v[120:123], v[162:165], v[178:181], v[120:123]
	s_cselect_b32 s62, s20, s26
	v_mfma_f32_16x16x32_bf16 v[112:115], v[170:173], v[178:181], v[112:115]
	s_cselect_b32 s37, s23, s29
	v_mfma_f32_16x16x32_bf16 v[104:107], v[162:165], v[186:189], v[104:107]
	s_cselect_b32 s36, s22, s28
	v_mfma_f32_16x16x32_bf16 v[96:99], v[170:173], v[186:189], v[96:99]
	v_mfma_f32_16x16x32_bf16 v[88:91], v[162:165], v[194:197], v[88:91]
	v_mfma_f32_16x16x32_bf16 v[80:83], v[170:173], v[194:197], v[80:83]
	v_mfma_f32_16x16x32_bf16 v[72:75], v[162:165], v[202:205], v[72:75]
	v_mfma_f32_16x16x32_bf16 v[60:63], v[170:173], v[202:205], v[60:63]
	s_barrier
	s_add_u32 s36, s36, s61
	s_addc_u32 s37, s37, 0
	s_mov_b32 m0, s49
	v_lshl_add_u64 v[218:219], s[36:37], 0, v[134:135]
	ds_read_b128 v[206:209], v154
	ds_read_b128 v[210:213], v154 offset:1024
	ds_read_b128 v[214:217], v154 offset:2048
	ds_read_b128 v[222:225], v154 offset:3072
	global_load_lds_dwordx4 v[218:219], off
	s_mov_b32 m0, s50
	v_lshl_add_u64 v[226:227], s[36:37], 0, v[130:131]
	global_load_lds_dwordx4 v[226:227], off
	s_barrier
	s_waitcnt lgkmcnt(0)
	v_mfma_f32_16x16x32_bf16 v[124:127], v[206:209], v[174:177], v[124:127]
	v_mfma_f32_16x16x32_bf16 v[116:119], v[214:217], v[174:177], v[116:119]
	v_mfma_f32_16x16x32_bf16 v[108:111], v[206:209], v[182:185], v[108:111]
	v_mfma_f32_16x16x32_bf16 v[100:103], v[214:217], v[182:185], v[100:103]
	v_mfma_f32_16x16x32_bf16 v[92:95], v[206:209], v[190:193], v[92:95]
	v_mfma_f32_16x16x32_bf16 v[84:87], v[214:217], v[190:193], v[84:87]
	v_mfma_f32_16x16x32_bf16 v[76:79], v[206:209], v[198:201], v[76:79]
	v_mfma_f32_16x16x32_bf16 v[64:67], v[214:217], v[198:201], v[64:67]
	v_mfma_f32_16x16x32_bf16 v[124:127], v[210:213], v[178:181], v[124:127]
	v_mfma_f32_16x16x32_bf16 v[116:119], v[222:225], v[178:181], v[116:119]
	v_mfma_f32_16x16x32_bf16 v[108:111], v[210:213], v[186:189], v[108:111]
	v_mfma_f32_16x16x32_bf16 v[100:103], v[222:225], v[186:189], v[100:103]
	v_mfma_f32_16x16x32_bf16 v[92:95], v[210:213], v[194:197], v[92:95]
	v_mfma_f32_16x16x32_bf16 v[84:87], v[222:225], v[194:197], v[84:87]
	v_mfma_f32_16x16x32_bf16 v[76:79], v[210:213], v[202:205], v[76:79]
	v_mfma_f32_16x16x32_bf16 v[64:67], v[222:225], v[202:205], v[64:67]
	s_add_u32 s62, s62, s61
	s_addc_u32 s63, s63, 0
	s_mov_b32 m0, s25
	v_lshl_add_u64 v[228:229], s[62:63], 0, v[136:137]
	s_barrier
	ds_read_b128 v[174:177], v153 offset:16384
	ds_read_b128 v[178:181], v153 offset:17408
	ds_read_b128 v[182:185], v153 offset:18432
	ds_read_b128 v[186:189], v153 offset:19456
	ds_read_b128 v[190:193], v153 offset:20480
	ds_read_b128 v[194:197], v153 offset:21504
	ds_read_b128 v[198:201], v153 offset:22528
	ds_read_b128 v[202:205], v153 offset:23552
	global_load_lds_dwordx4 v[228:229], off
	s_mov_b32 m0, s41
	v_lshl_add_u64 v[230:231], s[62:63], 0, v[132:133]
	global_load_lds_dwordx4 v[230:231], off
	s_barrier
	s_waitcnt lgkmcnt(0)
	v_mfma_f32_16x16x32_bf16 v[56:59], v[158:161], v[174:177], v[56:59]
	v_mfma_f32_16x16x32_bf16 v[48:51], v[166:169], v[174:177], v[48:51]
	v_mfma_f32_16x16x32_bf16 v[40:43], v[158:161], v[182:185], v[40:43]
	v_mfma_f32_16x16x32_bf16 v[32:35], v[166:169], v[182:185], v[32:35]
	v_mfma_f32_16x16x32_bf16 v[24:27], v[158:161], v[190:193], v[24:27]
	v_mfma_f32_16x16x32_bf16 v[16:19], v[166:169], v[190:193], v[16:19]
	v_mfma_f32_16x16x32_bf16 v[8:11], v[158:161], v[198:201], v[8:11]
	v_mfma_f32_16x16x32_bf16 v[0:3], v[166:169], v[198:201], v[0:3]
	v_mfma_f32_16x16x32_bf16 v[56:59], v[162:165], v[178:181], v[56:59]
	v_mfma_f32_16x16x32_bf16 v[48:51], v[170:173], v[178:181], v[48:51]
	v_mfma_f32_16x16x32_bf16 v[40:43], v[162:165], v[186:189], v[40:43]
	v_mfma_f32_16x16x32_bf16 v[32:35], v[170:173], v[186:189], v[32:35]
	v_mfma_f32_16x16x32_bf16 v[24:27], v[162:165], v[194:197], v[24:27]
	v_mfma_f32_16x16x32_bf16 v[16:19], v[170:173], v[194:197], v[16:19]
	v_mfma_f32_16x16x32_bf16 v[8:11], v[162:165], v[202:205], v[8:11]
	v_mfma_f32_16x16x32_bf16 v[0:3], v[170:173], v[202:205], v[0:3]
	s_barrier
	s_add_u32 s64, s36, 0x40000
	s_addc_u32 s65, s37, 0
	s_mov_b32 m0, s55
	v_lshl_add_u64 v[158:159], s[64:65], 0, v[134:135]
	global_load_lds_dwordx4 v[158:159], off
	s_mov_b32 m0, s56
	v_lshl_add_u64 v[158:159], s[64:65], 0, v[130:131]
	global_load_lds_dwordx4 v[158:159], off
	s_waitcnt vmcnt(6)
	s_barrier
	v_mfma_f32_16x16x32_bf16 v[68:71], v[206:209], v[174:177], v[68:71]
	v_mfma_f32_16x16x32_bf16 v[52:55], v[214:217], v[174:177], v[52:55]
	v_mfma_f32_16x16x32_bf16 v[44:47], v[206:209], v[182:185], v[44:47]
	v_mfma_f32_16x16x32_bf16 v[36:39], v[214:217], v[182:185], v[36:39]
	v_mfma_f32_16x16x32_bf16 v[28:31], v[206:209], v[190:193], v[28:31]
	v_mfma_f32_16x16x32_bf16 v[20:23], v[214:217], v[190:193], v[20:23]
	v_mfma_f32_16x16x32_bf16 v[12:15], v[206:209], v[198:201], v[12:15]
	v_mfma_f32_16x16x32_bf16 v[4:7], v[214:217], v[198:201], v[4:7]
	v_mfma_f32_16x16x32_bf16 v[68:71], v[210:213], v[178:181], v[68:71]
	v_mfma_f32_16x16x32_bf16 v[52:55], v[222:225], v[178:181], v[52:55]
	v_mfma_f32_16x16x32_bf16 v[44:47], v[210:213], v[186:189], v[44:47]
	v_mfma_f32_16x16x32_bf16 v[36:39], v[222:225], v[186:189], v[36:39]
	v_mfma_f32_16x16x32_bf16 v[28:31], v[210:213], v[194:197], v[28:31]
	v_mfma_f32_16x16x32_bf16 v[20:23], v[222:225], v[194:197], v[20:23]
	v_mfma_f32_16x16x32_bf16 v[12:15], v[210:213], v[202:205], v[12:15]
	v_mfma_f32_16x16x32_bf16 v[4:7], v[222:225], v[202:205], v[4:7]
	s_barrier
	ds_read_b128 v[158:161], v155
	ds_read_b128 v[162:165], v155 offset:1024
	ds_read_b128 v[166:169], v155 offset:2048
	ds_read_b128 v[170:173], v155 offset:3072
	s_add_u32 s62, s62, 0x40000
	s_addc_u32 s63, s63, 0
	s_mov_b32 m0, s42
	v_lshl_add_u64 v[206:207], s[62:63], 0, v[136:137]
	ds_read_b128 v[174:177], v153 offset:32768
	ds_read_b128 v[178:181], v153 offset:33792
	ds_read_b128 v[182:185], v153 offset:34816
	ds_read_b128 v[186:189], v153 offset:35840
	ds_read_b128 v[190:193], v153 offset:36864
	ds_read_b128 v[194:197], v153 offset:37888
	ds_read_b128 v[198:201], v153 offset:38912
	ds_read_b128 v[202:205], v153 offset:39936
	global_load_lds_dwordx4 v[206:207], off
	s_mov_b32 m0, s43
	v_lshl_add_u64 v[206:207], s[62:63], 0, v[132:133]
	global_load_lds_dwordx4 v[206:207], off
	s_waitcnt lgkmcnt(8)
	s_barrier
	s_waitcnt lgkmcnt(0)
	v_mfma_f32_16x16x32_bf16 v[120:123], v[158:161], v[174:177], v[120:123]
	v_mfma_f32_16x16x32_bf16 v[112:115], v[166:169], v[174:177], v[112:115]
	v_mfma_f32_16x16x32_bf16 v[104:107], v[158:161], v[182:185], v[104:107]
	v_mfma_f32_16x16x32_bf16 v[96:99], v[166:169], v[182:185], v[96:99]
	v_mfma_f32_16x16x32_bf16 v[88:91], v[158:161], v[190:193], v[88:91]
	v_mfma_f32_16x16x32_bf16 v[80:83], v[166:169], v[190:193], v[80:83]
	v_mfma_f32_16x16x32_bf16 v[72:75], v[158:161], v[198:201], v[72:75]
	v_mfma_f32_16x16x32_bf16 v[60:63], v[166:169], v[198:201], v[60:63]
	v_mfma_f32_16x16x32_bf16 v[120:123], v[162:165], v[178:181], v[120:123]
	v_mfma_f32_16x16x32_bf16 v[112:115], v[170:173], v[178:181], v[112:115]
	v_mfma_f32_16x16x32_bf16 v[104:107], v[162:165], v[186:189], v[104:107]
	v_mfma_f32_16x16x32_bf16 v[96:99], v[170:173], v[186:189], v[96:99]
	v_mfma_f32_16x16x32_bf16 v[88:91], v[162:165], v[194:197], v[88:91]
	v_mfma_f32_16x16x32_bf16 v[80:83], v[170:173], v[194:197], v[80:83]
	v_mfma_f32_16x16x32_bf16 v[72:75], v[162:165], v[202:205], v[72:75]
	v_mfma_f32_16x16x32_bf16 v[60:63], v[170:173], v[202:205], v[60:63]
	s_barrier
	s_mov_b32 m0, s57
	v_lshl_add_u64 v[218:219], v[218:219], 0, s[6:7]
	ds_read_b128 v[206:209], v156
	ds_read_b128 v[210:213], v156 offset:1024
	ds_read_b128 v[214:217], v156 offset:2048
	ds_read_b128 v[222:225], v156 offset:3072
	global_load_lds_dwordx4 v[218:219], off
	s_mov_b32 m0, s58
	v_lshl_add_u64 v[218:219], v[226:227], 0, s[6:7]
	global_load_lds_dwordx4 v[218:219], off
	s_barrier
	s_waitcnt lgkmcnt(0)
	v_mfma_f32_16x16x32_bf16 v[124:127], v[206:209], v[174:177], v[124:127]
	v_mfma_f32_16x16x32_bf16 v[116:119], v[214:217], v[174:177], v[116:119]
	v_mfma_f32_16x16x32_bf16 v[108:111], v[206:209], v[182:185], v[108:111]
	v_mfma_f32_16x16x32_bf16 v[100:103], v[214:217], v[182:185], v[100:103]
	v_mfma_f32_16x16x32_bf16 v[92:95], v[206:209], v[190:193], v[92:95]
	v_mfma_f32_16x16x32_bf16 v[84:87], v[214:217], v[190:193], v[84:87]
	v_mfma_f32_16x16x32_bf16 v[76:79], v[206:209], v[198:201], v[76:79]
	v_mfma_f32_16x16x32_bf16 v[64:67], v[214:217], v[198:201], v[64:67]
	v_mfma_f32_16x16x32_bf16 v[124:127], v[210:213], v[178:181], v[124:127]
	v_mfma_f32_16x16x32_bf16 v[116:119], v[222:225], v[178:181], v[116:119]
	v_mfma_f32_16x16x32_bf16 v[108:111], v[210:213], v[186:189], v[108:111]
	v_mfma_f32_16x16x32_bf16 v[100:103], v[222:225], v[186:189], v[100:103]
	v_mfma_f32_16x16x32_bf16 v[92:95], v[210:213], v[194:197], v[92:95]
	v_mfma_f32_16x16x32_bf16 v[84:87], v[222:225], v[194:197], v[84:87]
	v_mfma_f32_16x16x32_bf16 v[76:79], v[210:213], v[202:205], v[76:79]
	v_mfma_f32_16x16x32_bf16 v[64:67], v[222:225], v[202:205], v[64:67]
	s_mov_b32 m0, s44
	v_lshl_add_u64 v[218:219], v[228:229], 0, s[6:7]
	s_barrier
	ds_read_b128 v[174:177], v153 offset:49152
	ds_read_b128 v[178:181], v153 offset:50176
	ds_read_b128 v[182:185], v153 offset:51200
	ds_read_b128 v[186:189], v153 offset:52224
	ds_read_b128 v[190:193], v153 offset:53248
	ds_read_b128 v[194:197], v153 offset:54272
	ds_read_b128 v[198:201], v153 offset:55296
	ds_read_b128 v[202:205], v153 offset:56320
	global_load_lds_dwordx4 v[218:219], off
	s_mov_b32 m0, s45
	v_lshl_add_u64 v[218:219], v[230:231], 0, s[6:7]
	global_load_lds_dwordx4 v[218:219], off
	s_barrier
	s_waitcnt lgkmcnt(0)
	v_mfma_f32_16x16x32_bf16 v[56:59], v[158:161], v[174:177], v[56:59]
	v_mfma_f32_16x16x32_bf16 v[48:51], v[166:169], v[174:177], v[48:51]
	v_mfma_f32_16x16x32_bf16 v[40:43], v[158:161], v[182:185], v[40:43]
	v_mfma_f32_16x16x32_bf16 v[32:35], v[166:169], v[182:185], v[32:35]
	v_mfma_f32_16x16x32_bf16 v[24:27], v[158:161], v[190:193], v[24:27]
	v_mfma_f32_16x16x32_bf16 v[16:19], v[166:169], v[190:193], v[16:19]
	v_mfma_f32_16x16x32_bf16 v[8:11], v[158:161], v[198:201], v[8:11]
	v_mfma_f32_16x16x32_bf16 v[0:3], v[166:169], v[198:201], v[0:3]
	v_mfma_f32_16x16x32_bf16 v[56:59], v[162:165], v[178:181], v[56:59]
	v_mfma_f32_16x16x32_bf16 v[48:51], v[170:173], v[178:181], v[48:51]
	v_mfma_f32_16x16x32_bf16 v[40:43], v[162:165], v[186:189], v[40:43]
	v_mfma_f32_16x16x32_bf16 v[32:35], v[170:173], v[186:189], v[32:35]
	v_mfma_f32_16x16x32_bf16 v[24:27], v[162:165], v[194:197], v[24:27]
	v_mfma_f32_16x16x32_bf16 v[16:19], v[170:173], v[194:197], v[16:19]
	v_mfma_f32_16x16x32_bf16 v[8:11], v[162:165], v[202:205], v[8:11]
	v_mfma_f32_16x16x32_bf16 v[0:3], v[170:173], v[202:205], v[0:3]
	s_barrier
	s_add_u32 s36, s36, 0x40080
	s_addc_u32 s37, s37, 0
	s_mov_b32 m0, s59
	v_lshl_add_u64 v[158:159], s[36:37], 0, v[134:135]
	global_load_lds_dwordx4 v[158:159], off
	s_mov_b32 m0, s17
	v_lshl_add_u64 v[158:159], s[36:37], 0, v[130:131]
	global_load_lds_dwordx4 v[158:159], off
	s_waitcnt vmcnt(6)
	s_barrier
	v_mfma_f32_16x16x32_bf16 v[68:71], v[206:209], v[174:177], v[68:71]
	v_mfma_f32_16x16x32_bf16 v[52:55], v[214:217], v[174:177], v[52:55]
	v_mfma_f32_16x16x32_bf16 v[44:47], v[206:209], v[182:185], v[44:47]
	v_mfma_f32_16x16x32_bf16 v[36:39], v[214:217], v[182:185], v[36:39]
	v_mfma_f32_16x16x32_bf16 v[28:31], v[206:209], v[190:193], v[28:31]
	v_mfma_f32_16x16x32_bf16 v[20:23], v[214:217], v[190:193], v[20:23]
	v_mfma_f32_16x16x32_bf16 v[12:15], v[206:209], v[198:201], v[12:15]
	v_mfma_f32_16x16x32_bf16 v[4:7], v[214:217], v[198:201], v[4:7]
	v_mfma_f32_16x16x32_bf16 v[68:71], v[210:213], v[178:181], v[68:71]
	v_mfma_f32_16x16x32_bf16 v[52:55], v[222:225], v[178:181], v[52:55]
	v_mfma_f32_16x16x32_bf16 v[44:47], v[210:213], v[186:189], v[44:47]
	v_mfma_f32_16x16x32_bf16 v[36:39], v[222:225], v[186:189], v[36:39]
	v_mfma_f32_16x16x32_bf16 v[28:31], v[210:213], v[194:197], v[28:31]
	v_mfma_f32_16x16x32_bf16 v[20:23], v[222:225], v[194:197], v[20:23]
	v_mfma_f32_16x16x32_bf16 v[12:15], v[210:213], v[202:205], v[12:15]
	v_mfma_f32_16x16x32_bf16 v[4:7], v[222:225], v[202:205], v[4:7]
	s_add_i32 s19, s19, 2
	s_add_u32 s34, s34, 0x100
	s_addc_u32 s35, s35, 0
	s_cmp_gt_u32 s19, 13
	s_cbranch_scc0 .Lrot_232
	s_barrier
; __device__ __forceinline__ unsigned pk2(float lo, float hi) { unsigned r; asm volatile("v_cvt_pk_bf16_f32 %0, %1, %2" : "=v"(r) : "v"(lo), "v"(hi)); return r; }
; __device__ __forceinline__ unsigned pk2(float lo, float hi) { return f2bf(lo) | (f2bf(hi) << 16); }
;     __device__ __forceinline__ void epi(const f32x4 (&acc)[2][2][4][2], const Unit& u, int wr, int wc, int fr, int fq) const {
;         if ((PROBE & 32) && dry) { dry_epi(acc, nq, (float*)H); return; }
;         ConvHost<1> ch; ch.begin(cj, u.g, 2, wr * 4 + wc, fq * 16 + fr);
;         const int row0 = u.pm * 256 + wr * 64 + fr, col0 = u.pn * 128 + wc * 32 + 8 * fq;
; #pragma unroll
;         for (int ai = 0; ai < 2; ++ai)
; #pragma unroll
;             for (int m = 0; m < 4; ++m) {
;                 const int row = row0 + ai * 128 + m * 16; const float rs = rs_lds[((u.pm >> 3) & 1) * 256 + (row & 255)];
;                 const float rs2 = rs * -1.4426950408889634f, rsq = rs * rs;
;                 f32x2 v[4];
; #pragma unroll
;                 for (int n = 0; n < 2; ++n)
; #pragma unroll
;                     for (int jp = 0; jp < 2; ++jp) {
;                         const f32x2 gg = (f32x2){acc[ai][0][m][n][2 * jp], acc[ai][0][m][n][2 * jp + 1]}, uu = (f32x2){acc[ai][1][m][n][2 * jp], acc[ai][1][m][n][2 * jp + 1]};
;                         const f32x2 t = gg * rs2; f32x2 e; e.x = __builtin_amdgcn_exp2f(t.x); e.y = __builtin_amdgcn_exp2f(t.y);
;                         const f32x2 d = e + 1.0f; f32x2 r; r.x = __builtin_amdgcn_rcpf(d.x); r.y = __builtin_amdgcn_rcpf(d.y);
;                         v[n * 2 + jp] = (gg * uu) * (r * rsq);
;                     }
;                 u32x4 w; w.x = pk2(v[0].x, v[0].y); w.y = pk2(v[1].x, v[1].y); w.z = pk2(v[2].x, v[2].y); w.w = pk2(v[3].x, v[3].y);
;                 *(u32x4*)(H + (size_t)row * FF + col0) = w;
;             }
	s_lshl_b32 s17, s24, 7
	s_and_b32 s17, s17, 0x400
	s_add_i32 s17, s17, 0
	s_add_i32 s17, s17, 0x20000
	v_lshl_add_u32 v142, v151, 2, s17
	ds_read_b32 v143, v142
	v_lshl_add_u32 v142, s24, 8, v129
	v_lshl_or_b32 v144, s60, 7, v150
	v_ashrrev_i32_e32 v145, 31, v144
	s_and_b64 vcc, exec, s[14:15]
	s_waitcnt lgkmcnt(0)
	v_mul_f32_e32 v158, 0xbfb8aa3b, v143
	v_pk_mul_f32 v[160:161], v[120:121], v[158:159] op_sel_hi:[1,0]
	v_pk_mul_f32 v[164:165], v[122:123], v[158:159] op_sel_hi:[1,0]
	v_exp_f32_e32 v160, v160
	v_exp_f32_e32 v161, v161
	v_exp_f32_e32 v164, v164
	v_exp_f32_e32 v165, v165
	v_pk_mul_f32 v[122:123], v[122:123], v[126:127]
	v_pk_add_f32 v[160:161], v[160:161], 1.0 op_sel_hi:[1,0]
	v_mul_f32_e32 v162, v143, v143
	v_rcp_f32_e32 v160, v160
	v_rcp_f32_e32 v161, v161
	v_pk_add_f32 v[126:127], v[164:165], 1.0 op_sel_hi:[1,0]
	v_pk_mul_f32 v[120:121], v[120:121], v[124:125]
	v_rcp_f32_e32 v126, v126
	v_rcp_f32_e32 v127, v127
	v_pk_mul_f32 v[124:125], v[162:163], v[160:161] op_sel_hi:[0,1]
	v_pk_mul_f32 v[160:161], v[112:113], v[158:159] op_sel_hi:[1,0]
	v_pk_mul_f32 v[120:121], v[120:121], v[124:125]
	v_exp_f32_e32 v160, v160
	v_exp_f32_e32 v161, v161
	v_pk_mul_f32 v[124:125], v[162:163], v[126:127] op_sel_hi:[0,1]
	v_pk_mul_f32 v[126:127], v[114:115], v[158:159] op_sel_hi:[1,0]
	v_pk_mul_f32 v[122:123], v[122:123], v[124:125]
	v_exp_f32_e32 v126, v126
	v_exp_f32_e32 v127, v127
	v_pk_add_f32 v[124:125], v[160:161], 1.0 op_sel_hi:[1,0]
	v_pk_mul_f32 v[114:115], v[114:115], v[118:119]
	v_rcp_f32_e32 v124, v124
	v_rcp_f32_e32 v125, v125
	v_pk_add_f32 v[118:119], v[126:127], 1.0 op_sel_hi:[1,0]
	v_pk_mul_f32 v[112:113], v[112:113], v[116:117]
	v_rcp_f32_e32 v118, v118
	v_rcp_f32_e32 v119, v119
	v_pk_mul_f32 v[116:117], v[162:163], v[124:125] op_sel_hi:[0,1]
	v_pk_mul_f32 v[112:113], v[112:113], v[116:117]
	s_mov_b32 s60, s16
	v_pk_mul_f32 v[116:117], v[162:163], v[118:119] op_sel_hi:[0,1]
	v_pk_mul_f32 v[114:115], v[114:115], v[116:117]
	v_cvt_pk_bf16_f32 v116, v120, v121
	v_cvt_pk_bf16_f32 v117, v122, v123
	v_cvt_pk_bf16_f32 v118, v112, v113
	v_bitop3_b32 v112, v142, s52, 16 bitop3:0xc8
	v_lshl_add_u32 v112, v112, 2, s17
	v_cvt_pk_bf16_f32 v119, v114, v115
	ds_read_b32 v123, v112
	v_mov_b64_e32 v[112:113], s[2:3]
	v_mad_i64_i32 v[120:121], s[26:27], v142, s51, v[112:113]
	v_lshlrev_b64 v[114:115], 1, v[144:145]
	s_waitcnt lgkmcnt(0)
	v_mul_f32_e32 v122, 0xbfb8aa3b, v123
	v_pk_mul_f32 v[124:125], v[104:105], v[122:123] op_sel_hi:[1,0]
	v_lshl_add_u64 v[120:121], v[120:121], 0, v[114:115]
	v_exp_f32_e32 v124, v124
	v_exp_f32_e32 v125, v125
	global_store_dwordx4 v[120:121], v[116:119], off
	v_pk_mul_f32 v[120:121], v[106:107], v[122:123] op_sel_hi:[1,0]
	v_pk_mul_f32 v[106:107], v[106:107], v[110:111]
	v_exp_f32_e32 v120, v120
	v_exp_f32_e32 v121, v121
	v_pk_add_f32 v[118:119], v[124:125], 1.0 op_sel_hi:[1,0]
	v_mul_f32_e32 v116, v123, v123
	v_rcp_f32_e32 v118, v118
	v_rcp_f32_e32 v119, v119
	v_pk_add_f32 v[110:111], v[120:121], 1.0 op_sel_hi:[1,0]
	v_pk_mul_f32 v[104:105], v[104:105], v[108:109]
	v_rcp_f32_e32 v110, v110
	v_rcp_f32_e32 v111, v111
	v_pk_mul_f32 v[108:109], v[116:117], v[118:119] op_sel_hi:[0,1]
	v_pk_mul_f32 v[118:119], v[96:97], v[122:123] op_sel_hi:[1,0]
	v_pk_mul_f32 v[104:105], v[104:105], v[108:109]
	v_exp_f32_e32 v118, v118
	v_exp_f32_e32 v119, v119
	v_pk_mul_f32 v[108:109], v[116:117], v[110:111] op_sel_hi:[0,1]
	v_pk_mul_f32 v[110:111], v[98:99], v[122:123] op_sel_hi:[1,0]
	v_pk_mul_f32 v[106:107], v[106:107], v[108:109]
	v_exp_f32_e32 v110, v110
	v_exp_f32_e32 v111, v111
	v_pk_add_f32 v[108:109], v[118:119], 1.0 op_sel_hi:[1,0]
	v_pk_mul_f32 v[98:99], v[98:99], v[102:103]
	v_rcp_f32_e32 v108, v108
	v_rcp_f32_e32 v109, v109
	v_pk_add_f32 v[102:103], v[110:111], 1.0 op_sel_hi:[1,0]
	v_pk_mul_f32 v[96:97], v[96:97], v[100:101]
	v_rcp_f32_e32 v102, v102
	v_rcp_f32_e32 v103, v103
	v_pk_mul_f32 v[100:101], v[116:117], v[108:109] op_sel_hi:[0,1]
	v_pk_mul_f32 v[100:101], v[96:97], v[100:101]
	s_mov_b32 s24, s18
	v_pk_mul_f32 v[96:97], v[116:117], v[102:103] op_sel_hi:[0,1]
	v_pk_mul_f32 v[102:103], v[98:99], v[96:97]
	v_cvt_pk_bf16_f32 v96, v104, v105
	v_cvt_pk_bf16_f32 v97, v106, v107
	v_cvt_pk_bf16_f32 v98, v100, v101
	v_bitop3_b32 v100, v142, s53, 32 bitop3:0xc8
	v_lshl_add_u32 v100, v100, 2, s17
	v_cvt_pk_bf16_f32 v99, v102, v103
	ds_read_b32 v103, v100
	v_or_b32_e32 v100, 16, v142
	v_mad_i64_i32 v[100:101], s[26:27], v100, s51, v[112:113]
	v_lshl_add_u64 v[100:101], v[100:101], 0, v[114:115]
	s_waitcnt lgkmcnt(0)
	v_mul_f32_e32 v102, 0xbfb8aa3b, v103
	v_pk_mul_f32 v[104:105], v[88:89], v[102:103] op_sel_hi:[1,0]
	global_store_dwordx4 v[100:101], v[96:99], off
	v_exp_f32_e32 v104, v104
	v_exp_f32_e32 v105, v105
	v_pk_mul_f32 v[100:101], v[90:91], v[102:103] op_sel_hi:[1,0]
	v_pk_mul_f32 v[90:91], v[90:91], v[94:95]
	v_exp_f32_e32 v100, v100
	v_exp_f32_e32 v101, v101
	v_pk_add_f32 v[98:99], v[104:105], 1.0 op_sel_hi:[1,0]
	v_mul_f32_e32 v96, v103, v103
	v_rcp_f32_e32 v98, v98
	v_rcp_f32_e32 v99, v99
	v_pk_add_f32 v[94:95], v[100:101], 1.0 op_sel_hi:[1,0]
	v_pk_mul_f32 v[88:89], v[88:89], v[92:93]
	v_rcp_f32_e32 v94, v94
	v_rcp_f32_e32 v95, v95
	v_pk_mul_f32 v[92:93], v[96:97], v[98:99] op_sel_hi:[0,1]
	v_pk_mul_f32 v[98:99], v[80:81], v[102:103] op_sel_hi:[1,0]
	v_pk_mul_f32 v[88:89], v[88:89], v[92:93]
	v_exp_f32_e32 v98, v98
	v_exp_f32_e32 v99, v99
	v_pk_mul_f32 v[92:93], v[96:97], v[94:95] op_sel_hi:[0,1]
	v_pk_mul_f32 v[94:95], v[82:83], v[102:103] op_sel_hi:[1,0]
	v_pk_mul_f32 v[90:91], v[90:91], v[92:93]
	v_exp_f32_e32 v94, v94
	v_exp_f32_e32 v95, v95
	v_pk_add_f32 v[92:93], v[98:99], 1.0 op_sel_hi:[1,0]
	v_pk_mul_f32 v[82:83], v[82:83], v[86:87]
	v_rcp_f32_e32 v92, v92
	v_rcp_f32_e32 v93, v93
	v_pk_add_f32 v[86:87], v[94:95], 1.0 op_sel_hi:[1,0]
	v_pk_mul_f32 v[80:81], v[80:81], v[84:85]
	v_rcp_f32_e32 v86, v86
	v_rcp_f32_e32 v87, v87
	v_pk_mul_f32 v[84:85], v[96:97], v[92:93] op_sel_hi:[0,1]
	v_pk_mul_f32 v[84:85], v[80:81], v[84:85]
	s_mov_b64 s[28:29], s[22:23]
	v_pk_mul_f32 v[80:81], v[96:97], v[86:87] op_sel_hi:[0,1]
	v_pk_mul_f32 v[86:87], v[82:83], v[80:81]
	v_cvt_pk_bf16_f32 v80, v88, v89
	v_cvt_pk_bf16_f32 v81, v90, v91
	v_cvt_pk_bf16_f32 v82, v84, v85
	v_bitop3_b32 v84, v142, s54, 48 bitop3:0xc8
	v_lshl_add_u32 v84, v84, 2, s17
	v_cvt_pk_bf16_f32 v83, v86, v87
	ds_read_b32 v87, v84
	v_or_b32_e32 v84, 32, v142
	v_mad_i64_i32 v[84:85], s[26:27], v84, s51, v[112:113]
	v_lshl_add_u64 v[84:85], v[84:85], 0, v[114:115]
	s_waitcnt lgkmcnt(0)
; __device__ __forceinline__ unsigned pk2(float lo, float hi) { unsigned r; asm volatile("v_cvt_pk_bf16_f32 %0, %1, %2" : "=v"(r) : "v"(lo), "v"(hi)); return r; }
; __device__ __forceinline__ unsigned pk2(float lo, float hi) { return f2bf(lo) | (f2bf(hi) << 16); }
;     __device__ __forceinline__ void epi(const f32x4 (&acc)[2][2][4][2], const Unit& u, int wr, int wc, int fr, int fq) const {
;     ...
;             for (int m = 0; m < 4; ++m) {
;                 const int row = row0 + ai * 128 + m * 16; const float rs = rs_lds[((u.pm >> 3) & 1) * 256 + (row & 255)];
;                 const float rs2 = rs * -1.4426950408889634f, rsq = rs * rs;
;                 f32x2 v[4];
; #pragma unroll
;                 for (int n = 0; n < 2; ++n)
; #pragma unroll
;                     for (int jp = 0; jp < 2; ++jp) {
;                         const f32x2 gg = (f32x2){acc[ai][0][m][n][2 * jp], acc[ai][0][m][n][2 * jp + 1]}, uu = (f32x2){acc[ai][1][m][n][2 * jp], acc[ai][1][m][n][2 * jp + 1]};
;                         const f32x2 t = gg * rs2; f32x2 e; e.x = __builtin_amdgcn_exp2f(t.x); e.y = __builtin_amdgcn_exp2f(t.y);
;                         const f32x2 d = e + 1.0f; f32x2 r; r.x = __builtin_amdgcn_rcpf(d.x); r.y = __builtin_amdgcn_rcpf(d.y);
;                         v[n * 2 + jp] = (gg * uu) * (r * rsq);
;                     }
;                 u32x4 w; w.x = pk2(v[0].x, v[0].y); w.y = pk2(v[1].x, v[1].y); w.z = pk2(v[2].x, v[2].y); w.w = pk2(v[3].x, v[3].y);
;                 *(u32x4*)(H + (size_t)row * FF + col0) = w;
	v_mul_f32_e32 v86, 0xbfb8aa3b, v87
	v_pk_mul_f32 v[88:89], v[72:73], v[86:87] op_sel_hi:[1,0]
	global_store_dwordx4 v[84:85], v[80:83], off
	v_exp_f32_e32 v88, v88
	v_exp_f32_e32 v89, v89
	v_pk_mul_f32 v[84:85], v[74:75], v[86:87] op_sel_hi:[1,0]
	v_pk_mul_f32 v[74:75], v[74:75], v[78:79]
	v_exp_f32_e32 v84, v84
	v_exp_f32_e32 v85, v85
	v_pk_add_f32 v[82:83], v[88:89], 1.0 op_sel_hi:[1,0]
	v_mul_f32_e32 v80, v87, v87
	v_rcp_f32_e32 v82, v82
	v_rcp_f32_e32 v83, v83
	v_pk_add_f32 v[78:79], v[84:85], 1.0 op_sel_hi:[1,0]
	v_pk_mul_f32 v[72:73], v[72:73], v[76:77]
	v_rcp_f32_e32 v78, v78
	v_rcp_f32_e32 v79, v79
	v_pk_mul_f32 v[76:77], v[80:81], v[82:83] op_sel_hi:[0,1]
	v_pk_mul_f32 v[82:83], v[60:61], v[86:87] op_sel_hi:[1,0]
	v_pk_mul_f32 v[72:73], v[72:73], v[76:77]
	v_exp_f32_e32 v82, v82
	v_exp_f32_e32 v83, v83
	v_pk_mul_f32 v[76:77], v[80:81], v[78:79] op_sel_hi:[0,1]
	v_pk_mul_f32 v[78:79], v[62:63], v[86:87] op_sel_hi:[1,0]
	v_pk_mul_f32 v[74:75], v[74:75], v[76:77]
	v_exp_f32_e32 v78, v78
	v_exp_f32_e32 v79, v79
	v_pk_add_f32 v[76:77], v[82:83], 1.0 op_sel_hi:[1,0]
	v_pk_mul_f32 v[62:63], v[62:63], v[66:67]
	v_rcp_f32_e32 v76, v76
	v_rcp_f32_e32 v77, v77
	v_pk_add_f32 v[66:67], v[78:79], 1.0 op_sel_hi:[1,0]
	v_pk_mul_f32 v[60:61], v[60:61], v[64:65]
	v_rcp_f32_e32 v66, v66
	v_rcp_f32_e32 v67, v67
	v_pk_mul_f32 v[64:65], v[80:81], v[76:77] op_sel_hi:[0,1]
	v_pk_mul_f32 v[64:65], v[60:61], v[64:65]
	v_pk_mul_f32 v[60:61], v[80:81], v[66:67] op_sel_hi:[0,1]
	v_pk_mul_f32 v[66:67], v[62:63], v[60:61]
	v_cvt_pk_bf16_f32 v60, v72, v73
	v_cvt_pk_bf16_f32 v61, v74, v75
	v_cvt_pk_bf16_f32 v62, v64, v65
	s_nop 0
	v_cvt_pk_bf16_f32 v63, v66, v67
	v_add_u32_e32 v67, 0x80, v142
	v_and_b32_e32 v64, 0xcf, v67
	v_lshl_add_u32 v64, v64, 2, s17
	ds_read_b32 v74, v64
	v_or_b32_e32 v64, 48, v142
	v_mad_i64_i32 v[64:65], s[26:27], v64, s51, v[112:113]
	v_lshl_add_u64 v[64:65], v[64:65], 0, v[114:115]
	s_waitcnt lgkmcnt(0)
	v_mul_f32_e32 v66, 0xbfb8aa3b, v74
	v_pk_mul_f32 v[72:73], v[56:57], v[66:67] op_sel_hi:[1,0]
	global_store_dwordx4 v[64:65], v[60:63], off
	v_exp_f32_e32 v72, v72
	v_exp_f32_e32 v73, v73
	v_pk_mul_f32 v[64:65], v[58:59], v[66:67] op_sel_hi:[1,0]
	v_mul_f32_e32 v60, v74, v74
	v_exp_f32_e32 v64, v64
	v_exp_f32_e32 v65, v65
	v_pk_add_f32 v[62:63], v[72:73], 1.0 op_sel_hi:[1,0]
	v_pk_mul_f32 v[56:57], v[56:57], v[68:69]
	v_rcp_f32_e32 v62, v62
	v_rcp_f32_e32 v63, v63
	v_pk_add_f32 v[64:65], v[64:65], 1.0 op_sel_hi:[1,0]
	v_pk_mul_f32 v[68:69], v[48:49], v[66:67] op_sel_hi:[1,0]
	v_rcp_f32_e32 v64, v64
	v_rcp_f32_e32 v65, v65
	v_pk_mul_f32 v[62:63], v[60:61], v[62:63] op_sel_hi:[0,1]
	v_exp_f32_e32 v68, v68
	v_exp_f32_e32 v69, v69
	v_pk_mul_f32 v[56:57], v[56:57], v[62:63]
	v_pk_mul_f32 v[62:63], v[60:61], v[64:65] op_sel_hi:[0,1]
	v_pk_mul_f32 v[64:65], v[50:51], v[66:67] op_sel_hi:[1,0]
	v_pk_mul_f32 v[58:59], v[58:59], v[70:71]
	v_exp_f32_e32 v64, v64
	v_exp_f32_e32 v65, v65
	v_pk_mul_f32 v[58:59], v[58:59], v[62:63]
	v_pk_add_f32 v[62:63], v[68:69], 1.0 op_sel_hi:[1,0]
	v_pk_mul_f32 v[50:51], v[50:51], v[54:55]
	v_rcp_f32_e32 v62, v62
	v_rcp_f32_e32 v63, v63
	v_pk_add_f32 v[54:55], v[64:65], 1.0 op_sel_hi:[1,0]
	v_pk_mul_f32 v[48:49], v[48:49], v[52:53]
	v_rcp_f32_e32 v54, v54
	v_rcp_f32_e32 v55, v55
	v_pk_mul_f32 v[52:53], v[60:61], v[62:63] op_sel_hi:[0,1]
	v_pk_mul_f32 v[52:53], v[48:49], v[52:53]
	v_pk_mul_f32 v[48:49], v[60:61], v[54:55] op_sel_hi:[0,1]
	v_pk_mul_f32 v[54:55], v[50:51], v[48:49]
	v_cvt_pk_bf16_f32 v48, v56, v57
	v_cvt_pk_bf16_f32 v49, v58, v59
	v_cvt_pk_bf16_f32 v50, v52, v53
	s_nop 0
	v_cvt_pk_bf16_f32 v51, v54, v55
	v_add_u32_e32 v55, 0x90, v142
	v_and_b32_e32 v52, 0xdf, v55
	v_lshl_add_u32 v52, v52, 2, s17
	ds_read_b32 v58, v52
	v_mad_i64_i32 v[52:53], s[26:27], v67, s51, v[112:113]
	v_lshl_add_u64 v[52:53], v[52:53], 0, v[114:115]
	global_store_dwordx4 v[52:53], v[48:51], off
	s_waitcnt lgkmcnt(0)
; __device__ __forceinline__ unsigned pk2(float lo, float hi) { unsigned r; asm volatile("v_cvt_pk_bf16_f32 %0, %1, %2" : "=v"(r) : "v"(lo), "v"(hi)); return r; }
; __device__ __forceinline__ unsigned pk2(float lo, float hi) { return f2bf(lo) | (f2bf(hi) << 16); }
; #define G_WAIT_V(n) asm volatile("s_waitcnt vmcnt(" #n ")" ::: "memory")
; #define G_BAR __builtin_amdgcn_s_barrier()
;     ...
;         if (!has_next) break;
;         cur = nxt; cA = nA; cB = nB; cA2 = nA2; cB2 = nB2; ++ui;
;     }
;     G_WAIT_V(0);
;     if (wr == 0) G_BAR;
;     G_BAR;
;     __device__ __forceinline__ void epi(const f32x4 (&acc)[2][2][4][2], const Unit& u, int wr, int wc, int fr, int fq) const {
;     ...
;             for (int m = 0; m < 4; ++m) {
;                 const int row = row0 + ai * 128 + m * 16; const float rs = rs_lds[((u.pm >> 3) & 1) * 256 + (row & 255)];
;                 const float rs2 = rs * -1.4426950408889634f, rsq = rs * rs;
;                 f32x2 v[4];
; #pragma unroll
;                 for (int n = 0; n < 2; ++n)
; #pragma unroll
;                     for (int jp = 0; jp < 2; ++jp) {
;                         const f32x2 gg = (f32x2){acc[ai][0][m][n][2 * jp], acc[ai][0][m][n][2 * jp + 1]}, uu = (f32x2){acc[ai][1][m][n][2 * jp], acc[ai][1][m][n][2 * jp + 1]};
;                         const f32x2 t = gg * rs2; f32x2 e; e.x = __builtin_amdgcn_exp2f(t.x); e.y = __builtin_amdgcn_exp2f(t.y);
;                         const f32x2 d = e + 1.0f; f32x2 r; r.x = __builtin_amdgcn_rcpf(d.x); r.y = __builtin_amdgcn_rcpf(d.y);
;                         v[n * 2 + jp] = (gg * uu) * (r * rsq);
;                     }
;                 u32x4 w; w.x = pk2(v[0].x, v[0].y); w.y = pk2(v[1].x, v[1].y); w.z = pk2(v[2].x, v[2].y); w.w = pk2(v[3].x, v[3].y);
;                 *(u32x4*)(H + (size_t)row * FF + col0) = w;
	v_mul_f32_e32 v54, 0xbfb8aa3b, v58
	v_pk_mul_f32 v[56:57], v[40:41], v[54:55] op_sel_hi:[1,0]
	v_pk_mul_f32 v[52:53], v[42:43], v[54:55] op_sel_hi:[1,0]
	v_exp_f32_e32 v56, v56
	v_exp_f32_e32 v57, v57
	v_exp_f32_e32 v52, v52
	v_exp_f32_e32 v53, v53
	v_pk_mul_f32 v[42:43], v[42:43], v[46:47]
	v_pk_add_f32 v[50:51], v[56:57], 1.0 op_sel_hi:[1,0]
	v_mul_f32_e32 v48, v58, v58
	v_rcp_f32_e32 v50, v50
	v_rcp_f32_e32 v51, v51
	v_pk_add_f32 v[46:47], v[52:53], 1.0 op_sel_hi:[1,0]
	v_pk_mul_f32 v[40:41], v[40:41], v[44:45]
	v_rcp_f32_e32 v46, v46
	v_rcp_f32_e32 v47, v47
	v_pk_mul_f32 v[44:45], v[48:49], v[50:51] op_sel_hi:[0,1]
	v_pk_mul_f32 v[50:51], v[32:33], v[54:55] op_sel_hi:[1,0]
	v_pk_mul_f32 v[40:41], v[40:41], v[44:45]
	v_exp_f32_e32 v50, v50
	v_exp_f32_e32 v51, v51
	v_pk_mul_f32 v[44:45], v[48:49], v[46:47] op_sel_hi:[0,1]
	v_pk_mul_f32 v[46:47], v[34:35], v[54:55] op_sel_hi:[1,0]
	v_pk_mul_f32 v[42:43], v[42:43], v[44:45]
	v_exp_f32_e32 v46, v46
	v_exp_f32_e32 v47, v47
	v_pk_add_f32 v[44:45], v[50:51], 1.0 op_sel_hi:[1,0]
	v_pk_mul_f32 v[34:35], v[34:35], v[38:39]
	v_rcp_f32_e32 v44, v44
	v_rcp_f32_e32 v45, v45
	v_pk_add_f32 v[38:39], v[46:47], 1.0 op_sel_hi:[1,0]
	v_pk_mul_f32 v[32:33], v[32:33], v[36:37]
	v_rcp_f32_e32 v38, v38
	v_rcp_f32_e32 v39, v39
	v_pk_mul_f32 v[36:37], v[48:49], v[44:45] op_sel_hi:[0,1]
	v_pk_mul_f32 v[36:37], v[32:33], v[36:37]
	v_pk_mul_f32 v[32:33], v[48:49], v[38:39] op_sel_hi:[0,1]
	v_pk_mul_f32 v[38:39], v[34:35], v[32:33]
	v_cvt_pk_bf16_f32 v32, v40, v41
	v_cvt_pk_bf16_f32 v33, v42, v43
	v_cvt_pk_bf16_f32 v34, v36, v37
	s_nop 0
	v_cvt_pk_bf16_f32 v35, v38, v39
	v_add_u32_e32 v39, 0xa0, v142
	v_and_b32_e32 v36, 0xef, v39
	v_lshl_add_u32 v36, v36, 2, s17
	ds_read_b32 v42, v36
	v_mad_i64_i32 v[36:37], s[26:27], v55, s51, v[112:113]
	v_lshl_add_u64 v[36:37], v[36:37], 0, v[114:115]
	global_store_dwordx4 v[36:37], v[32:35], off
	s_waitcnt lgkmcnt(0)
	v_mul_f32_e32 v38, 0xbfb8aa3b, v42
	v_pk_mul_f32 v[40:41], v[24:25], v[38:39] op_sel_hi:[1,0]
	v_pk_mul_f32 v[36:37], v[26:27], v[38:39] op_sel_hi:[1,0]
	v_exp_f32_e32 v40, v40
	v_exp_f32_e32 v41, v41
	v_exp_f32_e32 v36, v36
	v_exp_f32_e32 v37, v37
	v_pk_mul_f32 v[26:27], v[26:27], v[30:31]
	v_pk_add_f32 v[34:35], v[40:41], 1.0 op_sel_hi:[1,0]
	v_mul_f32_e32 v32, v42, v42
	v_rcp_f32_e32 v34, v34
	v_rcp_f32_e32 v35, v35
	v_pk_add_f32 v[30:31], v[36:37], 1.0 op_sel_hi:[1,0]
	v_pk_mul_f32 v[24:25], v[24:25], v[28:29]
	v_rcp_f32_e32 v30, v30
	v_rcp_f32_e32 v31, v31
	v_pk_mul_f32 v[28:29], v[32:33], v[34:35] op_sel_hi:[0,1]
	v_pk_mul_f32 v[34:35], v[16:17], v[38:39] op_sel_hi:[1,0]
	v_pk_mul_f32 v[24:25], v[24:25], v[28:29]
	v_exp_f32_e32 v34, v34
	v_exp_f32_e32 v35, v35
	v_pk_mul_f32 v[28:29], v[32:33], v[30:31] op_sel_hi:[0,1]
	v_pk_mul_f32 v[30:31], v[18:19], v[38:39] op_sel_hi:[1,0]
	v_pk_mul_f32 v[26:27], v[26:27], v[28:29]
	v_exp_f32_e32 v30, v30
	v_exp_f32_e32 v31, v31
	v_pk_add_f32 v[28:29], v[34:35], 1.0 op_sel_hi:[1,0]
	v_pk_mul_f32 v[18:19], v[18:19], v[22:23]
	v_rcp_f32_e32 v28, v28
	v_rcp_f32_e32 v29, v29
	v_pk_add_f32 v[22:23], v[30:31], 1.0 op_sel_hi:[1,0]
	v_pk_mul_f32 v[16:17], v[16:17], v[20:21]
	v_rcp_f32_e32 v22, v22
	v_rcp_f32_e32 v23, v23
	v_pk_mul_f32 v[20:21], v[32:33], v[28:29] op_sel_hi:[0,1]
	v_pk_mul_f32 v[20:21], v[16:17], v[20:21]
	v_pk_mul_f32 v[16:17], v[32:33], v[22:23] op_sel_hi:[0,1]
	v_pk_mul_f32 v[22:23], v[18:19], v[16:17]
	v_cvt_pk_bf16_f32 v16, v24, v25
	v_cvt_pk_bf16_f32 v17, v26, v27
	v_cvt_pk_bf16_f32 v18, v20, v21
	s_nop 0
	v_cvt_pk_bf16_f32 v19, v22, v23
	v_add_u32_e32 v23, 0xb0, v142
	v_and_b32_e32 v20, 0xff, v23
	v_lshl_add_u32 v20, v20, 2, s17
	ds_read_b32 v26, v20
	v_mad_i64_i32 v[20:21], s[26:27], v39, s51, v[112:113]
	v_lshl_add_u64 v[20:21], v[20:21], 0, v[114:115]
	global_store_dwordx4 v[20:21], v[16:19], off
	s_waitcnt lgkmcnt(0)
	v_mul_f32_e32 v22, 0xbfb8aa3b, v26
	v_pk_mul_f32 v[24:25], v[8:9], v[22:23] op_sel_hi:[1,0]
	v_pk_mul_f32 v[20:21], v[10:11], v[22:23] op_sel_hi:[1,0]
	v_exp_f32_e32 v24, v24
	v_exp_f32_e32 v25, v25
	v_exp_f32_e32 v20, v20
	v_exp_f32_e32 v21, v21
	v_pk_mul_f32 v[10:11], v[10:11], v[14:15]
	v_pk_add_f32 v[18:19], v[24:25], 1.0 op_sel_hi:[1,0]
	v_mul_f32_e32 v16, v26, v26
	v_rcp_f32_e32 v18, v18
	v_rcp_f32_e32 v19, v19
	v_pk_add_f32 v[14:15], v[20:21], 1.0 op_sel_hi:[1,0]
	v_pk_mul_f32 v[8:9], v[8:9], v[12:13]
	v_rcp_f32_e32 v14, v14
	v_rcp_f32_e32 v15, v15
	v_pk_mul_f32 v[12:13], v[16:17], v[18:19] op_sel_hi:[0,1]
	v_pk_mul_f32 v[18:19], v[0:1], v[22:23] op_sel_hi:[1,0]
	v_pk_mul_f32 v[8:9], v[8:9], v[12:13]
	v_exp_f32_e32 v18, v18
	v_exp_f32_e32 v19, v19
	v_pk_mul_f32 v[12:13], v[16:17], v[14:15] op_sel_hi:[0,1]
	v_pk_mul_f32 v[14:15], v[2:3], v[22:23] op_sel_hi:[1,0]
	v_pk_mul_f32 v[10:11], v[10:11], v[12:13]
	v_exp_f32_e32 v14, v14
	v_exp_f32_e32 v15, v15
	v_pk_add_f32 v[12:13], v[18:19], 1.0 op_sel_hi:[1,0]
	v_pk_mul_f32 v[2:3], v[2:3], v[6:7]
	v_rcp_f32_e32 v12, v12
	v_rcp_f32_e32 v13, v13
	v_pk_add_f32 v[6:7], v[14:15], 1.0 op_sel_hi:[1,0]
	v_pk_mul_f32 v[0:1], v[0:1], v[4:5]
	v_rcp_f32_e32 v6, v6
	v_rcp_f32_e32 v7, v7
	v_pk_mul_f32 v[4:5], v[16:17], v[12:13] op_sel_hi:[0,1]
	v_pk_mul_f32 v[4:5], v[0:1], v[4:5]
	v_pk_mul_f32 v[0:1], v[16:17], v[6:7] op_sel_hi:[0,1]
	v_pk_mul_f32 v[6:7], v[2:3], v[0:1]
	v_cvt_pk_bf16_f32 v0, v8, v9
	v_cvt_pk_bf16_f32 v1, v10, v11
	v_cvt_pk_bf16_f32 v2, v4, v5
	v_mad_i64_i32 v[4:5], s[26:27], v23, s51, v[112:113]
	v_lshl_add_u64 v[4:5], v[4:5], 0, v[114:115]
	s_mov_b64 s[26:27], s[20:21]
	v_cvt_pk_bf16_f32 v3, v6, v7
	global_store_dwordx4 v[4:5], v[0:3], off
	s_cbranch_vccz .LBB0_229
	s_waitcnt vmcnt(0)
	s_cmpk_gt_u32 s38, 0xff
	s_cbranch_scc1 .LBB0_236
	s_barrier

.LBB0_356:
	s_waitcnt lgkmcnt(0)
	ds_read_b128 v[0:3], v190
	ds_read_b128 v[4:7], v190 offset:1024
	ds_read_b128 v[8:11], v190 offset:2048
	ds_read_b128 v[12:15], v190 offset:3072
	s_add_u32 s34, s28, 0xb0080
	s_addc_u32 s35, s29, 0
	s_mov_b32 m0, s54
	v_lshl_add_u64 v[48:49], s[34:35], 0, v[154:155]
	ds_read_b128 v[16:19], v191
	ds_read_b128 v[20:23], v191 offset:1024
	ds_read_b128 v[24:27], v191 offset:2048
	ds_read_b128 v[28:31], v191 offset:3072
	ds_read_b128 v[32:35], v191 offset:4096
	ds_read_b128 v[36:39], v191 offset:5120
	ds_read_b128 v[40:43], v191 offset:6144
	ds_read_b128 v[44:47], v191 offset:7168
	global_load_lds_dwordx4 v[48:49], off
	s_mov_b32 m0, s55
	v_lshl_add_u64 v[48:49], s[34:35], 0, v[158:159]
	global_load_lds_dwordx4 v[48:49], off
	s_waitcnt lgkmcnt(8)
	s_barrier
	s_waitcnt lgkmcnt(0)
	v_mfma_f32_16x16x32_bf16 v[48:51], v[0:3], v[16:19], 0
	v_mfma_f32_16x16x32_bf16 v[52:55], v[8:11], v[16:19], 0
	v_mfma_f32_16x16x32_bf16 v[56:59], v[0:3], v[24:27], 0
	v_mfma_f32_16x16x32_bf16 v[60:63], v[8:11], v[24:27], 0
	v_mfma_f32_16x16x32_bf16 v[64:67], v[0:3], v[32:35], 0
	v_mfma_f32_16x16x32_bf16 v[68:71], v[8:11], v[32:35], 0
	v_mfma_f32_16x16x32_bf16 v[72:75], v[0:3], v[40:43], 0
	v_mfma_f32_16x16x32_bf16 v[76:79], v[8:11], v[40:43], 0
	v_mfma_f32_16x16x32_bf16 v[48:51], v[4:7], v[20:23], v[48:51]
	v_mfma_f32_16x16x32_bf16 v[52:55], v[12:15], v[20:23], v[52:55]
	v_mfma_f32_16x16x32_bf16 v[56:59], v[4:7], v[28:31], v[56:59]
	v_mfma_f32_16x16x32_bf16 v[60:63], v[12:15], v[28:31], v[60:63]
	v_mfma_f32_16x16x32_bf16 v[64:67], v[4:7], v[36:39], v[64:67]
	v_mfma_f32_16x16x32_bf16 v[68:71], v[12:15], v[36:39], v[68:71]
	v_mfma_f32_16x16x32_bf16 v[72:75], v[4:7], v[44:47], v[72:75]
	v_mfma_f32_16x16x32_bf16 v[76:79], v[12:15], v[44:47], v[76:79]
	s_barrier
	v_lshl_add_u64 v[182:183], s[30:31], 0, v[156:157]
	s_mov_b32 m0, s56
	v_lshl_add_u64 v[96:97], v[182:183], 0, s[12:13]
	v_lshl_add_u64 v[218:219], s[30:31], 0, v[160:161]
	ds_read_b128 v[80:83], v192
	ds_read_b128 v[84:87], v192 offset:1024
	ds_read_b128 v[88:91], v192 offset:2048
	ds_read_b128 v[92:95], v192 offset:3072
	global_load_lds_dwordx4 v[96:97], off
	s_mov_b32 m0, s57
	v_lshl_add_u64 v[96:97], v[218:219], 0, s[12:13]
	global_load_lds_dwordx4 v[96:97], off
	s_barrier
	s_waitcnt lgkmcnt(0)
	v_mfma_f32_16x16x32_bf16 v[96:99], v[80:83], v[16:19], 0
	v_mfma_f32_16x16x32_bf16 v[16:19], v[88:91], v[16:19], 0
	v_mfma_f32_16x16x32_bf16 v[100:103], v[80:83], v[24:27], 0
	v_mfma_f32_16x16x32_bf16 v[24:27], v[88:91], v[24:27], 0
	v_mfma_f32_16x16x32_bf16 v[104:107], v[80:83], v[32:35], 0
	v_mfma_f32_16x16x32_bf16 v[32:35], v[88:91], v[32:35], 0
	v_mfma_f32_16x16x32_bf16 v[108:111], v[80:83], v[40:43], 0
	v_mfma_f32_16x16x32_bf16 v[40:43], v[88:91], v[40:43], 0
	v_mfma_f32_16x16x32_bf16 v[96:99], v[84:87], v[20:23], v[96:99]
	v_mfma_f32_16x16x32_bf16 v[16:19], v[92:95], v[20:23], v[16:19]
	v_mfma_f32_16x16x32_bf16 v[20:23], v[84:87], v[28:31], v[100:103]
	v_mfma_f32_16x16x32_bf16 v[24:27], v[92:95], v[28:31], v[24:27]
	v_mfma_f32_16x16x32_bf16 v[28:31], v[84:87], v[36:39], v[104:107]
	v_mfma_f32_16x16x32_bf16 v[32:35], v[92:95], v[36:39], v[32:35]
	v_mfma_f32_16x16x32_bf16 v[36:39], v[84:87], v[44:47], v[108:111]
	v_mfma_f32_16x16x32_bf16 v[40:43], v[92:95], v[44:47], v[40:43]
	v_lshl_add_u64 v[246:247], s[28:29], 0, v[154:155]
	s_mov_b32 m0, s46
	v_lshl_add_u64 v[128:129], v[246:247], 0, s[12:13]
	v_lshl_add_u64 v[248:249], s[28:29], 0, v[158:159]
	s_barrier
	ds_read_b128 v[44:47], v191 offset:16384
	ds_read_b128 v[100:103], v191 offset:17408
	ds_read_b128 v[104:107], v191 offset:18432
	ds_read_b128 v[108:111], v191 offset:19456
	ds_read_b128 v[112:115], v191 offset:20480
	ds_read_b128 v[116:119], v191 offset:21504
	ds_read_b128 v[120:123], v191 offset:22528
	ds_read_b128 v[124:127], v191 offset:23552
	global_load_lds_dwordx4 v[128:129], off
	s_mov_b32 m0, s47
	v_lshl_add_u64 v[128:129], v[248:249], 0, s[12:13]
	global_load_lds_dwordx4 v[128:129], off
	s_barrier
	s_waitcnt lgkmcnt(0)
	v_mfma_f32_16x16x32_bf16 v[128:131], v[0:3], v[44:47], 0
	v_mfma_f32_16x16x32_bf16 v[132:135], v[8:11], v[44:47], 0
	v_mfma_f32_16x16x32_bf16 v[136:139], v[0:3], v[104:107], 0
	v_mfma_f32_16x16x32_bf16 v[140:143], v[8:11], v[104:107], 0
	v_mfma_f32_16x16x32_bf16 v[144:147], v[0:3], v[112:115], 0
	v_mfma_f32_16x16x32_bf16 v[148:151], v[8:11], v[112:115], 0
	v_mfma_f32_16x16x32_bf16 v[0:3], v[0:3], v[120:123], 0
	v_mfma_f32_16x16x32_bf16 v[8:11], v[8:11], v[120:123], 0
	v_mfma_f32_16x16x32_bf16 v[128:131], v[4:7], v[100:103], v[128:131]
	v_mfma_f32_16x16x32_bf16 v[166:169], v[12:15], v[100:103], v[132:135]
	v_mfma_f32_16x16x32_bf16 v[134:137], v[4:7], v[108:111], v[136:139]
	v_mfma_f32_16x16x32_bf16 v[138:141], v[12:15], v[108:111], v[140:143]
	v_mfma_f32_16x16x32_bf16 v[142:145], v[4:7], v[116:119], v[144:147]
	v_mfma_f32_16x16x32_bf16 v[0:3], v[4:7], v[124:127], v[0:3]
	v_mfma_f32_16x16x32_bf16 v[4:7], v[12:15], v[124:127], v[8:11]
	v_mfma_f32_16x16x32_bf16 v[146:149], v[12:15], v[116:119], v[148:151]
	s_barrier
	s_add_u32 s34, s30, 0xb0100
	s_addc_u32 s35, s31, 0
	s_add_i32 s0, s53, s43
	v_lshl_add_u64 v[8:9], s[34:35], 0, v[156:157]
	s_mov_b32 m0, s0
	s_add_i32 s62, s0, 0x2000
	global_load_lds_dwordx4 v[8:9], off
	s_mov_b32 m0, s62
	v_lshl_add_u64 v[8:9], s[34:35], 0, v[160:161]
	global_load_lds_dwordx4 v[8:9], off
	s_waitcnt vmcnt(6)
	s_barrier
	v_mfma_f32_16x16x32_bf16 v[8:11], v[80:83], v[44:47], 0
	v_mfma_f32_16x16x32_bf16 v[12:15], v[88:91], v[44:47], 0
	v_mfma_f32_16x16x32_bf16 v[44:47], v[80:83], v[104:107], 0
	v_mfma_f32_16x16x32_bf16 v[104:107], v[88:91], v[104:107], 0
	v_mfma_f32_16x16x32_bf16 v[170:173], v[80:83], v[112:115], 0
	v_mfma_f32_16x16x32_bf16 v[112:115], v[88:91], v[112:115], 0
	v_mfma_f32_16x16x32_bf16 v[80:83], v[80:83], v[120:123], 0
	v_mfma_f32_16x16x32_bf16 v[88:91], v[88:91], v[120:123], 0
	v_mfma_f32_16x16x32_bf16 v[8:11], v[84:87], v[100:103], v[8:11]
	v_mfma_f32_16x16x32_bf16 v[174:177], v[92:95], v[100:103], v[12:15]
	v_mfma_f32_16x16x32_bf16 v[178:181], v[84:87], v[108:111], v[44:47]
	v_mfma_f32_16x16x32_bf16 v[194:197], v[92:95], v[108:111], v[104:107]
	v_mfma_f32_16x16x32_bf16 v[170:173], v[84:87], v[116:119], v[170:173]
	v_mfma_f32_16x16x32_bf16 v[198:201], v[92:95], v[116:119], v[112:115]
	v_mfma_f32_16x16x32_bf16 v[202:205], v[84:87], v[124:127], v[80:83]
	v_mfma_f32_16x16x32_bf16 v[206:209], v[92:95], v[124:127], v[88:91]
	s_add_i32 s63, 0, 0x18000
	v_add_u32_e32 v132, s63, v188
	s_barrier
	ds_read_b128 v[12:15], v132
	ds_read_b128 v[210:213], v132 offset:1024
	ds_read_b128 v[44:47], v132 offset:2048
	ds_read_b128 v[214:217], v132 offset:3072
	s_add_u32 s34, s28, 0xb0100
	s_addc_u32 s35, s29, 0
	s_mov_b32 m0, s48
	v_lshl_add_u64 v[88:89], s[34:35], 0, v[154:155]
	ds_read_b128 v[80:83], v191 offset:32768
	ds_read_b128 v[84:87], v191 offset:33792
	ds_read_b128 v[100:103], v191 offset:34816
	ds_read_b128 v[222:225], v191 offset:35840
	ds_read_b128 v[120:123], v191 offset:36864
	ds_read_b128 v[226:229], v191 offset:37888
	ds_read_b128 v[124:127], v191 offset:38912
	ds_read_b128 v[230:233], v191 offset:39936
	global_load_lds_dwordx4 v[88:89], off
	s_mov_b32 m0, s49
	v_lshl_add_u64 v[88:89], s[34:35], 0, v[158:159]
	global_load_lds_dwordx4 v[88:89], off
	s_waitcnt lgkmcnt(8)
	s_barrier
	s_waitcnt lgkmcnt(0)
	v_mfma_f32_16x16x32_bf16 v[48:51], v[12:15], v[80:83], v[48:51]
	v_mfma_f32_16x16x32_bf16 v[52:55], v[44:47], v[80:83], v[52:55]
	v_mfma_f32_16x16x32_bf16 v[56:59], v[12:15], v[100:103], v[56:59]
	v_mfma_f32_16x16x32_bf16 v[60:63], v[44:47], v[100:103], v[60:63]
	v_mfma_f32_16x16x32_bf16 v[64:67], v[12:15], v[120:123], v[64:67]
	v_mfma_f32_16x16x32_bf16 v[68:71], v[44:47], v[120:123], v[68:71]
	v_mfma_f32_16x16x32_bf16 v[72:75], v[12:15], v[124:127], v[72:75]
	v_mfma_f32_16x16x32_bf16 v[234:237], v[44:47], v[124:127], v[76:79]
	v_mfma_f32_16x16x32_bf16 v[116:119], v[210:213], v[84:87], v[48:51]
	v_mfma_f32_16x16x32_bf16 v[112:115], v[214:217], v[84:87], v[52:55]
	v_mfma_f32_16x16x32_bf16 v[108:111], v[210:213], v[222:225], v[56:59]
	v_mfma_f32_16x16x32_bf16 v[104:107], v[214:217], v[222:225], v[60:63]
	v_mfma_f32_16x16x32_bf16 v[92:95], v[210:213], v[226:229], v[64:67]
	v_mfma_f32_16x16x32_bf16 v[88:91], v[214:217], v[226:229], v[68:71]
	v_mfma_f32_16x16x32_bf16 v[76:79], v[210:213], v[230:233], v[72:75]
	v_mfma_f32_16x16x32_bf16 v[72:75], v[214:217], v[230:233], v[234:237]
	s_barrier
	s_add_i32 s65, 0, 0x1c000
	s_add_i32 s63, s63, s43
	v_add_u32_e32 v133, s65, v188
	v_lshl_add_u64 v[48:49], v[182:183], 0, s[14:15]
	s_mov_b32 m0, s63
	s_add_i32 s64, s63, 0x2000
	ds_read_b128 v[56:59], v133
	ds_read_b128 v[234:237], v133 offset:1024
	ds_read_b128 v[60:63], v133 offset:2048
	ds_read_b128 v[238:241], v133 offset:3072
	global_load_lds_dwordx4 v[48:49], off
	s_mov_b32 m0, s64
	v_lshl_add_u64 v[48:49], v[218:219], 0, s[14:15]
	global_load_lds_dwordx4 v[48:49], off
	s_barrier
	s_waitcnt lgkmcnt(0)
	v_mfma_f32_16x16x32_bf16 v[48:51], v[56:59], v[80:83], v[96:99]
	v_mfma_f32_16x16x32_bf16 v[16:19], v[60:63], v[80:83], v[16:19]
	v_mfma_f32_16x16x32_bf16 v[20:23], v[56:59], v[100:103], v[20:23]
	v_mfma_f32_16x16x32_bf16 v[24:27], v[60:63], v[100:103], v[24:27]
	v_mfma_f32_16x16x32_bf16 v[28:31], v[56:59], v[120:123], v[28:31]
	v_mfma_f32_16x16x32_bf16 v[32:35], v[60:63], v[120:123], v[32:35]
	v_mfma_f32_16x16x32_bf16 v[36:39], v[56:59], v[124:127], v[36:39]
	v_mfma_f32_16x16x32_bf16 v[40:43], v[60:63], v[124:127], v[40:43]
	v_mfma_f32_16x16x32_bf16 v[124:127], v[234:237], v[84:87], v[48:51]
	v_mfma_f32_16x16x32_bf16 v[120:123], v[238:241], v[84:87], v[16:19]
	v_mfma_f32_16x16x32_bf16 v[100:103], v[234:237], v[222:225], v[20:23]
	v_mfma_f32_16x16x32_bf16 v[96:99], v[238:241], v[222:225], v[24:27]
	v_mfma_f32_16x16x32_bf16 v[84:87], v[234:237], v[226:229], v[28:31]
	v_mfma_f32_16x16x32_bf16 v[80:83], v[238:241], v[226:229], v[32:35]
	v_mfma_f32_16x16x32_bf16 v[68:71], v[234:237], v[230:233], v[36:39]
	v_mfma_f32_16x16x32_bf16 v[64:67], v[238:241], v[230:233], v[40:43]
	s_mov_b32 m0, s51
	v_lshl_add_u64 v[20:21], v[246:247], 0, s[14:15]
	s_barrier
	ds_read_b128 v[16:19], v191 offset:49152
	ds_read_b128 v[24:27], v191 offset:50176
	ds_read_b128 v[32:35], v191 offset:51200
	ds_read_b128 v[222:225], v191 offset:52224
	ds_read_b128 v[40:43], v191 offset:53248
	ds_read_b128 v[226:229], v191 offset:54272
	ds_read_b128 v[230:233], v191 offset:55296
	ds_read_b128 v[242:245], v191 offset:56320
	global_load_lds_dwordx4 v[20:21], off
	s_mov_b32 m0, s52
	v_lshl_add_u64 v[20:21], v[248:249], 0, s[14:15]
	global_load_lds_dwordx4 v[20:21], off
	s_barrier
	s_waitcnt lgkmcnt(0)
	v_mfma_f32_16x16x32_bf16 v[20:23], v[12:15], v[16:19], v[128:131]
	v_mfma_f32_16x16x32_bf16 v[28:31], v[44:47], v[16:19], v[166:169]
	v_mfma_f32_16x16x32_bf16 v[36:39], v[12:15], v[32:35], v[134:137]
	v_mfma_f32_16x16x32_bf16 v[128:131], v[44:47], v[32:35], v[138:141]
	v_mfma_f32_16x16x32_bf16 v[134:137], v[12:15], v[40:43], v[142:145]
	v_mfma_f32_16x16x32_bf16 v[138:141], v[44:47], v[40:43], v[146:149]
	v_mfma_f32_16x16x32_bf16 v[0:3], v[12:15], v[230:233], v[0:3]
	v_mfma_f32_16x16x32_bf16 v[4:7], v[44:47], v[230:233], v[4:7]
	v_mfma_f32_16x16x32_bf16 v[52:55], v[210:213], v[24:27], v[20:23]
	v_mfma_f32_16x16x32_bf16 v[48:51], v[214:217], v[24:27], v[28:31]
	v_mfma_f32_16x16x32_bf16 v[44:47], v[210:213], v[222:225], v[36:39]
	v_mfma_f32_16x16x32_bf16 v[36:39], v[214:217], v[222:225], v[128:131]
	v_mfma_f32_16x16x32_bf16 v[28:31], v[210:213], v[226:229], v[134:137]
	v_mfma_f32_16x16x32_bf16 v[20:23], v[214:217], v[226:229], v[138:141]
	v_mfma_f32_16x16x32_bf16 v[12:15], v[210:213], v[242:245], v[0:3]
	v_mfma_f32_16x16x32_bf16 v[4:7], v[214:217], v[242:245], v[4:7]
	s_barrier
	s_add_u32 s34, s30, 0xb0180
	s_addc_u32 s35, s31, 0
	s_add_i32 s65, s65, s43
	v_lshl_add_u64 v[0:1], s[34:35], 0, v[156:157]
	s_mov_b32 m0, s65
	s_add_i32 s66, s65, 0x2000
	global_load_lds_dwordx4 v[0:1], off
	v_lshl_add_u64 v[0:1], s[34:35], 0, v[160:161]
	s_mov_b32 m0, s66
	s_mov_b64 s[34:35], 0xb0180
	global_load_lds_dwordx4 v[0:1], off
	s_waitcnt vmcnt(6)
	s_barrier
	v_mfma_f32_16x16x32_bf16 v[0:3], v[56:59], v[16:19], v[8:11]
	v_mfma_f32_16x16x32_bf16 v[8:11], v[60:63], v[16:19], v[174:177]
	v_mfma_f32_16x16x32_bf16 v[16:19], v[56:59], v[32:35], v[178:181]
	v_mfma_f32_16x16x32_bf16 v[32:35], v[60:63], v[32:35], v[194:197]
	v_mfma_f32_16x16x32_bf16 v[128:131], v[56:59], v[40:43], v[170:173]
	v_mfma_f32_16x16x32_bf16 v[134:137], v[60:63], v[40:43], v[198:201]
	v_mfma_f32_16x16x32_bf16 v[138:141], v[56:59], v[230:233], v[202:205]
	v_mfma_f32_16x16x32_bf16 v[142:145], v[60:63], v[230:233], v[206:209]
	v_mfma_f32_16x16x32_bf16 v[60:63], v[234:237], v[24:27], v[0:3]
	v_mfma_f32_16x16x32_bf16 v[56:59], v[238:241], v[24:27], v[8:11]
	v_mfma_f32_16x16x32_bf16 v[40:43], v[234:237], v[222:225], v[16:19]
	v_mfma_f32_16x16x32_bf16 v[32:35], v[238:241], v[222:225], v[32:35]
	v_mfma_f32_16x16x32_bf16 v[24:27], v[234:237], v[226:229], v[128:131]
	v_mfma_f32_16x16x32_bf16 v[16:19], v[238:241], v[226:229], v[134:137]
	v_mfma_f32_16x16x32_bf16 v[8:11], v[234:237], v[242:245], v[138:141]
	v_mfma_f32_16x16x32_bf16 v[0:3], v[238:241], v[242:245], v[142:145]
	v_lshl_add_u64 v[128:129], s[28:29], 0, v[162:163]
	v_lshl_add_u64 v[130:131], s[28:29], 0, v[164:165]
	s_mov_b32 s67, 0
.Lrot_357:
	s_barrier
.LBB0_357:
	ds_read_b128 v[134:137], v190
	ds_read_b128 v[138:141], v190 offset:1024
	ds_read_b128 v[142:145], v190 offset:2048
	ds_read_b128 v[146:149], v190 offset:3072
	s_mov_b32 m0, s54
	v_lshl_add_u64 v[150:151], v[128:129], 0, s[34:35]
	ds_read_b128 v[166:169], v191
	ds_read_b128 v[170:173], v191 offset:1024
	ds_read_b128 v[174:177], v191 offset:2048
	ds_read_b128 v[178:181], v191 offset:3072
	ds_read_b128 v[194:197], v191 offset:4096
	ds_read_b128 v[198:201], v191 offset:5120
	ds_read_b128 v[202:205], v191 offset:6144
	ds_read_b128 v[206:209], v191 offset:7168
	global_load_lds_dwordx4 v[150:151], off
	s_mov_b32 m0, s55
	v_lshl_add_u64 v[150:151], v[130:131], 0, s[34:35]
	global_load_lds_dwordx4 v[150:151], off
	s_waitcnt lgkmcnt(8)
	s_barrier
	s_waitcnt lgkmcnt(0)
	v_mfma_f32_16x16x32_bf16 v[116:119], v[134:137], v[166:169], v[116:119]
	s_add_i32 s36, s34, 0xfff50080
	v_mfma_f32_16x16x32_bf16 v[112:115], v[142:145], v[166:169], v[112:115]
	s_cmp_eq_u32 s67, 40
	v_mfma_f32_16x16x32_bf16 v[108:111], v[134:137], v[174:177], v[108:111]
	s_cselect_b32 s69, s27, s29
	v_mfma_f32_16x16x32_bf16 v[104:107], v[142:145], v[174:177], v[104:107]
	s_cselect_b32 s68, s26, s28
	v_mfma_f32_16x16x32_bf16 v[92:95], v[134:137], v[194:197], v[92:95]
	s_cselect_b32 s37, s9, s31
	v_mfma_f32_16x16x32_bf16 v[88:91], v[142:145], v[194:197], v[88:91]
	s_cselect_b32 s70, s8, s30
	v_mfma_f32_16x16x32_bf16 v[76:79], v[134:137], v[202:205], v[76:79]
	v_mfma_f32_16x16x32_bf16 v[72:75], v[142:145], v[202:205], v[72:75]
	v_mfma_f32_16x16x32_bf16 v[116:119], v[138:141], v[170:173], v[116:119]
	v_mfma_f32_16x16x32_bf16 v[112:115], v[146:149], v[170:173], v[112:115]
	v_mfma_f32_16x16x32_bf16 v[108:111], v[138:141], v[178:181], v[108:111]
	v_mfma_f32_16x16x32_bf16 v[104:107], v[146:149], v[178:181], v[104:107]
	v_mfma_f32_16x16x32_bf16 v[92:95], v[138:141], v[198:201], v[92:95]
	v_mfma_f32_16x16x32_bf16 v[88:91], v[146:149], v[198:201], v[88:91]
	v_mfma_f32_16x16x32_bf16 v[76:79], v[138:141], v[206:209], v[76:79]
	v_mfma_f32_16x16x32_bf16 v[72:75], v[146:149], v[206:209], v[72:75]
	s_barrier
	s_cselect_b32 s71, 0, s36
	s_add_u32 s36, s70, s71
	s_addc_u32 s37, s37, 0
	s_mov_b32 m0, s56
	v_lshl_add_u64 v[150:151], s[36:37], 0, v[156:157]
	ds_read_b128 v[210:213], v192
	ds_read_b128 v[214:217], v192 offset:1024
	ds_read_b128 v[222:225], v192 offset:2048
	ds_read_b128 v[226:229], v192 offset:3072
	global_load_lds_dwordx4 v[150:151], off
	s_mov_b32 m0, s57
	v_lshl_add_u64 v[182:183], s[36:37], 0, v[160:161]
	global_load_lds_dwordx4 v[182:183], off
	s_barrier
	s_waitcnt lgkmcnt(0)
	v_mfma_f32_16x16x32_bf16 v[124:127], v[210:213], v[166:169], v[124:127]
	v_mfma_f32_16x16x32_bf16 v[120:123], v[222:225], v[166:169], v[120:123]
	v_mfma_f32_16x16x32_bf16 v[100:103], v[210:213], v[174:177], v[100:103]
	v_mfma_f32_16x16x32_bf16 v[96:99], v[222:225], v[174:177], v[96:99]
	v_mfma_f32_16x16x32_bf16 v[84:87], v[210:213], v[194:197], v[84:87]
	v_mfma_f32_16x16x32_bf16 v[80:83], v[222:225], v[194:197], v[80:83]
	v_mfma_f32_16x16x32_bf16 v[68:71], v[210:213], v[202:205], v[68:71]
	v_mfma_f32_16x16x32_bf16 v[64:67], v[222:225], v[202:205], v[64:67]
	v_mfma_f32_16x16x32_bf16 v[124:127], v[214:217], v[170:173], v[124:127]
	v_mfma_f32_16x16x32_bf16 v[120:123], v[226:229], v[170:173], v[120:123]
	v_mfma_f32_16x16x32_bf16 v[100:103], v[214:217], v[178:181], v[100:103]
	v_mfma_f32_16x16x32_bf16 v[96:99], v[226:229], v[178:181], v[96:99]
	v_mfma_f32_16x16x32_bf16 v[84:87], v[214:217], v[198:201], v[84:87]
	v_mfma_f32_16x16x32_bf16 v[80:83], v[226:229], v[198:201], v[80:83]
	v_mfma_f32_16x16x32_bf16 v[68:71], v[214:217], v[206:209], v[68:71]
	v_mfma_f32_16x16x32_bf16 v[64:67], v[226:229], v[206:209], v[64:67]
	s_add_u32 s68, s68, s71
	s_addc_u32 s69, s69, 0
	s_mov_b32 m0, s46
	v_lshl_add_u64 v[218:219], s[68:69], 0, v[154:155]
	s_barrier
	ds_read_b128 v[166:169], v191 offset:16384
	ds_read_b128 v[170:173], v191 offset:17408
	ds_read_b128 v[174:177], v191 offset:18432
	ds_read_b128 v[178:181], v191 offset:19456
	ds_read_b128 v[194:197], v191 offset:20480
	ds_read_b128 v[198:201], v191 offset:21504
	ds_read_b128 v[202:205], v191 offset:22528
	ds_read_b128 v[206:209], v191 offset:23552
	global_load_lds_dwordx4 v[218:219], off
	s_mov_b32 m0, s47
	v_lshl_add_u64 v[230:231], s[68:69], 0, v[158:159]
	global_load_lds_dwordx4 v[230:231], off
	s_barrier
	s_waitcnt lgkmcnt(0)
	v_mfma_f32_16x16x32_bf16 v[52:55], v[134:137], v[166:169], v[52:55]
	v_mfma_f32_16x16x32_bf16 v[48:51], v[142:145], v[166:169], v[48:51]
	v_mfma_f32_16x16x32_bf16 v[44:47], v[134:137], v[174:177], v[44:47]
	v_mfma_f32_16x16x32_bf16 v[36:39], v[142:145], v[174:177], v[36:39]
	v_mfma_f32_16x16x32_bf16 v[28:31], v[134:137], v[194:197], v[28:31]
	v_mfma_f32_16x16x32_bf16 v[20:23], v[142:145], v[194:197], v[20:23]
	v_mfma_f32_16x16x32_bf16 v[12:15], v[134:137], v[202:205], v[12:15]
	v_mfma_f32_16x16x32_bf16 v[4:7], v[142:145], v[202:205], v[4:7]
	v_mfma_f32_16x16x32_bf16 v[52:55], v[138:141], v[170:173], v[52:55]
	v_mfma_f32_16x16x32_bf16 v[48:51], v[146:149], v[170:173], v[48:51]
	v_mfma_f32_16x16x32_bf16 v[44:47], v[138:141], v[178:181], v[44:47]
	v_mfma_f32_16x16x32_bf16 v[36:39], v[146:149], v[178:181], v[36:39]
	v_mfma_f32_16x16x32_bf16 v[28:31], v[138:141], v[198:201], v[28:31]
	v_mfma_f32_16x16x32_bf16 v[20:23], v[146:149], v[198:201], v[20:23]
	v_mfma_f32_16x16x32_bf16 v[12:15], v[138:141], v[206:209], v[12:15]
	v_mfma_f32_16x16x32_bf16 v[4:7], v[146:149], v[206:209], v[4:7]
	s_barrier
	s_add_u32 s70, s36, 0xb0000
	s_addc_u32 s71, s37, 0
	s_mov_b32 m0, s0
	v_lshl_add_u64 v[134:135], s[70:71], 0, v[156:157]
	global_load_lds_dwordx4 v[134:135], off
	s_mov_b32 m0, s62
	v_lshl_add_u64 v[134:135], s[70:71], 0, v[160:161]
	global_load_lds_dwordx4 v[134:135], off
	s_waitcnt vmcnt(6)
	s_barrier
	v_mfma_f32_16x16x32_bf16 v[60:63], v[210:213], v[166:169], v[60:63]
	v_mfma_f32_16x16x32_bf16 v[56:59], v[222:225], v[166:169], v[56:59]
	v_mfma_f32_16x16x32_bf16 v[40:43], v[210:213], v[174:177], v[40:43]
	v_mfma_f32_16x16x32_bf16 v[32:35], v[222:225], v[174:177], v[32:35]
	v_mfma_f32_16x16x32_bf16 v[24:27], v[210:213], v[194:197], v[24:27]
	v_mfma_f32_16x16x32_bf16 v[16:19], v[222:225], v[194:197], v[16:19]
	v_mfma_f32_16x16x32_bf16 v[8:11], v[210:213], v[202:205], v[8:11]
	v_mfma_f32_16x16x32_bf16 v[0:3], v[222:225], v[202:205], v[0:3]
	v_mfma_f32_16x16x32_bf16 v[60:63], v[214:217], v[170:173], v[60:63]
	v_mfma_f32_16x16x32_bf16 v[56:59], v[226:229], v[170:173], v[56:59]
	v_mfma_f32_16x16x32_bf16 v[40:43], v[214:217], v[178:181], v[40:43]
	v_mfma_f32_16x16x32_bf16 v[32:35], v[226:229], v[178:181], v[32:35]
	v_mfma_f32_16x16x32_bf16 v[24:27], v[214:217], v[198:201], v[24:27]
	v_mfma_f32_16x16x32_bf16 v[16:19], v[226:229], v[198:201], v[16:19]
	v_mfma_f32_16x16x32_bf16 v[8:11], v[214:217], v[206:209], v[8:11]
	v_mfma_f32_16x16x32_bf16 v[0:3], v[226:229], v[206:209], v[0:3]
	s_barrier
	ds_read_b128 v[134:137], v132
	ds_read_b128 v[138:141], v132 offset:1024
	ds_read_b128 v[142:145], v132 offset:2048
	ds_read_b128 v[146:149], v132 offset:3072
	s_add_u32 s68, s68, 0xb0000
	s_addc_u32 s69, s69, 0
	s_mov_b32 m0, s48
	v_lshl_add_u64 v[210:211], s[68:69], 0, v[154:155]
	ds_read_b128 v[166:169], v191 offset:32768
	ds_read_b128 v[170:173], v191 offset:33792
	ds_read_b128 v[174:177], v191 offset:34816
	ds_read_b128 v[178:181], v191 offset:35840
	ds_read_b128 v[194:197], v191 offset:36864
	ds_read_b128 v[198:201], v191 offset:37888
	ds_read_b128 v[202:205], v191 offset:38912
	ds_read_b128 v[206:209], v191 offset:39936
	global_load_lds_dwordx4 v[210:211], off
	s_mov_b32 m0, s49
	v_lshl_add_u64 v[210:211], s[68:69], 0, v[158:159]
	global_load_lds_dwordx4 v[210:211], off
	s_waitcnt lgkmcnt(8)
	s_barrier
	s_waitcnt lgkmcnt(0)
	v_mfma_f32_16x16x32_bf16 v[116:119], v[134:137], v[166:169], v[116:119]
	v_mfma_f32_16x16x32_bf16 v[112:115], v[142:145], v[166:169], v[112:115]
	v_mfma_f32_16x16x32_bf16 v[108:111], v[134:137], v[174:177], v[108:111]
	v_mfma_f32_16x16x32_bf16 v[104:107], v[142:145], v[174:177], v[104:107]
	v_mfma_f32_16x16x32_bf16 v[92:95], v[134:137], v[194:197], v[92:95]
	v_mfma_f32_16x16x32_bf16 v[88:91], v[142:145], v[194:197], v[88:91]
	v_mfma_f32_16x16x32_bf16 v[76:79], v[134:137], v[202:205], v[76:79]
	v_mfma_f32_16x16x32_bf16 v[72:75], v[142:145], v[202:205], v[72:75]
	v_mfma_f32_16x16x32_bf16 v[116:119], v[138:141], v[170:173], v[116:119]
	v_mfma_f32_16x16x32_bf16 v[112:115], v[146:149], v[170:173], v[112:115]
	v_mfma_f32_16x16x32_bf16 v[108:111], v[138:141], v[178:181], v[108:111]
	v_mfma_f32_16x16x32_bf16 v[104:107], v[146:149], v[178:181], v[104:107]
	v_mfma_f32_16x16x32_bf16 v[92:95], v[138:141], v[198:201], v[92:95]
	v_mfma_f32_16x16x32_bf16 v[88:91], v[146:149], v[198:201], v[88:91]
	v_mfma_f32_16x16x32_bf16 v[76:79], v[138:141], v[206:209], v[76:79]
	v_mfma_f32_16x16x32_bf16 v[72:75], v[146:149], v[206:209], v[72:75]
	s_barrier
	s_mov_b32 m0, s63
	v_lshl_add_u64 v[150:151], v[150:151], 0, s[10:11]
	ds_read_b128 v[210:213], v133
	ds_read_b128 v[214:217], v133 offset:1024
	ds_read_b128 v[222:225], v133 offset:2048
	ds_read_b128 v[226:229], v133 offset:3072
	global_load_lds_dwordx4 v[150:151], off
	s_mov_b32 m0, s64
	v_lshl_add_u64 v[150:151], v[182:183], 0, s[10:11]
	global_load_lds_dwordx4 v[150:151], off
	s_barrier
	s_waitcnt lgkmcnt(0)
	v_mfma_f32_16x16x32_bf16 v[124:127], v[210:213], v[166:169], v[124:127]
	v_mfma_f32_16x16x32_bf16 v[120:123], v[222:225], v[166:169], v[120:123]
	v_mfma_f32_16x16x32_bf16 v[100:103], v[210:213], v[174:177], v[100:103]
	v_mfma_f32_16x16x32_bf16 v[96:99], v[222:225], v[174:177], v[96:99]
	v_mfma_f32_16x16x32_bf16 v[84:87], v[210:213], v[194:197], v[84:87]
	v_mfma_f32_16x16x32_bf16 v[80:83], v[222:225], v[194:197], v[80:83]
	v_mfma_f32_16x16x32_bf16 v[68:71], v[210:213], v[202:205], v[68:71]
	v_mfma_f32_16x16x32_bf16 v[64:67], v[222:225], v[202:205], v[64:67]
	v_mfma_f32_16x16x32_bf16 v[124:127], v[214:217], v[170:173], v[124:127]
	v_mfma_f32_16x16x32_bf16 v[120:123], v[226:229], v[170:173], v[120:123]
	v_mfma_f32_16x16x32_bf16 v[100:103], v[214:217], v[178:181], v[100:103]
	v_mfma_f32_16x16x32_bf16 v[96:99], v[226:229], v[178:181], v[96:99]
	v_mfma_f32_16x16x32_bf16 v[84:87], v[214:217], v[198:201], v[84:87]
	v_mfma_f32_16x16x32_bf16 v[80:83], v[226:229], v[198:201], v[80:83]
	v_mfma_f32_16x16x32_bf16 v[68:71], v[214:217], v[206:209], v[68:71]
	v_mfma_f32_16x16x32_bf16 v[64:67], v[226:229], v[206:209], v[64:67]
	s_mov_b32 m0, s51
	v_lshl_add_u64 v[150:151], v[218:219], 0, s[10:11]
	s_barrier
	ds_read_b128 v[166:169], v191 offset:49152
	ds_read_b128 v[170:173], v191 offset:50176
	ds_read_b128 v[174:177], v191 offset:51200
	ds_read_b128 v[178:181], v191 offset:52224
	ds_read_b128 v[194:197], v191 offset:53248
	ds_read_b128 v[198:201], v191 offset:54272
	ds_read_b128 v[202:205], v191 offset:55296
	ds_read_b128 v[206:209], v191 offset:56320
	global_load_lds_dwordx4 v[150:151], off
	s_mov_b32 m0, s52
	v_lshl_add_u64 v[150:151], v[230:231], 0, s[10:11]
	global_load_lds_dwordx4 v[150:151], off
	s_barrier
	s_waitcnt lgkmcnt(0)
	v_mfma_f32_16x16x32_bf16 v[52:55], v[134:137], v[166:169], v[52:55]
	v_mfma_f32_16x16x32_bf16 v[48:51], v[142:145], v[166:169], v[48:51]
	v_mfma_f32_16x16x32_bf16 v[44:47], v[134:137], v[174:177], v[44:47]
	v_mfma_f32_16x16x32_bf16 v[36:39], v[142:145], v[174:177], v[36:39]
	v_mfma_f32_16x16x32_bf16 v[28:31], v[134:137], v[194:197], v[28:31]
	v_mfma_f32_16x16x32_bf16 v[20:23], v[142:145], v[194:197], v[20:23]
	v_mfma_f32_16x16x32_bf16 v[12:15], v[134:137], v[202:205], v[12:15]
	v_mfma_f32_16x16x32_bf16 v[4:7], v[142:145], v[202:205], v[4:7]
	v_mfma_f32_16x16x32_bf16 v[52:55], v[138:141], v[170:173], v[52:55]
	v_mfma_f32_16x16x32_bf16 v[48:51], v[146:149], v[170:173], v[48:51]
	v_mfma_f32_16x16x32_bf16 v[44:47], v[138:141], v[178:181], v[44:47]
	v_mfma_f32_16x16x32_bf16 v[36:39], v[146:149], v[178:181], v[36:39]
	v_mfma_f32_16x16x32_bf16 v[28:31], v[138:141], v[198:201], v[28:31]
	v_mfma_f32_16x16x32_bf16 v[20:23], v[146:149], v[198:201], v[20:23]
	v_mfma_f32_16x16x32_bf16 v[12:15], v[138:141], v[206:209], v[12:15]
	v_mfma_f32_16x16x32_bf16 v[4:7], v[146:149], v[206:209], v[4:7]
	s_barrier
	s_add_u32 s36, s36, 0xb0080
	s_addc_u32 s37, s37, 0
	s_mov_b32 m0, s65
	v_lshl_add_u64 v[134:135], s[36:37], 0, v[156:157]
	global_load_lds_dwordx4 v[134:135], off
	s_mov_b32 m0, s66
	v_lshl_add_u64 v[134:135], s[36:37], 0, v[160:161]
	global_load_lds_dwordx4 v[134:135], off
	s_waitcnt vmcnt(6)
	s_barrier
	v_mfma_f32_16x16x32_bf16 v[60:63], v[210:213], v[166:169], v[60:63]
	v_mfma_f32_16x16x32_bf16 v[56:59], v[222:225], v[166:169], v[56:59]
	v_mfma_f32_16x16x32_bf16 v[40:43], v[210:213], v[174:177], v[40:43]
	v_mfma_f32_16x16x32_bf16 v[32:35], v[222:225], v[174:177], v[32:35]
	v_mfma_f32_16x16x32_bf16 v[24:27], v[210:213], v[194:197], v[24:27]
	v_mfma_f32_16x16x32_bf16 v[16:19], v[222:225], v[194:197], v[16:19]
	v_mfma_f32_16x16x32_bf16 v[8:11], v[210:213], v[202:205], v[8:11]
	v_mfma_f32_16x16x32_bf16 v[0:3], v[222:225], v[202:205], v[0:3]
	v_mfma_f32_16x16x32_bf16 v[60:63], v[214:217], v[170:173], v[60:63]
	v_mfma_f32_16x16x32_bf16 v[56:59], v[226:229], v[170:173], v[56:59]
	v_mfma_f32_16x16x32_bf16 v[40:43], v[214:217], v[178:181], v[40:43]
	v_mfma_f32_16x16x32_bf16 v[32:35], v[226:229], v[178:181], v[32:35]
	v_mfma_f32_16x16x32_bf16 v[24:27], v[214:217], v[198:201], v[24:27]
	v_mfma_f32_16x16x32_bf16 v[16:19], v[226:229], v[198:201], v[16:19]
	v_mfma_f32_16x16x32_bf16 v[8:11], v[214:217], v[206:209], v[8:11]
	v_mfma_f32_16x16x32_bf16 v[0:3], v[226:229], v[206:209], v[0:3]
	s_add_i32 s67, s67, 2
	s_add_u32 s34, s34, 0x100
	s_addc_u32 s35, s35, 0
	s_cmp_gt_u32 s67, 39
	s_cbranch_scc0 .Lrot_357
	s_barrier
	ds_read_b128 v[134:137], v190
	ds_read_b128 v[138:141], v190 offset:1024
	ds_read_b128 v[142:145], v190 offset:2048
	ds_read_b128 v[146:149], v190 offset:3072
	s_mov_b32 m0, s54
	v_lshl_add_u64 v[150:151], v[128:129], 0, s[34:35]
	ds_read_b128 v[166:169], v191
	ds_read_b128 v[170:173], v191 offset:1024
	ds_read_b128 v[174:177], v191 offset:2048
	ds_read_b128 v[178:181], v191 offset:3072
	ds_read_b128 v[194:197], v191 offset:4096
	ds_read_b128 v[198:201], v191 offset:5120
	ds_read_b128 v[202:205], v191 offset:6144
	ds_read_b128 v[206:209], v191 offset:7168
	global_load_lds_dwordx4 v[150:151], off
	s_mov_b32 m0, s55
	v_lshl_add_u64 v[150:151], v[130:131], 0, s[34:35]
	global_load_lds_dwordx4 v[150:151], off
	s_waitcnt lgkmcnt(8)
	s_barrier
	s_waitcnt lgkmcnt(0)
	v_mfma_f32_16x16x32_bf16 v[116:119], v[134:137], v[166:169], v[116:119]
	s_add_i32 s36, s34, 0xfff50080
	v_mfma_f32_16x16x32_bf16 v[112:115], v[142:145], v[166:169], v[112:115]
	s_cmp_eq_u32 s67, 40
	v_mfma_f32_16x16x32_bf16 v[108:111], v[134:137], v[174:177], v[108:111]
	s_cselect_b32 s69, s27, s29
	v_mfma_f32_16x16x32_bf16 v[104:107], v[142:145], v[174:177], v[104:107]
	s_cselect_b32 s68, s26, s28
	v_mfma_f32_16x16x32_bf16 v[92:95], v[134:137], v[194:197], v[92:95]
	s_cselect_b32 s37, s9, s31
	v_mfma_f32_16x16x32_bf16 v[88:91], v[142:145], v[194:197], v[88:91]
	s_cselect_b32 s70, s8, s30
	v_mfma_f32_16x16x32_bf16 v[76:79], v[134:137], v[202:205], v[76:79]
	v_mfma_f32_16x16x32_bf16 v[72:75], v[142:145], v[202:205], v[72:75]
	v_mfma_f32_16x16x32_bf16 v[116:119], v[138:141], v[170:173], v[116:119]
	v_mfma_f32_16x16x32_bf16 v[112:115], v[146:149], v[170:173], v[112:115]
	v_mfma_f32_16x16x32_bf16 v[108:111], v[138:141], v[178:181], v[108:111]
	v_mfma_f32_16x16x32_bf16 v[104:107], v[146:149], v[178:181], v[104:107]
	v_mfma_f32_16x16x32_bf16 v[92:95], v[138:141], v[198:201], v[92:95]
	v_mfma_f32_16x16x32_bf16 v[88:91], v[146:149], v[198:201], v[88:91]
	v_mfma_f32_16x16x32_bf16 v[76:79], v[138:141], v[206:209], v[76:79]
	v_mfma_f32_16x16x32_bf16 v[72:75], v[146:149], v[206:209], v[72:75]
	s_barrier
	s_cselect_b32 s71, 0, s36
	s_add_u32 s36, s70, s71
	s_addc_u32 s37, s37, 0
	s_mov_b32 m0, s56
	v_lshl_add_u64 v[150:151], s[36:37], 0, v[156:157]
	ds_read_b128 v[210:213], v192
	ds_read_b128 v[214:217], v192 offset:1024
	ds_read_b128 v[222:225], v192 offset:2048
	ds_read_b128 v[226:229], v192 offset:3072
	global_load_lds_dwordx4 v[150:151], off
	s_mov_b32 m0, s57
	v_lshl_add_u64 v[182:183], s[36:37], 0, v[160:161]
	global_load_lds_dwordx4 v[182:183], off
	s_barrier
	s_waitcnt lgkmcnt(0)
	v_mfma_f32_16x16x32_bf16 v[124:127], v[210:213], v[166:169], v[124:127]
	v_mfma_f32_16x16x32_bf16 v[120:123], v[222:225], v[166:169], v[120:123]
	v_mfma_f32_16x16x32_bf16 v[100:103], v[210:213], v[174:177], v[100:103]
	v_mfma_f32_16x16x32_bf16 v[96:99], v[222:225], v[174:177], v[96:99]
	v_mfma_f32_16x16x32_bf16 v[84:87], v[210:213], v[194:197], v[84:87]
	v_mfma_f32_16x16x32_bf16 v[80:83], v[222:225], v[194:197], v[80:83]
	v_mfma_f32_16x16x32_bf16 v[68:71], v[210:213], v[202:205], v[68:71]
	v_mfma_f32_16x16x32_bf16 v[64:67], v[222:225], v[202:205], v[64:67]
	v_mfma_f32_16x16x32_bf16 v[124:127], v[214:217], v[170:173], v[124:127]
	v_mfma_f32_16x16x32_bf16 v[120:123], v[226:229], v[170:173], v[120:123]
	v_mfma_f32_16x16x32_bf16 v[100:103], v[214:217], v[178:181], v[100:103]
	v_mfma_f32_16x16x32_bf16 v[96:99], v[226:229], v[178:181], v[96:99]
	v_mfma_f32_16x16x32_bf16 v[84:87], v[214:217], v[198:201], v[84:87]
	v_mfma_f32_16x16x32_bf16 v[80:83], v[226:229], v[198:201], v[80:83]
	v_mfma_f32_16x16x32_bf16 v[68:71], v[214:217], v[206:209], v[68:71]
	v_mfma_f32_16x16x32_bf16 v[64:67], v[226:229], v[206:209], v[64:67]
	s_add_u32 s68, s68, s71
	s_addc_u32 s69, s69, 0
	s_mov_b32 m0, s46
	v_lshl_add_u64 v[218:219], s[68:69], 0, v[154:155]
	s_barrier
	ds_read_b128 v[166:169], v191 offset:16384
	ds_read_b128 v[170:173], v191 offset:17408
	ds_read_b128 v[174:177], v191 offset:18432
	ds_read_b128 v[178:181], v191 offset:19456
	ds_read_b128 v[194:197], v191 offset:20480
	ds_read_b128 v[198:201], v191 offset:21504
	ds_read_b128 v[202:205], v191 offset:22528
	ds_read_b128 v[206:209], v191 offset:23552
	global_load_lds_dwordx4 v[218:219], off
	s_mov_b32 m0, s47
	v_lshl_add_u64 v[230:231], s[68:69], 0, v[158:159]
	global_load_lds_dwordx4 v[230:231], off
	s_barrier
	s_waitcnt lgkmcnt(0)
	v_mfma_f32_16x16x32_bf16 v[52:55], v[134:137], v[166:169], v[52:55]
	v_mfma_f32_16x16x32_bf16 v[48:51], v[142:145], v[166:169], v[48:51]
	v_mfma_f32_16x16x32_bf16 v[44:47], v[134:137], v[174:177], v[44:47]
	v_mfma_f32_16x16x32_bf16 v[36:39], v[142:145], v[174:177], v[36:39]
	v_mfma_f32_16x16x32_bf16 v[28:31], v[134:137], v[194:197], v[28:31]
	v_mfma_f32_16x16x32_bf16 v[20:23], v[142:145], v[194:197], v[20:23]
	v_mfma_f32_16x16x32_bf16 v[12:15], v[134:137], v[202:205], v[12:15]
	v_mfma_f32_16x16x32_bf16 v[4:7], v[142:145], v[202:205], v[4:7]
	v_mfma_f32_16x16x32_bf16 v[52:55], v[138:141], v[170:173], v[52:55]
	v_mfma_f32_16x16x32_bf16 v[48:51], v[146:149], v[170:173], v[48:51]
	v_mfma_f32_16x16x32_bf16 v[44:47], v[138:141], v[178:181], v[44:47]
	v_mfma_f32_16x16x32_bf16 v[36:39], v[146:149], v[178:181], v[36:39]
	v_mfma_f32_16x16x32_bf16 v[28:31], v[138:141], v[198:201], v[28:31]
	v_mfma_f32_16x16x32_bf16 v[20:23], v[146:149], v[198:201], v[20:23]
	v_mfma_f32_16x16x32_bf16 v[12:15], v[138:141], v[206:209], v[12:15]
	v_mfma_f32_16x16x32_bf16 v[4:7], v[146:149], v[206:209], v[4:7]
	s_barrier
;     __device__ __forceinline__ void epi(const f32x4 (&acc)[2][2][4][2], const Unit& u, int wr, int wc, int fr, int fq) const {
;     ...
;                 for (int bj = 0; bj < 2; ++bj) xo[m][bj] = *(const u32x4*)(xb + (size_t)(row0 + ai * 128 + m * 16) * D + col0 + bj * 128);
	s_add_u32 s70, s36, 0xb0000
	s_addc_u32 s71, s37, 0
	s_mov_b32 m0, s0
	v_lshl_add_u64 v[134:135], s[70:71], 0, v[156:157]
	global_load_lds_dwordx4 v[134:135], off
	s_mov_b32 m0, s62
	v_lshl_add_u64 v[134:135], s[70:71], 0, v[160:161]
	global_load_lds_dwordx4 v[134:135], off
	s_waitcnt vmcnt(6)
	s_barrier
	v_mfma_f32_16x16x32_bf16 v[60:63], v[210:213], v[166:169], v[60:63]
	v_lshl_or_b32 v248, s40, 8, v189
	v_mfma_f32_16x16x32_bf16 v[56:59], v[222:225], v[166:169], v[56:59]
	v_lshl_add_u32 v250, s61, 8, v153
	v_mfma_f32_16x16x32_bf16 v[40:43], v[210:213], v[174:177], v[40:43]
	v_ashrrev_i32_e32 v249, 31, v248
	v_mfma_f32_16x16x32_bf16 v[32:35], v[222:225], v[174:177], v[32:35]
	v_lshlrev_b64 v[248:249], 1, v[248:249]
	v_mfma_f32_16x16x32_bf16 v[24:27], v[210:213], v[194:197], v[24:27]
	v_ashrrev_i32_e32 v251, 31, v250
	v_mfma_f32_16x16x32_bf16 v[16:19], v[222:225], v[194:197], v[16:19]
	v_lshl_add_u64 v[248:249], s[20:21], 0, v[248:249]
	v_mfma_f32_16x16x32_bf16 v[8:11], v[210:213], v[202:205], v[8:11]
	v_lshlrev_b64 v[250:251], 11, v[250:251]
	v_mfma_f32_16x16x32_bf16 v[0:3], v[222:225], v[202:205], v[0:3]
	v_lshl_add_u64 v[252:253], v[248:249], 0, v[250:251]
	v_mfma_f32_16x16x32_bf16 v[60:63], v[214:217], v[170:173], v[60:63]
	global_load_dwordx4 v[232:235], v[252:253], off
	v_mfma_f32_16x16x32_bf16 v[56:59], v[226:229], v[170:173], v[56:59]
	global_load_dwordx4 v[236:239], v[252:253], off offset:256
	v_mfma_f32_16x16x32_bf16 v[40:43], v[214:217], v[178:181], v[40:43]
	v_mov_b32_e32 v250, 0x8000
	v_mfma_f32_16x16x32_bf16 v[32:35], v[226:229], v[178:181], v[32:35]
	v_mov_b32_e32 v251, 0
	v_mfma_f32_16x16x32_bf16 v[24:27], v[214:217], v[198:201], v[24:27]
	v_lshl_add_u64 v[250:251], v[252:253], 0, v[250:251]
	v_mfma_f32_16x16x32_bf16 v[16:19], v[226:229], v[198:201], v[16:19]
	global_load_dwordx4 v[240:243], v[250:251], off
	v_mfma_f32_16x16x32_bf16 v[8:11], v[214:217], v[206:209], v[8:11]
	global_load_dwordx4 v[244:247], v[250:251], off offset:256
	v_mfma_f32_16x16x32_bf16 v[0:3], v[226:229], v[206:209], v[0:3]
	s_barrier
	ds_read_b128 v[134:137], v132
	ds_read_b128 v[138:141], v132 offset:1024
	ds_read_b128 v[142:145], v132 offset:2048
	ds_read_b128 v[146:149], v132 offset:3072
	s_add_u32 s68, s68, 0xb0000
	s_addc_u32 s69, s69, 0
	s_mov_b32 m0, s48
	v_lshl_add_u64 v[210:211], s[68:69], 0, v[154:155]
	ds_read_b128 v[166:169], v191 offset:32768
	ds_read_b128 v[170:173], v191 offset:33792
	ds_read_b128 v[174:177], v191 offset:34816
	ds_read_b128 v[178:181], v191 offset:35840
	ds_read_b128 v[194:197], v191 offset:36864
	ds_read_b128 v[198:201], v191 offset:37888
	ds_read_b128 v[202:205], v191 offset:38912
	ds_read_b128 v[206:209], v191 offset:39936
	global_load_lds_dwordx4 v[210:211], off
	s_mov_b32 m0, s49
	v_lshl_add_u64 v[210:211], s[68:69], 0, v[158:159]
	global_load_lds_dwordx4 v[210:211], off
	s_waitcnt lgkmcnt(8)
	s_barrier
	s_waitcnt lgkmcnt(0)
	v_mfma_f32_16x16x32_bf16 v[116:119], v[134:137], v[166:169], v[116:119]
	v_mfma_f32_16x16x32_bf16 v[112:115], v[142:145], v[166:169], v[112:115]
	v_mfma_f32_16x16x32_bf16 v[108:111], v[134:137], v[174:177], v[108:111]
	v_mfma_f32_16x16x32_bf16 v[104:107], v[142:145], v[174:177], v[104:107]
	v_mfma_f32_16x16x32_bf16 v[92:95], v[134:137], v[194:197], v[92:95]
	v_mfma_f32_16x16x32_bf16 v[88:91], v[142:145], v[194:197], v[88:91]
	v_mfma_f32_16x16x32_bf16 v[76:79], v[134:137], v[202:205], v[76:79]
	v_mfma_f32_16x16x32_bf16 v[72:75], v[142:145], v[202:205], v[72:75]
	v_mfma_f32_16x16x32_bf16 v[116:119], v[138:141], v[170:173], v[116:119]
	v_mfma_f32_16x16x32_bf16 v[112:115], v[146:149], v[170:173], v[112:115]
	v_mfma_f32_16x16x32_bf16 v[108:111], v[138:141], v[178:181], v[108:111]
	v_mfma_f32_16x16x32_bf16 v[104:107], v[146:149], v[178:181], v[104:107]
	v_mfma_f32_16x16x32_bf16 v[92:95], v[138:141], v[198:201], v[92:95]
	v_mfma_f32_16x16x32_bf16 v[88:91], v[146:149], v[198:201], v[88:91]
	v_mfma_f32_16x16x32_bf16 v[76:79], v[138:141], v[206:209], v[76:79]
	v_mfma_f32_16x16x32_bf16 v[72:75], v[146:149], v[206:209], v[72:75]
	s_barrier
	s_mov_b32 m0, s63
	v_lshl_add_u64 v[150:151], v[150:151], 0, s[10:11]
	ds_read_b128 v[210:213], v133
	ds_read_b128 v[214:217], v133 offset:1024
	ds_read_b128 v[222:225], v133 offset:2048
	ds_read_b128 v[226:229], v133 offset:3072
	global_load_lds_dwordx4 v[150:151], off
	s_mov_b32 m0, s64
	v_lshl_add_u64 v[150:151], v[182:183], 0, s[10:11]
	global_load_lds_dwordx4 v[150:151], off
	s_barrier
	s_waitcnt lgkmcnt(0)
	v_mfma_f32_16x16x32_bf16 v[124:127], v[210:213], v[166:169], v[124:127]
	v_mfma_f32_16x16x32_bf16 v[120:123], v[222:225], v[166:169], v[120:123]
	v_mfma_f32_16x16x32_bf16 v[100:103], v[210:213], v[174:177], v[100:103]
	v_mfma_f32_16x16x32_bf16 v[96:99], v[222:225], v[174:177], v[96:99]
	v_mfma_f32_16x16x32_bf16 v[84:87], v[210:213], v[194:197], v[84:87]
	v_mfma_f32_16x16x32_bf16 v[80:83], v[222:225], v[194:197], v[80:83]
	v_mfma_f32_16x16x32_bf16 v[68:71], v[210:213], v[202:205], v[68:71]
	v_mfma_f32_16x16x32_bf16 v[64:67], v[222:225], v[202:205], v[64:67]
	v_mfma_f32_16x16x32_bf16 v[124:127], v[214:217], v[170:173], v[124:127]
	v_mfma_f32_16x16x32_bf16 v[120:123], v[226:229], v[170:173], v[120:123]
	v_mfma_f32_16x16x32_bf16 v[100:103], v[214:217], v[178:181], v[100:103]
	v_mfma_f32_16x16x32_bf16 v[96:99], v[226:229], v[178:181], v[96:99]
	v_mfma_f32_16x16x32_bf16 v[84:87], v[214:217], v[198:201], v[84:87]
	v_mfma_f32_16x16x32_bf16 v[80:83], v[226:229], v[198:201], v[80:83]
	v_mfma_f32_16x16x32_bf16 v[68:71], v[214:217], v[206:209], v[68:71]
	v_mfma_f32_16x16x32_bf16 v[64:67], v[226:229], v[206:209], v[64:67]
	s_mov_b32 m0, s51
	v_lshl_add_u64 v[150:151], v[218:219], 0, s[10:11]
	s_barrier
;     ...
;         G_PAIR(0, 1);
; #pragma unroll 1
;         for (int t = 2; t < nt; t += 2) G_PAIR(t, 0);
	ds_read_b128 v[166:169], v191 offset:49152
	ds_read_b128 v[170:173], v191 offset:50176
	ds_read_b128 v[174:177], v191 offset:51200
	ds_read_b128 v[178:181], v191 offset:52224
	ds_read_b128 v[194:197], v191 offset:53248
	ds_read_b128 v[198:201], v191 offset:54272
	ds_read_b128 v[202:205], v191 offset:55296
	ds_read_b128 v[206:209], v191 offset:56320
	global_load_lds_dwordx4 v[150:151], off
	s_mov_b32 m0, s52
	v_lshl_add_u64 v[150:151], v[230:231], 0, s[10:11]
	global_load_lds_dwordx4 v[150:151], off
	s_barrier
	s_waitcnt lgkmcnt(0)
	v_mfma_f32_16x16x32_bf16 v[52:55], v[134:137], v[166:169], v[52:55]
	v_mfma_f32_16x16x32_bf16 v[48:51], v[142:145], v[166:169], v[48:51]
	v_mfma_f32_16x16x32_bf16 v[44:47], v[134:137], v[174:177], v[44:47]
	v_mfma_f32_16x16x32_bf16 v[36:39], v[142:145], v[174:177], v[36:39]
	v_mfma_f32_16x16x32_bf16 v[28:31], v[134:137], v[194:197], v[28:31]
	v_mfma_f32_16x16x32_bf16 v[20:23], v[142:145], v[194:197], v[20:23]
	v_mfma_f32_16x16x32_bf16 v[12:15], v[134:137], v[202:205], v[12:15]
	v_mfma_f32_16x16x32_bf16 v[4:7], v[142:145], v[202:205], v[4:7]
	v_mfma_f32_16x16x32_bf16 v[52:55], v[138:141], v[170:173], v[52:55]
	v_mfma_f32_16x16x32_bf16 v[48:51], v[146:149], v[170:173], v[48:51]
	v_mfma_f32_16x16x32_bf16 v[44:47], v[138:141], v[178:181], v[44:47]
	v_mfma_f32_16x16x32_bf16 v[36:39], v[146:149], v[178:181], v[36:39]
	v_mfma_f32_16x16x32_bf16 v[28:31], v[138:141], v[198:201], v[28:31]
	v_mfma_f32_16x16x32_bf16 v[20:23], v[146:149], v[198:201], v[20:23]
	v_mfma_f32_16x16x32_bf16 v[12:15], v[138:141], v[206:209], v[12:15]
	v_mfma_f32_16x16x32_bf16 v[4:7], v[146:149], v[206:209], v[4:7]
	s_barrier
	s_add_u32 s36, s36, 0xb0080
	s_addc_u32 s37, s37, 0
	s_mov_b32 m0, s65
	v_lshl_add_u64 v[134:135], s[36:37], 0, v[156:157]
	global_load_lds_dwordx4 v[134:135], off
	s_mov_b32 m0, s66
	v_lshl_add_u64 v[134:135], s[36:37], 0, v[160:161]
	global_load_lds_dwordx4 v[134:135], off
	s_waitcnt vmcnt(6)
	s_barrier
	v_mfma_f32_16x16x32_bf16 v[60:63], v[210:213], v[166:169], v[60:63]
	v_mfma_f32_16x16x32_bf16 v[56:59], v[222:225], v[166:169], v[56:59]
	v_mfma_f32_16x16x32_bf16 v[40:43], v[210:213], v[174:177], v[40:43]
	v_mfma_f32_16x16x32_bf16 v[32:35], v[222:225], v[174:177], v[32:35]
	v_mfma_f32_16x16x32_bf16 v[24:27], v[210:213], v[194:197], v[24:27]
	v_mfma_f32_16x16x32_bf16 v[16:19], v[222:225], v[194:197], v[16:19]
	v_mfma_f32_16x16x32_bf16 v[8:11], v[210:213], v[202:205], v[8:11]
	v_mfma_f32_16x16x32_bf16 v[0:3], v[222:225], v[202:205], v[0:3]
	v_mfma_f32_16x16x32_bf16 v[60:63], v[214:217], v[170:173], v[60:63]
	v_mfma_f32_16x16x32_bf16 v[56:59], v[226:229], v[170:173], v[56:59]
	v_mfma_f32_16x16x32_bf16 v[40:43], v[214:217], v[178:181], v[40:43]
	v_mfma_f32_16x16x32_bf16 v[32:35], v[226:229], v[178:181], v[32:35]
	v_mfma_f32_16x16x32_bf16 v[24:27], v[214:217], v[198:201], v[24:27]
	v_mfma_f32_16x16x32_bf16 v[16:19], v[226:229], v[198:201], v[16:19]
	v_mfma_f32_16x16x32_bf16 v[8:11], v[214:217], v[206:209], v[8:11]
	v_mfma_f32_16x16x32_bf16 v[0:3], v[226:229], v[206:209], v[0:3]
	s_add_i32 s67, s67, 2
	s_add_u32 s34, s34, 0x100
	s_addc_u32 s35, s35, 0
	s_cmp_gt_u32 s67, 41
	s_barrier
; __device__ __forceinline__ unsigned pk2(float lo, float hi) { unsigned r; asm volatile("v_cvt_pk_bf16_f32 %0, %1, %2" : "=v"(r) : "v"(lo), "v"(hi)); return r; }
; __device__ __forceinline__ unsigned pk2(float lo, float hi) { return f2bf(lo) | (f2bf(hi) << 16); }
;     __device__ __forceinline__ void epi(const f32x4 (&acc)[2][2][4][2], const Unit& u, int wr, int wc, int fr, int fq) const {
;         if ((PROBE & 64) && coef == 0.f) { dry_epi(acc, pool, rowss); return; }
;         ConvHost<3> ch; ch.begin(cj, u.g, 22, wr * 4 + wc, fq * 16 + fr);
;         const int row0 = u.pm * 256 + wr * 64 + fr, col0 = u.pn * 256 + wc * 32 + 8 * fq;
; #pragma unroll
;         for (int ai = 0; ai < 2; ++ai) {
;             u32x4 xo[4][2];
; #pragma unroll
;             for (int m = 0; m < 4; ++m)
; #pragma unroll
;                 for (int bj = 0; bj < 2; ++bj) xo[m][bj] = *(const u32x4*)(xb + (size_t)(row0 + ai * 128 + m * 16) * D + col0 + bj * 128);
; #pragma unroll
;             for (int m = 0; m < 4; ++m) {
;                 const int row = row0 + ai * 128 + m * 16; const size_t off = (size_t)row * D + col0; float ss = 0.f;
; #pragma unroll
;                 for (int bj = 0; bj < 2; ++bj) {
;                     const u32x4 o = xo[m][bj]; const f32x4 a0v = acc[ai][bj][m][0], a1v = acc[ai][bj][m][1];
;                     const float v0 = bf_lo(o.x) + coef * a0v[0], v1 = bf_hi(o.x) + coef * a0v[1], v2 = bf_lo(o.y) + coef * a0v[2], v3 = bf_hi(o.y) + coef * a0v[3];
;                     const float v4 = bf_lo(o.z) + coef * a1v[0], v5 = bf_hi(o.z) + coef * a1v[1], v6 = bf_lo(o.w) + coef * a1v[2], v7 = bf_hi(o.w) + coef * a1v[3];
;                     u32x4 w; w.x = pk2(v0, v1); w.y = pk2(v2, v3); w.z = pk2(v4, v5); w.w = pk2(v6, v7);
;                     *(u32x4*)(xb + off + bj * 128) = w;
;                     ss += ((v0 * v0 + v1 * v1) + (v2 * v2 + v3 * v3)) + ((v4 * v4 + v5 * v5) + (v6 * v6 + v7 * v7));
;                 }
;                 ss += __shfl_xor(ss, 16); ss += __shfl_xor(ss, 32);
;                 if (fq == 0) rowss[(size_t)row * 32 + u.pn * 4 + wc] = ss;
;             }
	v_lshl_or_b32 v166, s40, 8, v189
	v_lshl_add_u32 v170, s61, 8, v153
	v_ashrrev_i32_e32 v167, 31, v166
	v_lshlrev_b64 v[202:203], 1, v[166:167]
	v_ashrrev_i32_e32 v171, 31, v170
	v_lshl_add_u64 v[168:169], s[20:21], 0, v[202:203]
	v_lshlrev_b64 v[204:205], 11, v[170:171]
	v_lshl_add_u64 v[128:129], v[168:169], 0, v[204:205]
	v_mov_b32_e32 v218, 0x40000
	v_mov_b32_e32 v219, 0
	v_lshl_add_u64 v[216:217], v[128:129], 0, v[218:219]
	v_mov_b32_e32 v218, 0x8000
	s_waitcnt vmcnt(8)
	v_mov_b64_e32 v[194:195], v[232:233]
	v_mov_b64_e32 v[196:197], v[234:235]
	v_mov_b64_e32 v[198:199], v[236:237]
	v_mov_b64_e32 v[200:201], v[238:239]
	v_or_b32_e32 v180, 16, v170
	v_or_b32_e32 v176, 32, v170
	v_or_b32_e32 v172, 48, v170
	v_ashrrev_i32_e32 v181, 31, v180
	v_ashrrev_i32_e32 v177, 31, v176
	v_ashrrev_i32_e32 v173, 31, v172
	v_lshlrev_b64 v[182:183], 11, v[180:181]
	v_lshlrev_b64 v[178:179], 11, v[176:177]
	v_lshlrev_b64 v[174:175], 11, v[172:173]
	v_lshl_add_u64 v[128:129], v[168:169], 0, v[182:183]
	v_lshl_add_u64 v[130:131], v[168:169], 0, v[178:179]
	v_lshl_add_u64 v[206:207], v[168:169], 0, v[174:175]
	v_mov_b64_e32 v[148:149], v[240:241]
	v_mov_b64_e32 v[150:151], v[242:243]
	v_mov_b64_e32 v[144:145], v[244:245]
	v_mov_b64_e32 v[146:147], v[246:247]
	global_load_dwordx4 v[140:143], v[130:131], off
	global_load_dwordx4 v[136:139], v[130:131], off offset:256
	global_load_dwordx4 v[132:135], v[206:207], off
	s_nop 0
	global_load_dwordx4 v[128:131], v[206:207], off offset:256
	global_load_dwordx4 v[222:225], v[216:217], off
	global_load_dwordx4 v[226:229], v[216:217], off offset:256
	v_lshl_add_u64 v[216:217], v[216:217], 0, v[218:219]
	global_load_dwordx4 v[230:233], v[216:217], off
	global_load_dwordx4 v[234:237], v[216:217], off offset:256
	v_lshl_add_u64 v[216:217], v[216:217], 0, v[218:219]
	global_load_dwordx4 v[238:241], v[216:217], off
	global_load_dwordx4 v[242:245], v[216:217], off offset:256
	v_lshl_add_u64 v[216:217], v[216:217], 0, v[218:219]
	global_load_dwordx4 v[246:249], v[216:217], off
	global_load_dwordx4 v[250:253], v[216:217], off offset:256
	v_and_b32_e32 v206, 64, v193
	v_xor_b32_e32 v208, 16, v193
	v_add_u32_e32 v206, 64, v206
	v_cmp_lt_i32_e32 vcc, v208, v206
	v_lshlrev_b32_e32 v209, 16, v195
	v_cndmask_b32_e32 v207, v193, v208, vcc
	v_lshlrev_b32_e32 v208, 16, v194
	v_and_b32_e32 v194, 0xffff0000, v194
	v_and_b32_e32 v195, 0xffff0000, v195
	v_lshlrev_b32_e32 v210, 16, v196
	v_and_b32_e32 v196, 0xffff0000, v196
	v_lshlrev_b32_e32 v211, 16, v197
	v_and_b32_e32 v197, 0xffff0000, v197
	v_lshlrev_b32_e32 v212, 16, v198
	v_and_b32_e32 v198, 0xffff0000, v198
	v_lshlrev_b32_e32 v213, 16, v199
	v_and_b32_e32 v199, 0xffff0000, v199
	v_lshlrev_b32_e32 v214, 16, v200
	v_and_b32_e32 v200, 0xffff0000, v200
	v_lshlrev_b32_e32 v215, 16, v201
	v_and_b32_e32 v201, 0xffff0000, v201
	v_fmac_f32_e32 v194, 0.5, v117
	v_fmac_f32_e32 v195, 0.5, v119
	v_fmac_f32_e32 v196, 0.5, v113
	v_fmac_f32_e32 v197, 0.5, v115
	v_fmac_f32_e32 v198, 0.5, v125
	v_fmac_f32_e32 v199, 0.5, v127
	v_fmac_f32_e32 v200, 0.5, v121
	v_fmac_f32_e32 v201, 0.5, v123
	v_fmac_f32_e32 v208, 0.5, v116
	v_fmac_f32_e32 v209, 0.5, v118
	v_fmac_f32_e32 v210, 0.5, v112
	v_fmac_f32_e32 v211, 0.5, v114
	v_fmac_f32_e32 v212, 0.5, v124
	v_fmac_f32_e32 v213, 0.5, v126
	v_fmac_f32_e32 v214, 0.5, v120
	v_fmac_f32_e32 v215, 0.5, v122
	v_mul_f32_e32 v112, v194, v194
	v_mul_f32_e32 v113, v195, v195
	v_mul_f32_e32 v118, v196, v196
	v_mul_f32_e32 v119, v197, v197
	v_mul_f32_e32 v120, v198, v198
	v_mul_f32_e32 v121, v199, v199
	v_mul_f32_e32 v122, v200, v200
	v_mul_f32_e32 v123, v201, v201
	v_fmac_f32_e32 v112, v208, v208
	v_fmac_f32_e32 v113, v209, v209
	v_fmac_f32_e32 v118, v210, v210
	v_fmac_f32_e32 v119, v211, v211
	v_fmac_f32_e32 v120, v212, v212
	v_fmac_f32_e32 v121, v213, v213
	v_fmac_f32_e32 v122, v214, v214
	v_fmac_f32_e32 v123, v215, v215
	v_add_f32_e32 v112, v112, v113
	v_add_f32_e32 v113, v118, v119
	v_add_f32_e32 v118, v120, v121
	v_add_f32_e32 v119, v122, v123
	v_add_f32_e32 v112, v112, v113
	v_add_f32_e32 v113, v118, v119
	v_add_f32_e32 v113, v112, v113
	v_lshlrev_b32_e32 v112, 2, v207
	ds_bpermute_b32 v122, v112, v113
	v_lshl_add_u64 v[118:119], s[20:21], 0, v[204:205]
	v_cvt_pk_bf16_f32 v114, v208, v194
	v_lshl_add_u64 v[120:121], v[118:119], 0, v[202:203]
	v_cvt_pk_bf16_f32 v115, v209, v195
	v_cvt_pk_bf16_f32 v116, v210, v196
	v_cvt_pk_bf16_f32 v117, v211, v197
	global_store_dwordx4 v[120:121], v[114:117], off
	s_waitcnt lgkmcnt(0)
	s_nop 0
	v_add_f32_e32 v114, v113, v122
	v_xor_b32_e32 v113, 32, v193
	v_cmp_lt_i32_e32 vcc, v113, v206
	v_cvt_pk_bf16_f32 v116, v212, v198
	v_cvt_pk_bf16_f32 v117, v213, v199
	v_cvt_pk_bf16_f32 v118, v214, v200
	v_cvt_pk_bf16_f32 v119, v215, v201
	global_store_dwordx4 v[120:121], v[116:119], off offset:256
	s_nop 0
	v_cndmask_b32_e32 v113, v193, v113, vcc
	v_lshlrev_b32_e32 v113, 2, v113
	ds_bpermute_b32 v115, v113, v114
	s_and_saveexec_b64 s[28:29], s[6:7]
	s_cbranch_execz .LBB0_360
	s_waitcnt lgkmcnt(0)
	v_add_f32_e32 v116, v114, v115
	s_lshl_b32 s30, s40, 2
	v_lshlrev_b64 v[114:115], 7, v[170:171]
	s_ashr_i32 s31, s30, 31
	v_lshl_add_u64 v[114:115], s[2:3], 0, v[114:115]
	v_lshl_add_u64 v[114:115], s[30:31], 2, v[114:115]
	s_lshl_b32 s0, s50, 2
	v_lshl_add_u64 v[114:115], v[114:115], 0, s[0:1]
	global_store_dword v[114:115], v116, off

;     ...
;         G_PAIR(0, 1);
.LBB0_579:
	ds_read_b128 v[0:3], v144
	ds_read_b128 v[4:7], v144 offset:1024
	ds_read_b128 v[8:11], v144 offset:2048
	ds_read_b128 v[12:15], v144 offset:3072
	s_lshl_b64 s[44:45], s[44:45], 19
	s_add_u32 s1, s49, s44
	s_addc_u32 s12, s50, s45
	s_add_u32 s40, s1, s40
	s_addc_u32 s41, s12, s41
	s_add_u32 s44, s4, 0x40080
	s_addc_u32 s45, s5, 0
	s_add_i32 s1, s52, 0xc000
	v_lshl_add_u64 v[48:49], s[44:45], 0, v[130:131]
	s_mov_b32 m0, s1
	s_add_i32 s12, s52, 0xe000
	ds_read_b128 v[16:19], v145
	ds_read_b128 v[20:23], v145 offset:1024
	ds_read_b128 v[24:27], v145 offset:2048
	ds_read_b128 v[28:31], v145 offset:3072
	ds_read_b128 v[32:35], v145 offset:4096
	ds_read_b128 v[36:39], v145 offset:5120
	ds_read_b128 v[40:43], v145 offset:6144
	ds_read_b128 v[44:47], v145 offset:7168
	global_load_lds_dwordx4 v[48:49], off
	s_mov_b32 m0, s12
	v_lshl_add_u64 v[48:49], s[44:45], 0, v[128:129]
	global_load_lds_dwordx4 v[48:49], off
	s_waitcnt lgkmcnt(8)
	s_barrier
	s_waitcnt lgkmcnt(0)
	v_mfma_f32_16x16x32_bf16 v[48:51], v[0:3], v[16:19], 0
	v_mfma_f32_16x16x32_bf16 v[52:55], v[8:11], v[16:19], 0
	v_mfma_f32_16x16x32_bf16 v[56:59], v[0:3], v[24:27], 0
	v_mfma_f32_16x16x32_bf16 v[60:63], v[8:11], v[24:27], 0
	v_mfma_f32_16x16x32_bf16 v[64:67], v[0:3], v[32:35], 0
	v_mfma_f32_16x16x32_bf16 v[68:71], v[8:11], v[32:35], 0
	v_mfma_f32_16x16x32_bf16 v[72:75], v[0:3], v[40:43], 0
	v_mfma_f32_16x16x32_bf16 v[76:79], v[8:11], v[40:43], 0
	v_mfma_f32_16x16x32_bf16 v[48:51], v[4:7], v[20:23], v[48:51]
	v_mfma_f32_16x16x32_bf16 v[52:55], v[12:15], v[20:23], v[52:55]
	v_mfma_f32_16x16x32_bf16 v[56:59], v[4:7], v[28:31], v[56:59]
	v_mfma_f32_16x16x32_bf16 v[60:63], v[12:15], v[28:31], v[60:63]
	v_mfma_f32_16x16x32_bf16 v[64:67], v[4:7], v[36:39], v[64:67]
	v_mfma_f32_16x16x32_bf16 v[68:71], v[12:15], v[36:39], v[68:71]
	v_mfma_f32_16x16x32_bf16 v[72:75], v[4:7], v[44:47], v[72:75]
	v_mfma_f32_16x16x32_bf16 v[76:79], v[12:15], v[44:47], v[76:79]
	s_barrier
	v_lshl_add_u64 v[246:247], s[6:7], 0, v[130:131]
	s_add_i32 s35, s64, s51
	v_lshl_add_u64 v[96:97], v[246:247], 0, s[14:15]
	s_mov_b32 m0, s35
	v_lshl_add_u64 v[248:249], s[6:7], 0, v[128:129]
	s_add_i32 s73, s35, 0x2000
	ds_read_b128 v[80:83], v146
	ds_read_b128 v[84:87], v146 offset:1024
	ds_read_b128 v[88:91], v146 offset:2048
	ds_read_b128 v[92:95], v146 offset:3072
	global_load_lds_dwordx4 v[96:97], off
	s_mov_b32 m0, s73
	v_lshl_add_u64 v[96:97], v[248:249], 0, s[14:15]
	global_load_lds_dwordx4 v[96:97], off
	s_barrier
	s_waitcnt lgkmcnt(0)
	v_mfma_f32_16x16x32_bf16 v[96:99], v[80:83], v[16:19], 0
	v_mfma_f32_16x16x32_bf16 v[16:19], v[88:91], v[16:19], 0
	v_mfma_f32_16x16x32_bf16 v[100:103], v[80:83], v[24:27], 0
	v_mfma_f32_16x16x32_bf16 v[24:27], v[88:91], v[24:27], 0
	v_mfma_f32_16x16x32_bf16 v[104:107], v[80:83], v[32:35], 0
	v_mfma_f32_16x16x32_bf16 v[32:35], v[88:91], v[32:35], 0
	v_mfma_f32_16x16x32_bf16 v[108:111], v[80:83], v[40:43], 0
	v_mfma_f32_16x16x32_bf16 v[40:43], v[88:91], v[40:43], 0
	v_mfma_f32_16x16x32_bf16 v[96:99], v[84:87], v[20:23], v[96:99]
	v_mfma_f32_16x16x32_bf16 v[112:115], v[92:95], v[20:23], v[16:19]
	v_mfma_f32_16x16x32_bf16 v[100:103], v[84:87], v[28:31], v[100:103]
	v_mfma_f32_16x16x32_bf16 v[116:119], v[92:95], v[28:31], v[24:27]
	v_mfma_f32_16x16x32_bf16 v[104:107], v[84:87], v[36:39], v[104:107]
	v_mfma_f32_16x16x32_bf16 v[32:35], v[92:95], v[36:39], v[32:35]
	v_mfma_f32_16x16x32_bf16 v[36:39], v[84:87], v[44:47], v[108:111]
	v_mfma_f32_16x16x32_bf16 v[40:43], v[92:95], v[44:47], v[40:43]
	v_lshl_add_u64 v[250:251], s[4:5], 0, v[130:131]
	s_mov_b32 m0, s52
	v_lshl_add_u64 v[138:139], v[250:251], 0, s[14:15]
	v_lshl_add_u64 v[252:253], s[4:5], 0, v[128:129]
	s_barrier
	ds_read_b128 v[16:19], v145 offset:16384
	ds_read_b128 v[20:23], v145 offset:17408
	ds_read_b128 v[24:27], v145 offset:18432
	ds_read_b128 v[28:31], v145 offset:19456
	ds_read_b128 v[44:47], v145 offset:20480
	ds_read_b128 v[108:111], v145 offset:21504
	ds_read_b128 v[120:123], v145 offset:22528
	ds_read_b128 v[124:127], v145 offset:23552
	global_load_lds_dwordx4 v[138:139], off
	s_mov_b32 m0, s55
	v_lshl_add_u64 v[138:139], v[252:253], 0, s[14:15]
	global_load_lds_dwordx4 v[138:139], off
	s_barrier
	s_waitcnt lgkmcnt(0)
	v_mfma_f32_16x16x32_bf16 v[138:141], v[0:3], v[16:19], 0
	v_mfma_f32_16x16x32_bf16 v[148:151], v[8:11], v[16:19], 0
	v_mfma_f32_16x16x32_bf16 v[152:155], v[0:3], v[24:27], 0
	v_mfma_f32_16x16x32_bf16 v[156:159], v[8:11], v[24:27], 0
	v_mfma_f32_16x16x32_bf16 v[160:163], v[0:3], v[44:47], 0
	v_mfma_f32_16x16x32_bf16 v[164:167], v[8:11], v[44:47], 0
	v_mfma_f32_16x16x32_bf16 v[0:3], v[0:3], v[120:123], 0
	v_mfma_f32_16x16x32_bf16 v[8:11], v[8:11], v[120:123], 0
	v_mfma_f32_16x16x32_bf16 v[138:141], v[4:7], v[20:23], v[138:141]
	v_mfma_f32_16x16x32_bf16 v[168:171], v[12:15], v[20:23], v[148:151]
	v_mfma_f32_16x16x32_bf16 v[150:153], v[4:7], v[28:31], v[152:155]
	v_mfma_f32_16x16x32_bf16 v[154:157], v[12:15], v[28:31], v[156:159]
	v_mfma_f32_16x16x32_bf16 v[158:161], v[4:7], v[108:111], v[160:163]
	v_mfma_f32_16x16x32_bf16 v[162:165], v[12:15], v[108:111], v[164:167]
	v_mfma_f32_16x16x32_bf16 v[172:175], v[4:7], v[124:127], v[0:3]
	v_mfma_f32_16x16x32_bf16 v[176:179], v[12:15], v[124:127], v[8:11]
	s_barrier
	s_add_u32 s44, s6, 0x40100
	s_addc_u32 s45, s7, 0
	s_add_i32 s74, s66, s51
	v_lshl_add_u64 v[0:1], s[44:45], 0, v[130:131]
	s_mov_b32 m0, s74
	s_add_i32 s75, s74, 0x2000
	global_load_lds_dwordx4 v[0:1], off
	s_mov_b32 m0, s75
	v_lshl_add_u64 v[0:1], s[44:45], 0, v[128:129]
	global_load_lds_dwordx4 v[0:1], off
	s_waitcnt vmcnt(6)
	s_barrier
	v_mfma_f32_16x16x32_bf16 v[0:3], v[80:83], v[16:19], 0
	v_mfma_f32_16x16x32_bf16 v[4:7], v[88:91], v[16:19], 0
	v_mfma_f32_16x16x32_bf16 v[8:11], v[80:83], v[24:27], 0
	v_mfma_f32_16x16x32_bf16 v[12:15], v[88:91], v[24:27], 0
	v_mfma_f32_16x16x32_bf16 v[16:19], v[80:83], v[44:47], 0
	v_mfma_f32_16x16x32_bf16 v[24:27], v[88:91], v[44:47], 0
	v_mfma_f32_16x16x32_bf16 v[44:47], v[80:83], v[120:123], 0
	v_mfma_f32_16x16x32_bf16 v[80:83], v[88:91], v[120:123], 0
	v_mfma_f32_16x16x32_bf16 v[120:123], v[84:87], v[20:23], v[0:3]
	v_mfma_f32_16x16x32_bf16 v[192:195], v[84:87], v[108:111], v[16:19]
	v_mfma_f32_16x16x32_bf16 v[108:111], v[92:95], v[108:111], v[24:27]
	v_mfma_f32_16x16x32_bf16 v[196:199], v[84:87], v[124:127], v[44:47]
	v_mfma_f32_16x16x32_bf16 v[124:127], v[92:95], v[124:127], v[80:83]
	v_mfma_f32_16x16x32_bf16 v[180:183], v[92:95], v[20:23], v[4:7]
	v_mfma_f32_16x16x32_bf16 v[184:187], v[84:87], v[28:31], v[8:11]
	v_mfma_f32_16x16x32_bf16 v[188:191], v[92:95], v[28:31], v[12:15]
	s_add_i32 s76, 0, 0x18000
	v_add_u32_e32 v147, s76, v143
	s_barrier
	ds_read_b128 v[80:83], v147
	ds_read_b128 v[200:203], v147 offset:1024
	ds_read_b128 v[84:87], v147 offset:2048
	ds_read_b128 v[204:207], v147 offset:3072
	s_add_u32 s44, s4, 0x40100
	s_addc_u32 s45, s5, 0
	s_mov_b32 m0, s56
	v_lshl_add_u64 v[0:1], s[44:45], 0, v[130:131]
	ds_read_b128 v[44:47], v145 offset:32768
	ds_read_b128 v[88:91], v145 offset:33792
	ds_read_b128 v[92:95], v145 offset:34816
	ds_read_b128 v[208:211], v145 offset:35840
	ds_read_b128 v[212:215], v145 offset:36864
	ds_read_b128 v[216:219], v145 offset:37888
	ds_read_b128 v[222:225], v145 offset:38912
	ds_read_b128 v[226:229], v145 offset:39936
	global_load_lds_dwordx4 v[0:1], off
	s_mov_b32 m0, s57
	v_lshl_add_u64 v[0:1], s[44:45], 0, v[128:129]
	global_load_lds_dwordx4 v[0:1], off
	s_waitcnt lgkmcnt(8)
	s_barrier
	s_waitcnt lgkmcnt(0)
	v_mfma_f32_16x16x32_bf16 v[0:3], v[80:83], v[44:47], v[48:51]
	v_mfma_f32_16x16x32_bf16 v[4:7], v[84:87], v[44:47], v[52:55]
	v_mfma_f32_16x16x32_bf16 v[8:11], v[80:83], v[92:95], v[56:59]
	v_mfma_f32_16x16x32_bf16 v[12:15], v[84:87], v[92:95], v[60:63]
	v_mfma_f32_16x16x32_bf16 v[48:51], v[80:83], v[212:215], v[64:67]
	v_mfma_f32_16x16x32_bf16 v[52:55], v[84:87], v[212:215], v[68:71]
	v_mfma_f32_16x16x32_bf16 v[56:59], v[80:83], v[222:225], v[72:75]
	v_mfma_f32_16x16x32_bf16 v[60:63], v[84:87], v[222:225], v[76:79]
	v_mfma_f32_16x16x32_bf16 v[28:31], v[200:203], v[88:91], v[0:3]
	v_mfma_f32_16x16x32_bf16 v[24:27], v[204:207], v[88:91], v[4:7]
	v_mfma_f32_16x16x32_bf16 v[20:23], v[200:203], v[208:211], v[8:11]
	v_mfma_f32_16x16x32_bf16 v[16:19], v[204:207], v[208:211], v[12:15]
	v_mfma_f32_16x16x32_bf16 v[12:15], v[200:203], v[216:219], v[48:51]
	v_mfma_f32_16x16x32_bf16 v[8:11], v[204:207], v[216:219], v[52:55]
	v_mfma_f32_16x16x32_bf16 v[4:7], v[200:203], v[226:229], v[56:59]
	v_mfma_f32_16x16x32_bf16 v[0:3], v[204:207], v[226:229], v[60:63]
	s_barrier
	s_add_i32 s78, 0, 0x1c000
	s_add_i32 s76, s76, s51
	v_add_u32_e32 v148, s78, v143
	v_lshl_add_u64 v[48:49], v[246:247], 0, s[16:17]
	s_mov_b32 m0, s76
	s_add_i32 s77, s76, 0x2000
	ds_read_b128 v[230:233], v148
	ds_read_b128 v[234:237], v148 offset:1024
	ds_read_b128 v[238:241], v148 offset:2048
	ds_read_b128 v[242:245], v148 offset:3072
	global_load_lds_dwordx4 v[48:49], off
	s_mov_b32 m0, s77
	v_lshl_add_u64 v[48:49], v[248:249], 0, s[16:17]
	global_load_lds_dwordx4 v[48:49], off
	s_barrier
	s_waitcnt lgkmcnt(0)
	v_mfma_f32_16x16x32_bf16 v[48:51], v[230:233], v[44:47], v[96:99]
	v_mfma_f32_16x16x32_bf16 v[44:47], v[238:241], v[44:47], v[112:115]
	v_mfma_f32_16x16x32_bf16 v[52:55], v[230:233], v[92:95], v[100:103]
	v_mfma_f32_16x16x32_bf16 v[56:59], v[238:241], v[92:95], v[116:119]
	v_mfma_f32_16x16x32_bf16 v[60:63], v[230:233], v[212:215], v[104:107]
	v_mfma_f32_16x16x32_bf16 v[32:35], v[238:241], v[212:215], v[32:35]
	v_mfma_f32_16x16x32_bf16 v[36:39], v[230:233], v[222:225], v[36:39]
	v_mfma_f32_16x16x32_bf16 v[40:43], v[238:241], v[222:225], v[40:43]
	v_mfma_f32_16x16x32_bf16 v[92:95], v[234:237], v[88:91], v[48:51]
	v_mfma_f32_16x16x32_bf16 v[88:91], v[242:245], v[88:91], v[44:47]
	v_mfma_f32_16x16x32_bf16 v[76:79], v[234:237], v[208:211], v[52:55]
	v_mfma_f32_16x16x32_bf16 v[72:75], v[242:245], v[208:211], v[56:59]
	v_mfma_f32_16x16x32_bf16 v[60:63], v[234:237], v[216:219], v[60:63]
	v_mfma_f32_16x16x32_bf16 v[56:59], v[242:245], v[216:219], v[32:35]
	v_mfma_f32_16x16x32_bf16 v[44:47], v[234:237], v[226:229], v[36:39]
	v_mfma_f32_16x16x32_bf16 v[40:43], v[242:245], v[226:229], v[40:43]
	s_mov_b32 m0, s61
	v_lshl_add_u64 v[32:33], v[250:251], 0, s[16:17]
	s_barrier
	ds_read_b128 v[96:99], v145 offset:49152
	ds_read_b128 v[100:103], v145 offset:50176
	ds_read_b128 v[104:107], v145 offset:51200
	ds_read_b128 v[112:115], v145 offset:52224
	ds_read_b128 v[116:119], v145 offset:53248
	ds_read_b128 v[208:211], v145 offset:54272
	ds_read_b128 v[212:215], v145 offset:55296
	ds_read_b128 v[216:219], v145 offset:56320
	global_load_lds_dwordx4 v[32:33], off
	s_mov_b32 m0, s62
	v_lshl_add_u64 v[32:33], v[252:253], 0, s[16:17]
	global_load_lds_dwordx4 v[32:33], off
	s_barrier
;     ...
;         G_PAIR(0, 1);
; #pragma unroll 1
;         for (int t = 2; t < nt; t += 2) G_PAIR(t, 0);
	s_waitcnt lgkmcnt(0)
	v_mfma_f32_16x16x32_bf16 v[32:35], v[80:83], v[96:99], v[138:141]
	v_mfma_f32_16x16x32_bf16 v[36:39], v[84:87], v[96:99], v[168:171]
	v_mfma_f32_16x16x32_bf16 v[48:51], v[80:83], v[104:107], v[150:153]
	v_mfma_f32_16x16x32_bf16 v[52:55], v[84:87], v[104:107], v[154:157]
	v_mfma_f32_16x16x32_bf16 v[138:141], v[80:83], v[116:119], v[158:161]
	v_mfma_f32_16x16x32_bf16 v[150:153], v[84:87], v[116:119], v[162:165]
	v_mfma_f32_16x16x32_bf16 v[154:157], v[80:83], v[212:215], v[172:175]
	v_mfma_f32_16x16x32_bf16 v[158:161], v[84:87], v[212:215], v[176:179]
	v_mfma_f32_16x16x32_bf16 v[84:87], v[200:203], v[100:103], v[32:35]
	v_mfma_f32_16x16x32_bf16 v[80:83], v[204:207], v[100:103], v[36:39]
	v_mfma_f32_16x16x32_bf16 v[68:71], v[200:203], v[112:115], v[48:51]
	v_mfma_f32_16x16x32_bf16 v[64:67], v[204:207], v[112:115], v[52:55]
	v_mfma_f32_16x16x32_bf16 v[52:55], v[200:203], v[208:211], v[138:141]
	v_mfma_f32_16x16x32_bf16 v[48:51], v[204:207], v[208:211], v[150:153]
	v_mfma_f32_16x16x32_bf16 v[36:39], v[200:203], v[216:219], v[154:157]
	v_mfma_f32_16x16x32_bf16 v[32:35], v[204:207], v[216:219], v[158:161]
	s_barrier
	s_add_u32 s44, s6, 0x40180
	s_addc_u32 s45, s7, 0
	s_add_i32 s78, s78, s51
	v_lshl_add_u64 v[138:139], s[44:45], 0, v[130:131]
	s_mov_b32 m0, s78
	s_add_i32 s79, s78, 0x2000
	global_load_lds_dwordx4 v[138:139], off
	v_lshl_add_u64 v[138:139], s[44:45], 0, v[128:129]
	s_mov_b32 m0, s79
	s_mov_b64 s[44:45], 0x40180
	global_load_lds_dwordx4 v[138:139], off
	s_waitcnt vmcnt(6)
	s_barrier
	v_mfma_f32_16x16x32_bf16 v[120:123], v[230:233], v[96:99], v[120:123]
	v_mfma_f32_16x16x32_bf16 v[96:99], v[238:241], v[96:99], v[180:183]
	v_mfma_f32_16x16x32_bf16 v[138:141], v[230:233], v[104:107], v[184:187]
	v_mfma_f32_16x16x32_bf16 v[104:107], v[238:241], v[104:107], v[188:191]
	v_mfma_f32_16x16x32_bf16 v[150:153], v[230:233], v[116:119], v[192:195]
	v_mfma_f32_16x16x32_bf16 v[154:157], v[238:241], v[116:119], v[108:111]
	v_mfma_f32_16x16x32_bf16 v[158:161], v[230:233], v[212:215], v[196:199]
	v_mfma_f32_16x16x32_bf16 v[162:165], v[238:241], v[212:215], v[124:127]
	v_mfma_f32_16x16x32_bf16 v[124:127], v[234:237], v[100:103], v[120:123]
	v_mfma_f32_16x16x32_bf16 v[120:123], v[242:245], v[100:103], v[96:99]
	v_mfma_f32_16x16x32_bf16 v[116:119], v[234:237], v[112:115], v[138:141]
	v_mfma_f32_16x16x32_bf16 v[112:115], v[242:245], v[112:115], v[104:107]
	v_mfma_f32_16x16x32_bf16 v[108:111], v[234:237], v[208:211], v[150:153]
	v_mfma_f32_16x16x32_bf16 v[104:107], v[242:245], v[208:211], v[154:157]
	v_mfma_f32_16x16x32_bf16 v[100:103], v[234:237], v[216:219], v[158:161]
	v_mfma_f32_16x16x32_bf16 v[96:99], v[242:245], v[216:219], v[162:165]
	v_lshl_add_u64 v[138:139], s[4:5], 0, v[134:135]
	v_lshl_add_u64 v[140:141], s[4:5], 0, v[136:137]
	s_mov_b32 s80, 0
.Lrot_580:
	s_barrier
.LBB0_580:
	ds_read_b128 v[150:153], v144
	ds_read_b128 v[154:157], v144 offset:1024
	ds_read_b128 v[158:161], v144 offset:2048
	ds_read_b128 v[162:165], v144 offset:3072
	s_mov_b32 m0, s1
	v_lshl_add_u64 v[198:199], v[138:139], 0, s[44:45]
	ds_read_b128 v[166:169], v145
	ds_read_b128 v[170:173], v145 offset:1024
	ds_read_b128 v[174:177], v145 offset:2048
	ds_read_b128 v[178:181], v145 offset:3072
	ds_read_b128 v[182:185], v145 offset:4096
	ds_read_b128 v[186:189], v145 offset:5120
	ds_read_b128 v[190:193], v145 offset:6144
	ds_read_b128 v[194:197], v145 offset:7168
	global_load_lds_dwordx4 v[198:199], off
	s_mov_b32 m0, s12
	v_lshl_add_u64 v[198:199], v[140:141], 0, s[44:45]
	global_load_lds_dwordx4 v[198:199], off
	s_waitcnt lgkmcnt(8)
	s_barrier
	s_waitcnt lgkmcnt(0)
	v_mfma_f32_16x16x32_bf16 v[28:31], v[150:153], v[166:169], v[28:31]
	s_add_i32 s81, s44, 0xfffc0080
	v_mfma_f32_16x16x32_bf16 v[24:27], v[158:161], v[166:169], v[24:27]
	s_cmp_eq_u32 s80, 4
	v_mfma_f32_16x16x32_bf16 v[20:23], v[150:153], v[174:177], v[20:23]
	s_cselect_b64 s[46:47], -1, 0
	v_mfma_f32_16x16x32_bf16 v[16:19], v[158:161], v[174:177], v[16:19]
	s_and_b64 s[82:83], s[46:47], exec
	v_mfma_f32_16x16x32_bf16 v[12:15], v[150:153], v[182:185], v[12:15]
	s_cselect_b32 s83, s39, s5
	v_mfma_f32_16x16x32_bf16 v[8:11], v[158:161], v[182:185], v[8:11]
	s_cselect_b32 s82, s38, s4
	v_mfma_f32_16x16x32_bf16 v[4:7], v[150:153], v[190:193], v[4:7]
	s_cselect_b32 s81, 0, s81
	v_mfma_f32_16x16x32_bf16 v[0:3], v[158:161], v[190:193], v[0:3]
	s_and_b64 s[46:47], s[42:43], s[46:47]
	v_mfma_f32_16x16x32_bf16 v[28:31], v[154:157], v[170:173], v[28:31]
	s_and_b64 s[46:47], s[46:47], exec
	v_mfma_f32_16x16x32_bf16 v[24:27], v[162:165], v[170:173], v[24:27]
	s_cselect_b32 s47, s41, s7
	v_mfma_f32_16x16x32_bf16 v[20:23], v[154:157], v[178:181], v[20:23]
	s_cselect_b32 s46, s40, s6
	v_mfma_f32_16x16x32_bf16 v[16:19], v[162:165], v[178:181], v[16:19]
	v_mfma_f32_16x16x32_bf16 v[12:15], v[154:157], v[186:189], v[12:15]
	v_mfma_f32_16x16x32_bf16 v[8:11], v[162:165], v[186:189], v[8:11]
	v_mfma_f32_16x16x32_bf16 v[4:7], v[154:157], v[194:197], v[4:7]
	v_mfma_f32_16x16x32_bf16 v[0:3], v[162:165], v[194:197], v[0:3]
	s_barrier
	s_add_u32 s46, s46, s81
	s_addc_u32 s47, s47, 0
	s_mov_b32 m0, s35
	v_lshl_add_u64 v[214:215], s[46:47], 0, v[130:131]
	ds_read_b128 v[198:201], v146
	ds_read_b128 v[202:205], v146 offset:1024
	ds_read_b128 v[206:209], v146 offset:2048
	ds_read_b128 v[210:213], v146 offset:3072
	global_load_lds_dwordx4 v[214:215], off
	s_mov_b32 m0, s73
	v_lshl_add_u64 v[216:217], s[46:47], 0, v[128:129]
	global_load_lds_dwordx4 v[216:217], off
	s_barrier
	s_waitcnt lgkmcnt(0)
	v_mfma_f32_16x16x32_bf16 v[92:95], v[198:201], v[166:169], v[92:95]
	v_mfma_f32_16x16x32_bf16 v[88:91], v[206:209], v[166:169], v[88:91]
	v_mfma_f32_16x16x32_bf16 v[76:79], v[198:201], v[174:177], v[76:79]
	v_mfma_f32_16x16x32_bf16 v[72:75], v[206:209], v[174:177], v[72:75]
	v_mfma_f32_16x16x32_bf16 v[60:63], v[198:201], v[182:185], v[60:63]
	v_mfma_f32_16x16x32_bf16 v[56:59], v[206:209], v[182:185], v[56:59]
	v_mfma_f32_16x16x32_bf16 v[44:47], v[198:201], v[190:193], v[44:47]
	v_mfma_f32_16x16x32_bf16 v[40:43], v[206:209], v[190:193], v[40:43]
	v_mfma_f32_16x16x32_bf16 v[92:95], v[202:205], v[170:173], v[92:95]
	v_mfma_f32_16x16x32_bf16 v[88:91], v[210:213], v[170:173], v[88:91]
	v_mfma_f32_16x16x32_bf16 v[76:79], v[202:205], v[178:181], v[76:79]
	v_mfma_f32_16x16x32_bf16 v[72:75], v[210:213], v[178:181], v[72:75]
	v_mfma_f32_16x16x32_bf16 v[60:63], v[202:205], v[186:189], v[60:63]
	v_mfma_f32_16x16x32_bf16 v[56:59], v[210:213], v[186:189], v[56:59]
	v_mfma_f32_16x16x32_bf16 v[44:47], v[202:205], v[194:197], v[44:47]
	v_mfma_f32_16x16x32_bf16 v[40:43], v[210:213], v[194:197], v[40:43]
	s_add_u32 s82, s82, s81
	s_addc_u32 s83, s83, 0
	s_mov_b32 m0, s52
	v_lshl_add_u64 v[218:219], s[82:83], 0, v[130:131]
	s_barrier
	ds_read_b128 v[166:169], v145 offset:16384
	ds_read_b128 v[170:173], v145 offset:17408
	ds_read_b128 v[174:177], v145 offset:18432
	ds_read_b128 v[178:181], v145 offset:19456
	ds_read_b128 v[182:185], v145 offset:20480
	ds_read_b128 v[186:189], v145 offset:21504
	ds_read_b128 v[190:193], v145 offset:22528
	ds_read_b128 v[194:197], v145 offset:23552
	global_load_lds_dwordx4 v[218:219], off
	s_mov_b32 m0, s55
	v_lshl_add_u64 v[222:223], s[82:83], 0, v[128:129]
	global_load_lds_dwordx4 v[222:223], off
	s_barrier
	s_waitcnt lgkmcnt(0)
	v_mfma_f32_16x16x32_bf16 v[84:87], v[150:153], v[166:169], v[84:87]
	v_mfma_f32_16x16x32_bf16 v[80:83], v[158:161], v[166:169], v[80:83]
	v_mfma_f32_16x16x32_bf16 v[68:71], v[150:153], v[174:177], v[68:71]
	v_mfma_f32_16x16x32_bf16 v[64:67], v[158:161], v[174:177], v[64:67]
	v_mfma_f32_16x16x32_bf16 v[52:55], v[150:153], v[182:185], v[52:55]
	v_mfma_f32_16x16x32_bf16 v[48:51], v[158:161], v[182:185], v[48:51]
	v_mfma_f32_16x16x32_bf16 v[36:39], v[150:153], v[190:193], v[36:39]
	v_mfma_f32_16x16x32_bf16 v[32:35], v[158:161], v[190:193], v[32:35]
	v_mfma_f32_16x16x32_bf16 v[84:87], v[154:157], v[170:173], v[84:87]
	v_mfma_f32_16x16x32_bf16 v[80:83], v[162:165], v[170:173], v[80:83]
	v_mfma_f32_16x16x32_bf16 v[68:71], v[154:157], v[178:181], v[68:71]
	v_mfma_f32_16x16x32_bf16 v[64:67], v[162:165], v[178:181], v[64:67]
	v_mfma_f32_16x16x32_bf16 v[52:55], v[154:157], v[186:189], v[52:55]
	v_mfma_f32_16x16x32_bf16 v[48:51], v[162:165], v[186:189], v[48:51]
	v_mfma_f32_16x16x32_bf16 v[36:39], v[154:157], v[194:197], v[36:39]
	v_mfma_f32_16x16x32_bf16 v[32:35], v[162:165], v[194:197], v[32:35]
	s_barrier
	s_add_u32 s84, s46, 0x40000
	s_addc_u32 s85, s47, 0
	s_mov_b32 m0, s74
	v_lshl_add_u64 v[150:151], s[84:85], 0, v[130:131]
	global_load_lds_dwordx4 v[150:151], off
	s_mov_b32 m0, s75
	v_lshl_add_u64 v[150:151], s[84:85], 0, v[128:129]
	global_load_lds_dwordx4 v[150:151], off
	s_waitcnt vmcnt(6)
	s_barrier
	v_mfma_f32_16x16x32_bf16 v[124:127], v[198:201], v[166:169], v[124:127]
	v_mfma_f32_16x16x32_bf16 v[120:123], v[206:209], v[166:169], v[120:123]
	v_mfma_f32_16x16x32_bf16 v[116:119], v[198:201], v[174:177], v[116:119]
	v_mfma_f32_16x16x32_bf16 v[112:115], v[206:209], v[174:177], v[112:115]
	v_mfma_f32_16x16x32_bf16 v[108:111], v[198:201], v[182:185], v[108:111]
	v_mfma_f32_16x16x32_bf16 v[104:107], v[206:209], v[182:185], v[104:107]
	v_mfma_f32_16x16x32_bf16 v[100:103], v[198:201], v[190:193], v[100:103]
	v_mfma_f32_16x16x32_bf16 v[96:99], v[206:209], v[190:193], v[96:99]
	v_mfma_f32_16x16x32_bf16 v[124:127], v[202:205], v[170:173], v[124:127]
	v_mfma_f32_16x16x32_bf16 v[120:123], v[210:213], v[170:173], v[120:123]
	v_mfma_f32_16x16x32_bf16 v[116:119], v[202:205], v[178:181], v[116:119]
	v_mfma_f32_16x16x32_bf16 v[112:115], v[210:213], v[178:181], v[112:115]
	v_mfma_f32_16x16x32_bf16 v[108:111], v[202:205], v[186:189], v[108:111]
	v_mfma_f32_16x16x32_bf16 v[104:107], v[210:213], v[186:189], v[104:107]
	v_mfma_f32_16x16x32_bf16 v[100:103], v[202:205], v[194:197], v[100:103]
	v_mfma_f32_16x16x32_bf16 v[96:99], v[210:213], v[194:197], v[96:99]
	s_barrier
	ds_read_b128 v[150:153], v147
	ds_read_b128 v[154:157], v147 offset:1024
	ds_read_b128 v[158:161], v147 offset:2048
	ds_read_b128 v[162:165], v147 offset:3072
	s_add_u32 s82, s82, 0x40000
	s_addc_u32 s83, s83, 0
	s_mov_b32 m0, s56
	v_lshl_add_u64 v[198:199], s[82:83], 0, v[130:131]
	ds_read_b128 v[166:169], v145 offset:32768
	ds_read_b128 v[170:173], v145 offset:33792
	ds_read_b128 v[174:177], v145 offset:34816
	ds_read_b128 v[178:181], v145 offset:35840
	ds_read_b128 v[182:185], v145 offset:36864
	ds_read_b128 v[186:189], v145 offset:37888
	ds_read_b128 v[190:193], v145 offset:38912
	ds_read_b128 v[194:197], v145 offset:39936
	global_load_lds_dwordx4 v[198:199], off
	s_mov_b32 m0, s57
	v_lshl_add_u64 v[198:199], s[82:83], 0, v[128:129]
	global_load_lds_dwordx4 v[198:199], off
	s_waitcnt lgkmcnt(8)
	s_barrier
	s_waitcnt lgkmcnt(0)
	v_mfma_f32_16x16x32_bf16 v[28:31], v[150:153], v[166:169], v[28:31]
	v_mfma_f32_16x16x32_bf16 v[24:27], v[158:161], v[166:169], v[24:27]
	v_mfma_f32_16x16x32_bf16 v[20:23], v[150:153], v[174:177], v[20:23]
	v_mfma_f32_16x16x32_bf16 v[16:19], v[158:161], v[174:177], v[16:19]
	v_mfma_f32_16x16x32_bf16 v[12:15], v[150:153], v[182:185], v[12:15]
	v_mfma_f32_16x16x32_bf16 v[8:11], v[158:161], v[182:185], v[8:11]
	v_mfma_f32_16x16x32_bf16 v[4:7], v[150:153], v[190:193], v[4:7]
	v_mfma_f32_16x16x32_bf16 v[0:3], v[158:161], v[190:193], v[0:3]
	v_mfma_f32_16x16x32_bf16 v[28:31], v[154:157], v[170:173], v[28:31]
	v_mfma_f32_16x16x32_bf16 v[24:27], v[162:165], v[170:173], v[24:27]
	v_mfma_f32_16x16x32_bf16 v[20:23], v[154:157], v[178:181], v[20:23]
	v_mfma_f32_16x16x32_bf16 v[16:19], v[162:165], v[178:181], v[16:19]
	v_mfma_f32_16x16x32_bf16 v[12:15], v[154:157], v[186:189], v[12:15]
	v_mfma_f32_16x16x32_bf16 v[8:11], v[162:165], v[186:189], v[8:11]
	v_mfma_f32_16x16x32_bf16 v[4:7], v[154:157], v[194:197], v[4:7]
	v_mfma_f32_16x16x32_bf16 v[0:3], v[162:165], v[194:197], v[0:3]
	s_barrier
	s_mov_b32 m0, s76
	v_lshl_add_u64 v[214:215], v[214:215], 0, s[2:3]
	ds_read_b128 v[198:201], v148
	ds_read_b128 v[202:205], v148 offset:1024
	ds_read_b128 v[206:209], v148 offset:2048
	ds_read_b128 v[210:213], v148 offset:3072
	global_load_lds_dwordx4 v[214:215], off
	s_mov_b32 m0, s77
	v_lshl_add_u64 v[214:215], v[216:217], 0, s[2:3]
	global_load_lds_dwordx4 v[214:215], off
	s_barrier
	s_waitcnt lgkmcnt(0)
	v_mfma_f32_16x16x32_bf16 v[92:95], v[198:201], v[166:169], v[92:95]
	v_mfma_f32_16x16x32_bf16 v[88:91], v[206:209], v[166:169], v[88:91]
	v_mfma_f32_16x16x32_bf16 v[76:79], v[198:201], v[174:177], v[76:79]
	v_mfma_f32_16x16x32_bf16 v[72:75], v[206:209], v[174:177], v[72:75]
	v_mfma_f32_16x16x32_bf16 v[60:63], v[198:201], v[182:185], v[60:63]
	v_mfma_f32_16x16x32_bf16 v[56:59], v[206:209], v[182:185], v[56:59]
	v_mfma_f32_16x16x32_bf16 v[44:47], v[198:201], v[190:193], v[44:47]
	v_mfma_f32_16x16x32_bf16 v[40:43], v[206:209], v[190:193], v[40:43]
	v_mfma_f32_16x16x32_bf16 v[92:95], v[202:205], v[170:173], v[92:95]
	v_mfma_f32_16x16x32_bf16 v[88:91], v[210:213], v[170:173], v[88:91]
	v_mfma_f32_16x16x32_bf16 v[76:79], v[202:205], v[178:181], v[76:79]
	v_mfma_f32_16x16x32_bf16 v[72:75], v[210:213], v[178:181], v[72:75]
	v_mfma_f32_16x16x32_bf16 v[60:63], v[202:205], v[186:189], v[60:63]
	v_mfma_f32_16x16x32_bf16 v[56:59], v[210:213], v[186:189], v[56:59]
	v_mfma_f32_16x16x32_bf16 v[44:47], v[202:205], v[194:197], v[44:47]
	v_mfma_f32_16x16x32_bf16 v[40:43], v[210:213], v[194:197], v[40:43]
	s_mov_b32 m0, s61
	v_lshl_add_u64 v[214:215], v[218:219], 0, s[2:3]
	s_barrier
	ds_read_b128 v[166:169], v145 offset:49152
	ds_read_b128 v[170:173], v145 offset:50176
	ds_read_b128 v[174:177], v145 offset:51200
	ds_read_b128 v[178:181], v145 offset:52224
	ds_read_b128 v[182:185], v145 offset:53248
	ds_read_b128 v[186:189], v145 offset:54272
	ds_read_b128 v[190:193], v145 offset:55296
	ds_read_b128 v[194:197], v145 offset:56320
	global_load_lds_dwordx4 v[214:215], off
	s_mov_b32 m0, s62
	v_lshl_add_u64 v[214:215], v[222:223], 0, s[2:3]
	global_load_lds_dwordx4 v[214:215], off
	s_barrier
	s_waitcnt lgkmcnt(0)
	v_mfma_f32_16x16x32_bf16 v[84:87], v[150:153], v[166:169], v[84:87]
	v_mfma_f32_16x16x32_bf16 v[80:83], v[158:161], v[166:169], v[80:83]
	v_mfma_f32_16x16x32_bf16 v[68:71], v[150:153], v[174:177], v[68:71]
	v_mfma_f32_16x16x32_bf16 v[64:67], v[158:161], v[174:177], v[64:67]
	v_mfma_f32_16x16x32_bf16 v[52:55], v[150:153], v[182:185], v[52:55]
	v_mfma_f32_16x16x32_bf16 v[48:51], v[158:161], v[182:185], v[48:51]
	v_mfma_f32_16x16x32_bf16 v[36:39], v[150:153], v[190:193], v[36:39]
	v_mfma_f32_16x16x32_bf16 v[32:35], v[158:161], v[190:193], v[32:35]
	v_mfma_f32_16x16x32_bf16 v[84:87], v[154:157], v[170:173], v[84:87]
	v_mfma_f32_16x16x32_bf16 v[80:83], v[162:165], v[170:173], v[80:83]
	v_mfma_f32_16x16x32_bf16 v[68:71], v[154:157], v[178:181], v[68:71]
	v_mfma_f32_16x16x32_bf16 v[64:67], v[162:165], v[178:181], v[64:67]
	v_mfma_f32_16x16x32_bf16 v[52:55], v[154:157], v[186:189], v[52:55]
	v_mfma_f32_16x16x32_bf16 v[48:51], v[162:165], v[186:189], v[48:51]
	v_mfma_f32_16x16x32_bf16 v[36:39], v[154:157], v[194:197], v[36:39]
	v_mfma_f32_16x16x32_bf16 v[32:35], v[162:165], v[194:197], v[32:35]
	s_barrier
	s_add_u32 s46, s46, 0x40080
	s_addc_u32 s47, s47, 0
	s_mov_b32 m0, s78
	v_lshl_add_u64 v[150:151], s[46:47], 0, v[130:131]
	global_load_lds_dwordx4 v[150:151], off
	s_mov_b32 m0, s79
	v_lshl_add_u64 v[150:151], s[46:47], 0, v[128:129]
	global_load_lds_dwordx4 v[150:151], off
	s_waitcnt vmcnt(6)
	s_barrier
; #define G_WAIT_V(n) asm volatile("s_waitcnt vmcnt(" #n ")" ::: "memory")
; #define G_BAR __builtin_amdgcn_s_barrier()
;     ...
;         G_PAIR(0, 1);
; #pragma unroll 1
;         for (int t = 2; t < nt; t += 2) G_PAIR(t, 0);
;         p.epi(acc, cur, wr, wc, fr, fq);
;         if (!has_next) break;
;         cur = nxt; cA = nA; cB = nB; cA2 = nA2; cB2 = nB2; ++ui;
;     }
;     G_WAIT_V(0);
;     if (wr == 0) G_BAR;
;     G_BAR;
;     __device__ __forceinline__ void epi(const f32x4 (&acc)[2][2][4][2], const Unit& u, int wr, int wc, int fr, int fq) const {
;         const int row0 = u.pm * 256 + wr * 64 + fr, col0 = wc * 32 + 4 * fq;
; #pragma unroll
;         for (int ai = 0; ai < 2; ++ai)
; #pragma unroll
;             for (int m = 0; m < 4; ++m) {
;                 float* rowp = Send + (size_t)u.pn * NG * NCH * 256 + ((size_t)u.g * NCH + row0 + ai * 128 + m * 16) * 256 + col0;
; #pragma unroll
;                 for (int bj = 0; bj < 2; ++bj)
; #pragma unroll
;                     for (int n = 0; n < 2; ++n) *(f32x4*)(rowp + bj * 128 + n * 16) = acc[ai][bj][m][n];
;             }
	v_mfma_f32_16x16x32_bf16 v[124:127], v[198:201], v[166:169], v[124:127]
	v_mfma_f32_16x16x32_bf16 v[120:123], v[206:209], v[166:169], v[120:123]
	v_mfma_f32_16x16x32_bf16 v[116:119], v[198:201], v[174:177], v[116:119]
	v_mfma_f32_16x16x32_bf16 v[112:115], v[206:209], v[174:177], v[112:115]
	v_mfma_f32_16x16x32_bf16 v[108:111], v[198:201], v[182:185], v[108:111]
	v_mfma_f32_16x16x32_bf16 v[104:107], v[206:209], v[182:185], v[104:107]
	v_mfma_f32_16x16x32_bf16 v[100:103], v[198:201], v[190:193], v[100:103]
	v_mfma_f32_16x16x32_bf16 v[96:99], v[206:209], v[190:193], v[96:99]
	v_mfma_f32_16x16x32_bf16 v[124:127], v[202:205], v[170:173], v[124:127]
	v_mfma_f32_16x16x32_bf16 v[120:123], v[210:213], v[170:173], v[120:123]
	v_mfma_f32_16x16x32_bf16 v[116:119], v[202:205], v[178:181], v[116:119]
	v_mfma_f32_16x16x32_bf16 v[112:115], v[210:213], v[178:181], v[112:115]
	v_mfma_f32_16x16x32_bf16 v[108:111], v[202:205], v[186:189], v[108:111]
	v_mfma_f32_16x16x32_bf16 v[104:107], v[210:213], v[186:189], v[104:107]
	v_mfma_f32_16x16x32_bf16 v[100:103], v[202:205], v[194:197], v[100:103]
	v_mfma_f32_16x16x32_bf16 v[96:99], v[210:213], v[194:197], v[96:99]
	s_add_i32 s80, s80, 2
	s_add_u32 s44, s44, 0x100
	s_addc_u32 s45, s45, 0
	s_cmp_gt_u32 s80, 5
	s_cbranch_scc0 .Lrot_580
	s_barrier
	s_lshl_b32 s1, s53, 25
	s_add_u32 s4, s59, s1
	s_addc_u32 s5, s60, 0
	s_ashr_i32 s1, s0, 31
	v_lshl_add_u32 v138, s54, 8, v142
	s_lshl_b64 s[0:1], s[0:1], 19
	v_ashrrev_i32_e32 v139, 31, v138
	s_add_u32 s0, s4, s0
	v_lshlrev_b64 v[138:139], 10, v[138:139]
	s_addc_u32 s1, s5, s1
	v_lshl_add_u64 v[138:139], s[0:1], 0, v[138:139]
	v_lshl_add_u64 v[138:139], v[138:139], 0, v[132:133]
	global_store_dwordx4 v[138:139], v[28:31], off
	global_store_dwordx4 v[138:139], v[24:27], off offset:64
	global_store_dwordx4 v[138:139], v[92:95], off offset:512
	global_store_dwordx4 v[138:139], v[88:91], off offset:576
	v_add_co_u32_e32 v26, vcc, s58, v138
	v_lshl_add_u64 v[24:25], v[138:139], 0, s[18:19]
	s_nop 0
	v_addc_co_u32_e32 v27, vcc, 0, v139, vcc
	global_store_dwordx4 v[26:27], v[20:23], off
	global_store_dwordx4 v[24:25], v[16:19], off offset:64
	global_store_dwordx4 v[24:25], v[76:79], off offset:512
	global_store_dwordx4 v[24:25], v[72:75], off offset:576
	v_add_co_u32_e32 v18, vcc, s63, v138
	v_lshl_add_u64 v[16:17], v[138:139], 0, s[20:21]
	s_nop 0
	v_addc_co_u32_e32 v19, vcc, 0, v139, vcc
	global_store_dwordx4 v[18:19], v[12:15], off
	global_store_dwordx4 v[16:17], v[8:11], off offset:64
	global_store_dwordx4 v[16:17], v[60:63], off offset:512
	global_store_dwordx4 v[16:17], v[56:59], off offset:576
	v_add_co_u32_e32 v10, vcc, s65, v138
	v_lshl_add_u64 v[8:9], v[138:139], 0, s[22:23]
	s_nop 0
	v_addc_co_u32_e32 v11, vcc, 0, v139, vcc
	global_store_dwordx4 v[10:11], v[4:7], off
	global_store_dwordx4 v[8:9], v[0:3], off offset:64
	global_store_dwordx4 v[8:9], v[44:47], off offset:512
	global_store_dwordx4 v[8:9], v[40:43], off offset:576
	v_add_co_u32_e32 v2, vcc, s67, v138
	v_lshl_add_u64 v[0:1], v[138:139], 0, s[24:25]
	s_nop 0
	v_addc_co_u32_e32 v3, vcc, 0, v139, vcc
	global_store_dwordx4 v[2:3], v[84:87], off
	global_store_dwordx4 v[0:1], v[80:83], off offset:64
	global_store_dwordx4 v[0:1], v[124:127], off offset:512
	global_store_dwordx4 v[0:1], v[120:123], off offset:576
	v_add_co_u32_e32 v2, vcc, s68, v138
	v_lshl_add_u64 v[0:1], v[138:139], 0, s[26:27]
	s_nop 0
	v_addc_co_u32_e32 v3, vcc, 0, v139, vcc
	global_store_dwordx4 v[2:3], v[68:71], off
	global_store_dwordx4 v[0:1], v[64:67], off offset:64
	global_store_dwordx4 v[0:1], v[116:119], off offset:512
	global_store_dwordx4 v[0:1], v[112:115], off offset:576
	v_add_co_u32_e32 v2, vcc, s69, v138
	v_lshl_add_u64 v[0:1], v[138:139], 0, s[28:29]
	s_nop 0
	v_addc_co_u32_e32 v3, vcc, 0, v139, vcc
	global_store_dwordx4 v[2:3], v[52:55], off
	global_store_dwordx4 v[0:1], v[48:51], off offset:64
	global_store_dwordx4 v[0:1], v[108:111], off offset:512
	global_store_dwordx4 v[0:1], v[104:107], off offset:576
	v_add_co_u32_e32 v2, vcc, 0x2c000, v138
	s_mov_b32 s54, s72
	s_nop 0
	v_addc_co_u32_e32 v3, vcc, 0, v139, vcc
	v_readlane_b32 s72, v254, 3
	v_readlane_b32 s74, v254, 5
	s_and_b64 vcc, exec, s[36:37]
	s_mov_b32 s0, s34
	s_mov_b32 s53, s71
	s_mov_b64 s[6:7], s[40:41]
	s_mov_b64 s[4:5], s[38:39]
	v_readlane_b32 s73, v254, 4
	v_readlane_b32 s75, v254, 6
	v_lshl_add_u64 v[0:1], v[138:139], 0, s[30:31]
	global_store_dwordx4 v[2:3], v[36:39], off
	global_store_dwordx4 v[0:1], v[32:35], off offset:64
	global_store_dwordx4 v[0:1], v[100:103], off offset:512
	global_store_dwordx4 v[0:1], v[96:99], off offset:576
	s_cbranch_vccz .LBB0_575
	s_waitcnt vmcnt(0)
	s_cmpk_gt_u32 s48, 0xff
	s_cbranch_scc1 .LBB0_584
	s_barrier

;     ...
;         G_PAIR(0, 1);
.LBB0_919:
	s_ashr_i32 s19, s18, 31
	s_waitcnt lgkmcnt(0)
	ds_read_b128 v[0:3], v172
	ds_read_b128 v[4:7], v172 offset:1024
	ds_read_b128 v[8:11], v172 offset:2048
	ds_read_b128 v[12:15], v172 offset:3072
	s_lshl_b64 s[20:21], s[18:19], 19
	s_add_u32 s20, s37, s20
	s_addc_u32 s21, s38, s21
	s_ashr_i32 s17, s16, 31
	s_lshl_b64 s[22:23], s[16:17], 19
	s_add_u32 s22, s39, s22
	s_addc_u32 s23, s40, s23
	s_add_u32 s30, s24, 0x40080
	s_addc_u32 s31, s25, 0
	s_mov_b32 m0, s48
	v_lshl_add_u64 v[48:49], s[30:31], 0, v[146:147]
	ds_read_b128 v[16:19], v173
	ds_read_b128 v[20:23], v173 offset:1024
	ds_read_b128 v[24:27], v173 offset:2048
	ds_read_b128 v[28:31], v173 offset:3072
	ds_read_b128 v[32:35], v173 offset:4096
	ds_read_b128 v[36:39], v173 offset:5120
	ds_read_b128 v[40:43], v173 offset:6144
	ds_read_b128 v[44:47], v173 offset:7168
	global_load_lds_dwordx4 v[48:49], off
	s_mov_b32 m0, s49
	v_lshl_add_u64 v[48:49], s[30:31], 0, v[142:143]
	global_load_lds_dwordx4 v[48:49], off
	s_waitcnt lgkmcnt(8)
	s_barrier
	s_waitcnt lgkmcnt(0)
	v_mfma_f32_16x16x32_bf16 v[48:51], v[0:3], v[16:19], 0
	v_mfma_f32_16x16x32_bf16 v[52:55], v[8:11], v[16:19], 0
	v_mfma_f32_16x16x32_bf16 v[56:59], v[0:3], v[24:27], 0
	v_mfma_f32_16x16x32_bf16 v[60:63], v[8:11], v[24:27], 0
	v_mfma_f32_16x16x32_bf16 v[64:67], v[0:3], v[32:35], 0
	v_mfma_f32_16x16x32_bf16 v[68:71], v[8:11], v[32:35], 0
	v_mfma_f32_16x16x32_bf16 v[72:75], v[0:3], v[40:43], 0
	v_mfma_f32_16x16x32_bf16 v[76:79], v[8:11], v[40:43], 0
	v_mfma_f32_16x16x32_bf16 v[48:51], v[4:7], v[20:23], v[48:51]
	v_mfma_f32_16x16x32_bf16 v[52:55], v[12:15], v[20:23], v[52:55]
	v_mfma_f32_16x16x32_bf16 v[56:59], v[4:7], v[28:31], v[56:59]
	v_mfma_f32_16x16x32_bf16 v[60:63], v[12:15], v[28:31], v[60:63]
	v_mfma_f32_16x16x32_bf16 v[64:67], v[4:7], v[36:39], v[64:67]
	v_mfma_f32_16x16x32_bf16 v[68:71], v[12:15], v[36:39], v[68:71]
	v_mfma_f32_16x16x32_bf16 v[72:75], v[4:7], v[44:47], v[72:75]
	v_mfma_f32_16x16x32_bf16 v[76:79], v[12:15], v[44:47], v[76:79]
	s_barrier
	v_lshl_add_u64 v[168:169], s[26:27], 0, v[144:145]
	s_mov_b32 m0, s50
	v_lshl_add_u64 v[96:97], v[168:169], 0, s[10:11]
	v_lshl_add_u64 v[218:219], s[26:27], 0, v[140:141]
	ds_read_b128 v[80:83], v174
	ds_read_b128 v[84:87], v174 offset:1024
	ds_read_b128 v[88:91], v174 offset:2048
	ds_read_b128 v[92:95], v174 offset:3072
	global_load_lds_dwordx4 v[96:97], off
	s_mov_b32 m0, s51
	v_lshl_add_u64 v[96:97], v[218:219], 0, s[10:11]
	global_load_lds_dwordx4 v[96:97], off
	s_barrier
	s_waitcnt lgkmcnt(0)
	v_mfma_f32_16x16x32_bf16 v[96:99], v[80:83], v[16:19], 0
	v_mfma_f32_16x16x32_bf16 v[16:19], v[88:91], v[16:19], 0
	v_mfma_f32_16x16x32_bf16 v[100:103], v[80:83], v[24:27], 0
	v_mfma_f32_16x16x32_bf16 v[24:27], v[88:91], v[24:27], 0
	v_mfma_f32_16x16x32_bf16 v[104:107], v[80:83], v[32:35], 0
	v_mfma_f32_16x16x32_bf16 v[32:35], v[88:91], v[32:35], 0
	v_mfma_f32_16x16x32_bf16 v[108:111], v[80:83], v[40:43], 0
	v_mfma_f32_16x16x32_bf16 v[40:43], v[88:91], v[40:43], 0
	v_mfma_f32_16x16x32_bf16 v[120:123], v[84:87], v[20:23], v[96:99]
	v_mfma_f32_16x16x32_bf16 v[16:19], v[92:95], v[20:23], v[16:19]
	v_mfma_f32_16x16x32_bf16 v[20:23], v[84:87], v[28:31], v[100:103]
	v_mfma_f32_16x16x32_bf16 v[24:27], v[92:95], v[28:31], v[24:27]
	v_mfma_f32_16x16x32_bf16 v[28:31], v[84:87], v[36:39], v[104:107]
	v_mfma_f32_16x16x32_bf16 v[32:35], v[92:95], v[36:39], v[32:35]
	v_mfma_f32_16x16x32_bf16 v[36:39], v[84:87], v[44:47], v[108:111]
	v_mfma_f32_16x16x32_bf16 v[40:43], v[92:95], v[44:47], v[40:43]
	v_lshl_add_u64 v[242:243], s[24:25], 0, v[146:147]
	s_mov_b32 m0, s41
	v_lshl_add_u64 v[128:129], v[242:243], 0, s[10:11]
	v_lshl_add_u64 v[244:245], s[24:25], 0, v[142:143]
	s_barrier
	ds_read_b128 v[44:47], v173 offset:16384
	ds_read_b128 v[96:99], v173 offset:17408
	ds_read_b128 v[100:103], v173 offset:18432
	ds_read_b128 v[104:107], v173 offset:19456
	ds_read_b128 v[108:111], v173 offset:20480
	ds_read_b128 v[112:115], v173 offset:21504
	ds_read_b128 v[116:119], v173 offset:22528
	ds_read_b128 v[124:127], v173 offset:23552
	global_load_lds_dwordx4 v[128:129], off
	s_mov_b32 m0, s42
	v_lshl_add_u64 v[128:129], v[244:245], 0, s[10:11]
	global_load_lds_dwordx4 v[128:129], off
	s_barrier
	s_waitcnt lgkmcnt(0)
	v_mfma_f32_16x16x32_bf16 v[128:131], v[0:3], v[44:47], 0
	v_mfma_f32_16x16x32_bf16 v[132:135], v[8:11], v[44:47], 0
	v_mfma_f32_16x16x32_bf16 v[136:139], v[0:3], v[100:103], 0
	v_mfma_f32_16x16x32_bf16 v[152:155], v[8:11], v[100:103], 0
	v_mfma_f32_16x16x32_bf16 v[156:159], v[0:3], v[108:111], 0
	v_mfma_f32_16x16x32_bf16 v[160:163], v[8:11], v[108:111], 0
	v_mfma_f32_16x16x32_bf16 v[0:3], v[0:3], v[116:119], 0
	v_mfma_f32_16x16x32_bf16 v[8:11], v[8:11], v[116:119], 0
	v_mfma_f32_16x16x32_bf16 v[164:167], v[4:7], v[96:99], v[128:131]
	v_mfma_f32_16x16x32_bf16 v[136:139], v[4:7], v[104:107], v[136:139]
	v_mfma_f32_16x16x32_bf16 v[156:159], v[4:7], v[112:115], v[156:159]
	v_mfma_f32_16x16x32_bf16 v[0:3], v[4:7], v[124:127], v[0:3]
	v_mfma_f32_16x16x32_bf16 v[4:7], v[12:15], v[124:127], v[8:11]
	v_mfma_f32_16x16x32_bf16 v[132:135], v[12:15], v[96:99], v[132:135]
	v_mfma_f32_16x16x32_bf16 v[152:155], v[12:15], v[104:107], v[152:155]
	v_mfma_f32_16x16x32_bf16 v[160:163], v[12:15], v[112:115], v[160:163]
	s_barrier
	s_add_u32 s30, s26, 0x40100
	s_addc_u32 s31, s27, 0
	s_mov_b32 m0, s52
	v_lshl_add_u64 v[8:9], s[30:31], 0, v[144:145]
	global_load_lds_dwordx4 v[8:9], off
	s_mov_b32 m0, s53
	v_lshl_add_u64 v[8:9], s[30:31], 0, v[140:141]
	global_load_lds_dwordx4 v[8:9], off
	s_waitcnt vmcnt(6)
	s_barrier
	v_mfma_f32_16x16x32_bf16 v[8:11], v[80:83], v[44:47], 0
	v_mfma_f32_16x16x32_bf16 v[12:15], v[88:91], v[44:47], 0
	v_mfma_f32_16x16x32_bf16 v[44:47], v[80:83], v[100:103], 0
	v_mfma_f32_16x16x32_bf16 v[100:103], v[88:91], v[100:103], 0
	v_mfma_f32_16x16x32_bf16 v[128:131], v[80:83], v[108:111], 0
	v_mfma_f32_16x16x32_bf16 v[108:111], v[88:91], v[108:111], 0
	v_mfma_f32_16x16x32_bf16 v[80:83], v[80:83], v[116:119], 0
	v_mfma_f32_16x16x32_bf16 v[88:91], v[88:91], v[116:119], 0
	v_mfma_f32_16x16x32_bf16 v[8:11], v[84:87], v[96:99], v[8:11]
	v_mfma_f32_16x16x32_bf16 v[12:15], v[92:95], v[96:99], v[12:15]
	v_mfma_f32_16x16x32_bf16 v[44:47], v[84:87], v[104:107], v[44:47]
	v_mfma_f32_16x16x32_bf16 v[178:181], v[92:95], v[104:107], v[100:103]
	v_mfma_f32_16x16x32_bf16 v[182:185], v[84:87], v[112:115], v[128:131]
	v_mfma_f32_16x16x32_bf16 v[186:189], v[92:95], v[112:115], v[108:111]
	v_mfma_f32_16x16x32_bf16 v[190:193], v[84:87], v[124:127], v[80:83]
	v_mfma_f32_16x16x32_bf16 v[194:197], v[92:95], v[124:127], v[88:91]
	s_barrier
	ds_read_b128 v[198:201], v176
	ds_read_b128 v[202:205], v176 offset:1024
	ds_read_b128 v[206:209], v176 offset:2048
	ds_read_b128 v[210:213], v176 offset:3072
	s_add_u32 s30, s24, 0x40100
	s_addc_u32 s31, s25, 0
	s_mov_b32 m0, s43
	v_lshl_add_u64 v[80:81], s[30:31], 0, v[146:147]
	ds_read_b128 v[88:91], v173 offset:32768
	ds_read_b128 v[92:95], v173 offset:33792
	ds_read_b128 v[104:107], v173 offset:34816
	ds_read_b128 v[214:217], v173 offset:35840
	ds_read_b128 v[108:111], v173 offset:36864
	ds_read_b128 v[222:225], v173 offset:37888
	ds_read_b128 v[124:127], v173 offset:38912
	ds_read_b128 v[226:229], v173 offset:39936
	global_load_lds_dwordx4 v[80:81], off
	s_mov_b32 m0, s44
	v_lshl_add_u64 v[80:81], s[30:31], 0, v[142:143]
	global_load_lds_dwordx4 v[80:81], off
	s_waitcnt lgkmcnt(8)
	s_barrier
	s_waitcnt lgkmcnt(0)
	v_mfma_f32_16x16x32_bf16 v[48:51], v[198:201], v[88:91], v[48:51]
	v_mfma_f32_16x16x32_bf16 v[52:55], v[206:209], v[88:91], v[52:55]
	v_mfma_f32_16x16x32_bf16 v[56:59], v[198:201], v[104:107], v[56:59]
	v_mfma_f32_16x16x32_bf16 v[60:63], v[206:209], v[104:107], v[60:63]
	v_mfma_f32_16x16x32_bf16 v[64:67], v[198:201], v[108:111], v[64:67]
	v_mfma_f32_16x16x32_bf16 v[68:71], v[206:209], v[108:111], v[68:71]
	v_mfma_f32_16x16x32_bf16 v[72:75], v[198:201], v[124:127], v[72:75]
	v_mfma_f32_16x16x32_bf16 v[76:79], v[206:209], v[124:127], v[76:79]
	v_mfma_f32_16x16x32_bf16 v[116:119], v[202:205], v[92:95], v[48:51]
	v_mfma_f32_16x16x32_bf16 v[112:115], v[210:213], v[92:95], v[52:55]
	v_mfma_f32_16x16x32_bf16 v[100:103], v[202:205], v[214:217], v[56:59]
	v_mfma_f32_16x16x32_bf16 v[96:99], v[210:213], v[214:217], v[60:63]
	v_mfma_f32_16x16x32_bf16 v[84:87], v[202:205], v[222:225], v[64:67]
	v_mfma_f32_16x16x32_bf16 v[80:83], v[210:213], v[222:225], v[68:71]
	v_mfma_f32_16x16x32_bf16 v[68:71], v[202:205], v[226:229], v[72:75]
	v_mfma_f32_16x16x32_bf16 v[64:67], v[210:213], v[226:229], v[76:79]
	s_barrier
	s_mov_b32 m0, s54
	v_lshl_add_u64 v[48:49], v[168:169], 0, s[12:13]
	ds_read_b128 v[56:59], v177
	ds_read_b128 v[230:233], v177 offset:1024
	ds_read_b128 v[60:63], v177 offset:2048
	ds_read_b128 v[234:237], v177 offset:3072
	global_load_lds_dwordx4 v[48:49], off
	s_mov_b32 m0, s55
	v_lshl_add_u64 v[48:49], v[218:219], 0, s[12:13]
	global_load_lds_dwordx4 v[48:49], off
	s_barrier
	s_waitcnt lgkmcnt(0)
	v_mfma_f32_16x16x32_bf16 v[48:51], v[56:59], v[88:91], v[120:123]
	v_mfma_f32_16x16x32_bf16 v[16:19], v[60:63], v[88:91], v[16:19]
	v_mfma_f32_16x16x32_bf16 v[20:23], v[56:59], v[104:107], v[20:23]
	v_mfma_f32_16x16x32_bf16 v[24:27], v[60:63], v[104:107], v[24:27]
	v_mfma_f32_16x16x32_bf16 v[28:31], v[56:59], v[108:111], v[28:31]
	v_mfma_f32_16x16x32_bf16 v[32:35], v[60:63], v[108:111], v[32:35]
	v_mfma_f32_16x16x32_bf16 v[36:39], v[56:59], v[124:127], v[36:39]
	v_mfma_f32_16x16x32_bf16 v[40:43], v[60:63], v[124:127], v[40:43]
	v_mfma_f32_16x16x32_bf16 v[128:131], v[230:233], v[92:95], v[48:51]
	v_mfma_f32_16x16x32_bf16 v[124:127], v[234:237], v[92:95], v[16:19]
	v_mfma_f32_16x16x32_bf16 v[108:111], v[230:233], v[214:217], v[20:23]
	v_mfma_f32_16x16x32_bf16 v[104:107], v[234:237], v[214:217], v[24:27]
	v_mfma_f32_16x16x32_bf16 v[92:95], v[230:233], v[222:225], v[28:31]
	v_mfma_f32_16x16x32_bf16 v[88:91], v[234:237], v[222:225], v[32:35]
	v_mfma_f32_16x16x32_bf16 v[76:79], v[230:233], v[226:229], v[36:39]
	v_mfma_f32_16x16x32_bf16 v[72:75], v[234:237], v[226:229], v[40:43]
	s_mov_b32 m0, s46
	v_lshl_add_u64 v[16:17], v[242:243], 0, s[12:13]
	s_barrier
	ds_read_b128 v[24:27], v173 offset:49152
	ds_read_b128 v[28:31], v173 offset:50176
	ds_read_b128 v[40:43], v173 offset:51200
	ds_read_b128 v[120:123], v173 offset:52224
	ds_read_b128 v[214:217], v173 offset:53248
	ds_read_b128 v[222:225], v173 offset:54272
	ds_read_b128 v[226:229], v173 offset:55296
	ds_read_b128 v[238:241], v173 offset:56320
	global_load_lds_dwordx4 v[16:17], off
	s_mov_b32 m0, s47
	v_lshl_add_u64 v[16:17], v[244:245], 0, s[12:13]
	global_load_lds_dwordx4 v[16:17], off
	s_barrier
	s_waitcnt lgkmcnt(0)
	v_mfma_f32_16x16x32_bf16 v[16:19], v[198:201], v[24:27], v[164:167]
	v_mfma_f32_16x16x32_bf16 v[20:23], v[206:209], v[24:27], v[132:135]
	v_mfma_f32_16x16x32_bf16 v[32:35], v[198:201], v[40:43], v[136:139]
	v_mfma_f32_16x16x32_bf16 v[132:135], v[206:209], v[40:43], v[152:155]
	v_mfma_f32_16x16x32_bf16 v[136:139], v[198:201], v[214:217], v[156:159]
	v_mfma_f32_16x16x32_bf16 v[152:155], v[206:209], v[214:217], v[160:163]
	v_mfma_f32_16x16x32_bf16 v[0:3], v[198:201], v[226:229], v[0:3]
	v_mfma_f32_16x16x32_bf16 v[156:159], v[206:209], v[226:229], v[4:7]
	v_mfma_f32_16x16x32_bf16 v[52:55], v[202:205], v[28:31], v[16:19]
	v_mfma_f32_16x16x32_bf16 v[48:51], v[210:213], v[28:31], v[20:23]
	v_mfma_f32_16x16x32_bf16 v[36:39], v[202:205], v[120:123], v[32:35]
	v_mfma_f32_16x16x32_bf16 v[32:35], v[210:213], v[120:123], v[132:135]
	v_mfma_f32_16x16x32_bf16 v[20:23], v[202:205], v[222:225], v[136:139]
	v_mfma_f32_16x16x32_bf16 v[16:19], v[210:213], v[222:225], v[152:155]
	v_mfma_f32_16x16x32_bf16 v[4:7], v[202:205], v[238:241], v[0:3]
	v_mfma_f32_16x16x32_bf16 v[0:3], v[210:213], v[238:241], v[156:159]
	s_barrier
;     ...
;         G_PAIR(0, 1);
; #pragma unroll 1
;         for (int t = 2; t < nt; t += 2) G_PAIR(t, 0);
	s_add_u32 s30, s26, 0x40180
	s_addc_u32 s31, s27, 0
	s_mov_b32 m0, s56
	v_lshl_add_u64 v[132:133], s[30:31], 0, v[144:145]
	global_load_lds_dwordx4 v[132:133], off
	v_lshl_add_u64 v[132:133], s[30:31], 0, v[140:141]
	s_mov_b32 m0, s57
	s_mov_b64 s[30:31], 0x40180
	global_load_lds_dwordx4 v[132:133], off
	s_waitcnt vmcnt(6)
	s_barrier
	v_mfma_f32_16x16x32_bf16 v[8:11], v[56:59], v[24:27], v[8:11]
	v_mfma_f32_16x16x32_bf16 v[12:15], v[60:63], v[24:27], v[12:15]
	v_mfma_f32_16x16x32_bf16 v[24:27], v[56:59], v[40:43], v[44:47]
	v_mfma_f32_16x16x32_bf16 v[40:43], v[60:63], v[40:43], v[178:181]
	v_mfma_f32_16x16x32_bf16 v[132:135], v[56:59], v[214:217], v[182:185]
	v_mfma_f32_16x16x32_bf16 v[136:139], v[60:63], v[214:217], v[186:189]
	v_mfma_f32_16x16x32_bf16 v[152:155], v[56:59], v[226:229], v[190:193]
	v_mfma_f32_16x16x32_bf16 v[156:159], v[60:63], v[226:229], v[194:197]
	v_mfma_f32_16x16x32_bf16 v[60:63], v[230:233], v[28:31], v[8:11]
	v_mfma_f32_16x16x32_bf16 v[56:59], v[234:237], v[28:31], v[12:15]
	v_mfma_f32_16x16x32_bf16 v[44:47], v[230:233], v[120:123], v[24:27]
	v_mfma_f32_16x16x32_bf16 v[40:43], v[234:237], v[120:123], v[40:43]
	v_mfma_f32_16x16x32_bf16 v[28:31], v[230:233], v[222:225], v[132:135]
	v_mfma_f32_16x16x32_bf16 v[24:27], v[234:237], v[222:225], v[136:139]
	v_mfma_f32_16x16x32_bf16 v[12:15], v[230:233], v[238:241], v[152:155]
	v_mfma_f32_16x16x32_bf16 v[8:11], v[234:237], v[238:241], v[156:159]
	v_lshl_add_u64 v[120:121], s[24:25], 0, v[148:149]
	v_lshl_add_u64 v[122:123], s[24:25], 0, v[150:151]
	s_mov_b32 s17, 0
.Lrot_920:
	s_barrier
.LBB0_920:
	ds_read_b128 v[132:135], v172
	ds_read_b128 v[136:139], v172 offset:1024
	ds_read_b128 v[152:155], v172 offset:2048
	ds_read_b128 v[156:159], v172 offset:3072
	s_mov_b32 m0, s48
	v_lshl_add_u64 v[168:169], v[120:121], 0, s[30:31]
	ds_read_b128 v[160:163], v173
	ds_read_b128 v[164:167], v173 offset:1024
	ds_read_b128 v[178:181], v173 offset:2048
	ds_read_b128 v[182:185], v173 offset:3072
	ds_read_b128 v[186:189], v173 offset:4096
	ds_read_b128 v[190:193], v173 offset:5120
	ds_read_b128 v[194:197], v173 offset:6144
	ds_read_b128 v[198:201], v173 offset:7168
	global_load_lds_dwordx4 v[168:169], off
	s_mov_b32 m0, s49
	v_lshl_add_u64 v[168:169], v[122:123], 0, s[30:31]
	global_load_lds_dwordx4 v[168:169], off
	s_waitcnt lgkmcnt(8)
	s_barrier
	s_waitcnt lgkmcnt(0)
	v_mfma_f32_16x16x32_bf16 v[116:119], v[132:135], v[160:163], v[116:119]
	s_add_i32 s19, s30, 0xfffc0080
	v_mfma_f32_16x16x32_bf16 v[112:115], v[152:155], v[160:163], v[112:115]
	s_cmp_eq_u32 s17, 12
	v_mfma_f32_16x16x32_bf16 v[100:103], v[132:135], v[178:181], v[100:103]
	s_cselect_b64 s[34:35], -1, 0
	v_mfma_f32_16x16x32_bf16 v[96:99], v[152:155], v[178:181], v[96:99]
	s_and_b64 s[60:61], s[34:35], exec
	v_mfma_f32_16x16x32_bf16 v[84:87], v[132:135], v[186:189], v[84:87]
	s_cselect_b32 s19, 0, s19
	v_mfma_f32_16x16x32_bf16 v[80:83], v[152:155], v[186:189], v[80:83]
	s_and_b64 s[34:35], s[28:29], s[34:35]
	v_mfma_f32_16x16x32_bf16 v[68:71], v[132:135], v[194:197], v[68:71]
	s_and_b64 s[34:35], s[34:35], exec
	v_mfma_f32_16x16x32_bf16 v[64:67], v[152:155], v[194:197], v[64:67]
	s_cselect_b32 s61, s21, s25
	v_mfma_f32_16x16x32_bf16 v[116:119], v[136:139], v[164:167], v[116:119]
	s_cselect_b32 s60, s20, s24
	v_mfma_f32_16x16x32_bf16 v[112:115], v[156:159], v[164:167], v[112:115]
	s_cselect_b32 s35, s23, s27
	v_mfma_f32_16x16x32_bf16 v[100:103], v[136:139], v[182:185], v[100:103]
	s_cselect_b32 s34, s22, s26
	v_mfma_f32_16x16x32_bf16 v[96:99], v[156:159], v[182:185], v[96:99]
	v_mfma_f32_16x16x32_bf16 v[84:87], v[136:139], v[190:193], v[84:87]
	v_mfma_f32_16x16x32_bf16 v[80:83], v[156:159], v[190:193], v[80:83]
	v_mfma_f32_16x16x32_bf16 v[68:71], v[136:139], v[198:201], v[68:71]
	v_mfma_f32_16x16x32_bf16 v[64:67], v[156:159], v[198:201], v[64:67]
	s_barrier
	s_add_u32 s34, s34, s19
	s_addc_u32 s35, s35, 0
	s_mov_b32 m0, s50
	v_lshl_add_u64 v[168:169], s[34:35], 0, v[144:145]
	ds_read_b128 v[202:205], v174
	ds_read_b128 v[206:209], v174 offset:1024
	ds_read_b128 v[210:213], v174 offset:2048
	ds_read_b128 v[214:217], v174 offset:3072
	global_load_lds_dwordx4 v[168:169], off
	s_mov_b32 m0, s51
	v_lshl_add_u64 v[218:219], s[34:35], 0, v[140:141]
	global_load_lds_dwordx4 v[218:219], off
	s_barrier
	s_waitcnt lgkmcnt(0)
	v_mfma_f32_16x16x32_bf16 v[128:131], v[202:205], v[160:163], v[128:131]
	v_mfma_f32_16x16x32_bf16 v[124:127], v[210:213], v[160:163], v[124:127]
	v_mfma_f32_16x16x32_bf16 v[108:111], v[202:205], v[178:181], v[108:111]
	v_mfma_f32_16x16x32_bf16 v[104:107], v[210:213], v[178:181], v[104:107]
	v_mfma_f32_16x16x32_bf16 v[92:95], v[202:205], v[186:189], v[92:95]
	v_mfma_f32_16x16x32_bf16 v[88:91], v[210:213], v[186:189], v[88:91]
	v_mfma_f32_16x16x32_bf16 v[76:79], v[202:205], v[194:197], v[76:79]
	v_mfma_f32_16x16x32_bf16 v[72:75], v[210:213], v[194:197], v[72:75]
	v_mfma_f32_16x16x32_bf16 v[128:131], v[206:209], v[164:167], v[128:131]
	v_mfma_f32_16x16x32_bf16 v[124:127], v[214:217], v[164:167], v[124:127]
	v_mfma_f32_16x16x32_bf16 v[108:111], v[206:209], v[182:185], v[108:111]
	v_mfma_f32_16x16x32_bf16 v[104:107], v[214:217], v[182:185], v[104:107]
	v_mfma_f32_16x16x32_bf16 v[92:95], v[206:209], v[190:193], v[92:95]
	v_mfma_f32_16x16x32_bf16 v[88:91], v[214:217], v[190:193], v[88:91]
	v_mfma_f32_16x16x32_bf16 v[76:79], v[206:209], v[198:201], v[76:79]
	v_mfma_f32_16x16x32_bf16 v[72:75], v[214:217], v[198:201], v[72:75]
	s_add_u32 s60, s60, s19
	s_addc_u32 s61, s61, 0
	s_mov_b32 m0, s41
	v_lshl_add_u64 v[222:223], s[60:61], 0, v[146:147]
	s_barrier
	ds_read_b128 v[160:163], v173 offset:16384
	ds_read_b128 v[164:167], v173 offset:17408
	ds_read_b128 v[178:181], v173 offset:18432
	ds_read_b128 v[182:185], v173 offset:19456
	ds_read_b128 v[186:189], v173 offset:20480
	ds_read_b128 v[190:193], v173 offset:21504
	ds_read_b128 v[194:197], v173 offset:22528
	ds_read_b128 v[198:201], v173 offset:23552
	global_load_lds_dwordx4 v[222:223], off
	s_mov_b32 m0, s42
	v_lshl_add_u64 v[224:225], s[60:61], 0, v[142:143]
	global_load_lds_dwordx4 v[224:225], off
	s_barrier
	s_waitcnt lgkmcnt(0)
	v_mfma_f32_16x16x32_bf16 v[52:55], v[132:135], v[160:163], v[52:55]
	v_mfma_f32_16x16x32_bf16 v[48:51], v[152:155], v[160:163], v[48:51]
	v_mfma_f32_16x16x32_bf16 v[36:39], v[132:135], v[178:181], v[36:39]
	v_mfma_f32_16x16x32_bf16 v[32:35], v[152:155], v[178:181], v[32:35]
	v_mfma_f32_16x16x32_bf16 v[20:23], v[132:135], v[186:189], v[20:23]
	v_mfma_f32_16x16x32_bf16 v[16:19], v[152:155], v[186:189], v[16:19]
	v_mfma_f32_16x16x32_bf16 v[4:7], v[132:135], v[194:197], v[4:7]
	v_mfma_f32_16x16x32_bf16 v[0:3], v[152:155], v[194:197], v[0:3]
	v_mfma_f32_16x16x32_bf16 v[52:55], v[136:139], v[164:167], v[52:55]
	v_mfma_f32_16x16x32_bf16 v[48:51], v[156:159], v[164:167], v[48:51]
	v_mfma_f32_16x16x32_bf16 v[36:39], v[136:139], v[182:185], v[36:39]
	v_mfma_f32_16x16x32_bf16 v[32:35], v[156:159], v[182:185], v[32:35]
	v_mfma_f32_16x16x32_bf16 v[20:23], v[136:139], v[190:193], v[20:23]
	v_mfma_f32_16x16x32_bf16 v[16:19], v[156:159], v[190:193], v[16:19]
	v_mfma_f32_16x16x32_bf16 v[4:7], v[136:139], v[198:201], v[4:7]
	v_mfma_f32_16x16x32_bf16 v[0:3], v[156:159], v[198:201], v[0:3]
	s_barrier
	s_add_u32 s62, s34, 0x40000
	s_addc_u32 s63, s35, 0
	s_mov_b32 m0, s52
	v_lshl_add_u64 v[132:133], s[62:63], 0, v[144:145]
	global_load_lds_dwordx4 v[132:133], off
	s_mov_b32 m0, s53
	v_lshl_add_u64 v[132:133], s[62:63], 0, v[140:141]
	global_load_lds_dwordx4 v[132:133], off
	s_waitcnt vmcnt(6)
	s_barrier
	v_mfma_f32_16x16x32_bf16 v[60:63], v[202:205], v[160:163], v[60:63]
	v_mfma_f32_16x16x32_bf16 v[56:59], v[210:213], v[160:163], v[56:59]
	v_mfma_f32_16x16x32_bf16 v[44:47], v[202:205], v[178:181], v[44:47]
	v_mfma_f32_16x16x32_bf16 v[40:43], v[210:213], v[178:181], v[40:43]
	v_mfma_f32_16x16x32_bf16 v[28:31], v[202:205], v[186:189], v[28:31]
	v_mfma_f32_16x16x32_bf16 v[24:27], v[210:213], v[186:189], v[24:27]
	v_mfma_f32_16x16x32_bf16 v[12:15], v[202:205], v[194:197], v[12:15]
	v_mfma_f32_16x16x32_bf16 v[8:11], v[210:213], v[194:197], v[8:11]
	v_mfma_f32_16x16x32_bf16 v[60:63], v[206:209], v[164:167], v[60:63]
	v_mfma_f32_16x16x32_bf16 v[56:59], v[214:217], v[164:167], v[56:59]
	v_mfma_f32_16x16x32_bf16 v[44:47], v[206:209], v[182:185], v[44:47]
	v_mfma_f32_16x16x32_bf16 v[40:43], v[214:217], v[182:185], v[40:43]
	v_mfma_f32_16x16x32_bf16 v[28:31], v[206:209], v[190:193], v[28:31]
	v_mfma_f32_16x16x32_bf16 v[24:27], v[214:217], v[190:193], v[24:27]
	v_mfma_f32_16x16x32_bf16 v[12:15], v[206:209], v[198:201], v[12:15]
	v_mfma_f32_16x16x32_bf16 v[8:11], v[214:217], v[198:201], v[8:11]
	s_barrier
	ds_read_b128 v[132:135], v176
	ds_read_b128 v[136:139], v176 offset:1024
	ds_read_b128 v[152:155], v176 offset:2048
	ds_read_b128 v[156:159], v176 offset:3072
	s_add_u32 s60, s60, 0x40000
	s_addc_u32 s61, s61, 0
	s_mov_b32 m0, s43
	v_lshl_add_u64 v[202:203], s[60:61], 0, v[146:147]
	ds_read_b128 v[160:163], v173 offset:32768
	ds_read_b128 v[164:167], v173 offset:33792
	ds_read_b128 v[178:181], v173 offset:34816
	ds_read_b128 v[182:185], v173 offset:35840
	ds_read_b128 v[186:189], v173 offset:36864
	ds_read_b128 v[190:193], v173 offset:37888
	ds_read_b128 v[194:197], v173 offset:38912
	ds_read_b128 v[198:201], v173 offset:39936
	global_load_lds_dwordx4 v[202:203], off
	s_mov_b32 m0, s44
	v_lshl_add_u64 v[202:203], s[60:61], 0, v[142:143]
	global_load_lds_dwordx4 v[202:203], off
	s_waitcnt lgkmcnt(8)
	s_barrier
	s_waitcnt lgkmcnt(0)
	v_mfma_f32_16x16x32_bf16 v[116:119], v[132:135], v[160:163], v[116:119]
	v_mfma_f32_16x16x32_bf16 v[112:115], v[152:155], v[160:163], v[112:115]
	v_mfma_f32_16x16x32_bf16 v[100:103], v[132:135], v[178:181], v[100:103]
	v_mfma_f32_16x16x32_bf16 v[96:99], v[152:155], v[178:181], v[96:99]
	v_mfma_f32_16x16x32_bf16 v[84:87], v[132:135], v[186:189], v[84:87]
	v_mfma_f32_16x16x32_bf16 v[80:83], v[152:155], v[186:189], v[80:83]
	v_mfma_f32_16x16x32_bf16 v[68:71], v[132:135], v[194:197], v[68:71]
	v_mfma_f32_16x16x32_bf16 v[64:67], v[152:155], v[194:197], v[64:67]
	v_mfma_f32_16x16x32_bf16 v[116:119], v[136:139], v[164:167], v[116:119]
	v_mfma_f32_16x16x32_bf16 v[112:115], v[156:159], v[164:167], v[112:115]
	v_mfma_f32_16x16x32_bf16 v[100:103], v[136:139], v[182:185], v[100:103]
	v_mfma_f32_16x16x32_bf16 v[96:99], v[156:159], v[182:185], v[96:99]
	v_mfma_f32_16x16x32_bf16 v[84:87], v[136:139], v[190:193], v[84:87]
	v_mfma_f32_16x16x32_bf16 v[80:83], v[156:159], v[190:193], v[80:83]
	v_mfma_f32_16x16x32_bf16 v[68:71], v[136:139], v[198:201], v[68:71]
	v_mfma_f32_16x16x32_bf16 v[64:67], v[156:159], v[198:201], v[64:67]
	s_barrier
	s_mov_b32 m0, s54
	v_lshl_add_u64 v[168:169], v[168:169], 0, s[6:7]
	ds_read_b128 v[202:205], v177
	ds_read_b128 v[206:209], v177 offset:1024
	ds_read_b128 v[210:213], v177 offset:2048
	ds_read_b128 v[214:217], v177 offset:3072
	global_load_lds_dwordx4 v[168:169], off
	s_mov_b32 m0, s55
	v_lshl_add_u64 v[168:169], v[218:219], 0, s[6:7]
	global_load_lds_dwordx4 v[168:169], off
	s_barrier
;     ...
;         G_PAIR(0, 1);
; #pragma unroll 1
;         for (int t = 2; t < nt; t += 2) G_PAIR(t, 0);
	s_waitcnt lgkmcnt(0)
	v_mfma_f32_16x16x32_bf16 v[128:131], v[202:205], v[160:163], v[128:131]
	v_mfma_f32_16x16x32_bf16 v[124:127], v[210:213], v[160:163], v[124:127]
	v_mfma_f32_16x16x32_bf16 v[108:111], v[202:205], v[178:181], v[108:111]
	v_mfma_f32_16x16x32_bf16 v[104:107], v[210:213], v[178:181], v[104:107]
	v_mfma_f32_16x16x32_bf16 v[92:95], v[202:205], v[186:189], v[92:95]
	v_mfma_f32_16x16x32_bf16 v[88:91], v[210:213], v[186:189], v[88:91]
	v_mfma_f32_16x16x32_bf16 v[76:79], v[202:205], v[194:197], v[76:79]
	v_mfma_f32_16x16x32_bf16 v[72:75], v[210:213], v[194:197], v[72:75]
	v_mfma_f32_16x16x32_bf16 v[128:131], v[206:209], v[164:167], v[128:131]
	v_mfma_f32_16x16x32_bf16 v[124:127], v[214:217], v[164:167], v[124:127]
	v_mfma_f32_16x16x32_bf16 v[108:111], v[206:209], v[182:185], v[108:111]
	v_mfma_f32_16x16x32_bf16 v[104:107], v[214:217], v[182:185], v[104:107]
	v_mfma_f32_16x16x32_bf16 v[92:95], v[206:209], v[190:193], v[92:95]
	v_mfma_f32_16x16x32_bf16 v[88:91], v[214:217], v[190:193], v[88:91]
	v_mfma_f32_16x16x32_bf16 v[76:79], v[206:209], v[198:201], v[76:79]
	v_mfma_f32_16x16x32_bf16 v[72:75], v[214:217], v[198:201], v[72:75]
	s_mov_b32 m0, s46
	v_lshl_add_u64 v[168:169], v[222:223], 0, s[6:7]
	s_barrier
	ds_read_b128 v[160:163], v173 offset:49152
	ds_read_b128 v[164:167], v173 offset:50176
	ds_read_b128 v[178:181], v173 offset:51200
	ds_read_b128 v[182:185], v173 offset:52224
	ds_read_b128 v[186:189], v173 offset:53248
	ds_read_b128 v[190:193], v173 offset:54272
	ds_read_b128 v[194:197], v173 offset:55296
	ds_read_b128 v[198:201], v173 offset:56320
	global_load_lds_dwordx4 v[168:169], off
	s_mov_b32 m0, s47
	v_lshl_add_u64 v[168:169], v[224:225], 0, s[6:7]
	global_load_lds_dwordx4 v[168:169], off
	s_barrier
	s_waitcnt lgkmcnt(0)
	v_mfma_f32_16x16x32_bf16 v[52:55], v[132:135], v[160:163], v[52:55]
	v_mfma_f32_16x16x32_bf16 v[48:51], v[152:155], v[160:163], v[48:51]
	v_mfma_f32_16x16x32_bf16 v[36:39], v[132:135], v[178:181], v[36:39]
	v_mfma_f32_16x16x32_bf16 v[32:35], v[152:155], v[178:181], v[32:35]
	v_mfma_f32_16x16x32_bf16 v[20:23], v[132:135], v[186:189], v[20:23]
	v_mfma_f32_16x16x32_bf16 v[16:19], v[152:155], v[186:189], v[16:19]
	v_mfma_f32_16x16x32_bf16 v[4:7], v[132:135], v[194:197], v[4:7]
	v_mfma_f32_16x16x32_bf16 v[0:3], v[152:155], v[194:197], v[0:3]
	v_mfma_f32_16x16x32_bf16 v[52:55], v[136:139], v[164:167], v[52:55]
	v_mfma_f32_16x16x32_bf16 v[48:51], v[156:159], v[164:167], v[48:51]
	v_mfma_f32_16x16x32_bf16 v[36:39], v[136:139], v[182:185], v[36:39]
	v_mfma_f32_16x16x32_bf16 v[32:35], v[156:159], v[182:185], v[32:35]
	v_mfma_f32_16x16x32_bf16 v[20:23], v[136:139], v[190:193], v[20:23]
	v_mfma_f32_16x16x32_bf16 v[16:19], v[156:159], v[190:193], v[16:19]
	v_mfma_f32_16x16x32_bf16 v[4:7], v[136:139], v[198:201], v[4:7]
	v_mfma_f32_16x16x32_bf16 v[0:3], v[156:159], v[198:201], v[0:3]
	s_barrier
	s_add_u32 s34, s34, 0x40080
	s_addc_u32 s35, s35, 0
	s_mov_b32 m0, s56
	v_lshl_add_u64 v[132:133], s[34:35], 0, v[144:145]
	global_load_lds_dwordx4 v[132:133], off
	s_mov_b32 m0, s57
	v_lshl_add_u64 v[132:133], s[34:35], 0, v[140:141]
	global_load_lds_dwordx4 v[132:133], off
	s_waitcnt vmcnt(6)
	s_barrier
	v_mfma_f32_16x16x32_bf16 v[60:63], v[202:205], v[160:163], v[60:63]
	v_mfma_f32_16x16x32_bf16 v[56:59], v[210:213], v[160:163], v[56:59]
	v_mfma_f32_16x16x32_bf16 v[44:47], v[202:205], v[178:181], v[44:47]
	v_mfma_f32_16x16x32_bf16 v[40:43], v[210:213], v[178:181], v[40:43]
	v_mfma_f32_16x16x32_bf16 v[28:31], v[202:205], v[186:189], v[28:31]
	v_mfma_f32_16x16x32_bf16 v[24:27], v[210:213], v[186:189], v[24:27]
	v_mfma_f32_16x16x32_bf16 v[12:15], v[202:205], v[194:197], v[12:15]
	v_mfma_f32_16x16x32_bf16 v[8:11], v[210:213], v[194:197], v[8:11]
	v_mfma_f32_16x16x32_bf16 v[60:63], v[206:209], v[164:167], v[60:63]
	v_mfma_f32_16x16x32_bf16 v[56:59], v[214:217], v[164:167], v[56:59]
	v_mfma_f32_16x16x32_bf16 v[44:47], v[206:209], v[182:185], v[44:47]
	v_mfma_f32_16x16x32_bf16 v[40:43], v[214:217], v[182:185], v[40:43]
	v_mfma_f32_16x16x32_bf16 v[28:31], v[206:209], v[190:193], v[28:31]
	v_mfma_f32_16x16x32_bf16 v[24:27], v[214:217], v[190:193], v[24:27]
	v_mfma_f32_16x16x32_bf16 v[12:15], v[206:209], v[198:201], v[12:15]
	v_mfma_f32_16x16x32_bf16 v[8:11], v[214:217], v[198:201], v[8:11]
	s_add_i32 s17, s17, 2
	s_add_u32 s30, s30, 0x100
	s_addc_u32 s31, s31, 0
	s_cmp_gt_u32 s17, 13
	s_cbranch_scc0 .Lrot_920
	s_barrier
; __device__ __forceinline__ unsigned pk2(float lo, float hi) { unsigned r; asm volatile("v_cvt_pk_bf16_f32 %0, %1, %2" : "=v"(r) : "v"(lo), "v"(hi)); return r; }
; __device__ __forceinline__ unsigned pk2(float lo, float hi) { return f2bf(lo) | (f2bf(hi) << 16); }
; __device__ __forceinline__ float fast_sigmoid(float z) { return __builtin_amdgcn_rcpf(1.0f + __expf(-z)); }
;     __device__ __forceinline__ void epi(const f32x4 (&acc)[2][2][4][2], const Unit& u, int wr, int wc, int fr, int fq) const {
;         const int row0 = u.pm * 256 + wr * 64 + fr, col0 = u.pn * 128 + wc * 32 + 8 * fq;
; #pragma unroll
;         for (int ai = 0; ai < 2; ++ai) {
;             u32x4 xo[4];
; #pragma unroll
;             for (int m = 0; m < 4; ++m) xo[m] = *(const u32x4*)(xb + (size_t)(row0 + ai * 128 + m * 16) * D + col0);
; #pragma unroll
;             for (int m = 0; m < 4; ++m) {
;                 const int row = row0 + ai * 128 + m * 16; const size_t off = (size_t)row * D + col0;
;                 const u32x4 o = xo[m]; const f32x4 a0v = acc[ai][0][m][0], a1v = acc[ai][0][m][1], b0v = acc[ai][1][m][0], b1v = acc[ai][1][m][1];
;                 const float v0 = bf_lo(o.x) + coef * a0v[0] * fast_sigmoid(b0v[0]), v1 = bf_hi(o.x) + coef * a0v[1] * fast_sigmoid(b0v[1]);
;                 const float v2 = bf_lo(o.y) + coef * a0v[2] * fast_sigmoid(b0v[2]), v3 = bf_hi(o.y) + coef * a0v[3] * fast_sigmoid(b0v[3]);
;                 const float v4 = bf_lo(o.z) + coef * a1v[0] * fast_sigmoid(b1v[0]), v5 = bf_hi(o.z) + coef * a1v[1] * fast_sigmoid(b1v[1]);
;                 const float v6 = bf_lo(o.w) + coef * a1v[2] * fast_sigmoid(b1v[2]), v7 = bf_hi(o.w) + coef * a1v[3] * fast_sigmoid(b1v[3]);
;                 u32x4 w; w.x = pk2(v0, v1); w.y = pk2(v2, v3); w.z = pk2(v4, v5); w.w = pk2(v6, v7);
;                 *(u32x4*)(xb + off) = w;
;                 float ss = ((v0 * v0 + v1 * v1) + (v2 * v2 + v3 * v3)) + ((v4 * v4 + v5 * v5) + (v6 * v6 + v7 * v7));
;                 ss += __shfl_xor(ss, 16); ss += __shfl_xor(ss, 32);
;                 if (fq == 0) rowss[(size_t)row * 32 + u.pn * 4 + wc] = ss;
	v_lshl_or_b32 v152, s59, 7, v171
	v_lshl_add_u32 v156, s8, 8, v170
	v_ashrrev_i32_e32 v153, 31, v152
	v_lshlrev_b64 v[182:183], 1, v[152:153]
	v_ashrrev_i32_e32 v157, 31, v156
	v_lshl_add_u64 v[154:155], s[0:1], 0, v[182:183]
	v_lshlrev_b64 v[184:185], 11, v[156:157]
	v_lshl_add_u64 v[120:121], v[154:155], 0, v[184:185]
	v_mov_b32_e32 v236, 0x40000
	v_mov_b32_e32 v237, 0
	v_lshl_add_u64 v[234:235], v[120:121], 0, v[236:237]
	v_mov_b32_e32 v236, 0x8000
	global_load_dwordx4 v[178:181], v[120:121], off
	v_or_b32_e32 v166, 16, v156
	v_or_b32_e32 v162, 32, v156
	v_or_b32_e32 v158, 48, v156
	v_ashrrev_i32_e32 v167, 31, v166
	v_ashrrev_i32_e32 v163, 31, v162
	v_ashrrev_i32_e32 v159, 31, v158
	v_lshlrev_b64 v[168:169], 11, v[166:167]
	v_lshlrev_b64 v[164:165], 11, v[162:163]
	v_lshlrev_b64 v[160:161], 11, v[158:159]
	v_lshl_add_u64 v[120:121], v[154:155], 0, v[168:169]
	v_lshl_add_u64 v[122:123], v[154:155], 0, v[164:165]
	v_lshl_add_u64 v[186:187], v[154:155], 0, v[160:161]
	global_load_dwordx4 v[136:139], v[120:121], off
	global_load_dwordx4 v[132:135], v[122:123], off
	s_nop 0
	global_load_dwordx4 v[120:123], v[186:187], off
	global_load_dwordx4 v[238:241], v[234:235], off
	v_lshl_add_u64 v[234:235], v[234:235], 0, v[236:237]
	global_load_dwordx4 v[242:245], v[234:235], off
	v_lshl_add_u64 v[234:235], v[234:235], 0, v[236:237]
	global_load_dwordx4 v[246:249], v[234:235], off
	v_lshl_add_u64 v[234:235], v[234:235], 0, v[236:237]
	global_load_dwordx4 v[250:253], v[234:235], off
	v_mul_f32_e32 v129, 0xbfb8aa3b, v129
	v_mul_f32_e32 v131, 0xbfb8aa3b, v131
	v_mul_f32_e32 v125, 0xbfb8aa3b, v125
	v_mul_f32_e32 v127, 0xbfb8aa3b, v127
	v_mul_f32_e32 v128, 0xbfb8aa3b, v128
	v_mul_f32_e32 v130, 0xbfb8aa3b, v130
	v_mul_f32_e32 v124, 0xbfb8aa3b, v124
	v_mul_f32_e32 v126, 0xbfb8aa3b, v126
	v_exp_f32_e32 v129, v129
	v_exp_f32_e32 v131, v131
	v_exp_f32_e32 v125, v125
	v_exp_f32_e32 v127, v127
	v_exp_f32_e32 v128, v128
	v_exp_f32_e32 v130, v130
	v_exp_f32_e32 v189, v124
	v_exp_f32_e32 v126, v126
	v_and_b32_e32 v187, 64, v175
	v_xor_b32_e32 v186, 16, v175
	v_add_u32_e32 v187, 64, v187
	v_cmp_lt_i32_e32 vcc, v186, v187
	v_add_f32_e32 v129, 1.0, v129
	v_add_f32_e32 v131, 1.0, v131
	v_add_f32_e32 v125, 1.0, v125
	v_add_f32_e32 v127, 1.0, v127
	v_cndmask_b32_e32 v124, v175, v186, vcc
	v_add_f32_e32 v128, 1.0, v128
	v_add_f32_e32 v130, 1.0, v130
	v_add_f32_e32 v186, 1.0, v189
	v_add_f32_e32 v126, 1.0, v126
	v_rcp_f32_e32 v129, v129
	v_rcp_f32_e32 v131, v131
	v_rcp_f32_e32 v125, v125
	v_rcp_f32_e32 v127, v127
	v_rcp_f32_e32 v128, v128
	v_rcp_f32_e32 v130, v130
	v_rcp_f32_e32 v186, v186
	v_rcp_f32_e32 v126, v126
	v_lshlrev_b32_e32 v124, 2, v124
	v_xor_b32_e32 v188, 32, v175
	v_cmp_lt_i32_e32 vcc, v188, v187
	s_lshl_b32 s24, s59, 2
	s_ashr_i32 s25, s24, 31
	s_waitcnt vmcnt(4)
	v_lshlrev_b32_e32 v189, 16, v178
	v_and_b32_e32 v178, 0xffff0000, v178
	v_lshlrev_b32_e32 v190, 16, v179
	v_and_b32_e32 v179, 0xffff0000, v179
	v_lshlrev_b32_e32 v191, 16, v180
	v_and_b32_e32 v180, 0xffff0000, v180
	v_lshlrev_b32_e32 v192, 16, v181
	v_and_b32_e32 v181, 0xffff0000, v181
	v_fmac_f32_e32 v178, v117, v129
	v_fmac_f32_e32 v179, v119, v131
	v_fmac_f32_e32 v180, v113, v125
	v_fmac_f32_e32 v181, v115, v127
	v_fmac_f32_e32 v189, v116, v128
	v_fmac_f32_e32 v190, v118, v130
	v_fmac_f32_e32 v191, v112, v186
	v_fmac_f32_e32 v192, v114, v126
	v_mul_f32_e32 v112, v178, v178
	v_mul_f32_e32 v113, v179, v179
	v_mul_f32_e32 v114, v180, v180
	v_mul_f32_e32 v115, v181, v181
	v_fmac_f32_e32 v112, v189, v189
	v_fmac_f32_e32 v113, v190, v190
	v_fmac_f32_e32 v114, v191, v191
	v_fmac_f32_e32 v115, v192, v192
	v_add_f32_e32 v112, v112, v113
	v_add_f32_e32 v113, v114, v115
	v_add_f32_e32 v112, v112, v113
	ds_bpermute_b32 v113, v124, v112
	v_lshl_add_u64 v[126:127], s[0:1], 0, v[184:185]
	v_lshl_add_u64 v[126:127], v[126:127], 0, v[182:183]
	v_cvt_pk_bf16_f32 v116, v189, v178
	v_cvt_pk_bf16_f32 v117, v190, v179
	s_waitcnt lgkmcnt(0)
	v_add_f32_e32 v113, v112, v113
	v_cndmask_b32_e32 v112, v175, v188, vcc
	v_lshlrev_b32_e32 v112, 2, v112
	ds_bpermute_b32 v114, v112, v113
	v_cvt_pk_bf16_f32 v118, v191, v180
	v_cvt_pk_bf16_f32 v119, v192, v181
	global_store_dwordx4 v[126:127], v[116:119], off
	s_and_saveexec_b64 s[26:27], s[4:5]
	s_cbranch_execz .LBB0_923
	v_lshlrev_b64 v[116:117], 7, v[156:157]
	v_lshl_add_u64 v[116:117], s[2:3], 0, v[116:117]
	v_lshl_add_u64 v[116:117], s[24:25], 2, v[116:117]
	s_lshl_b32 s8, s45, 2
	v_lshl_add_u64 v[116:117], v[116:117], 0, s[8:9]
	s_waitcnt lgkmcnt(0)
	v_add_f32_e32 v113, v113, v114
	global_store_dword v[116:117], v113, off

;     ...
;         G_PAIR(0, 1);
.LBB0_1041:
	s_ashr_i32 s19, s18, 31
	ds_read_b128 v[0:3], v152
	ds_read_b128 v[4:7], v152 offset:1024
	ds_read_b128 v[8:11], v152 offset:2048
	ds_read_b128 v[12:15], v152 offset:3072
	s_lshl_b64 s[20:21], s[18:19], 19
	s_add_u32 s20, s10, s20
	s_addc_u32 s21, s11, s21
	s_ashr_i32 s17, s16, 31
	s_lshl_b64 s[22:23], s[16:17], 19
	s_add_u32 s22, s39, s22
	s_addc_u32 s23, s40, s23
	s_add_u32 s34, s26, 0x40080
	s_addc_u32 s35, s27, 0
	s_mov_b32 m0, s47
	v_lshl_add_u64 v[48:49], s[34:35], 0, v[136:137]
	ds_read_b128 v[16:19], v153
	ds_read_b128 v[20:23], v153 offset:1024
	ds_read_b128 v[24:27], v153 offset:2048
	ds_read_b128 v[28:31], v153 offset:3072
	ds_read_b128 v[32:35], v153 offset:4096
	ds_read_b128 v[36:39], v153 offset:5120
	ds_read_b128 v[40:43], v153 offset:6144
	ds_read_b128 v[44:47], v153 offset:7168
	global_load_lds_dwordx4 v[48:49], off
	s_mov_b32 m0, s48
	v_lshl_add_u64 v[48:49], s[34:35], 0, v[132:133]
	global_load_lds_dwordx4 v[48:49], off
	s_waitcnt lgkmcnt(8)
	s_barrier
	s_waitcnt lgkmcnt(0)
	v_mfma_f32_16x16x32_bf16 v[48:51], v[0:3], v[16:19], 0
	v_mfma_f32_16x16x32_bf16 v[52:55], v[8:11], v[16:19], 0
	v_mfma_f32_16x16x32_bf16 v[56:59], v[0:3], v[24:27], 0
	v_mfma_f32_16x16x32_bf16 v[60:63], v[8:11], v[24:27], 0
	v_mfma_f32_16x16x32_bf16 v[64:67], v[0:3], v[32:35], 0
	v_mfma_f32_16x16x32_bf16 v[68:71], v[8:11], v[32:35], 0
	v_mfma_f32_16x16x32_bf16 v[72:75], v[0:3], v[40:43], 0
	v_mfma_f32_16x16x32_bf16 v[76:79], v[8:11], v[40:43], 0
	v_mfma_f32_16x16x32_bf16 v[48:51], v[4:7], v[20:23], v[48:51]
	v_mfma_f32_16x16x32_bf16 v[52:55], v[12:15], v[20:23], v[52:55]
	v_mfma_f32_16x16x32_bf16 v[56:59], v[4:7], v[28:31], v[56:59]
	v_mfma_f32_16x16x32_bf16 v[60:63], v[12:15], v[28:31], v[60:63]
	v_mfma_f32_16x16x32_bf16 v[64:67], v[4:7], v[36:39], v[64:67]
	v_mfma_f32_16x16x32_bf16 v[68:71], v[12:15], v[36:39], v[68:71]
	v_mfma_f32_16x16x32_bf16 v[72:75], v[4:7], v[44:47], v[72:75]
	v_mfma_f32_16x16x32_bf16 v[76:79], v[12:15], v[44:47], v[76:79]
	s_barrier
	v_lshl_add_u64 v[218:219], s[28:29], 0, v[134:135]
	s_mov_b32 m0, s49
	v_lshl_add_u64 v[96:97], v[218:219], 0, s[8:9]
	v_lshl_add_u64 v[238:239], s[28:29], 0, v[130:131]
	ds_read_b128 v[80:83], v154
	ds_read_b128 v[84:87], v154 offset:1024
	ds_read_b128 v[88:91], v154 offset:2048
	ds_read_b128 v[92:95], v154 offset:3072
	global_load_lds_dwordx4 v[96:97], off
	s_mov_b32 m0, s50
	v_lshl_add_u64 v[96:97], v[238:239], 0, s[8:9]
	global_load_lds_dwordx4 v[96:97], off
	s_barrier
	s_waitcnt lgkmcnt(0)
	v_mfma_f32_16x16x32_bf16 v[96:99], v[80:83], v[16:19], 0
	v_mfma_f32_16x16x32_bf16 v[16:19], v[88:91], v[16:19], 0
	v_mfma_f32_16x16x32_bf16 v[100:103], v[80:83], v[24:27], 0
	v_mfma_f32_16x16x32_bf16 v[24:27], v[88:91], v[24:27], 0
	v_mfma_f32_16x16x32_bf16 v[104:107], v[80:83], v[32:35], 0
	v_mfma_f32_16x16x32_bf16 v[32:35], v[88:91], v[32:35], 0
	v_mfma_f32_16x16x32_bf16 v[108:111], v[80:83], v[40:43], 0
	v_mfma_f32_16x16x32_bf16 v[40:43], v[88:91], v[40:43], 0
	v_mfma_f32_16x16x32_bf16 v[116:119], v[84:87], v[20:23], v[96:99]
	v_mfma_f32_16x16x32_bf16 v[16:19], v[92:95], v[20:23], v[16:19]
	v_mfma_f32_16x16x32_bf16 v[20:23], v[84:87], v[28:31], v[100:103]
	v_mfma_f32_16x16x32_bf16 v[24:27], v[92:95], v[28:31], v[24:27]
	v_mfma_f32_16x16x32_bf16 v[28:31], v[84:87], v[36:39], v[104:107]
	v_mfma_f32_16x16x32_bf16 v[32:35], v[92:95], v[36:39], v[32:35]
	v_mfma_f32_16x16x32_bf16 v[36:39], v[84:87], v[44:47], v[108:111]
	v_mfma_f32_16x16x32_bf16 v[40:43], v[92:95], v[44:47], v[40:43]
	v_lshl_add_u64 v[246:247], s[26:27], 0, v[136:137]
	s_mov_b32 m0, s25
	v_lshl_add_u64 v[142:143], v[246:247], 0, s[8:9]
	v_lshl_add_u64 v[248:249], s[26:27], 0, v[132:133]
	s_barrier
	ds_read_b128 v[44:47], v153 offset:16384
	ds_read_b128 v[96:99], v153 offset:17408
	ds_read_b128 v[100:103], v153 offset:18432
	ds_read_b128 v[104:107], v153 offset:19456
	ds_read_b128 v[108:111], v153 offset:20480
	ds_read_b128 v[112:115], v153 offset:21504
	ds_read_b128 v[120:123], v153 offset:22528
	ds_read_b128 v[124:127], v153 offset:23552
	global_load_lds_dwordx4 v[142:143], off
	s_mov_b32 m0, s41
	v_lshl_add_u64 v[142:143], v[248:249], 0, s[8:9]
	global_load_lds_dwordx4 v[142:143], off
	s_barrier
	s_waitcnt lgkmcnt(0)
	v_mfma_f32_16x16x32_bf16 v[142:145], v[0:3], v[44:47], 0
	v_mfma_f32_16x16x32_bf16 v[158:161], v[8:11], v[44:47], 0
	v_mfma_f32_16x16x32_bf16 v[162:165], v[0:3], v[100:103], 0
	v_mfma_f32_16x16x32_bf16 v[166:169], v[8:11], v[100:103], 0
	v_mfma_f32_16x16x32_bf16 v[170:173], v[0:3], v[108:111], 0
	v_mfma_f32_16x16x32_bf16 v[174:177], v[8:11], v[108:111], 0
	v_mfma_f32_16x16x32_bf16 v[0:3], v[0:3], v[120:123], 0
	v_mfma_f32_16x16x32_bf16 v[8:11], v[8:11], v[120:123], 0
	v_mfma_f32_16x16x32_bf16 v[142:145], v[4:7], v[96:99], v[142:145]
	v_mfma_f32_16x16x32_bf16 v[162:165], v[4:7], v[104:107], v[162:165]
	v_mfma_f32_16x16x32_bf16 v[170:173], v[4:7], v[112:115], v[170:173]
	v_mfma_f32_16x16x32_bf16 v[0:3], v[4:7], v[124:127], v[0:3]
	v_mfma_f32_16x16x32_bf16 v[4:7], v[12:15], v[124:127], v[8:11]
	v_mfma_f32_16x16x32_bf16 v[158:161], v[12:15], v[96:99], v[158:161]
	v_mfma_f32_16x16x32_bf16 v[166:169], v[12:15], v[104:107], v[166:169]
	v_mfma_f32_16x16x32_bf16 v[174:177], v[12:15], v[112:115], v[174:177]
	s_barrier
	s_add_u32 s34, s28, 0x40100
	s_addc_u32 s35, s29, 0
	s_mov_b32 m0, s55
	v_lshl_add_u64 v[8:9], s[34:35], 0, v[134:135]
	global_load_lds_dwordx4 v[8:9], off
	s_mov_b32 m0, s56
	v_lshl_add_u64 v[8:9], s[34:35], 0, v[130:131]
	global_load_lds_dwordx4 v[8:9], off
	s_waitcnt vmcnt(6)
	s_barrier
	v_mfma_f32_16x16x32_bf16 v[8:11], v[80:83], v[44:47], 0
	v_mfma_f32_16x16x32_bf16 v[12:15], v[88:91], v[44:47], 0
	v_mfma_f32_16x16x32_bf16 v[44:47], v[80:83], v[100:103], 0
	v_mfma_f32_16x16x32_bf16 v[100:103], v[88:91], v[100:103], 0
	v_mfma_f32_16x16x32_bf16 v[178:181], v[80:83], v[108:111], 0
	v_mfma_f32_16x16x32_bf16 v[108:111], v[88:91], v[108:111], 0
	v_mfma_f32_16x16x32_bf16 v[80:83], v[80:83], v[120:123], 0
	v_mfma_f32_16x16x32_bf16 v[88:91], v[88:91], v[120:123], 0
	v_mfma_f32_16x16x32_bf16 v[12:15], v[92:95], v[96:99], v[12:15]
	v_mfma_f32_16x16x32_bf16 v[44:47], v[84:87], v[104:107], v[44:47]
	v_mfma_f32_16x16x32_bf16 v[182:185], v[84:87], v[96:99], v[8:11]
	v_mfma_f32_16x16x32_bf16 v[186:189], v[92:95], v[104:107], v[100:103]
	v_mfma_f32_16x16x32_bf16 v[178:181], v[84:87], v[112:115], v[178:181]
	v_mfma_f32_16x16x32_bf16 v[190:193], v[92:95], v[112:115], v[108:111]
	v_mfma_f32_16x16x32_bf16 v[194:197], v[84:87], v[124:127], v[80:83]
	v_mfma_f32_16x16x32_bf16 v[198:201], v[92:95], v[124:127], v[88:91]
	s_barrier
	ds_read_b128 v[8:11], v155
	ds_read_b128 v[202:205], v155 offset:1024
	ds_read_b128 v[206:209], v155 offset:2048
	ds_read_b128 v[210:213], v155 offset:3072
	s_add_u32 s34, s26, 0x40100
	s_addc_u32 s35, s27, 0
	s_mov_b32 m0, s42
	v_lshl_add_u64 v[80:81], s[34:35], 0, v[136:137]
	ds_read_b128 v[84:87], v153 offset:32768
	ds_read_b128 v[92:95], v153 offset:33792
	ds_read_b128 v[100:103], v153 offset:34816
	ds_read_b128 v[214:217], v153 offset:35840
	ds_read_b128 v[108:111], v153 offset:36864
	ds_read_b128 v[222:225], v153 offset:37888
	ds_read_b128 v[124:127], v153 offset:38912
	ds_read_b128 v[226:229], v153 offset:39936
	global_load_lds_dwordx4 v[80:81], off
	s_mov_b32 m0, s43
	v_lshl_add_u64 v[80:81], s[34:35], 0, v[132:133]
	global_load_lds_dwordx4 v[80:81], off
	s_waitcnt lgkmcnt(8)
	s_barrier
	s_waitcnt lgkmcnt(0)
	v_mfma_f32_16x16x32_bf16 v[48:51], v[8:11], v[84:87], v[48:51]
	v_mfma_f32_16x16x32_bf16 v[52:55], v[206:209], v[84:87], v[52:55]
	v_mfma_f32_16x16x32_bf16 v[56:59], v[8:11], v[100:103], v[56:59]
	v_mfma_f32_16x16x32_bf16 v[60:63], v[206:209], v[100:103], v[60:63]
	v_mfma_f32_16x16x32_bf16 v[64:67], v[8:11], v[108:111], v[64:67]
	v_mfma_f32_16x16x32_bf16 v[68:71], v[206:209], v[108:111], v[68:71]
	v_mfma_f32_16x16x32_bf16 v[72:75], v[8:11], v[124:127], v[72:75]
	v_mfma_f32_16x16x32_bf16 v[76:79], v[206:209], v[124:127], v[76:79]
	v_mfma_f32_16x16x32_bf16 v[120:123], v[202:205], v[92:95], v[48:51]
	v_mfma_f32_16x16x32_bf16 v[112:115], v[210:213], v[92:95], v[52:55]
	v_mfma_f32_16x16x32_bf16 v[104:107], v[202:205], v[214:217], v[56:59]
	v_mfma_f32_16x16x32_bf16 v[96:99], v[210:213], v[214:217], v[60:63]
	v_mfma_f32_16x16x32_bf16 v[88:91], v[202:205], v[222:225], v[64:67]
	v_mfma_f32_16x16x32_bf16 v[80:83], v[210:213], v[222:225], v[68:71]
	v_mfma_f32_16x16x32_bf16 v[72:75], v[202:205], v[226:229], v[72:75]
	v_mfma_f32_16x16x32_bf16 v[60:63], v[210:213], v[226:229], v[76:79]
	s_barrier
	s_mov_b32 m0, s57
	v_lshl_add_u64 v[48:49], v[218:219], 0, s[12:13]
	ds_read_b128 v[52:55], v156
	ds_read_b128 v[230:233], v156 offset:1024
	ds_read_b128 v[68:71], v156 offset:2048
	ds_read_b128 v[234:237], v156 offset:3072
	global_load_lds_dwordx4 v[48:49], off
	s_mov_b32 m0, s58
	v_lshl_add_u64 v[48:49], v[238:239], 0, s[12:13]
	global_load_lds_dwordx4 v[48:49], off
	s_barrier
;     ...
;         G_PAIR(0, 1);
; #pragma unroll 1
;         for (int t = 2; t < nt; t += 2) G_PAIR(t, 0);
	s_waitcnt lgkmcnt(0)
	v_mfma_f32_16x16x32_bf16 v[48:51], v[52:55], v[84:87], v[116:119]
	v_mfma_f32_16x16x32_bf16 v[16:19], v[68:71], v[84:87], v[16:19]
	v_mfma_f32_16x16x32_bf16 v[20:23], v[52:55], v[100:103], v[20:23]
	v_mfma_f32_16x16x32_bf16 v[24:27], v[68:71], v[100:103], v[24:27]
	v_mfma_f32_16x16x32_bf16 v[28:31], v[52:55], v[108:111], v[28:31]
	v_mfma_f32_16x16x32_bf16 v[32:35], v[68:71], v[108:111], v[32:35]
	v_mfma_f32_16x16x32_bf16 v[36:39], v[52:55], v[124:127], v[36:39]
	v_mfma_f32_16x16x32_bf16 v[40:43], v[68:71], v[124:127], v[40:43]
	v_mfma_f32_16x16x32_bf16 v[124:127], v[230:233], v[92:95], v[48:51]
	v_mfma_f32_16x16x32_bf16 v[116:119], v[234:237], v[92:95], v[16:19]
	v_mfma_f32_16x16x32_bf16 v[108:111], v[230:233], v[214:217], v[20:23]
	v_mfma_f32_16x16x32_bf16 v[100:103], v[234:237], v[214:217], v[24:27]
	v_mfma_f32_16x16x32_bf16 v[92:95], v[230:233], v[222:225], v[28:31]
	v_mfma_f32_16x16x32_bf16 v[84:87], v[234:237], v[222:225], v[32:35]
	v_mfma_f32_16x16x32_bf16 v[76:79], v[230:233], v[226:229], v[36:39]
	v_mfma_f32_16x16x32_bf16 v[64:67], v[234:237], v[226:229], v[40:43]
	s_mov_b32 m0, s44
	v_lshl_add_u64 v[16:17], v[246:247], 0, s[12:13]
	s_barrier
	ds_read_b128 v[20:23], v153 offset:49152
	ds_read_b128 v[28:31], v153 offset:50176
	ds_read_b128 v[36:39], v153 offset:51200
	ds_read_b128 v[214:217], v153 offset:52224
	ds_read_b128 v[222:225], v153 offset:53248
	ds_read_b128 v[226:229], v153 offset:54272
	ds_read_b128 v[238:241], v153 offset:55296
	ds_read_b128 v[242:245], v153 offset:56320
	global_load_lds_dwordx4 v[16:17], off
	s_mov_b32 m0, s45
	v_lshl_add_u64 v[16:17], v[248:249], 0, s[12:13]
	global_load_lds_dwordx4 v[16:17], off
	s_barrier
	s_waitcnt lgkmcnt(0)
	v_mfma_f32_16x16x32_bf16 v[16:19], v[8:11], v[20:23], v[142:145]
	v_mfma_f32_16x16x32_bf16 v[24:27], v[206:209], v[20:23], v[158:161]
	v_mfma_f32_16x16x32_bf16 v[32:35], v[8:11], v[36:39], v[162:165]
	v_mfma_f32_16x16x32_bf16 v[142:145], v[206:209], v[36:39], v[166:169]
	v_mfma_f32_16x16x32_bf16 v[158:161], v[8:11], v[222:225], v[170:173]
	v_mfma_f32_16x16x32_bf16 v[162:165], v[206:209], v[222:225], v[174:177]
	v_mfma_f32_16x16x32_bf16 v[0:3], v[8:11], v[238:241], v[0:3]
	v_mfma_f32_16x16x32_bf16 v[4:7], v[206:209], v[238:241], v[4:7]
	v_mfma_f32_16x16x32_bf16 v[56:59], v[202:205], v[28:31], v[16:19]
	v_mfma_f32_16x16x32_bf16 v[48:51], v[210:213], v[28:31], v[24:27]
	v_mfma_f32_16x16x32_bf16 v[40:43], v[202:205], v[214:217], v[32:35]
	v_mfma_f32_16x16x32_bf16 v[32:35], v[210:213], v[214:217], v[142:145]
	v_mfma_f32_16x16x32_bf16 v[24:27], v[202:205], v[226:229], v[158:161]
	v_mfma_f32_16x16x32_bf16 v[16:19], v[210:213], v[226:229], v[162:165]
	v_mfma_f32_16x16x32_bf16 v[8:11], v[202:205], v[242:245], v[0:3]
	v_mfma_f32_16x16x32_bf16 v[0:3], v[210:213], v[242:245], v[4:7]
	s_barrier
	s_add_u32 s34, s28, 0x40180
	s_addc_u32 s35, s29, 0
	s_mov_b32 m0, s59
	v_lshl_add_u64 v[4:5], s[34:35], 0, v[134:135]
	s_add_i32 s17, s59, 0x2000
	global_load_lds_dwordx4 v[4:5], off
	v_lshl_add_u64 v[4:5], s[34:35], 0, v[130:131]
	s_mov_b32 m0, s17
	s_mov_b64 s[34:35], 0x40180
	global_load_lds_dwordx4 v[4:5], off
	s_waitcnt vmcnt(6)
	s_barrier
	v_mfma_f32_16x16x32_bf16 v[4:7], v[52:55], v[20:23], v[182:185]
	v_mfma_f32_16x16x32_bf16 v[12:15], v[68:71], v[20:23], v[12:15]
	v_mfma_f32_16x16x32_bf16 v[20:23], v[52:55], v[36:39], v[44:47]
	v_mfma_f32_16x16x32_bf16 v[36:39], v[68:71], v[36:39], v[186:189]
	v_mfma_f32_16x16x32_bf16 v[142:145], v[52:55], v[222:225], v[178:181]
	v_mfma_f32_16x16x32_bf16 v[158:161], v[68:71], v[222:225], v[190:193]
	v_mfma_f32_16x16x32_bf16 v[162:165], v[52:55], v[238:241], v[194:197]
	v_mfma_f32_16x16x32_bf16 v[166:169], v[68:71], v[238:241], v[198:201]
	v_mfma_f32_16x16x32_bf16 v[68:71], v[230:233], v[28:31], v[4:7]
	v_mfma_f32_16x16x32_bf16 v[52:55], v[234:237], v[28:31], v[12:15]
	v_mfma_f32_16x16x32_bf16 v[44:47], v[230:233], v[214:217], v[20:23]
	v_mfma_f32_16x16x32_bf16 v[36:39], v[234:237], v[214:217], v[36:39]
	v_mfma_f32_16x16x32_bf16 v[28:31], v[230:233], v[226:229], v[142:145]
	v_mfma_f32_16x16x32_bf16 v[20:23], v[234:237], v[226:229], v[158:161]
	v_mfma_f32_16x16x32_bf16 v[12:15], v[230:233], v[242:245], v[162:165]
	v_mfma_f32_16x16x32_bf16 v[4:7], v[234:237], v[242:245], v[166:169]
	v_lshl_add_u64 v[142:143], s[26:27], 0, v[138:139]
	v_lshl_add_u64 v[144:145], s[26:27], 0, v[140:141]
	s_mov_b32 s19, 0
.Lrot_1042:
	s_barrier

;     ...
;         G_PAIR(0, 1);
.LBB0_1166:
	s_waitcnt lgkmcnt(0)
	ds_read_b128 v[0:3], v190
	ds_read_b128 v[4:7], v190 offset:1024
	ds_read_b128 v[8:11], v190 offset:2048
	ds_read_b128 v[12:15], v190 offset:3072
	s_add_u32 s34, s28, 0xb0080
	s_addc_u32 s35, s29, 0
	s_mov_b32 m0, s54
	v_lshl_add_u64 v[48:49], s[34:35], 0, v[154:155]
	ds_read_b128 v[16:19], v191
	ds_read_b128 v[20:23], v191 offset:1024
	ds_read_b128 v[24:27], v191 offset:2048
	ds_read_b128 v[28:31], v191 offset:3072
	ds_read_b128 v[32:35], v191 offset:4096
	ds_read_b128 v[36:39], v191 offset:5120
	ds_read_b128 v[40:43], v191 offset:6144
	ds_read_b128 v[44:47], v191 offset:7168
	global_load_lds_dwordx4 v[48:49], off
	s_mov_b32 m0, s55
	v_lshl_add_u64 v[48:49], s[34:35], 0, v[158:159]
	global_load_lds_dwordx4 v[48:49], off
	s_waitcnt lgkmcnt(8)
	s_barrier
	s_waitcnt lgkmcnt(0)
	v_mfma_f32_16x16x32_bf16 v[48:51], v[0:3], v[16:19], 0
	v_mfma_f32_16x16x32_bf16 v[52:55], v[8:11], v[16:19], 0
	v_mfma_f32_16x16x32_bf16 v[56:59], v[0:3], v[24:27], 0
	v_mfma_f32_16x16x32_bf16 v[60:63], v[8:11], v[24:27], 0
	v_mfma_f32_16x16x32_bf16 v[64:67], v[0:3], v[32:35], 0
	v_mfma_f32_16x16x32_bf16 v[68:71], v[8:11], v[32:35], 0
	v_mfma_f32_16x16x32_bf16 v[72:75], v[0:3], v[40:43], 0
	v_mfma_f32_16x16x32_bf16 v[76:79], v[8:11], v[40:43], 0
	v_mfma_f32_16x16x32_bf16 v[48:51], v[4:7], v[20:23], v[48:51]
	v_mfma_f32_16x16x32_bf16 v[52:55], v[12:15], v[20:23], v[52:55]
	v_mfma_f32_16x16x32_bf16 v[56:59], v[4:7], v[28:31], v[56:59]
	v_mfma_f32_16x16x32_bf16 v[60:63], v[12:15], v[28:31], v[60:63]
	v_mfma_f32_16x16x32_bf16 v[64:67], v[4:7], v[36:39], v[64:67]
	v_mfma_f32_16x16x32_bf16 v[68:71], v[12:15], v[36:39], v[68:71]
	v_mfma_f32_16x16x32_bf16 v[72:75], v[4:7], v[44:47], v[72:75]
	v_mfma_f32_16x16x32_bf16 v[76:79], v[12:15], v[44:47], v[76:79]
	s_barrier
	v_lshl_add_u64 v[182:183], s[30:31], 0, v[156:157]
	s_mov_b32 m0, s56
	v_lshl_add_u64 v[96:97], v[182:183], 0, s[12:13]
	v_lshl_add_u64 v[218:219], s[30:31], 0, v[160:161]
	ds_read_b128 v[80:83], v192
	ds_read_b128 v[84:87], v192 offset:1024
	ds_read_b128 v[88:91], v192 offset:2048
	ds_read_b128 v[92:95], v192 offset:3072
	global_load_lds_dwordx4 v[96:97], off
	s_mov_b32 m0, s57
	v_lshl_add_u64 v[96:97], v[218:219], 0, s[12:13]
	global_load_lds_dwordx4 v[96:97], off
	s_barrier
	s_waitcnt lgkmcnt(0)
	v_mfma_f32_16x16x32_bf16 v[96:99], v[80:83], v[16:19], 0
	v_mfma_f32_16x16x32_bf16 v[16:19], v[88:91], v[16:19], 0
	v_mfma_f32_16x16x32_bf16 v[100:103], v[80:83], v[24:27], 0
	v_mfma_f32_16x16x32_bf16 v[24:27], v[88:91], v[24:27], 0
	v_mfma_f32_16x16x32_bf16 v[104:107], v[80:83], v[32:35], 0
	v_mfma_f32_16x16x32_bf16 v[32:35], v[88:91], v[32:35], 0
	v_mfma_f32_16x16x32_bf16 v[108:111], v[80:83], v[40:43], 0
	v_mfma_f32_16x16x32_bf16 v[40:43], v[88:91], v[40:43], 0
	v_mfma_f32_16x16x32_bf16 v[96:99], v[84:87], v[20:23], v[96:99]
	v_mfma_f32_16x16x32_bf16 v[16:19], v[92:95], v[20:23], v[16:19]
	v_mfma_f32_16x16x32_bf16 v[20:23], v[84:87], v[28:31], v[100:103]
	v_mfma_f32_16x16x32_bf16 v[24:27], v[92:95], v[28:31], v[24:27]
	v_mfma_f32_16x16x32_bf16 v[28:31], v[84:87], v[36:39], v[104:107]
	v_mfma_f32_16x16x32_bf16 v[32:35], v[92:95], v[36:39], v[32:35]
	v_mfma_f32_16x16x32_bf16 v[36:39], v[84:87], v[44:47], v[108:111]
	v_mfma_f32_16x16x32_bf16 v[40:43], v[92:95], v[44:47], v[40:43]
	v_lshl_add_u64 v[246:247], s[28:29], 0, v[154:155]
	s_mov_b32 m0, s46
	v_lshl_add_u64 v[128:129], v[246:247], 0, s[12:13]
	v_lshl_add_u64 v[248:249], s[28:29], 0, v[158:159]
	s_barrier
	ds_read_b128 v[44:47], v191 offset:16384
	ds_read_b128 v[100:103], v191 offset:17408
	ds_read_b128 v[104:107], v191 offset:18432
	ds_read_b128 v[108:111], v191 offset:19456
	ds_read_b128 v[112:115], v191 offset:20480
	ds_read_b128 v[116:119], v191 offset:21504
	ds_read_b128 v[120:123], v191 offset:22528
	ds_read_b128 v[124:127], v191 offset:23552
	global_load_lds_dwordx4 v[128:129], off
	s_mov_b32 m0, s47
	v_lshl_add_u64 v[128:129], v[248:249], 0, s[12:13]
	global_load_lds_dwordx4 v[128:129], off
	s_barrier
	s_waitcnt lgkmcnt(0)
	v_mfma_f32_16x16x32_bf16 v[128:131], v[0:3], v[44:47], 0
	v_mfma_f32_16x16x32_bf16 v[132:135], v[8:11], v[44:47], 0
	v_mfma_f32_16x16x32_bf16 v[136:139], v[0:3], v[104:107], 0
	v_mfma_f32_16x16x32_bf16 v[140:143], v[8:11], v[104:107], 0
	v_mfma_f32_16x16x32_bf16 v[144:147], v[0:3], v[112:115], 0
	v_mfma_f32_16x16x32_bf16 v[148:151], v[8:11], v[112:115], 0
	v_mfma_f32_16x16x32_bf16 v[0:3], v[0:3], v[120:123], 0
	v_mfma_f32_16x16x32_bf16 v[8:11], v[8:11], v[120:123], 0
	v_mfma_f32_16x16x32_bf16 v[128:131], v[4:7], v[100:103], v[128:131]
	v_mfma_f32_16x16x32_bf16 v[166:169], v[12:15], v[100:103], v[132:135]
	v_mfma_f32_16x16x32_bf16 v[134:137], v[4:7], v[108:111], v[136:139]
	v_mfma_f32_16x16x32_bf16 v[138:141], v[12:15], v[108:111], v[140:143]
	v_mfma_f32_16x16x32_bf16 v[142:145], v[4:7], v[116:119], v[144:147]
	v_mfma_f32_16x16x32_bf16 v[0:3], v[4:7], v[124:127], v[0:3]
	v_mfma_f32_16x16x32_bf16 v[4:7], v[12:15], v[124:127], v[8:11]
	v_mfma_f32_16x16x32_bf16 v[146:149], v[12:15], v[116:119], v[148:151]
	s_barrier
	s_add_u32 s34, s30, 0xb0100
	s_addc_u32 s35, s31, 0
	s_add_i32 s0, s53, s43
	v_lshl_add_u64 v[8:9], s[34:35], 0, v[156:157]
	s_mov_b32 m0, s0
	s_add_i32 s62, s0, 0x2000
	global_load_lds_dwordx4 v[8:9], off
	s_mov_b32 m0, s62
	v_lshl_add_u64 v[8:9], s[34:35], 0, v[160:161]
	global_load_lds_dwordx4 v[8:9], off
	s_waitcnt vmcnt(6)
	s_barrier
	v_mfma_f32_16x16x32_bf16 v[8:11], v[80:83], v[44:47], 0
	v_mfma_f32_16x16x32_bf16 v[12:15], v[88:91], v[44:47], 0
	v_mfma_f32_16x16x32_bf16 v[44:47], v[80:83], v[104:107], 0
	v_mfma_f32_16x16x32_bf16 v[104:107], v[88:91], v[104:107], 0
	v_mfma_f32_16x16x32_bf16 v[170:173], v[80:83], v[112:115], 0
	v_mfma_f32_16x16x32_bf16 v[112:115], v[88:91], v[112:115], 0
	v_mfma_f32_16x16x32_bf16 v[80:83], v[80:83], v[120:123], 0
	v_mfma_f32_16x16x32_bf16 v[88:91], v[88:91], v[120:123], 0
	v_mfma_f32_16x16x32_bf16 v[8:11], v[84:87], v[100:103], v[8:11]
	v_mfma_f32_16x16x32_bf16 v[174:177], v[92:95], v[100:103], v[12:15]
	v_mfma_f32_16x16x32_bf16 v[178:181], v[84:87], v[108:111], v[44:47]
	v_mfma_f32_16x16x32_bf16 v[194:197], v[92:95], v[108:111], v[104:107]
	v_mfma_f32_16x16x32_bf16 v[170:173], v[84:87], v[116:119], v[170:173]
	v_mfma_f32_16x16x32_bf16 v[198:201], v[92:95], v[116:119], v[112:115]
	v_mfma_f32_16x16x32_bf16 v[202:205], v[84:87], v[124:127], v[80:83]
	v_mfma_f32_16x16x32_bf16 v[206:209], v[92:95], v[124:127], v[88:91]
	s_add_i32 s63, 0, 0x18000
	v_add_u32_e32 v132, s63, v188
	s_barrier
	ds_read_b128 v[12:15], v132
	ds_read_b128 v[210:213], v132 offset:1024
	ds_read_b128 v[44:47], v132 offset:2048
	ds_read_b128 v[214:217], v132 offset:3072
	s_add_u32 s34, s28, 0xb0100
	s_addc_u32 s35, s29, 0
	s_mov_b32 m0, s48
	v_lshl_add_u64 v[88:89], s[34:35], 0, v[154:155]
	ds_read_b128 v[80:83], v191 offset:32768
	ds_read_b128 v[84:87], v191 offset:33792
	ds_read_b128 v[100:103], v191 offset:34816
	ds_read_b128 v[222:225], v191 offset:35840
	ds_read_b128 v[120:123], v191 offset:36864
	ds_read_b128 v[226:229], v191 offset:37888
	ds_read_b128 v[124:127], v191 offset:38912
	ds_read_b128 v[230:233], v191 offset:39936
	global_load_lds_dwordx4 v[88:89], off
	s_mov_b32 m0, s49
	v_lshl_add_u64 v[88:89], s[34:35], 0, v[158:159]
	global_load_lds_dwordx4 v[88:89], off
	s_waitcnt lgkmcnt(8)
	s_barrier
	s_waitcnt lgkmcnt(0)
	v_mfma_f32_16x16x32_bf16 v[48:51], v[12:15], v[80:83], v[48:51]
	v_mfma_f32_16x16x32_bf16 v[52:55], v[44:47], v[80:83], v[52:55]
	v_mfma_f32_16x16x32_bf16 v[56:59], v[12:15], v[100:103], v[56:59]
	v_mfma_f32_16x16x32_bf16 v[60:63], v[44:47], v[100:103], v[60:63]
	v_mfma_f32_16x16x32_bf16 v[64:67], v[12:15], v[120:123], v[64:67]
	v_mfma_f32_16x16x32_bf16 v[68:71], v[44:47], v[120:123], v[68:71]
	v_mfma_f32_16x16x32_bf16 v[72:75], v[12:15], v[124:127], v[72:75]
	v_mfma_f32_16x16x32_bf16 v[234:237], v[44:47], v[124:127], v[76:79]
	v_mfma_f32_16x16x32_bf16 v[116:119], v[210:213], v[84:87], v[48:51]
	v_mfma_f32_16x16x32_bf16 v[112:115], v[214:217], v[84:87], v[52:55]
	v_mfma_f32_16x16x32_bf16 v[108:111], v[210:213], v[222:225], v[56:59]
	v_mfma_f32_16x16x32_bf16 v[104:107], v[214:217], v[222:225], v[60:63]
	v_mfma_f32_16x16x32_bf16 v[92:95], v[210:213], v[226:229], v[64:67]
	v_mfma_f32_16x16x32_bf16 v[88:91], v[214:217], v[226:229], v[68:71]
	v_mfma_f32_16x16x32_bf16 v[76:79], v[210:213], v[230:233], v[72:75]
	v_mfma_f32_16x16x32_bf16 v[72:75], v[214:217], v[230:233], v[234:237]
	s_barrier
	s_add_i32 s65, 0, 0x1c000
	s_add_i32 s63, s63, s43
	v_add_u32_e32 v133, s65, v188
	v_lshl_add_u64 v[48:49], v[182:183], 0, s[14:15]
	s_mov_b32 m0, s63
	s_add_i32 s64, s63, 0x2000
	ds_read_b128 v[56:59], v133
	ds_read_b128 v[234:237], v133 offset:1024
	ds_read_b128 v[60:63], v133 offset:2048
	ds_read_b128 v[238:241], v133 offset:3072
	global_load_lds_dwordx4 v[48:49], off
	s_mov_b32 m0, s64
	v_lshl_add_u64 v[48:49], v[218:219], 0, s[14:15]
	global_load_lds_dwordx4 v[48:49], off
	s_barrier
;     ...
;         G_PAIR(0, 1);
; #pragma unroll 1
;         for (int t = 2; t < nt; t += 2) G_PAIR(t, 0);
	s_waitcnt lgkmcnt(0)
	v_mfma_f32_16x16x32_bf16 v[48:51], v[56:59], v[80:83], v[96:99]
	v_mfma_f32_16x16x32_bf16 v[16:19], v[60:63], v[80:83], v[16:19]
	v_mfma_f32_16x16x32_bf16 v[20:23], v[56:59], v[100:103], v[20:23]
	v_mfma_f32_16x16x32_bf16 v[24:27], v[60:63], v[100:103], v[24:27]
	v_mfma_f32_16x16x32_bf16 v[28:31], v[56:59], v[120:123], v[28:31]
	v_mfma_f32_16x16x32_bf16 v[32:35], v[60:63], v[120:123], v[32:35]
	v_mfma_f32_16x16x32_bf16 v[36:39], v[56:59], v[124:127], v[36:39]
	v_mfma_f32_16x16x32_bf16 v[40:43], v[60:63], v[124:127], v[40:43]
	v_mfma_f32_16x16x32_bf16 v[124:127], v[234:237], v[84:87], v[48:51]
	v_mfma_f32_16x16x32_bf16 v[120:123], v[238:241], v[84:87], v[16:19]
	v_mfma_f32_16x16x32_bf16 v[100:103], v[234:237], v[222:225], v[20:23]
	v_mfma_f32_16x16x32_bf16 v[96:99], v[238:241], v[222:225], v[24:27]
	v_mfma_f32_16x16x32_bf16 v[84:87], v[234:237], v[226:229], v[28:31]
	v_mfma_f32_16x16x32_bf16 v[80:83], v[238:241], v[226:229], v[32:35]
	v_mfma_f32_16x16x32_bf16 v[68:71], v[234:237], v[230:233], v[36:39]
	v_mfma_f32_16x16x32_bf16 v[64:67], v[238:241], v[230:233], v[40:43]
	s_mov_b32 m0, s51
	v_lshl_add_u64 v[20:21], v[246:247], 0, s[14:15]
	s_barrier
	ds_read_b128 v[16:19], v191 offset:49152
	ds_read_b128 v[24:27], v191 offset:50176
	ds_read_b128 v[32:35], v191 offset:51200
	ds_read_b128 v[222:225], v191 offset:52224
	ds_read_b128 v[40:43], v191 offset:53248
	ds_read_b128 v[226:229], v191 offset:54272
	ds_read_b128 v[230:233], v191 offset:55296
	ds_read_b128 v[242:245], v191 offset:56320
	global_load_lds_dwordx4 v[20:21], off
	s_mov_b32 m0, s52
	v_lshl_add_u64 v[20:21], v[248:249], 0, s[14:15]
	global_load_lds_dwordx4 v[20:21], off
	s_barrier
	s_waitcnt lgkmcnt(0)
	v_mfma_f32_16x16x32_bf16 v[20:23], v[12:15], v[16:19], v[128:131]
	v_mfma_f32_16x16x32_bf16 v[28:31], v[44:47], v[16:19], v[166:169]
	v_mfma_f32_16x16x32_bf16 v[36:39], v[12:15], v[32:35], v[134:137]
	v_mfma_f32_16x16x32_bf16 v[128:131], v[44:47], v[32:35], v[138:141]
	v_mfma_f32_16x16x32_bf16 v[134:137], v[12:15], v[40:43], v[142:145]
	v_mfma_f32_16x16x32_bf16 v[138:141], v[44:47], v[40:43], v[146:149]
	v_mfma_f32_16x16x32_bf16 v[0:3], v[12:15], v[230:233], v[0:3]
	v_mfma_f32_16x16x32_bf16 v[4:7], v[44:47], v[230:233], v[4:7]
	v_mfma_f32_16x16x32_bf16 v[52:55], v[210:213], v[24:27], v[20:23]
	v_mfma_f32_16x16x32_bf16 v[48:51], v[214:217], v[24:27], v[28:31]
	v_mfma_f32_16x16x32_bf16 v[44:47], v[210:213], v[222:225], v[36:39]
	v_mfma_f32_16x16x32_bf16 v[36:39], v[214:217], v[222:225], v[128:131]
	v_mfma_f32_16x16x32_bf16 v[28:31], v[210:213], v[226:229], v[134:137]
	v_mfma_f32_16x16x32_bf16 v[20:23], v[214:217], v[226:229], v[138:141]
	v_mfma_f32_16x16x32_bf16 v[12:15], v[210:213], v[242:245], v[0:3]
	v_mfma_f32_16x16x32_bf16 v[4:7], v[214:217], v[242:245], v[4:7]
	s_barrier
	s_add_u32 s34, s30, 0xb0180
	s_addc_u32 s35, s31, 0
	s_add_i32 s65, s65, s43
	v_lshl_add_u64 v[0:1], s[34:35], 0, v[156:157]
	s_mov_b32 m0, s65
	s_add_i32 s66, s65, 0x2000
	global_load_lds_dwordx4 v[0:1], off
	v_lshl_add_u64 v[0:1], s[34:35], 0, v[160:161]
	s_mov_b32 m0, s66
	s_mov_b64 s[34:35], 0xb0180
	global_load_lds_dwordx4 v[0:1], off
	s_waitcnt vmcnt(6)
	s_barrier
	v_mfma_f32_16x16x32_bf16 v[0:3], v[56:59], v[16:19], v[8:11]
	v_mfma_f32_16x16x32_bf16 v[8:11], v[60:63], v[16:19], v[174:177]
	v_mfma_f32_16x16x32_bf16 v[16:19], v[56:59], v[32:35], v[178:181]
	v_mfma_f32_16x16x32_bf16 v[32:35], v[60:63], v[32:35], v[194:197]
	v_mfma_f32_16x16x32_bf16 v[128:131], v[56:59], v[40:43], v[170:173]
	v_mfma_f32_16x16x32_bf16 v[134:137], v[60:63], v[40:43], v[198:201]
	v_mfma_f32_16x16x32_bf16 v[138:141], v[56:59], v[230:233], v[202:205]
	v_mfma_f32_16x16x32_bf16 v[142:145], v[60:63], v[230:233], v[206:209]
	v_mfma_f32_16x16x32_bf16 v[60:63], v[234:237], v[24:27], v[0:3]
	v_mfma_f32_16x16x32_bf16 v[56:59], v[238:241], v[24:27], v[8:11]
	v_mfma_f32_16x16x32_bf16 v[40:43], v[234:237], v[222:225], v[16:19]
	v_mfma_f32_16x16x32_bf16 v[32:35], v[238:241], v[222:225], v[32:35]
	v_mfma_f32_16x16x32_bf16 v[24:27], v[234:237], v[226:229], v[128:131]
	v_mfma_f32_16x16x32_bf16 v[16:19], v[238:241], v[226:229], v[134:137]
	v_mfma_f32_16x16x32_bf16 v[8:11], v[234:237], v[242:245], v[138:141]
	v_mfma_f32_16x16x32_bf16 v[0:3], v[238:241], v[242:245], v[142:145]
	v_lshl_add_u64 v[128:129], s[28:29], 0, v[162:163]
	v_lshl_add_u64 v[130:131], s[28:29], 0, v[164:165]
	s_mov_b32 s67, 0
.Lrot_1167:
	s_barrier

;     ...
;         G_PAIR(0, 1);
.LBB0_1305:
	s_ashr_i32 s19, s18, 31
	ds_read_b128 v[0:3], v152
	ds_read_b128 v[4:7], v152 offset:1024
	ds_read_b128 v[8:11], v152 offset:2048
	ds_read_b128 v[12:15], v152 offset:3072
	s_lshl_b64 s[20:21], s[18:19], 19
	s_add_u32 s20, s10, s20
	s_addc_u32 s21, s11, s21
	s_ashr_i32 s17, s16, 31
	s_lshl_b64 s[22:23], s[16:17], 19
	s_add_u32 s22, s39, s22
	s_addc_u32 s23, s40, s23
	s_add_u32 s34, s26, 0x40080
	s_addc_u32 s35, s27, 0
	s_mov_b32 m0, s47
	v_lshl_add_u64 v[48:49], s[34:35], 0, v[136:137]
	ds_read_b128 v[16:19], v153
	ds_read_b128 v[20:23], v153 offset:1024
	ds_read_b128 v[24:27], v153 offset:2048
	ds_read_b128 v[28:31], v153 offset:3072
	ds_read_b128 v[32:35], v153 offset:4096
	ds_read_b128 v[36:39], v153 offset:5120
	ds_read_b128 v[40:43], v153 offset:6144
	ds_read_b128 v[44:47], v153 offset:7168
	global_load_lds_dwordx4 v[48:49], off
	s_mov_b32 m0, s48
	v_lshl_add_u64 v[48:49], s[34:35], 0, v[132:133]
	global_load_lds_dwordx4 v[48:49], off
	s_waitcnt lgkmcnt(8)
	s_barrier
	s_waitcnt lgkmcnt(0)
	v_mfma_f32_16x16x32_bf16 v[48:51], v[0:3], v[16:19], 0
	v_mfma_f32_16x16x32_bf16 v[52:55], v[8:11], v[16:19], 0
	v_mfma_f32_16x16x32_bf16 v[56:59], v[0:3], v[24:27], 0
	v_mfma_f32_16x16x32_bf16 v[60:63], v[8:11], v[24:27], 0
	v_mfma_f32_16x16x32_bf16 v[64:67], v[0:3], v[32:35], 0
	v_mfma_f32_16x16x32_bf16 v[68:71], v[8:11], v[32:35], 0
	v_mfma_f32_16x16x32_bf16 v[72:75], v[0:3], v[40:43], 0
	v_mfma_f32_16x16x32_bf16 v[76:79], v[8:11], v[40:43], 0
	v_mfma_f32_16x16x32_bf16 v[48:51], v[4:7], v[20:23], v[48:51]
	v_mfma_f32_16x16x32_bf16 v[52:55], v[12:15], v[20:23], v[52:55]
	v_mfma_f32_16x16x32_bf16 v[56:59], v[4:7], v[28:31], v[56:59]
	v_mfma_f32_16x16x32_bf16 v[60:63], v[12:15], v[28:31], v[60:63]
	v_mfma_f32_16x16x32_bf16 v[64:67], v[4:7], v[36:39], v[64:67]
	v_mfma_f32_16x16x32_bf16 v[68:71], v[12:15], v[36:39], v[68:71]
	v_mfma_f32_16x16x32_bf16 v[72:75], v[4:7], v[44:47], v[72:75]
	v_mfma_f32_16x16x32_bf16 v[76:79], v[12:15], v[44:47], v[76:79]
	s_barrier
	v_lshl_add_u64 v[218:219], s[28:29], 0, v[134:135]
	s_mov_b32 m0, s49
	v_lshl_add_u64 v[96:97], v[218:219], 0, s[8:9]
	v_lshl_add_u64 v[238:239], s[28:29], 0, v[130:131]
	ds_read_b128 v[80:83], v154
	ds_read_b128 v[84:87], v154 offset:1024
	ds_read_b128 v[88:91], v154 offset:2048
	ds_read_b128 v[92:95], v154 offset:3072
	global_load_lds_dwordx4 v[96:97], off
	s_mov_b32 m0, s50
	v_lshl_add_u64 v[96:97], v[238:239], 0, s[8:9]
	global_load_lds_dwordx4 v[96:97], off
	s_barrier
	s_waitcnt lgkmcnt(0)
	v_mfma_f32_16x16x32_bf16 v[96:99], v[80:83], v[16:19], 0
	v_mfma_f32_16x16x32_bf16 v[16:19], v[88:91], v[16:19], 0
	v_mfma_f32_16x16x32_bf16 v[100:103], v[80:83], v[24:27], 0
	v_mfma_f32_16x16x32_bf16 v[24:27], v[88:91], v[24:27], 0
	v_mfma_f32_16x16x32_bf16 v[104:107], v[80:83], v[32:35], 0
	v_mfma_f32_16x16x32_bf16 v[32:35], v[88:91], v[32:35], 0
	v_mfma_f32_16x16x32_bf16 v[108:111], v[80:83], v[40:43], 0
	v_mfma_f32_16x16x32_bf16 v[40:43], v[88:91], v[40:43], 0
	v_mfma_f32_16x16x32_bf16 v[116:119], v[84:87], v[20:23], v[96:99]
	v_mfma_f32_16x16x32_bf16 v[16:19], v[92:95], v[20:23], v[16:19]
	v_mfma_f32_16x16x32_bf16 v[20:23], v[84:87], v[28:31], v[100:103]
	v_mfma_f32_16x16x32_bf16 v[24:27], v[92:95], v[28:31], v[24:27]
	v_mfma_f32_16x16x32_bf16 v[28:31], v[84:87], v[36:39], v[104:107]
	v_mfma_f32_16x16x32_bf16 v[32:35], v[92:95], v[36:39], v[32:35]
	v_mfma_f32_16x16x32_bf16 v[36:39], v[84:87], v[44:47], v[108:111]
	v_mfma_f32_16x16x32_bf16 v[40:43], v[92:95], v[44:47], v[40:43]
	v_lshl_add_u64 v[246:247], s[26:27], 0, v[136:137]
	s_mov_b32 m0, s25
	v_lshl_add_u64 v[142:143], v[246:247], 0, s[8:9]
	v_lshl_add_u64 v[248:249], s[26:27], 0, v[132:133]
	s_barrier
	ds_read_b128 v[44:47], v153 offset:16384
	ds_read_b128 v[96:99], v153 offset:17408
	ds_read_b128 v[100:103], v153 offset:18432
	ds_read_b128 v[104:107], v153 offset:19456
	ds_read_b128 v[108:111], v153 offset:20480
	ds_read_b128 v[112:115], v153 offset:21504
	ds_read_b128 v[120:123], v153 offset:22528
	ds_read_b128 v[124:127], v153 offset:23552
	global_load_lds_dwordx4 v[142:143], off
	s_mov_b32 m0, s41
	v_lshl_add_u64 v[142:143], v[248:249], 0, s[8:9]
	global_load_lds_dwordx4 v[142:143], off
	s_barrier
	s_waitcnt lgkmcnt(0)
	v_mfma_f32_16x16x32_bf16 v[142:145], v[0:3], v[44:47], 0
	v_mfma_f32_16x16x32_bf16 v[158:161], v[8:11], v[44:47], 0
	v_mfma_f32_16x16x32_bf16 v[162:165], v[0:3], v[100:103], 0
	v_mfma_f32_16x16x32_bf16 v[166:169], v[8:11], v[100:103], 0
	v_mfma_f32_16x16x32_bf16 v[170:173], v[0:3], v[108:111], 0
	v_mfma_f32_16x16x32_bf16 v[174:177], v[8:11], v[108:111], 0
	v_mfma_f32_16x16x32_bf16 v[0:3], v[0:3], v[120:123], 0
	v_mfma_f32_16x16x32_bf16 v[8:11], v[8:11], v[120:123], 0
	v_mfma_f32_16x16x32_bf16 v[142:145], v[4:7], v[96:99], v[142:145]
	v_mfma_f32_16x16x32_bf16 v[162:165], v[4:7], v[104:107], v[162:165]
	v_mfma_f32_16x16x32_bf16 v[170:173], v[4:7], v[112:115], v[170:173]
	v_mfma_f32_16x16x32_bf16 v[0:3], v[4:7], v[124:127], v[0:3]
	v_mfma_f32_16x16x32_bf16 v[4:7], v[12:15], v[124:127], v[8:11]
	v_mfma_f32_16x16x32_bf16 v[158:161], v[12:15], v[96:99], v[158:161]
	v_mfma_f32_16x16x32_bf16 v[166:169], v[12:15], v[104:107], v[166:169]
	v_mfma_f32_16x16x32_bf16 v[174:177], v[12:15], v[112:115], v[174:177]
	s_barrier
	s_add_u32 s34, s28, 0x40100
	s_addc_u32 s35, s29, 0
	s_mov_b32 m0, s55
	v_lshl_add_u64 v[8:9], s[34:35], 0, v[134:135]
	global_load_lds_dwordx4 v[8:9], off
	s_mov_b32 m0, s56
	v_lshl_add_u64 v[8:9], s[34:35], 0, v[130:131]
	global_load_lds_dwordx4 v[8:9], off
	s_waitcnt vmcnt(6)
	s_barrier
	v_mfma_f32_16x16x32_bf16 v[8:11], v[80:83], v[44:47], 0
	v_mfma_f32_16x16x32_bf16 v[12:15], v[88:91], v[44:47], 0
	v_mfma_f32_16x16x32_bf16 v[44:47], v[80:83], v[100:103], 0
	v_mfma_f32_16x16x32_bf16 v[100:103], v[88:91], v[100:103], 0
	v_mfma_f32_16x16x32_bf16 v[178:181], v[80:83], v[108:111], 0
	v_mfma_f32_16x16x32_bf16 v[108:111], v[88:91], v[108:111], 0
	v_mfma_f32_16x16x32_bf16 v[80:83], v[80:83], v[120:123], 0
	v_mfma_f32_16x16x32_bf16 v[88:91], v[88:91], v[120:123], 0
	v_mfma_f32_16x16x32_bf16 v[12:15], v[92:95], v[96:99], v[12:15]
	v_mfma_f32_16x16x32_bf16 v[44:47], v[84:87], v[104:107], v[44:47]
	v_mfma_f32_16x16x32_bf16 v[182:185], v[84:87], v[96:99], v[8:11]
	v_mfma_f32_16x16x32_bf16 v[186:189], v[92:95], v[104:107], v[100:103]
	v_mfma_f32_16x16x32_bf16 v[178:181], v[84:87], v[112:115], v[178:181]
	v_mfma_f32_16x16x32_bf16 v[190:193], v[92:95], v[112:115], v[108:111]
	v_mfma_f32_16x16x32_bf16 v[194:197], v[84:87], v[124:127], v[80:83]
	v_mfma_f32_16x16x32_bf16 v[198:201], v[92:95], v[124:127], v[88:91]
	s_barrier
	ds_read_b128 v[8:11], v155
	ds_read_b128 v[202:205], v155 offset:1024
	ds_read_b128 v[206:209], v155 offset:2048
	ds_read_b128 v[210:213], v155 offset:3072
	s_add_u32 s34, s26, 0x40100
	s_addc_u32 s35, s27, 0
	s_mov_b32 m0, s42
	v_lshl_add_u64 v[80:81], s[34:35], 0, v[136:137]
	ds_read_b128 v[84:87], v153 offset:32768
	ds_read_b128 v[92:95], v153 offset:33792
	ds_read_b128 v[100:103], v153 offset:34816
	ds_read_b128 v[214:217], v153 offset:35840
	ds_read_b128 v[108:111], v153 offset:36864
	ds_read_b128 v[222:225], v153 offset:37888
	ds_read_b128 v[124:127], v153 offset:38912
	ds_read_b128 v[226:229], v153 offset:39936
	global_load_lds_dwordx4 v[80:81], off
	s_mov_b32 m0, s43
	v_lshl_add_u64 v[80:81], s[34:35], 0, v[132:133]
	global_load_lds_dwordx4 v[80:81], off
	s_waitcnt lgkmcnt(8)
	s_barrier
	s_waitcnt lgkmcnt(0)
	v_mfma_f32_16x16x32_bf16 v[48:51], v[8:11], v[84:87], v[48:51]
	v_mfma_f32_16x16x32_bf16 v[52:55], v[206:209], v[84:87], v[52:55]
	v_mfma_f32_16x16x32_bf16 v[56:59], v[8:11], v[100:103], v[56:59]
	v_mfma_f32_16x16x32_bf16 v[60:63], v[206:209], v[100:103], v[60:63]
	v_mfma_f32_16x16x32_bf16 v[64:67], v[8:11], v[108:111], v[64:67]
	v_mfma_f32_16x16x32_bf16 v[68:71], v[206:209], v[108:111], v[68:71]
	v_mfma_f32_16x16x32_bf16 v[72:75], v[8:11], v[124:127], v[72:75]
	v_mfma_f32_16x16x32_bf16 v[76:79], v[206:209], v[124:127], v[76:79]
	v_mfma_f32_16x16x32_bf16 v[120:123], v[202:205], v[92:95], v[48:51]
	v_mfma_f32_16x16x32_bf16 v[112:115], v[210:213], v[92:95], v[52:55]
	v_mfma_f32_16x16x32_bf16 v[104:107], v[202:205], v[214:217], v[56:59]
	v_mfma_f32_16x16x32_bf16 v[96:99], v[210:213], v[214:217], v[60:63]
	v_mfma_f32_16x16x32_bf16 v[88:91], v[202:205], v[222:225], v[64:67]
	v_mfma_f32_16x16x32_bf16 v[80:83], v[210:213], v[222:225], v[68:71]
	v_mfma_f32_16x16x32_bf16 v[72:75], v[202:205], v[226:229], v[72:75]
	v_mfma_f32_16x16x32_bf16 v[60:63], v[210:213], v[226:229], v[76:79]
	s_barrier
	s_mov_b32 m0, s57
	v_lshl_add_u64 v[48:49], v[218:219], 0, s[12:13]
	ds_read_b128 v[52:55], v156
	ds_read_b128 v[230:233], v156 offset:1024
	ds_read_b128 v[68:71], v156 offset:2048
	ds_read_b128 v[234:237], v156 offset:3072
	global_load_lds_dwordx4 v[48:49], off
	s_mov_b32 m0, s58
	v_lshl_add_u64 v[48:49], v[238:239], 0, s[12:13]
	global_load_lds_dwordx4 v[48:49], off
	s_barrier
;     ...
;         G_PAIR(0, 1);
; #pragma unroll 1
;         for (int t = 2; t < nt; t += 2) G_PAIR(t, 0);
	s_waitcnt lgkmcnt(0)
	v_mfma_f32_16x16x32_bf16 v[48:51], v[52:55], v[84:87], v[116:119]
	v_mfma_f32_16x16x32_bf16 v[16:19], v[68:71], v[84:87], v[16:19]
	v_mfma_f32_16x16x32_bf16 v[20:23], v[52:55], v[100:103], v[20:23]
	v_mfma_f32_16x16x32_bf16 v[24:27], v[68:71], v[100:103], v[24:27]
	v_mfma_f32_16x16x32_bf16 v[28:31], v[52:55], v[108:111], v[28:31]
	v_mfma_f32_16x16x32_bf16 v[32:35], v[68:71], v[108:111], v[32:35]
	v_mfma_f32_16x16x32_bf16 v[36:39], v[52:55], v[124:127], v[36:39]
	v_mfma_f32_16x16x32_bf16 v[40:43], v[68:71], v[124:127], v[40:43]
	v_mfma_f32_16x16x32_bf16 v[124:127], v[230:233], v[92:95], v[48:51]
	v_mfma_f32_16x16x32_bf16 v[116:119], v[234:237], v[92:95], v[16:19]
	v_mfma_f32_16x16x32_bf16 v[108:111], v[230:233], v[214:217], v[20:23]
	v_mfma_f32_16x16x32_bf16 v[100:103], v[234:237], v[214:217], v[24:27]
	v_mfma_f32_16x16x32_bf16 v[92:95], v[230:233], v[222:225], v[28:31]
	v_mfma_f32_16x16x32_bf16 v[84:87], v[234:237], v[222:225], v[32:35]
	v_mfma_f32_16x16x32_bf16 v[76:79], v[230:233], v[226:229], v[36:39]
	v_mfma_f32_16x16x32_bf16 v[64:67], v[234:237], v[226:229], v[40:43]
	s_mov_b32 m0, s44
	v_lshl_add_u64 v[16:17], v[246:247], 0, s[12:13]
	s_barrier
	ds_read_b128 v[20:23], v153 offset:49152
	ds_read_b128 v[28:31], v153 offset:50176
	ds_read_b128 v[36:39], v153 offset:51200
	ds_read_b128 v[214:217], v153 offset:52224
	ds_read_b128 v[222:225], v153 offset:53248
	ds_read_b128 v[226:229], v153 offset:54272
	ds_read_b128 v[238:241], v153 offset:55296
	ds_read_b128 v[242:245], v153 offset:56320
	global_load_lds_dwordx4 v[16:17], off
	s_mov_b32 m0, s45
	v_lshl_add_u64 v[16:17], v[248:249], 0, s[12:13]
	global_load_lds_dwordx4 v[16:17], off
	s_barrier
	s_waitcnt lgkmcnt(0)
	v_mfma_f32_16x16x32_bf16 v[16:19], v[8:11], v[20:23], v[142:145]
	v_mfma_f32_16x16x32_bf16 v[24:27], v[206:209], v[20:23], v[158:161]
	v_mfma_f32_16x16x32_bf16 v[32:35], v[8:11], v[36:39], v[162:165]
	v_mfma_f32_16x16x32_bf16 v[142:145], v[206:209], v[36:39], v[166:169]
	v_mfma_f32_16x16x32_bf16 v[158:161], v[8:11], v[222:225], v[170:173]
	v_mfma_f32_16x16x32_bf16 v[162:165], v[206:209], v[222:225], v[174:177]
	v_mfma_f32_16x16x32_bf16 v[0:3], v[8:11], v[238:241], v[0:3]
	v_mfma_f32_16x16x32_bf16 v[4:7], v[206:209], v[238:241], v[4:7]
	v_mfma_f32_16x16x32_bf16 v[56:59], v[202:205], v[28:31], v[16:19]
	v_mfma_f32_16x16x32_bf16 v[48:51], v[210:213], v[28:31], v[24:27]
	v_mfma_f32_16x16x32_bf16 v[40:43], v[202:205], v[214:217], v[32:35]
	v_mfma_f32_16x16x32_bf16 v[32:35], v[210:213], v[214:217], v[142:145]
	v_mfma_f32_16x16x32_bf16 v[24:27], v[202:205], v[226:229], v[158:161]
	v_mfma_f32_16x16x32_bf16 v[16:19], v[210:213], v[226:229], v[162:165]
	v_mfma_f32_16x16x32_bf16 v[8:11], v[202:205], v[242:245], v[0:3]
	v_mfma_f32_16x16x32_bf16 v[0:3], v[210:213], v[242:245], v[4:7]
	s_barrier
	s_add_u32 s34, s28, 0x40180
	s_addc_u32 s35, s29, 0
	s_mov_b32 m0, s59
	v_lshl_add_u64 v[4:5], s[34:35], 0, v[134:135]
	s_add_i32 s17, s59, 0x2000
	global_load_lds_dwordx4 v[4:5], off
	v_lshl_add_u64 v[4:5], s[34:35], 0, v[130:131]
	s_mov_b32 m0, s17
	s_mov_b64 s[34:35], 0x40180
	global_load_lds_dwordx4 v[4:5], off
	s_waitcnt vmcnt(6)
	s_barrier
	v_mfma_f32_16x16x32_bf16 v[4:7], v[52:55], v[20:23], v[182:185]
	v_mfma_f32_16x16x32_bf16 v[12:15], v[68:71], v[20:23], v[12:15]
	v_mfma_f32_16x16x32_bf16 v[20:23], v[52:55], v[36:39], v[44:47]
	v_mfma_f32_16x16x32_bf16 v[36:39], v[68:71], v[36:39], v[186:189]
	v_mfma_f32_16x16x32_bf16 v[142:145], v[52:55], v[222:225], v[178:181]
	v_mfma_f32_16x16x32_bf16 v[158:161], v[68:71], v[222:225], v[190:193]
	v_mfma_f32_16x16x32_bf16 v[162:165], v[52:55], v[238:241], v[194:197]
	v_mfma_f32_16x16x32_bf16 v[166:169], v[68:71], v[238:241], v[198:201]
	v_mfma_f32_16x16x32_bf16 v[68:71], v[230:233], v[28:31], v[4:7]
	v_mfma_f32_16x16x32_bf16 v[52:55], v[234:237], v[28:31], v[12:15]
	v_mfma_f32_16x16x32_bf16 v[44:47], v[230:233], v[214:217], v[20:23]
	v_mfma_f32_16x16x32_bf16 v[36:39], v[234:237], v[214:217], v[36:39]
	v_mfma_f32_16x16x32_bf16 v[28:31], v[230:233], v[226:229], v[142:145]
	v_mfma_f32_16x16x32_bf16 v[20:23], v[234:237], v[226:229], v[158:161]
	v_mfma_f32_16x16x32_bf16 v[12:15], v[230:233], v[242:245], v[162:165]
	v_mfma_f32_16x16x32_bf16 v[4:7], v[234:237], v[242:245], v[166:169]
	v_lshl_add_u64 v[142:143], s[26:27], 0, v[138:139]
	v_lshl_add_u64 v[144:145], s[26:27], 0, v[140:141]
	s_mov_b32 s19, 0
.Lrot_1306:
	s_barrier

;     ...
;         G_PAIR(0, 1);
.LBB0_1430:
	s_waitcnt lgkmcnt(0)
	ds_read_b128 v[0:3], v190
	ds_read_b128 v[4:7], v190 offset:1024
	ds_read_b128 v[8:11], v190 offset:2048
	ds_read_b128 v[12:15], v190 offset:3072
	s_add_u32 s34, s28, 0xb0080
	s_addc_u32 s35, s29, 0
	s_mov_b32 m0, s54
	v_lshl_add_u64 v[48:49], s[34:35], 0, v[154:155]
	ds_read_b128 v[16:19], v191
	ds_read_b128 v[20:23], v191 offset:1024
	ds_read_b128 v[24:27], v191 offset:2048
	ds_read_b128 v[28:31], v191 offset:3072
	ds_read_b128 v[32:35], v191 offset:4096
	ds_read_b128 v[36:39], v191 offset:5120
	ds_read_b128 v[40:43], v191 offset:6144
	ds_read_b128 v[44:47], v191 offset:7168
	global_load_lds_dwordx4 v[48:49], off
	s_mov_b32 m0, s55
	v_lshl_add_u64 v[48:49], s[34:35], 0, v[158:159]
	global_load_lds_dwordx4 v[48:49], off
	s_waitcnt lgkmcnt(8)
	s_barrier
	s_waitcnt lgkmcnt(0)
	v_mfma_f32_16x16x32_bf16 v[48:51], v[0:3], v[16:19], 0
	v_mfma_f32_16x16x32_bf16 v[52:55], v[8:11], v[16:19], 0
	v_mfma_f32_16x16x32_bf16 v[56:59], v[0:3], v[24:27], 0
	v_mfma_f32_16x16x32_bf16 v[60:63], v[8:11], v[24:27], 0
	v_mfma_f32_16x16x32_bf16 v[64:67], v[0:3], v[32:35], 0
	v_mfma_f32_16x16x32_bf16 v[68:71], v[8:11], v[32:35], 0
	v_mfma_f32_16x16x32_bf16 v[72:75], v[0:3], v[40:43], 0
	v_mfma_f32_16x16x32_bf16 v[76:79], v[8:11], v[40:43], 0
	v_mfma_f32_16x16x32_bf16 v[48:51], v[4:7], v[20:23], v[48:51]
	v_mfma_f32_16x16x32_bf16 v[52:55], v[12:15], v[20:23], v[52:55]
	v_mfma_f32_16x16x32_bf16 v[56:59], v[4:7], v[28:31], v[56:59]
	v_mfma_f32_16x16x32_bf16 v[60:63], v[12:15], v[28:31], v[60:63]
	v_mfma_f32_16x16x32_bf16 v[64:67], v[4:7], v[36:39], v[64:67]
	v_mfma_f32_16x16x32_bf16 v[68:71], v[12:15], v[36:39], v[68:71]
	v_mfma_f32_16x16x32_bf16 v[72:75], v[4:7], v[44:47], v[72:75]
	v_mfma_f32_16x16x32_bf16 v[76:79], v[12:15], v[44:47], v[76:79]
	s_barrier
	v_lshl_add_u64 v[182:183], s[30:31], 0, v[156:157]
	s_mov_b32 m0, s56
	v_lshl_add_u64 v[96:97], v[182:183], 0, s[12:13]
	v_lshl_add_u64 v[218:219], s[30:31], 0, v[160:161]
	ds_read_b128 v[80:83], v192
	ds_read_b128 v[84:87], v192 offset:1024
	ds_read_b128 v[88:91], v192 offset:2048
	ds_read_b128 v[92:95], v192 offset:3072
	global_load_lds_dwordx4 v[96:97], off
	s_mov_b32 m0, s57
	v_lshl_add_u64 v[96:97], v[218:219], 0, s[12:13]
	global_load_lds_dwordx4 v[96:97], off
	s_barrier
	s_waitcnt lgkmcnt(0)
	v_mfma_f32_16x16x32_bf16 v[96:99], v[80:83], v[16:19], 0
	v_mfma_f32_16x16x32_bf16 v[16:19], v[88:91], v[16:19], 0
	v_mfma_f32_16x16x32_bf16 v[100:103], v[80:83], v[24:27], 0
	v_mfma_f32_16x16x32_bf16 v[24:27], v[88:91], v[24:27], 0
	v_mfma_f32_16x16x32_bf16 v[104:107], v[80:83], v[32:35], 0
	v_mfma_f32_16x16x32_bf16 v[32:35], v[88:91], v[32:35], 0
	v_mfma_f32_16x16x32_bf16 v[108:111], v[80:83], v[40:43], 0
	v_mfma_f32_16x16x32_bf16 v[40:43], v[88:91], v[40:43], 0
	v_mfma_f32_16x16x32_bf16 v[96:99], v[84:87], v[20:23], v[96:99]
	v_mfma_f32_16x16x32_bf16 v[16:19], v[92:95], v[20:23], v[16:19]
	v_mfma_f32_16x16x32_bf16 v[20:23], v[84:87], v[28:31], v[100:103]
	v_mfma_f32_16x16x32_bf16 v[24:27], v[92:95], v[28:31], v[24:27]
	v_mfma_f32_16x16x32_bf16 v[28:31], v[84:87], v[36:39], v[104:107]
	v_mfma_f32_16x16x32_bf16 v[32:35], v[92:95], v[36:39], v[32:35]
	v_mfma_f32_16x16x32_bf16 v[36:39], v[84:87], v[44:47], v[108:111]
	v_mfma_f32_16x16x32_bf16 v[40:43], v[92:95], v[44:47], v[40:43]
	v_lshl_add_u64 v[246:247], s[28:29], 0, v[154:155]
	s_mov_b32 m0, s46
	v_lshl_add_u64 v[128:129], v[246:247], 0, s[12:13]
	v_lshl_add_u64 v[248:249], s[28:29], 0, v[158:159]
	s_barrier
	ds_read_b128 v[44:47], v191 offset:16384
	ds_read_b128 v[100:103], v191 offset:17408
	ds_read_b128 v[104:107], v191 offset:18432
	ds_read_b128 v[108:111], v191 offset:19456
	ds_read_b128 v[112:115], v191 offset:20480
	ds_read_b128 v[116:119], v191 offset:21504
	ds_read_b128 v[120:123], v191 offset:22528
	ds_read_b128 v[124:127], v191 offset:23552
	global_load_lds_dwordx4 v[128:129], off
	s_mov_b32 m0, s47
	v_lshl_add_u64 v[128:129], v[248:249], 0, s[12:13]
	global_load_lds_dwordx4 v[128:129], off
	s_barrier
	s_waitcnt lgkmcnt(0)
	v_mfma_f32_16x16x32_bf16 v[128:131], v[0:3], v[44:47], 0
	v_mfma_f32_16x16x32_bf16 v[132:135], v[8:11], v[44:47], 0
	v_mfma_f32_16x16x32_bf16 v[136:139], v[0:3], v[104:107], 0
	v_mfma_f32_16x16x32_bf16 v[140:143], v[8:11], v[104:107], 0
	v_mfma_f32_16x16x32_bf16 v[144:147], v[0:3], v[112:115], 0
	v_mfma_f32_16x16x32_bf16 v[148:151], v[8:11], v[112:115], 0
	v_mfma_f32_16x16x32_bf16 v[0:3], v[0:3], v[120:123], 0
	v_mfma_f32_16x16x32_bf16 v[8:11], v[8:11], v[120:123], 0
	v_mfma_f32_16x16x32_bf16 v[128:131], v[4:7], v[100:103], v[128:131]
	v_mfma_f32_16x16x32_bf16 v[166:169], v[12:15], v[100:103], v[132:135]
	v_mfma_f32_16x16x32_bf16 v[134:137], v[4:7], v[108:111], v[136:139]
	v_mfma_f32_16x16x32_bf16 v[138:141], v[12:15], v[108:111], v[140:143]
	v_mfma_f32_16x16x32_bf16 v[142:145], v[4:7], v[116:119], v[144:147]
	v_mfma_f32_16x16x32_bf16 v[0:3], v[4:7], v[124:127], v[0:3]
	v_mfma_f32_16x16x32_bf16 v[4:7], v[12:15], v[124:127], v[8:11]
	v_mfma_f32_16x16x32_bf16 v[146:149], v[12:15], v[116:119], v[148:151]
	s_barrier
	s_add_u32 s34, s30, 0xb0100
	s_addc_u32 s35, s31, 0
	s_add_i32 s0, s53, s43
	v_lshl_add_u64 v[8:9], s[34:35], 0, v[156:157]
	s_mov_b32 m0, s0
	s_add_i32 s62, s0, 0x2000
	global_load_lds_dwordx4 v[8:9], off
	s_mov_b32 m0, s62
	v_lshl_add_u64 v[8:9], s[34:35], 0, v[160:161]
	global_load_lds_dwordx4 v[8:9], off
	s_waitcnt vmcnt(6)
	s_barrier
	v_mfma_f32_16x16x32_bf16 v[8:11], v[80:83], v[44:47], 0
	v_mfma_f32_16x16x32_bf16 v[12:15], v[88:91], v[44:47], 0
	v_mfma_f32_16x16x32_bf16 v[44:47], v[80:83], v[104:107], 0
	v_mfma_f32_16x16x32_bf16 v[104:107], v[88:91], v[104:107], 0
	v_mfma_f32_16x16x32_bf16 v[170:173], v[80:83], v[112:115], 0
	v_mfma_f32_16x16x32_bf16 v[112:115], v[88:91], v[112:115], 0
	v_mfma_f32_16x16x32_bf16 v[80:83], v[80:83], v[120:123], 0
	v_mfma_f32_16x16x32_bf16 v[88:91], v[88:91], v[120:123], 0
	v_mfma_f32_16x16x32_bf16 v[8:11], v[84:87], v[100:103], v[8:11]
	v_mfma_f32_16x16x32_bf16 v[174:177], v[92:95], v[100:103], v[12:15]
	v_mfma_f32_16x16x32_bf16 v[178:181], v[84:87], v[108:111], v[44:47]
	v_mfma_f32_16x16x32_bf16 v[194:197], v[92:95], v[108:111], v[104:107]
	v_mfma_f32_16x16x32_bf16 v[170:173], v[84:87], v[116:119], v[170:173]
	v_mfma_f32_16x16x32_bf16 v[198:201], v[92:95], v[116:119], v[112:115]
	v_mfma_f32_16x16x32_bf16 v[202:205], v[84:87], v[124:127], v[80:83]
	v_mfma_f32_16x16x32_bf16 v[206:209], v[92:95], v[124:127], v[88:91]
	s_add_i32 s63, 0, 0x18000
	v_add_u32_e32 v132, s63, v188
	s_barrier
	ds_read_b128 v[12:15], v132
	ds_read_b128 v[210:213], v132 offset:1024
	ds_read_b128 v[44:47], v132 offset:2048
	ds_read_b128 v[214:217], v132 offset:3072
	s_add_u32 s34, s28, 0xb0100
	s_addc_u32 s35, s29, 0
	s_mov_b32 m0, s48
	v_lshl_add_u64 v[88:89], s[34:35], 0, v[154:155]
	ds_read_b128 v[80:83], v191 offset:32768
	ds_read_b128 v[84:87], v191 offset:33792
	ds_read_b128 v[100:103], v191 offset:34816
	ds_read_b128 v[222:225], v191 offset:35840
	ds_read_b128 v[120:123], v191 offset:36864
	ds_read_b128 v[226:229], v191 offset:37888
	ds_read_b128 v[124:127], v191 offset:38912
	ds_read_b128 v[230:233], v191 offset:39936
	global_load_lds_dwordx4 v[88:89], off
	s_mov_b32 m0, s49
	v_lshl_add_u64 v[88:89], s[34:35], 0, v[158:159]
	global_load_lds_dwordx4 v[88:89], off
	s_waitcnt lgkmcnt(8)
	s_barrier
	s_waitcnt lgkmcnt(0)
	v_mfma_f32_16x16x32_bf16 v[48:51], v[12:15], v[80:83], v[48:51]
	v_mfma_f32_16x16x32_bf16 v[52:55], v[44:47], v[80:83], v[52:55]
	v_mfma_f32_16x16x32_bf16 v[56:59], v[12:15], v[100:103], v[56:59]
	v_mfma_f32_16x16x32_bf16 v[60:63], v[44:47], v[100:103], v[60:63]
	v_mfma_f32_16x16x32_bf16 v[64:67], v[12:15], v[120:123], v[64:67]
	v_mfma_f32_16x16x32_bf16 v[68:71], v[44:47], v[120:123], v[68:71]
	v_mfma_f32_16x16x32_bf16 v[72:75], v[12:15], v[124:127], v[72:75]
	v_mfma_f32_16x16x32_bf16 v[234:237], v[44:47], v[124:127], v[76:79]
	v_mfma_f32_16x16x32_bf16 v[116:119], v[210:213], v[84:87], v[48:51]
	v_mfma_f32_16x16x32_bf16 v[112:115], v[214:217], v[84:87], v[52:55]
	v_mfma_f32_16x16x32_bf16 v[108:111], v[210:213], v[222:225], v[56:59]
	v_mfma_f32_16x16x32_bf16 v[104:107], v[214:217], v[222:225], v[60:63]
	v_mfma_f32_16x16x32_bf16 v[92:95], v[210:213], v[226:229], v[64:67]
	v_mfma_f32_16x16x32_bf16 v[88:91], v[214:217], v[226:229], v[68:71]
	v_mfma_f32_16x16x32_bf16 v[76:79], v[210:213], v[230:233], v[72:75]
	v_mfma_f32_16x16x32_bf16 v[72:75], v[214:217], v[230:233], v[234:237]
	s_barrier
	s_add_i32 s65, 0, 0x1c000
	s_add_i32 s63, s63, s43
	v_add_u32_e32 v133, s65, v188
	v_lshl_add_u64 v[48:49], v[182:183], 0, s[14:15]
	s_mov_b32 m0, s63
	s_add_i32 s64, s63, 0x2000
	ds_read_b128 v[56:59], v133
	ds_read_b128 v[234:237], v133 offset:1024
	ds_read_b128 v[60:63], v133 offset:2048
	ds_read_b128 v[238:241], v133 offset:3072
	global_load_lds_dwordx4 v[48:49], off
	s_mov_b32 m0, s64
	v_lshl_add_u64 v[48:49], v[218:219], 0, s[14:15]
	global_load_lds_dwordx4 v[48:49], off
	s_barrier
;     ...
;         G_PAIR(0, 1);
; #pragma unroll 1
;         for (int t = 2; t < nt; t += 2) G_PAIR(t, 0);
	s_waitcnt lgkmcnt(0)
	v_mfma_f32_16x16x32_bf16 v[48:51], v[56:59], v[80:83], v[96:99]
	v_mfma_f32_16x16x32_bf16 v[16:19], v[60:63], v[80:83], v[16:19]
	v_mfma_f32_16x16x32_bf16 v[20:23], v[56:59], v[100:103], v[20:23]
	v_mfma_f32_16x16x32_bf16 v[24:27], v[60:63], v[100:103], v[24:27]
	v_mfma_f32_16x16x32_bf16 v[28:31], v[56:59], v[120:123], v[28:31]
	v_mfma_f32_16x16x32_bf16 v[32:35], v[60:63], v[120:123], v[32:35]
	v_mfma_f32_16x16x32_bf16 v[36:39], v[56:59], v[124:127], v[36:39]
	v_mfma_f32_16x16x32_bf16 v[40:43], v[60:63], v[124:127], v[40:43]
	v_mfma_f32_16x16x32_bf16 v[124:127], v[234:237], v[84:87], v[48:51]
	v_mfma_f32_16x16x32_bf16 v[120:123], v[238:241], v[84:87], v[16:19]
	v_mfma_f32_16x16x32_bf16 v[100:103], v[234:237], v[222:225], v[20:23]
	v_mfma_f32_16x16x32_bf16 v[96:99], v[238:241], v[222:225], v[24:27]
	v_mfma_f32_16x16x32_bf16 v[84:87], v[234:237], v[226:229], v[28:31]
	v_mfma_f32_16x16x32_bf16 v[80:83], v[238:241], v[226:229], v[32:35]
	v_mfma_f32_16x16x32_bf16 v[68:71], v[234:237], v[230:233], v[36:39]
	v_mfma_f32_16x16x32_bf16 v[64:67], v[238:241], v[230:233], v[40:43]
	s_mov_b32 m0, s51
	v_lshl_add_u64 v[20:21], v[246:247], 0, s[14:15]
	s_barrier
	ds_read_b128 v[16:19], v191 offset:49152
	ds_read_b128 v[24:27], v191 offset:50176
	ds_read_b128 v[32:35], v191 offset:51200
	ds_read_b128 v[222:225], v191 offset:52224
	ds_read_b128 v[40:43], v191 offset:53248
	ds_read_b128 v[226:229], v191 offset:54272
	ds_read_b128 v[230:233], v191 offset:55296
	ds_read_b128 v[242:245], v191 offset:56320
	global_load_lds_dwordx4 v[20:21], off
	s_mov_b32 m0, s52
	v_lshl_add_u64 v[20:21], v[248:249], 0, s[14:15]
	global_load_lds_dwordx4 v[20:21], off
	s_barrier
	s_waitcnt lgkmcnt(0)
	v_mfma_f32_16x16x32_bf16 v[20:23], v[12:15], v[16:19], v[128:131]
	v_mfma_f32_16x16x32_bf16 v[28:31], v[44:47], v[16:19], v[166:169]
	v_mfma_f32_16x16x32_bf16 v[36:39], v[12:15], v[32:35], v[134:137]
	v_mfma_f32_16x16x32_bf16 v[128:131], v[44:47], v[32:35], v[138:141]
	v_mfma_f32_16x16x32_bf16 v[134:137], v[12:15], v[40:43], v[142:145]
	v_mfma_f32_16x16x32_bf16 v[138:141], v[44:47], v[40:43], v[146:149]
	v_mfma_f32_16x16x32_bf16 v[0:3], v[12:15], v[230:233], v[0:3]
	v_mfma_f32_16x16x32_bf16 v[4:7], v[44:47], v[230:233], v[4:7]
	v_mfma_f32_16x16x32_bf16 v[52:55], v[210:213], v[24:27], v[20:23]
	v_mfma_f32_16x16x32_bf16 v[48:51], v[214:217], v[24:27], v[28:31]
	v_mfma_f32_16x16x32_bf16 v[44:47], v[210:213], v[222:225], v[36:39]
	v_mfma_f32_16x16x32_bf16 v[36:39], v[214:217], v[222:225], v[128:131]
	v_mfma_f32_16x16x32_bf16 v[28:31], v[210:213], v[226:229], v[134:137]
	v_mfma_f32_16x16x32_bf16 v[20:23], v[214:217], v[226:229], v[138:141]
	v_mfma_f32_16x16x32_bf16 v[12:15], v[210:213], v[242:245], v[0:3]
	v_mfma_f32_16x16x32_bf16 v[4:7], v[214:217], v[242:245], v[4:7]
	s_barrier
	s_add_u32 s34, s30, 0xb0180
	s_addc_u32 s35, s31, 0
	s_add_i32 s65, s65, s43
	v_lshl_add_u64 v[0:1], s[34:35], 0, v[156:157]
	s_mov_b32 m0, s65
	s_add_i32 s66, s65, 0x2000
	global_load_lds_dwordx4 v[0:1], off
	v_lshl_add_u64 v[0:1], s[34:35], 0, v[160:161]
	s_mov_b32 m0, s66
	s_mov_b64 s[34:35], 0xb0180
	global_load_lds_dwordx4 v[0:1], off
	s_waitcnt vmcnt(6)
	s_barrier
	v_mfma_f32_16x16x32_bf16 v[0:3], v[56:59], v[16:19], v[8:11]
	v_mfma_f32_16x16x32_bf16 v[8:11], v[60:63], v[16:19], v[174:177]
	v_mfma_f32_16x16x32_bf16 v[16:19], v[56:59], v[32:35], v[178:181]
	v_mfma_f32_16x16x32_bf16 v[32:35], v[60:63], v[32:35], v[194:197]
	v_mfma_f32_16x16x32_bf16 v[128:131], v[56:59], v[40:43], v[170:173]
	v_mfma_f32_16x16x32_bf16 v[134:137], v[60:63], v[40:43], v[198:201]
	v_mfma_f32_16x16x32_bf16 v[138:141], v[56:59], v[230:233], v[202:205]
	v_mfma_f32_16x16x32_bf16 v[142:145], v[60:63], v[230:233], v[206:209]
	v_mfma_f32_16x16x32_bf16 v[60:63], v[234:237], v[24:27], v[0:3]
	v_mfma_f32_16x16x32_bf16 v[56:59], v[238:241], v[24:27], v[8:11]
	v_mfma_f32_16x16x32_bf16 v[40:43], v[234:237], v[222:225], v[16:19]
	v_mfma_f32_16x16x32_bf16 v[32:35], v[238:241], v[222:225], v[32:35]
	v_mfma_f32_16x16x32_bf16 v[24:27], v[234:237], v[226:229], v[128:131]
	v_mfma_f32_16x16x32_bf16 v[16:19], v[238:241], v[226:229], v[134:137]
	v_mfma_f32_16x16x32_bf16 v[8:11], v[234:237], v[242:245], v[138:141]
	v_mfma_f32_16x16x32_bf16 v[0:3], v[238:241], v[242:245], v[142:145]
	v_lshl_add_u64 v[128:129], s[28:29], 0, v[162:163]
	v_lshl_add_u64 v[130:131], s[28:29], 0, v[164:165]
	s_mov_b32 s67, 0
.Lrot_1431:
	s_barrier

;     __device__ __forceinline__ bool unit(int L, Unit& u) const { u.g = L; return order_mn(L, T / 256, NGU / 256, u.pm, u.pn); }
;     __device__ __forceinline__ bool unit(int L, Unit& u) const { u.g = L; return order_mn(L, T / 256, D / 256, u.pm, u.pn); }
;     __device__ __forceinline__ bool unit(int L, Unit& u) const { u.g = 0; return order_mn(L, T / 256, 8, u.pm, u.pn); }
;     __device__ __forceinline__ bool unit(int L, Unit& u) const { if (L >= NG * 4) return false; u.g = L >> 2; u.pm = (L >> 1) & 1; u.pn = L & 1; return true; }
;     __device__ __forceinline__ bool unit(int L, Unit& u) const { if (L >= NG * 8) return false; u.g = L >> 3; u.pm = (L >> 2) & 1; u.pn = L & 3; return true; }
;     ...
;         const bool has_next = p.unit((ui + 1) * G + c, nxt);
;         const char* nA = has_next ? p.a0(nxt) : cA; const char* nB = has_next ? p.b0(nxt) : cB;
;         const char* nA2 = P::SEG ? (has_next ? p.a1(nxt) : cA2) : nA; const char* nB2 = P::SEG ? (has_next ? p.b1(nxt) : cB2) : nB;
.LBB0_1790:
	s_ashr_i32 s19, s18, 31
	ds_read_b128 v[0:3], v152
	ds_read_b128 v[4:7], v152 offset:1024
	ds_read_b128 v[8:11], v152 offset:2048
	ds_read_b128 v[12:15], v152 offset:3072
	s_lshl_b64 s[20:21], s[18:19], 19
	s_add_u32 s20, s10, s20
	s_addc_u32 s21, s11, s21
	s_ashr_i32 s17, s16, 31
	s_lshl_b64 s[22:23], s[16:17], 19
	s_add_u32 s22, s39, s22
	s_addc_u32 s23, s40, s23
	s_add_u32 s34, s26, 0x40080
	s_addc_u32 s35, s27, 0
	s_mov_b32 m0, s47
	v_lshl_add_u64 v[48:49], s[34:35], 0, v[136:137]
	ds_read_b128 v[16:19], v153
	ds_read_b128 v[20:23], v153 offset:1024
	ds_read_b128 v[24:27], v153 offset:2048
	ds_read_b128 v[28:31], v153 offset:3072
	ds_read_b128 v[32:35], v153 offset:4096
	ds_read_b128 v[36:39], v153 offset:5120
	ds_read_b128 v[40:43], v153 offset:6144
	ds_read_b128 v[44:47], v153 offset:7168
	global_load_lds_dwordx4 v[48:49], off
	s_mov_b32 m0, s48
	v_lshl_add_u64 v[48:49], s[34:35], 0, v[132:133]
	global_load_lds_dwordx4 v[48:49], off
	s_waitcnt lgkmcnt(8)
	s_barrier
	s_waitcnt lgkmcnt(0)
	v_mfma_f32_16x16x32_bf16 v[48:51], v[0:3], v[16:19], 0
	v_mfma_f32_16x16x32_bf16 v[52:55], v[8:11], v[16:19], 0
	v_mfma_f32_16x16x32_bf16 v[56:59], v[0:3], v[24:27], 0
	v_mfma_f32_16x16x32_bf16 v[60:63], v[8:11], v[24:27], 0
	v_mfma_f32_16x16x32_bf16 v[64:67], v[0:3], v[32:35], 0
	v_mfma_f32_16x16x32_bf16 v[68:71], v[8:11], v[32:35], 0
	v_mfma_f32_16x16x32_bf16 v[72:75], v[0:3], v[40:43], 0
	v_mfma_f32_16x16x32_bf16 v[76:79], v[8:11], v[40:43], 0
	v_mfma_f32_16x16x32_bf16 v[48:51], v[4:7], v[20:23], v[48:51]
	v_mfma_f32_16x16x32_bf16 v[52:55], v[12:15], v[20:23], v[52:55]
	v_mfma_f32_16x16x32_bf16 v[56:59], v[4:7], v[28:31], v[56:59]
	v_mfma_f32_16x16x32_bf16 v[60:63], v[12:15], v[28:31], v[60:63]
	v_mfma_f32_16x16x32_bf16 v[64:67], v[4:7], v[36:39], v[64:67]
	v_mfma_f32_16x16x32_bf16 v[68:71], v[12:15], v[36:39], v[68:71]
	v_mfma_f32_16x16x32_bf16 v[72:75], v[4:7], v[44:47], v[72:75]
	v_mfma_f32_16x16x32_bf16 v[76:79], v[12:15], v[44:47], v[76:79]
	s_barrier
	v_lshl_add_u64 v[218:219], s[28:29], 0, v[134:135]
	s_mov_b32 m0, s49
	v_lshl_add_u64 v[96:97], v[218:219], 0, s[8:9]
	v_lshl_add_u64 v[238:239], s[28:29], 0, v[130:131]
	ds_read_b128 v[80:83], v154
	ds_read_b128 v[84:87], v154 offset:1024
	ds_read_b128 v[88:91], v154 offset:2048
	ds_read_b128 v[92:95], v154 offset:3072
	global_load_lds_dwordx4 v[96:97], off
	s_mov_b32 m0, s50
	v_lshl_add_u64 v[96:97], v[238:239], 0, s[8:9]
	global_load_lds_dwordx4 v[96:97], off
	s_barrier
	s_waitcnt lgkmcnt(0)
	v_mfma_f32_16x16x32_bf16 v[96:99], v[80:83], v[16:19], 0
	v_mfma_f32_16x16x32_bf16 v[16:19], v[88:91], v[16:19], 0
	v_mfma_f32_16x16x32_bf16 v[100:103], v[80:83], v[24:27], 0
	v_mfma_f32_16x16x32_bf16 v[24:27], v[88:91], v[24:27], 0
	v_mfma_f32_16x16x32_bf16 v[104:107], v[80:83], v[32:35], 0
	v_mfma_f32_16x16x32_bf16 v[32:35], v[88:91], v[32:35], 0
	v_mfma_f32_16x16x32_bf16 v[108:111], v[80:83], v[40:43], 0
	v_mfma_f32_16x16x32_bf16 v[40:43], v[88:91], v[40:43], 0
	v_mfma_f32_16x16x32_bf16 v[116:119], v[84:87], v[20:23], v[96:99]
	v_mfma_f32_16x16x32_bf16 v[16:19], v[92:95], v[20:23], v[16:19]
	v_mfma_f32_16x16x32_bf16 v[20:23], v[84:87], v[28:31], v[100:103]
	v_mfma_f32_16x16x32_bf16 v[24:27], v[92:95], v[28:31], v[24:27]
	v_mfma_f32_16x16x32_bf16 v[28:31], v[84:87], v[36:39], v[104:107]
	v_mfma_f32_16x16x32_bf16 v[32:35], v[92:95], v[36:39], v[32:35]
	v_mfma_f32_16x16x32_bf16 v[36:39], v[84:87], v[44:47], v[108:111]
	v_mfma_f32_16x16x32_bf16 v[40:43], v[92:95], v[44:47], v[40:43]
	v_lshl_add_u64 v[246:247], s[26:27], 0, v[136:137]
	s_mov_b32 m0, s25
	v_lshl_add_u64 v[142:143], v[246:247], 0, s[8:9]
	v_lshl_add_u64 v[248:249], s[26:27], 0, v[132:133]
	s_barrier
	ds_read_b128 v[44:47], v153 offset:16384
	ds_read_b128 v[96:99], v153 offset:17408
	ds_read_b128 v[100:103], v153 offset:18432
	ds_read_b128 v[104:107], v153 offset:19456
	ds_read_b128 v[108:111], v153 offset:20480
	ds_read_b128 v[112:115], v153 offset:21504
	ds_read_b128 v[120:123], v153 offset:22528
	ds_read_b128 v[124:127], v153 offset:23552
	global_load_lds_dwordx4 v[142:143], off
	s_mov_b32 m0, s41
	v_lshl_add_u64 v[142:143], v[248:249], 0, s[8:9]
	global_load_lds_dwordx4 v[142:143], off
	s_barrier
	s_waitcnt lgkmcnt(0)
	v_mfma_f32_16x16x32_bf16 v[142:145], v[0:3], v[44:47], 0
	v_mfma_f32_16x16x32_bf16 v[158:161], v[8:11], v[44:47], 0
	v_mfma_f32_16x16x32_bf16 v[162:165], v[0:3], v[100:103], 0
	v_mfma_f32_16x16x32_bf16 v[166:169], v[8:11], v[100:103], 0
	v_mfma_f32_16x16x32_bf16 v[170:173], v[0:3], v[108:111], 0
	v_mfma_f32_16x16x32_bf16 v[174:177], v[8:11], v[108:111], 0
	v_mfma_f32_16x16x32_bf16 v[0:3], v[0:3], v[120:123], 0
	v_mfma_f32_16x16x32_bf16 v[8:11], v[8:11], v[120:123], 0
	v_mfma_f32_16x16x32_bf16 v[142:145], v[4:7], v[96:99], v[142:145]
	v_mfma_f32_16x16x32_bf16 v[162:165], v[4:7], v[104:107], v[162:165]
	v_mfma_f32_16x16x32_bf16 v[170:173], v[4:7], v[112:115], v[170:173]
	v_mfma_f32_16x16x32_bf16 v[0:3], v[4:7], v[124:127], v[0:3]
	v_mfma_f32_16x16x32_bf16 v[4:7], v[12:15], v[124:127], v[8:11]
	v_mfma_f32_16x16x32_bf16 v[158:161], v[12:15], v[96:99], v[158:161]
	v_mfma_f32_16x16x32_bf16 v[166:169], v[12:15], v[104:107], v[166:169]
	v_mfma_f32_16x16x32_bf16 v[174:177], v[12:15], v[112:115], v[174:177]
	s_barrier
	s_add_u32 s34, s28, 0x40100
	s_addc_u32 s35, s29, 0
	s_mov_b32 m0, s55
	v_lshl_add_u64 v[8:9], s[34:35], 0, v[134:135]
	global_load_lds_dwordx4 v[8:9], off
	s_mov_b32 m0, s56
	v_lshl_add_u64 v[8:9], s[34:35], 0, v[130:131]
	global_load_lds_dwordx4 v[8:9], off
	s_waitcnt vmcnt(6)
	s_barrier
	v_mfma_f32_16x16x32_bf16 v[8:11], v[80:83], v[44:47], 0
	v_mfma_f32_16x16x32_bf16 v[12:15], v[88:91], v[44:47], 0
	v_mfma_f32_16x16x32_bf16 v[44:47], v[80:83], v[100:103], 0
	v_mfma_f32_16x16x32_bf16 v[100:103], v[88:91], v[100:103], 0
	v_mfma_f32_16x16x32_bf16 v[178:181], v[80:83], v[108:111], 0
	v_mfma_f32_16x16x32_bf16 v[108:111], v[88:91], v[108:111], 0
	v_mfma_f32_16x16x32_bf16 v[80:83], v[80:83], v[120:123], 0
	v_mfma_f32_16x16x32_bf16 v[88:91], v[88:91], v[120:123], 0
	v_mfma_f32_16x16x32_bf16 v[12:15], v[92:95], v[96:99], v[12:15]
	v_mfma_f32_16x16x32_bf16 v[44:47], v[84:87], v[104:107], v[44:47]
	v_mfma_f32_16x16x32_bf16 v[182:185], v[84:87], v[96:99], v[8:11]
	v_mfma_f32_16x16x32_bf16 v[186:189], v[92:95], v[104:107], v[100:103]
	v_mfma_f32_16x16x32_bf16 v[178:181], v[84:87], v[112:115], v[178:181]
	v_mfma_f32_16x16x32_bf16 v[190:193], v[92:95], v[112:115], v[108:111]
	v_mfma_f32_16x16x32_bf16 v[194:197], v[84:87], v[124:127], v[80:83]
	v_mfma_f32_16x16x32_bf16 v[198:201], v[92:95], v[124:127], v[88:91]
	s_barrier
	ds_read_b128 v[8:11], v155
	ds_read_b128 v[202:205], v155 offset:1024
	ds_read_b128 v[206:209], v155 offset:2048
	ds_read_b128 v[210:213], v155 offset:3072
	s_add_u32 s34, s26, 0x40100
	s_addc_u32 s35, s27, 0
	s_mov_b32 m0, s42
	v_lshl_add_u64 v[80:81], s[34:35], 0, v[136:137]
	ds_read_b128 v[84:87], v153 offset:32768
	ds_read_b128 v[92:95], v153 offset:33792
	ds_read_b128 v[100:103], v153 offset:34816
	ds_read_b128 v[214:217], v153 offset:35840
	ds_read_b128 v[108:111], v153 offset:36864
	ds_read_b128 v[222:225], v153 offset:37888
	ds_read_b128 v[124:127], v153 offset:38912
	ds_read_b128 v[226:229], v153 offset:39936
	global_load_lds_dwordx4 v[80:81], off
	s_mov_b32 m0, s43
	v_lshl_add_u64 v[80:81], s[34:35], 0, v[132:133]
	global_load_lds_dwordx4 v[80:81], off
	s_waitcnt lgkmcnt(8)
	s_barrier
	s_waitcnt lgkmcnt(0)
	v_mfma_f32_16x16x32_bf16 v[48:51], v[8:11], v[84:87], v[48:51]
	v_mfma_f32_16x16x32_bf16 v[52:55], v[206:209], v[84:87], v[52:55]
	v_mfma_f32_16x16x32_bf16 v[56:59], v[8:11], v[100:103], v[56:59]
	v_mfma_f32_16x16x32_bf16 v[60:63], v[206:209], v[100:103], v[60:63]
	v_mfma_f32_16x16x32_bf16 v[64:67], v[8:11], v[108:111], v[64:67]
	v_mfma_f32_16x16x32_bf16 v[68:71], v[206:209], v[108:111], v[68:71]
	v_mfma_f32_16x16x32_bf16 v[72:75], v[8:11], v[124:127], v[72:75]
	v_mfma_f32_16x16x32_bf16 v[76:79], v[206:209], v[124:127], v[76:79]
	v_mfma_f32_16x16x32_bf16 v[120:123], v[202:205], v[92:95], v[48:51]
	v_mfma_f32_16x16x32_bf16 v[112:115], v[210:213], v[92:95], v[52:55]
	v_mfma_f32_16x16x32_bf16 v[104:107], v[202:205], v[214:217], v[56:59]
	v_mfma_f32_16x16x32_bf16 v[96:99], v[210:213], v[214:217], v[60:63]
	v_mfma_f32_16x16x32_bf16 v[88:91], v[202:205], v[222:225], v[64:67]
	v_mfma_f32_16x16x32_bf16 v[80:83], v[210:213], v[222:225], v[68:71]
	v_mfma_f32_16x16x32_bf16 v[72:75], v[202:205], v[226:229], v[72:75]
	v_mfma_f32_16x16x32_bf16 v[60:63], v[210:213], v[226:229], v[76:79]
	s_barrier
	s_mov_b32 m0, s57
	v_lshl_add_u64 v[48:49], v[218:219], 0, s[12:13]
	ds_read_b128 v[52:55], v156
	ds_read_b128 v[230:233], v156 offset:1024
	ds_read_b128 v[68:71], v156 offset:2048
	ds_read_b128 v[234:237], v156 offset:3072
	global_load_lds_dwordx4 v[48:49], off
	s_mov_b32 m0, s58
	v_lshl_add_u64 v[48:49], v[238:239], 0, s[12:13]
	global_load_lds_dwordx4 v[48:49], off
	s_barrier
;     ...
;         G_PAIR(0, 1);
; #pragma unroll 1
;         for (int t = 2; t < nt; t += 2) G_PAIR(t, 0);
	s_waitcnt lgkmcnt(0)
	v_mfma_f32_16x16x32_bf16 v[48:51], v[52:55], v[84:87], v[116:119]
	v_mfma_f32_16x16x32_bf16 v[16:19], v[68:71], v[84:87], v[16:19]
	v_mfma_f32_16x16x32_bf16 v[20:23], v[52:55], v[100:103], v[20:23]
	v_mfma_f32_16x16x32_bf16 v[24:27], v[68:71], v[100:103], v[24:27]
	v_mfma_f32_16x16x32_bf16 v[28:31], v[52:55], v[108:111], v[28:31]
	v_mfma_f32_16x16x32_bf16 v[32:35], v[68:71], v[108:111], v[32:35]
	v_mfma_f32_16x16x32_bf16 v[36:39], v[52:55], v[124:127], v[36:39]
	v_mfma_f32_16x16x32_bf16 v[40:43], v[68:71], v[124:127], v[40:43]
	v_mfma_f32_16x16x32_bf16 v[124:127], v[230:233], v[92:95], v[48:51]
	v_mfma_f32_16x16x32_bf16 v[116:119], v[234:237], v[92:95], v[16:19]
	v_mfma_f32_16x16x32_bf16 v[108:111], v[230:233], v[214:217], v[20:23]
	v_mfma_f32_16x16x32_bf16 v[100:103], v[234:237], v[214:217], v[24:27]
	v_mfma_f32_16x16x32_bf16 v[92:95], v[230:233], v[222:225], v[28:31]
	v_mfma_f32_16x16x32_bf16 v[84:87], v[234:237], v[222:225], v[32:35]
	v_mfma_f32_16x16x32_bf16 v[76:79], v[230:233], v[226:229], v[36:39]
	v_mfma_f32_16x16x32_bf16 v[64:67], v[234:237], v[226:229], v[40:43]
	s_mov_b32 m0, s44
	v_lshl_add_u64 v[16:17], v[246:247], 0, s[12:13]
	s_barrier
	ds_read_b128 v[20:23], v153 offset:49152
	ds_read_b128 v[28:31], v153 offset:50176
	ds_read_b128 v[36:39], v153 offset:51200
	ds_read_b128 v[214:217], v153 offset:52224
	ds_read_b128 v[222:225], v153 offset:53248
	ds_read_b128 v[226:229], v153 offset:54272
	ds_read_b128 v[238:241], v153 offset:55296
	ds_read_b128 v[242:245], v153 offset:56320
	global_load_lds_dwordx4 v[16:17], off
	s_mov_b32 m0, s45
	v_lshl_add_u64 v[16:17], v[248:249], 0, s[12:13]
	global_load_lds_dwordx4 v[16:17], off
	s_barrier
	s_waitcnt lgkmcnt(0)
	v_mfma_f32_16x16x32_bf16 v[16:19], v[8:11], v[20:23], v[142:145]
	v_mfma_f32_16x16x32_bf16 v[24:27], v[206:209], v[20:23], v[158:161]
	v_mfma_f32_16x16x32_bf16 v[32:35], v[8:11], v[36:39], v[162:165]
	v_mfma_f32_16x16x32_bf16 v[142:145], v[206:209], v[36:39], v[166:169]
	v_mfma_f32_16x16x32_bf16 v[158:161], v[8:11], v[222:225], v[170:173]
	v_mfma_f32_16x16x32_bf16 v[162:165], v[206:209], v[222:225], v[174:177]
	v_mfma_f32_16x16x32_bf16 v[0:3], v[8:11], v[238:241], v[0:3]
	v_mfma_f32_16x16x32_bf16 v[4:7], v[206:209], v[238:241], v[4:7]
	v_mfma_f32_16x16x32_bf16 v[56:59], v[202:205], v[28:31], v[16:19]
	v_mfma_f32_16x16x32_bf16 v[48:51], v[210:213], v[28:31], v[24:27]
	v_mfma_f32_16x16x32_bf16 v[40:43], v[202:205], v[214:217], v[32:35]
	v_mfma_f32_16x16x32_bf16 v[32:35], v[210:213], v[214:217], v[142:145]
	v_mfma_f32_16x16x32_bf16 v[24:27], v[202:205], v[226:229], v[158:161]
	v_mfma_f32_16x16x32_bf16 v[16:19], v[210:213], v[226:229], v[162:165]
	v_mfma_f32_16x16x32_bf16 v[8:11], v[202:205], v[242:245], v[0:3]
	v_mfma_f32_16x16x32_bf16 v[0:3], v[210:213], v[242:245], v[4:7]
	s_barrier
	s_add_u32 s34, s28, 0x40180
	s_addc_u32 s35, s29, 0
	s_mov_b32 m0, s59
	v_lshl_add_u64 v[4:5], s[34:35], 0, v[134:135]
	s_add_i32 s17, s59, 0x2000
	global_load_lds_dwordx4 v[4:5], off
	v_lshl_add_u64 v[4:5], s[34:35], 0, v[130:131]
	s_mov_b32 m0, s17
	s_mov_b64 s[34:35], 0x40180
	global_load_lds_dwordx4 v[4:5], off
	s_waitcnt vmcnt(6)
	s_barrier
	v_mfma_f32_16x16x32_bf16 v[4:7], v[52:55], v[20:23], v[182:185]
	v_mfma_f32_16x16x32_bf16 v[12:15], v[68:71], v[20:23], v[12:15]
	v_mfma_f32_16x16x32_bf16 v[20:23], v[52:55], v[36:39], v[44:47]
	v_mfma_f32_16x16x32_bf16 v[36:39], v[68:71], v[36:39], v[186:189]
	v_mfma_f32_16x16x32_bf16 v[142:145], v[52:55], v[222:225], v[178:181]
	v_mfma_f32_16x16x32_bf16 v[158:161], v[68:71], v[222:225], v[190:193]
	v_mfma_f32_16x16x32_bf16 v[162:165], v[52:55], v[238:241], v[194:197]
	v_mfma_f32_16x16x32_bf16 v[166:169], v[68:71], v[238:241], v[198:201]
	v_mfma_f32_16x16x32_bf16 v[68:71], v[230:233], v[28:31], v[4:7]
	v_mfma_f32_16x16x32_bf16 v[52:55], v[234:237], v[28:31], v[12:15]
	v_mfma_f32_16x16x32_bf16 v[44:47], v[230:233], v[214:217], v[20:23]
	v_mfma_f32_16x16x32_bf16 v[36:39], v[234:237], v[214:217], v[36:39]
	v_mfma_f32_16x16x32_bf16 v[28:31], v[230:233], v[226:229], v[142:145]
	v_mfma_f32_16x16x32_bf16 v[20:23], v[234:237], v[226:229], v[158:161]
	v_mfma_f32_16x16x32_bf16 v[12:15], v[230:233], v[242:245], v[162:165]
	v_mfma_f32_16x16x32_bf16 v[4:7], v[234:237], v[242:245], v[166:169]
	v_lshl_add_u64 v[142:143], s[26:27], 0, v[138:139]
	v_lshl_add_u64 v[144:145], s[26:27], 0, v[140:141]
	s_mov_b32 s19, 0
.Lrot_1791:
	s_barrier

.LBB0_1905:
	s_waitcnt lgkmcnt(0)
	ds_read_b128 v[0:3], v185
	ds_read_b128 v[4:7], v185 offset:1024
	ds_read_b128 v[8:11], v185 offset:2048
	ds_read_b128 v[12:15], v185 offset:3072
	s_add_u32 s24, s20, 0xb0080
	s_addc_u32 s25, s21, 0
	s_mov_b32 m0, s45
	v_lshl_add_u64 v[48:49], s[24:25], 0, v[152:153]
	ds_read_b128 v[16:19], v186
	ds_read_b128 v[20:23], v186 offset:1024
	ds_read_b128 v[24:27], v186 offset:2048
	ds_read_b128 v[28:31], v186 offset:3072
	ds_read_b128 v[32:35], v186 offset:4096
	ds_read_b128 v[36:39], v186 offset:5120
	ds_read_b128 v[40:43], v186 offset:6144
	ds_read_b128 v[44:47], v186 offset:7168
	global_load_lds_dwordx4 v[48:49], off
	s_mov_b32 m0, s46
	v_lshl_add_u64 v[48:49], s[24:25], 0, v[156:157]
	global_load_lds_dwordx4 v[48:49], off
	s_waitcnt lgkmcnt(8)
	s_barrier
	s_waitcnt lgkmcnt(0)
	v_mfma_f32_16x16x32_bf16 v[48:51], v[0:3], v[16:19], 0
	v_mfma_f32_16x16x32_bf16 v[52:55], v[8:11], v[16:19], 0
	v_mfma_f32_16x16x32_bf16 v[56:59], v[0:3], v[24:27], 0
	v_mfma_f32_16x16x32_bf16 v[60:63], v[8:11], v[24:27], 0
	v_mfma_f32_16x16x32_bf16 v[64:67], v[0:3], v[32:35], 0
	v_mfma_f32_16x16x32_bf16 v[68:71], v[8:11], v[32:35], 0
	v_mfma_f32_16x16x32_bf16 v[72:75], v[0:3], v[40:43], 0
	v_mfma_f32_16x16x32_bf16 v[76:79], v[8:11], v[40:43], 0
	v_mfma_f32_16x16x32_bf16 v[48:51], v[4:7], v[20:23], v[48:51]
	v_mfma_f32_16x16x32_bf16 v[52:55], v[12:15], v[20:23], v[52:55]
	v_mfma_f32_16x16x32_bf16 v[56:59], v[4:7], v[28:31], v[56:59]
	v_mfma_f32_16x16x32_bf16 v[60:63], v[12:15], v[28:31], v[60:63]
	v_mfma_f32_16x16x32_bf16 v[64:67], v[4:7], v[36:39], v[64:67]
	v_mfma_f32_16x16x32_bf16 v[68:71], v[12:15], v[36:39], v[68:71]
	v_mfma_f32_16x16x32_bf16 v[72:75], v[4:7], v[44:47], v[72:75]
	v_mfma_f32_16x16x32_bf16 v[76:79], v[12:15], v[44:47], v[76:79]
	s_barrier
	v_lshl_add_u64 v[180:181], s[22:23], 0, v[154:155]
	s_mov_b32 m0, s47
	v_lshl_add_u64 v[96:97], v[180:181], 0, s[12:13]
	v_lshl_add_u64 v[218:219], s[22:23], 0, v[158:159]
	ds_read_b128 v[80:83], v187
	ds_read_b128 v[84:87], v187 offset:1024
	ds_read_b128 v[88:91], v187 offset:2048
	ds_read_b128 v[92:95], v187 offset:3072
	global_load_lds_dwordx4 v[96:97], off
	s_mov_b32 m0, s48
	v_lshl_add_u64 v[96:97], v[218:219], 0, s[12:13]
	global_load_lds_dwordx4 v[96:97], off
	s_barrier
	s_waitcnt lgkmcnt(0)
	v_mfma_f32_16x16x32_bf16 v[96:99], v[80:83], v[16:19], 0
	v_mfma_f32_16x16x32_bf16 v[16:19], v[88:91], v[16:19], 0
	v_mfma_f32_16x16x32_bf16 v[100:103], v[80:83], v[24:27], 0
	v_mfma_f32_16x16x32_bf16 v[24:27], v[88:91], v[24:27], 0
	v_mfma_f32_16x16x32_bf16 v[104:107], v[80:83], v[32:35], 0
	v_mfma_f32_16x16x32_bf16 v[32:35], v[88:91], v[32:35], 0
	v_mfma_f32_16x16x32_bf16 v[108:111], v[80:83], v[40:43], 0
	v_mfma_f32_16x16x32_bf16 v[40:43], v[88:91], v[40:43], 0
	v_mfma_f32_16x16x32_bf16 v[96:99], v[84:87], v[20:23], v[96:99]
	v_mfma_f32_16x16x32_bf16 v[16:19], v[92:95], v[20:23], v[16:19]
	v_mfma_f32_16x16x32_bf16 v[20:23], v[84:87], v[28:31], v[100:103]
	v_mfma_f32_16x16x32_bf16 v[24:27], v[92:95], v[28:31], v[24:27]
	v_mfma_f32_16x16x32_bf16 v[28:31], v[84:87], v[36:39], v[104:107]
	v_mfma_f32_16x16x32_bf16 v[32:35], v[92:95], v[36:39], v[32:35]
	v_mfma_f32_16x16x32_bf16 v[36:39], v[84:87], v[44:47], v[108:111]
	v_mfma_f32_16x16x32_bf16 v[40:43], v[92:95], v[44:47], v[40:43]
	v_lshl_add_u64 v[242:243], s[20:21], 0, v[152:153]
	s_mov_b32 m0, s37
	v_lshl_add_u64 v[128:129], v[242:243], 0, s[12:13]
	v_lshl_add_u64 v[244:245], s[20:21], 0, v[156:157]
	s_barrier
	ds_read_b128 v[44:47], v186 offset:16384
	ds_read_b128 v[100:103], v186 offset:17408
	ds_read_b128 v[104:107], v186 offset:18432
	ds_read_b128 v[108:111], v186 offset:19456
	ds_read_b128 v[112:115], v186 offset:20480
	ds_read_b128 v[116:119], v186 offset:21504
	ds_read_b128 v[120:123], v186 offset:22528
	ds_read_b128 v[124:127], v186 offset:23552
	global_load_lds_dwordx4 v[128:129], off
	s_mov_b32 m0, s38
	v_lshl_add_u64 v[128:129], v[244:245], 0, s[12:13]
	global_load_lds_dwordx4 v[128:129], off
	s_barrier
	s_waitcnt lgkmcnt(0)
	v_mfma_f32_16x16x32_bf16 v[128:131], v[0:3], v[44:47], 0
	v_mfma_f32_16x16x32_bf16 v[132:135], v[8:11], v[44:47], 0
	v_mfma_f32_16x16x32_bf16 v[136:139], v[0:3], v[104:107], 0
	v_mfma_f32_16x16x32_bf16 v[140:143], v[8:11], v[104:107], 0
	v_mfma_f32_16x16x32_bf16 v[144:147], v[0:3], v[112:115], 0
	v_mfma_f32_16x16x32_bf16 v[148:151], v[8:11], v[112:115], 0
	v_mfma_f32_16x16x32_bf16 v[0:3], v[0:3], v[120:123], 0
	v_mfma_f32_16x16x32_bf16 v[8:11], v[8:11], v[120:123], 0
	v_mfma_f32_16x16x32_bf16 v[128:131], v[4:7], v[100:103], v[128:131]
	v_mfma_f32_16x16x32_bf16 v[164:167], v[12:15], v[100:103], v[132:135]
	v_mfma_f32_16x16x32_bf16 v[134:137], v[4:7], v[108:111], v[136:139]
	v_mfma_f32_16x16x32_bf16 v[138:141], v[12:15], v[108:111], v[140:143]
	v_mfma_f32_16x16x32_bf16 v[142:145], v[4:7], v[116:119], v[144:147]
	v_mfma_f32_16x16x32_bf16 v[0:3], v[4:7], v[124:127], v[0:3]
	v_mfma_f32_16x16x32_bf16 v[4:7], v[12:15], v[124:127], v[8:11]
	v_mfma_f32_16x16x32_bf16 v[146:149], v[12:15], v[116:119], v[148:151]
	s_barrier
	s_add_u32 s24, s22, 0xb0100
	s_addc_u32 s25, s23, 0
	s_add_i32 s52, s44, s36
	v_lshl_add_u64 v[8:9], s[24:25], 0, v[154:155]
	s_mov_b32 m0, s52
	s_add_i32 s53, s52, 0x2000
	global_load_lds_dwordx4 v[8:9], off
	s_mov_b32 m0, s53
	v_lshl_add_u64 v[8:9], s[24:25], 0, v[158:159]
	global_load_lds_dwordx4 v[8:9], off
	s_waitcnt vmcnt(6)
	s_barrier
	v_mfma_f32_16x16x32_bf16 v[8:11], v[80:83], v[44:47], 0
	v_mfma_f32_16x16x32_bf16 v[12:15], v[88:91], v[44:47], 0
	v_mfma_f32_16x16x32_bf16 v[44:47], v[80:83], v[104:107], 0
	v_mfma_f32_16x16x32_bf16 v[104:107], v[88:91], v[104:107], 0
	v_mfma_f32_16x16x32_bf16 v[168:171], v[80:83], v[112:115], 0
	v_mfma_f32_16x16x32_bf16 v[112:115], v[88:91], v[112:115], 0
	v_mfma_f32_16x16x32_bf16 v[80:83], v[80:83], v[120:123], 0
	v_mfma_f32_16x16x32_bf16 v[88:91], v[88:91], v[120:123], 0
	v_mfma_f32_16x16x32_bf16 v[8:11], v[84:87], v[100:103], v[8:11]
	v_mfma_f32_16x16x32_bf16 v[172:175], v[92:95], v[100:103], v[12:15]
	v_mfma_f32_16x16x32_bf16 v[176:179], v[84:87], v[108:111], v[44:47]
	v_mfma_f32_16x16x32_bf16 v[190:193], v[92:95], v[108:111], v[104:107]
	v_mfma_f32_16x16x32_bf16 v[168:171], v[84:87], v[116:119], v[168:171]
	v_mfma_f32_16x16x32_bf16 v[194:197], v[92:95], v[116:119], v[112:115]
	v_mfma_f32_16x16x32_bf16 v[198:201], v[84:87], v[124:127], v[80:83]
	v_mfma_f32_16x16x32_bf16 v[202:205], v[92:95], v[124:127], v[88:91]
	s_add_i32 s54, 0, 0x18000
	v_add_u32_e32 v132, s54, v183
	s_barrier
	ds_read_b128 v[12:15], v132
	ds_read_b128 v[206:209], v132 offset:1024
	ds_read_b128 v[44:47], v132 offset:2048
	ds_read_b128 v[210:213], v132 offset:3072
	s_add_u32 s24, s20, 0xb0100
	s_addc_u32 s25, s21, 0
	s_mov_b32 m0, s39
	v_lshl_add_u64 v[88:89], s[24:25], 0, v[152:153]
	ds_read_b128 v[80:83], v186 offset:32768
	ds_read_b128 v[84:87], v186 offset:33792
	ds_read_b128 v[100:103], v186 offset:34816
	ds_read_b128 v[214:217], v186 offset:35840
	ds_read_b128 v[120:123], v186 offset:36864
	ds_read_b128 v[222:225], v186 offset:37888
	ds_read_b128 v[124:127], v186 offset:38912
	ds_read_b128 v[226:229], v186 offset:39936
	global_load_lds_dwordx4 v[88:89], off
	s_mov_b32 m0, s40
	v_lshl_add_u64 v[88:89], s[24:25], 0, v[156:157]
	global_load_lds_dwordx4 v[88:89], off
	s_waitcnt lgkmcnt(8)
	s_barrier
	s_waitcnt lgkmcnt(0)
	v_mfma_f32_16x16x32_bf16 v[48:51], v[12:15], v[80:83], v[48:51]
	v_mfma_f32_16x16x32_bf16 v[52:55], v[44:47], v[80:83], v[52:55]
	v_mfma_f32_16x16x32_bf16 v[56:59], v[12:15], v[100:103], v[56:59]
	v_mfma_f32_16x16x32_bf16 v[60:63], v[44:47], v[100:103], v[60:63]
	v_mfma_f32_16x16x32_bf16 v[64:67], v[12:15], v[120:123], v[64:67]
	v_mfma_f32_16x16x32_bf16 v[68:71], v[44:47], v[120:123], v[68:71]
	v_mfma_f32_16x16x32_bf16 v[72:75], v[12:15], v[124:127], v[72:75]
	v_mfma_f32_16x16x32_bf16 v[230:233], v[44:47], v[124:127], v[76:79]
	v_mfma_f32_16x16x32_bf16 v[116:119], v[206:209], v[84:87], v[48:51]
	v_mfma_f32_16x16x32_bf16 v[112:115], v[210:213], v[84:87], v[52:55]
	v_mfma_f32_16x16x32_bf16 v[108:111], v[206:209], v[214:217], v[56:59]
	v_mfma_f32_16x16x32_bf16 v[104:107], v[210:213], v[214:217], v[60:63]
	v_mfma_f32_16x16x32_bf16 v[92:95], v[206:209], v[222:225], v[64:67]
	v_mfma_f32_16x16x32_bf16 v[88:91], v[210:213], v[222:225], v[68:71]
	v_mfma_f32_16x16x32_bf16 v[76:79], v[206:209], v[226:229], v[72:75]
	v_mfma_f32_16x16x32_bf16 v[72:75], v[210:213], v[226:229], v[230:233]
	s_barrier
	s_add_i32 s56, 0, 0x1c000
	s_add_i32 s54, s54, s36
	v_add_u32_e32 v133, s56, v183
	v_lshl_add_u64 v[48:49], v[180:181], 0, s[14:15]
	s_mov_b32 m0, s54
	s_add_i32 s55, s54, 0x2000
	ds_read_b128 v[56:59], v133
	ds_read_b128 v[230:233], v133 offset:1024
	ds_read_b128 v[60:63], v133 offset:2048
	ds_read_b128 v[234:237], v133 offset:3072
	global_load_lds_dwordx4 v[48:49], off
	s_mov_b32 m0, s55
	v_lshl_add_u64 v[48:49], v[218:219], 0, s[14:15]
	global_load_lds_dwordx4 v[48:49], off
	s_barrier
	s_waitcnt lgkmcnt(0)
	v_mfma_f32_16x16x32_bf16 v[48:51], v[56:59], v[80:83], v[96:99]
	v_mfma_f32_16x16x32_bf16 v[16:19], v[60:63], v[80:83], v[16:19]
	v_mfma_f32_16x16x32_bf16 v[20:23], v[56:59], v[100:103], v[20:23]
	v_mfma_f32_16x16x32_bf16 v[24:27], v[60:63], v[100:103], v[24:27]
	v_mfma_f32_16x16x32_bf16 v[28:31], v[56:59], v[120:123], v[28:31]
	v_mfma_f32_16x16x32_bf16 v[32:35], v[60:63], v[120:123], v[32:35]
	v_mfma_f32_16x16x32_bf16 v[36:39], v[56:59], v[124:127], v[36:39]
	v_mfma_f32_16x16x32_bf16 v[40:43], v[60:63], v[124:127], v[40:43]
	v_mfma_f32_16x16x32_bf16 v[124:127], v[230:233], v[84:87], v[48:51]
	v_mfma_f32_16x16x32_bf16 v[120:123], v[234:237], v[84:87], v[16:19]
	v_mfma_f32_16x16x32_bf16 v[100:103], v[230:233], v[214:217], v[20:23]
	v_mfma_f32_16x16x32_bf16 v[96:99], v[234:237], v[214:217], v[24:27]
	v_mfma_f32_16x16x32_bf16 v[84:87], v[230:233], v[222:225], v[28:31]
	v_mfma_f32_16x16x32_bf16 v[80:83], v[234:237], v[222:225], v[32:35]
	v_mfma_f32_16x16x32_bf16 v[68:71], v[230:233], v[226:229], v[36:39]
	v_mfma_f32_16x16x32_bf16 v[64:67], v[234:237], v[226:229], v[40:43]
	s_mov_b32 m0, s42
	v_lshl_add_u64 v[20:21], v[242:243], 0, s[14:15]
	s_barrier
	ds_read_b128 v[16:19], v186 offset:49152
	ds_read_b128 v[24:27], v186 offset:50176
	ds_read_b128 v[32:35], v186 offset:51200
	ds_read_b128 v[214:217], v186 offset:52224
	ds_read_b128 v[40:43], v186 offset:53248
	ds_read_b128 v[222:225], v186 offset:54272
	ds_read_b128 v[226:229], v186 offset:55296
	ds_read_b128 v[238:241], v186 offset:56320
	global_load_lds_dwordx4 v[20:21], off
	s_mov_b32 m0, s43
	v_lshl_add_u64 v[20:21], v[244:245], 0, s[14:15]
	global_load_lds_dwordx4 v[20:21], off
	s_barrier
;     ...
;         G_PAIR(0, 1);
; #pragma unroll 1
;         for (int t = 2; t < nt; t += 2) G_PAIR(t, 0);
	s_waitcnt lgkmcnt(0)
	v_mfma_f32_16x16x32_bf16 v[20:23], v[12:15], v[16:19], v[128:131]
	v_mfma_f32_16x16x32_bf16 v[28:31], v[44:47], v[16:19], v[164:167]
	v_mfma_f32_16x16x32_bf16 v[36:39], v[12:15], v[32:35], v[134:137]
	v_mfma_f32_16x16x32_bf16 v[128:131], v[44:47], v[32:35], v[138:141]
	v_mfma_f32_16x16x32_bf16 v[134:137], v[12:15], v[40:43], v[142:145]
	v_mfma_f32_16x16x32_bf16 v[138:141], v[44:47], v[40:43], v[146:149]
	v_mfma_f32_16x16x32_bf16 v[0:3], v[12:15], v[226:229], v[0:3]
	v_mfma_f32_16x16x32_bf16 v[4:7], v[44:47], v[226:229], v[4:7]
	v_mfma_f32_16x16x32_bf16 v[52:55], v[206:209], v[24:27], v[20:23]
	v_mfma_f32_16x16x32_bf16 v[48:51], v[210:213], v[24:27], v[28:31]
	v_mfma_f32_16x16x32_bf16 v[44:47], v[206:209], v[214:217], v[36:39]
	v_mfma_f32_16x16x32_bf16 v[36:39], v[210:213], v[214:217], v[128:131]
	v_mfma_f32_16x16x32_bf16 v[28:31], v[206:209], v[222:225], v[134:137]
	v_mfma_f32_16x16x32_bf16 v[20:23], v[210:213], v[222:225], v[138:141]
	v_mfma_f32_16x16x32_bf16 v[12:15], v[206:209], v[238:241], v[0:3]
	v_mfma_f32_16x16x32_bf16 v[4:7], v[210:213], v[238:241], v[4:7]
	s_barrier
	s_add_u32 s24, s22, 0xb0180
	s_addc_u32 s25, s23, 0
	s_add_i32 s56, s56, s36
	v_lshl_add_u64 v[0:1], s[24:25], 0, v[154:155]
	s_mov_b32 m0, s56
	s_add_i32 s57, s56, 0x2000
	global_load_lds_dwordx4 v[0:1], off
	v_lshl_add_u64 v[0:1], s[24:25], 0, v[158:159]
	s_mov_b32 m0, s57
	s_mov_b64 s[24:25], 0xb0180
	global_load_lds_dwordx4 v[0:1], off
	s_waitcnt vmcnt(6)
	s_barrier
	v_mfma_f32_16x16x32_bf16 v[0:3], v[56:59], v[16:19], v[8:11]
	v_mfma_f32_16x16x32_bf16 v[8:11], v[60:63], v[16:19], v[172:175]
	v_mfma_f32_16x16x32_bf16 v[16:19], v[56:59], v[32:35], v[176:179]
	v_mfma_f32_16x16x32_bf16 v[32:35], v[60:63], v[32:35], v[190:193]
	v_mfma_f32_16x16x32_bf16 v[128:131], v[56:59], v[40:43], v[168:171]
	v_mfma_f32_16x16x32_bf16 v[134:137], v[60:63], v[40:43], v[194:197]
	v_mfma_f32_16x16x32_bf16 v[138:141], v[56:59], v[226:229], v[198:201]
	v_mfma_f32_16x16x32_bf16 v[142:145], v[60:63], v[226:229], v[202:205]
	v_mfma_f32_16x16x32_bf16 v[60:63], v[230:233], v[24:27], v[0:3]
	v_mfma_f32_16x16x32_bf16 v[56:59], v[234:237], v[24:27], v[8:11]
	v_mfma_f32_16x16x32_bf16 v[40:43], v[230:233], v[214:217], v[16:19]
	v_mfma_f32_16x16x32_bf16 v[32:35], v[234:237], v[214:217], v[32:35]
	v_mfma_f32_16x16x32_bf16 v[24:27], v[230:233], v[222:225], v[128:131]
	v_mfma_f32_16x16x32_bf16 v[16:19], v[234:237], v[222:225], v[134:137]
	v_mfma_f32_16x16x32_bf16 v[8:11], v[230:233], v[238:241], v[138:141]
	v_mfma_f32_16x16x32_bf16 v[0:3], v[234:237], v[238:241], v[142:145]
	v_lshl_add_u64 v[128:129], s[20:21], 0, v[160:161]
	v_lshl_add_u64 v[130:131], s[20:21], 0, v[162:163]
	s_mov_b32 s58, 0
.Lrot_1906:
	s_barrier
.LBB0_1906:
	ds_read_b128 v[134:137], v185
	ds_read_b128 v[138:141], v185 offset:1024
	ds_read_b128 v[142:145], v185 offset:2048
	ds_read_b128 v[146:149], v185 offset:3072
	s_mov_b32 m0, s45
	v_lshl_add_u64 v[150:151], v[128:129], 0, s[24:25]
	ds_read_b128 v[164:167], v186
	ds_read_b128 v[168:171], v186 offset:1024
	ds_read_b128 v[172:175], v186 offset:2048
	ds_read_b128 v[176:179], v186 offset:3072
	ds_read_b128 v[190:193], v186 offset:4096
	ds_read_b128 v[194:197], v186 offset:5120
	ds_read_b128 v[198:201], v186 offset:6144
	ds_read_b128 v[202:205], v186 offset:7168
	global_load_lds_dwordx4 v[150:151], off
	s_mov_b32 m0, s46
	v_lshl_add_u64 v[150:151], v[130:131], 0, s[24:25]
	global_load_lds_dwordx4 v[150:151], off
	s_waitcnt lgkmcnt(8)
	s_barrier
	s_waitcnt lgkmcnt(0)
	v_mfma_f32_16x16x32_bf16 v[116:119], v[134:137], v[164:167], v[116:119]
	s_add_i32 s26, s24, 0xfff50080
	v_mfma_f32_16x16x32_bf16 v[112:115], v[142:145], v[164:167], v[112:115]
	s_cmp_eq_u32 s58, 40
	v_mfma_f32_16x16x32_bf16 v[108:111], v[134:137], v[172:175], v[108:111]
	s_cselect_b32 s59, s19, s21
	v_mfma_f32_16x16x32_bf16 v[104:107], v[142:145], v[172:175], v[104:107]
	s_cselect_b32 s60, s18, s20
	v_mfma_f32_16x16x32_bf16 v[92:95], v[134:137], v[190:193], v[92:95]
	s_cselect_b32 s27, s7, s23
	v_mfma_f32_16x16x32_bf16 v[88:91], v[142:145], v[190:193], v[88:91]
	s_cselect_b32 s61, s6, s22
	v_mfma_f32_16x16x32_bf16 v[76:79], v[134:137], v[198:201], v[76:79]
	v_mfma_f32_16x16x32_bf16 v[72:75], v[142:145], v[198:201], v[72:75]
	v_mfma_f32_16x16x32_bf16 v[116:119], v[138:141], v[168:171], v[116:119]
	v_mfma_f32_16x16x32_bf16 v[112:115], v[146:149], v[168:171], v[112:115]
	v_mfma_f32_16x16x32_bf16 v[108:111], v[138:141], v[176:179], v[108:111]
	v_mfma_f32_16x16x32_bf16 v[104:107], v[146:149], v[176:179], v[104:107]
	v_mfma_f32_16x16x32_bf16 v[92:95], v[138:141], v[194:197], v[92:95]
	v_mfma_f32_16x16x32_bf16 v[88:91], v[146:149], v[194:197], v[88:91]
	v_mfma_f32_16x16x32_bf16 v[76:79], v[138:141], v[202:205], v[76:79]
	v_mfma_f32_16x16x32_bf16 v[72:75], v[146:149], v[202:205], v[72:75]
	s_barrier
	s_cselect_b32 s62, 0, s26
	s_add_u32 s26, s61, s62
	s_addc_u32 s27, s27, 0
	s_mov_b32 m0, s47
	v_lshl_add_u64 v[150:151], s[26:27], 0, v[154:155]
	ds_read_b128 v[206:209], v187
	ds_read_b128 v[210:213], v187 offset:1024
	ds_read_b128 v[214:217], v187 offset:2048
	ds_read_b128 v[222:225], v187 offset:3072
	global_load_lds_dwordx4 v[150:151], off
	s_mov_b32 m0, s48
	v_lshl_add_u64 v[180:181], s[26:27], 0, v[158:159]
	global_load_lds_dwordx4 v[180:181], off
	s_barrier
	s_waitcnt lgkmcnt(0)
	v_mfma_f32_16x16x32_bf16 v[124:127], v[206:209], v[164:167], v[124:127]
	v_mfma_f32_16x16x32_bf16 v[120:123], v[214:217], v[164:167], v[120:123]
	v_mfma_f32_16x16x32_bf16 v[100:103], v[206:209], v[172:175], v[100:103]
	v_mfma_f32_16x16x32_bf16 v[96:99], v[214:217], v[172:175], v[96:99]
	v_mfma_f32_16x16x32_bf16 v[84:87], v[206:209], v[190:193], v[84:87]
	v_mfma_f32_16x16x32_bf16 v[80:83], v[214:217], v[190:193], v[80:83]
	v_mfma_f32_16x16x32_bf16 v[68:71], v[206:209], v[198:201], v[68:71]
	v_mfma_f32_16x16x32_bf16 v[64:67], v[214:217], v[198:201], v[64:67]
	v_mfma_f32_16x16x32_bf16 v[124:127], v[210:213], v[168:171], v[124:127]
	v_mfma_f32_16x16x32_bf16 v[120:123], v[222:225], v[168:171], v[120:123]
	v_mfma_f32_16x16x32_bf16 v[100:103], v[210:213], v[176:179], v[100:103]
	v_mfma_f32_16x16x32_bf16 v[96:99], v[222:225], v[176:179], v[96:99]
	v_mfma_f32_16x16x32_bf16 v[84:87], v[210:213], v[194:197], v[84:87]
	v_mfma_f32_16x16x32_bf16 v[80:83], v[222:225], v[194:197], v[80:83]
	v_mfma_f32_16x16x32_bf16 v[68:71], v[210:213], v[202:205], v[68:71]
	v_mfma_f32_16x16x32_bf16 v[64:67], v[222:225], v[202:205], v[64:67]
	s_add_u32 s60, s60, s62
	s_addc_u32 s61, s59, 0
	s_mov_b32 m0, s37
	v_lshl_add_u64 v[218:219], s[60:61], 0, v[152:153]
	s_barrier
	ds_read_b128 v[164:167], v186 offset:16384
	ds_read_b128 v[168:171], v186 offset:17408
	ds_read_b128 v[172:175], v186 offset:18432
	ds_read_b128 v[176:179], v186 offset:19456
	ds_read_b128 v[190:193], v186 offset:20480
	ds_read_b128 v[194:197], v186 offset:21504
	ds_read_b128 v[198:201], v186 offset:22528
	ds_read_b128 v[202:205], v186 offset:23552
	global_load_lds_dwordx4 v[218:219], off
	s_mov_b32 m0, s38
	v_lshl_add_u64 v[226:227], s[60:61], 0, v[156:157]
	global_load_lds_dwordx4 v[226:227], off
	s_barrier
	s_waitcnt lgkmcnt(0)
	v_mfma_f32_16x16x32_bf16 v[52:55], v[134:137], v[164:167], v[52:55]
	v_mfma_f32_16x16x32_bf16 v[48:51], v[142:145], v[164:167], v[48:51]
	v_mfma_f32_16x16x32_bf16 v[44:47], v[134:137], v[172:175], v[44:47]
	v_mfma_f32_16x16x32_bf16 v[36:39], v[142:145], v[172:175], v[36:39]
	v_mfma_f32_16x16x32_bf16 v[28:31], v[134:137], v[190:193], v[28:31]
	v_mfma_f32_16x16x32_bf16 v[20:23], v[142:145], v[190:193], v[20:23]
	v_mfma_f32_16x16x32_bf16 v[12:15], v[134:137], v[198:201], v[12:15]
	v_mfma_f32_16x16x32_bf16 v[4:7], v[142:145], v[198:201], v[4:7]
	v_mfma_f32_16x16x32_bf16 v[52:55], v[138:141], v[168:171], v[52:55]
	v_mfma_f32_16x16x32_bf16 v[48:51], v[146:149], v[168:171], v[48:51]
	v_mfma_f32_16x16x32_bf16 v[44:47], v[138:141], v[176:179], v[44:47]
	v_mfma_f32_16x16x32_bf16 v[36:39], v[146:149], v[176:179], v[36:39]
	v_mfma_f32_16x16x32_bf16 v[28:31], v[138:141], v[194:197], v[28:31]
	v_mfma_f32_16x16x32_bf16 v[20:23], v[146:149], v[194:197], v[20:23]
	v_mfma_f32_16x16x32_bf16 v[12:15], v[138:141], v[202:205], v[12:15]
	v_mfma_f32_16x16x32_bf16 v[4:7], v[146:149], v[202:205], v[4:7]
	s_barrier
	s_add_u32 s62, s26, 0xb0000
	s_addc_u32 s63, s27, 0
	s_mov_b32 m0, s52
	v_lshl_add_u64 v[134:135], s[62:63], 0, v[154:155]
	global_load_lds_dwordx4 v[134:135], off
	s_mov_b32 m0, s53
	v_lshl_add_u64 v[134:135], s[62:63], 0, v[158:159]
	global_load_lds_dwordx4 v[134:135], off
	s_waitcnt vmcnt(6)
	s_barrier
	v_mfma_f32_16x16x32_bf16 v[60:63], v[206:209], v[164:167], v[60:63]
	v_mfma_f32_16x16x32_bf16 v[56:59], v[214:217], v[164:167], v[56:59]
	v_mfma_f32_16x16x32_bf16 v[40:43], v[206:209], v[172:175], v[40:43]
	v_mfma_f32_16x16x32_bf16 v[32:35], v[214:217], v[172:175], v[32:35]
	v_mfma_f32_16x16x32_bf16 v[24:27], v[206:209], v[190:193], v[24:27]
	v_mfma_f32_16x16x32_bf16 v[16:19], v[214:217], v[190:193], v[16:19]
	v_mfma_f32_16x16x32_bf16 v[8:11], v[206:209], v[198:201], v[8:11]
	v_mfma_f32_16x16x32_bf16 v[0:3], v[214:217], v[198:201], v[0:3]
	v_mfma_f32_16x16x32_bf16 v[60:63], v[210:213], v[168:171], v[60:63]
	v_mfma_f32_16x16x32_bf16 v[56:59], v[222:225], v[168:171], v[56:59]
	v_mfma_f32_16x16x32_bf16 v[40:43], v[210:213], v[176:179], v[40:43]
	v_mfma_f32_16x16x32_bf16 v[32:35], v[222:225], v[176:179], v[32:35]
	v_mfma_f32_16x16x32_bf16 v[24:27], v[210:213], v[194:197], v[24:27]
	v_mfma_f32_16x16x32_bf16 v[16:19], v[222:225], v[194:197], v[16:19]
	v_mfma_f32_16x16x32_bf16 v[8:11], v[210:213], v[202:205], v[8:11]
	v_mfma_f32_16x16x32_bf16 v[0:3], v[222:225], v[202:205], v[0:3]
	s_barrier
	ds_read_b128 v[134:137], v132
	ds_read_b128 v[138:141], v132 offset:1024
	ds_read_b128 v[142:145], v132 offset:2048
	ds_read_b128 v[146:149], v132 offset:3072
	s_add_u32 s60, s60, 0xb0000
	s_addc_u32 s61, s61, 0
	s_mov_b32 m0, s39
	v_lshl_add_u64 v[206:207], s[60:61], 0, v[152:153]
	ds_read_b128 v[164:167], v186 offset:32768
	ds_read_b128 v[168:171], v186 offset:33792
	ds_read_b128 v[172:175], v186 offset:34816
	ds_read_b128 v[176:179], v186 offset:35840
	ds_read_b128 v[190:193], v186 offset:36864
	ds_read_b128 v[194:197], v186 offset:37888
	ds_read_b128 v[198:201], v186 offset:38912
	ds_read_b128 v[202:205], v186 offset:39936
	global_load_lds_dwordx4 v[206:207], off
	s_mov_b32 m0, s40
	v_lshl_add_u64 v[206:207], s[60:61], 0, v[156:157]
	global_load_lds_dwordx4 v[206:207], off
	s_waitcnt lgkmcnt(8)
	s_barrier
;     ...
;         G_PAIR(0, 1);
; #pragma unroll 1
;         for (int t = 2; t < nt; t += 2) G_PAIR(t, 0);
	s_waitcnt lgkmcnt(0)
	v_mfma_f32_16x16x32_bf16 v[116:119], v[134:137], v[164:167], v[116:119]
	v_mfma_f32_16x16x32_bf16 v[112:115], v[142:145], v[164:167], v[112:115]
	v_mfma_f32_16x16x32_bf16 v[108:111], v[134:137], v[172:175], v[108:111]
	v_mfma_f32_16x16x32_bf16 v[104:107], v[142:145], v[172:175], v[104:107]
	v_mfma_f32_16x16x32_bf16 v[92:95], v[134:137], v[190:193], v[92:95]
	v_mfma_f32_16x16x32_bf16 v[88:91], v[142:145], v[190:193], v[88:91]
	v_mfma_f32_16x16x32_bf16 v[76:79], v[134:137], v[198:201], v[76:79]
	v_mfma_f32_16x16x32_bf16 v[72:75], v[142:145], v[198:201], v[72:75]
	v_mfma_f32_16x16x32_bf16 v[116:119], v[138:141], v[168:171], v[116:119]
	v_mfma_f32_16x16x32_bf16 v[112:115], v[146:149], v[168:171], v[112:115]
	v_mfma_f32_16x16x32_bf16 v[108:111], v[138:141], v[176:179], v[108:111]
	v_mfma_f32_16x16x32_bf16 v[104:107], v[146:149], v[176:179], v[104:107]
	v_mfma_f32_16x16x32_bf16 v[92:95], v[138:141], v[194:197], v[92:95]
	v_mfma_f32_16x16x32_bf16 v[88:91], v[146:149], v[194:197], v[88:91]
	v_mfma_f32_16x16x32_bf16 v[76:79], v[138:141], v[202:205], v[76:79]
	v_mfma_f32_16x16x32_bf16 v[72:75], v[146:149], v[202:205], v[72:75]
	s_barrier
	s_mov_b32 m0, s54
	v_lshl_add_u64 v[150:151], v[150:151], 0, s[10:11]
	ds_read_b128 v[206:209], v133
	ds_read_b128 v[210:213], v133 offset:1024
	ds_read_b128 v[214:217], v133 offset:2048
	ds_read_b128 v[222:225], v133 offset:3072
	global_load_lds_dwordx4 v[150:151], off
	s_mov_b32 m0, s55
	v_lshl_add_u64 v[150:151], v[180:181], 0, s[10:11]
	global_load_lds_dwordx4 v[150:151], off
	s_barrier
	s_waitcnt lgkmcnt(0)
	v_mfma_f32_16x16x32_bf16 v[124:127], v[206:209], v[164:167], v[124:127]
	v_mfma_f32_16x16x32_bf16 v[120:123], v[214:217], v[164:167], v[120:123]
	v_mfma_f32_16x16x32_bf16 v[100:103], v[206:209], v[172:175], v[100:103]
	v_mfma_f32_16x16x32_bf16 v[96:99], v[214:217], v[172:175], v[96:99]
	v_mfma_f32_16x16x32_bf16 v[84:87], v[206:209], v[190:193], v[84:87]
	v_mfma_f32_16x16x32_bf16 v[80:83], v[214:217], v[190:193], v[80:83]
	v_mfma_f32_16x16x32_bf16 v[68:71], v[206:209], v[198:201], v[68:71]
	v_mfma_f32_16x16x32_bf16 v[64:67], v[214:217], v[198:201], v[64:67]
	v_mfma_f32_16x16x32_bf16 v[124:127], v[210:213], v[168:171], v[124:127]
	v_mfma_f32_16x16x32_bf16 v[120:123], v[222:225], v[168:171], v[120:123]
	v_mfma_f32_16x16x32_bf16 v[100:103], v[210:213], v[176:179], v[100:103]
	v_mfma_f32_16x16x32_bf16 v[96:99], v[222:225], v[176:179], v[96:99]
	v_mfma_f32_16x16x32_bf16 v[84:87], v[210:213], v[194:197], v[84:87]
	v_mfma_f32_16x16x32_bf16 v[80:83], v[222:225], v[194:197], v[80:83]
	v_mfma_f32_16x16x32_bf16 v[68:71], v[210:213], v[202:205], v[68:71]
	v_mfma_f32_16x16x32_bf16 v[64:67], v[222:225], v[202:205], v[64:67]
	s_mov_b32 m0, s42
	v_lshl_add_u64 v[150:151], v[218:219], 0, s[10:11]
	s_barrier
	ds_read_b128 v[164:167], v186 offset:49152
	ds_read_b128 v[168:171], v186 offset:50176
	ds_read_b128 v[172:175], v186 offset:51200
	ds_read_b128 v[176:179], v186 offset:52224
	ds_read_b128 v[190:193], v186 offset:53248
	ds_read_b128 v[194:197], v186 offset:54272
	ds_read_b128 v[198:201], v186 offset:55296
	ds_read_b128 v[202:205], v186 offset:56320
	global_load_lds_dwordx4 v[150:151], off
	s_mov_b32 m0, s43
	v_lshl_add_u64 v[150:151], v[226:227], 0, s[10:11]
	global_load_lds_dwordx4 v[150:151], off
	s_barrier
	s_waitcnt lgkmcnt(0)
	v_mfma_f32_16x16x32_bf16 v[52:55], v[134:137], v[164:167], v[52:55]
	v_mfma_f32_16x16x32_bf16 v[48:51], v[142:145], v[164:167], v[48:51]
	v_mfma_f32_16x16x32_bf16 v[44:47], v[134:137], v[172:175], v[44:47]
	v_mfma_f32_16x16x32_bf16 v[36:39], v[142:145], v[172:175], v[36:39]
	v_mfma_f32_16x16x32_bf16 v[28:31], v[134:137], v[190:193], v[28:31]
	v_mfma_f32_16x16x32_bf16 v[20:23], v[142:145], v[190:193], v[20:23]
	v_mfma_f32_16x16x32_bf16 v[12:15], v[134:137], v[198:201], v[12:15]
	v_mfma_f32_16x16x32_bf16 v[4:7], v[142:145], v[198:201], v[4:7]
	v_mfma_f32_16x16x32_bf16 v[52:55], v[138:141], v[168:171], v[52:55]
	v_mfma_f32_16x16x32_bf16 v[48:51], v[146:149], v[168:171], v[48:51]
	v_mfma_f32_16x16x32_bf16 v[44:47], v[138:141], v[176:179], v[44:47]
	v_mfma_f32_16x16x32_bf16 v[36:39], v[146:149], v[176:179], v[36:39]
	v_mfma_f32_16x16x32_bf16 v[28:31], v[138:141], v[194:197], v[28:31]
	v_mfma_f32_16x16x32_bf16 v[20:23], v[146:149], v[194:197], v[20:23]
	v_mfma_f32_16x16x32_bf16 v[12:15], v[138:141], v[202:205], v[12:15]
	v_mfma_f32_16x16x32_bf16 v[4:7], v[146:149], v[202:205], v[4:7]
	s_barrier
	s_add_u32 s26, s26, 0xb0080
	s_addc_u32 s27, s27, 0
	s_mov_b32 m0, s56
	v_lshl_add_u64 v[134:135], s[26:27], 0, v[154:155]
	global_load_lds_dwordx4 v[134:135], off
	s_mov_b32 m0, s57
	v_lshl_add_u64 v[134:135], s[26:27], 0, v[158:159]
	global_load_lds_dwordx4 v[134:135], off
	s_waitcnt vmcnt(6)
	s_barrier
	v_mfma_f32_16x16x32_bf16 v[60:63], v[206:209], v[164:167], v[60:63]
	v_mfma_f32_16x16x32_bf16 v[56:59], v[214:217], v[164:167], v[56:59]
	v_mfma_f32_16x16x32_bf16 v[40:43], v[206:209], v[172:175], v[40:43]
	v_mfma_f32_16x16x32_bf16 v[32:35], v[214:217], v[172:175], v[32:35]
	v_mfma_f32_16x16x32_bf16 v[24:27], v[206:209], v[190:193], v[24:27]
	v_mfma_f32_16x16x32_bf16 v[16:19], v[214:217], v[190:193], v[16:19]
	v_mfma_f32_16x16x32_bf16 v[8:11], v[206:209], v[198:201], v[8:11]
	v_mfma_f32_16x16x32_bf16 v[0:3], v[214:217], v[198:201], v[0:3]
	v_mfma_f32_16x16x32_bf16 v[60:63], v[210:213], v[168:171], v[60:63]
	v_mfma_f32_16x16x32_bf16 v[56:59], v[222:225], v[168:171], v[56:59]
	v_mfma_f32_16x16x32_bf16 v[40:43], v[210:213], v[176:179], v[40:43]
	v_mfma_f32_16x16x32_bf16 v[32:35], v[222:225], v[176:179], v[32:35]
	v_mfma_f32_16x16x32_bf16 v[24:27], v[210:213], v[194:197], v[24:27]
	v_mfma_f32_16x16x32_bf16 v[16:19], v[222:225], v[194:197], v[16:19]
	v_mfma_f32_16x16x32_bf16 v[8:11], v[210:213], v[202:205], v[8:11]
	v_mfma_f32_16x16x32_bf16 v[0:3], v[222:225], v[202:205], v[0:3]
	s_add_i32 s58, s58, 2
	s_add_u32 s24, s24, 0x100
	s_addc_u32 s25, s25, 0
	s_cmp_gt_u32 s58, 39
	s_cbranch_scc0 .Lrot_1906
	s_barrier
	ds_read_b128 v[134:137], v185
	ds_read_b128 v[138:141], v185 offset:1024
	ds_read_b128 v[142:145], v185 offset:2048
	ds_read_b128 v[146:149], v185 offset:3072
	s_mov_b32 m0, s45
	v_lshl_add_u64 v[150:151], v[128:129], 0, s[24:25]
	ds_read_b128 v[164:167], v186
	ds_read_b128 v[168:171], v186 offset:1024
	ds_read_b128 v[172:175], v186 offset:2048
	ds_read_b128 v[176:179], v186 offset:3072
	ds_read_b128 v[190:193], v186 offset:4096
	ds_read_b128 v[194:197], v186 offset:5120
	ds_read_b128 v[198:201], v186 offset:6144
	ds_read_b128 v[202:205], v186 offset:7168
	global_load_lds_dwordx4 v[150:151], off
	s_mov_b32 m0, s46
	v_lshl_add_u64 v[150:151], v[130:131], 0, s[24:25]
	global_load_lds_dwordx4 v[150:151], off
	s_waitcnt lgkmcnt(8)
	s_barrier
	s_waitcnt lgkmcnt(0)
	v_mfma_f32_16x16x32_bf16 v[116:119], v[134:137], v[164:167], v[116:119]
	s_add_i32 s26, s24, 0xfff50080
	v_mfma_f32_16x16x32_bf16 v[112:115], v[142:145], v[164:167], v[112:115]
	s_cmp_eq_u32 s58, 40
	v_mfma_f32_16x16x32_bf16 v[108:111], v[134:137], v[172:175], v[108:111]
	s_cselect_b32 s59, s19, s21
	v_mfma_f32_16x16x32_bf16 v[104:107], v[142:145], v[172:175], v[104:107]
	s_cselect_b32 s60, s18, s20
	v_mfma_f32_16x16x32_bf16 v[92:95], v[134:137], v[190:193], v[92:95]
	s_cselect_b32 s27, s7, s23
	v_mfma_f32_16x16x32_bf16 v[88:91], v[142:145], v[190:193], v[88:91]
	s_cselect_b32 s61, s6, s22
	v_mfma_f32_16x16x32_bf16 v[76:79], v[134:137], v[198:201], v[76:79]
	v_mfma_f32_16x16x32_bf16 v[72:75], v[142:145], v[198:201], v[72:75]
	v_mfma_f32_16x16x32_bf16 v[116:119], v[138:141], v[168:171], v[116:119]
	v_mfma_f32_16x16x32_bf16 v[112:115], v[146:149], v[168:171], v[112:115]
	v_mfma_f32_16x16x32_bf16 v[108:111], v[138:141], v[176:179], v[108:111]
	v_mfma_f32_16x16x32_bf16 v[104:107], v[146:149], v[176:179], v[104:107]
	v_mfma_f32_16x16x32_bf16 v[92:95], v[138:141], v[194:197], v[92:95]
	v_mfma_f32_16x16x32_bf16 v[88:91], v[146:149], v[194:197], v[88:91]
	v_mfma_f32_16x16x32_bf16 v[76:79], v[138:141], v[202:205], v[76:79]
	v_mfma_f32_16x16x32_bf16 v[72:75], v[146:149], v[202:205], v[72:75]
	s_barrier
	s_cselect_b32 s62, 0, s26
	s_add_u32 s26, s61, s62
	s_addc_u32 s27, s27, 0
	s_mov_b32 m0, s47
	v_lshl_add_u64 v[150:151], s[26:27], 0, v[154:155]
	ds_read_b128 v[206:209], v187
	ds_read_b128 v[210:213], v187 offset:1024
	ds_read_b128 v[214:217], v187 offset:2048
	ds_read_b128 v[222:225], v187 offset:3072
	global_load_lds_dwordx4 v[150:151], off
	s_mov_b32 m0, s48
	v_lshl_add_u64 v[180:181], s[26:27], 0, v[158:159]
	global_load_lds_dwordx4 v[180:181], off
	s_barrier
	s_waitcnt lgkmcnt(0)
	v_mfma_f32_16x16x32_bf16 v[124:127], v[206:209], v[164:167], v[124:127]
	v_mfma_f32_16x16x32_bf16 v[120:123], v[214:217], v[164:167], v[120:123]
	v_mfma_f32_16x16x32_bf16 v[100:103], v[206:209], v[172:175], v[100:103]
	v_mfma_f32_16x16x32_bf16 v[96:99], v[214:217], v[172:175], v[96:99]
	v_mfma_f32_16x16x32_bf16 v[84:87], v[206:209], v[190:193], v[84:87]
	v_mfma_f32_16x16x32_bf16 v[80:83], v[214:217], v[190:193], v[80:83]
	v_mfma_f32_16x16x32_bf16 v[68:71], v[206:209], v[198:201], v[68:71]
	v_mfma_f32_16x16x32_bf16 v[64:67], v[214:217], v[198:201], v[64:67]
	v_mfma_f32_16x16x32_bf16 v[124:127], v[210:213], v[168:171], v[124:127]
	v_mfma_f32_16x16x32_bf16 v[120:123], v[222:225], v[168:171], v[120:123]
	v_mfma_f32_16x16x32_bf16 v[100:103], v[210:213], v[176:179], v[100:103]
	v_mfma_f32_16x16x32_bf16 v[96:99], v[222:225], v[176:179], v[96:99]
	v_mfma_f32_16x16x32_bf16 v[84:87], v[210:213], v[194:197], v[84:87]
	v_mfma_f32_16x16x32_bf16 v[80:83], v[222:225], v[194:197], v[80:83]
	v_mfma_f32_16x16x32_bf16 v[68:71], v[210:213], v[202:205], v[68:71]
	v_mfma_f32_16x16x32_bf16 v[64:67], v[222:225], v[202:205], v[64:67]
	s_add_u32 s60, s60, s62
	s_addc_u32 s61, s59, 0
	s_mov_b32 m0, s37
	v_lshl_add_u64 v[218:219], s[60:61], 0, v[152:153]
	s_barrier
	ds_read_b128 v[164:167], v186 offset:16384
	ds_read_b128 v[168:171], v186 offset:17408
	ds_read_b128 v[172:175], v186 offset:18432
	ds_read_b128 v[176:179], v186 offset:19456
	ds_read_b128 v[190:193], v186 offset:20480
	ds_read_b128 v[194:197], v186 offset:21504
	ds_read_b128 v[198:201], v186 offset:22528
	ds_read_b128 v[202:205], v186 offset:23552
	global_load_lds_dwordx4 v[218:219], off
	s_mov_b32 m0, s38
	v_lshl_add_u64 v[226:227], s[60:61], 0, v[156:157]
	global_load_lds_dwordx4 v[226:227], off
	s_barrier
	s_waitcnt lgkmcnt(0)
	v_mfma_f32_16x16x32_bf16 v[52:55], v[134:137], v[164:167], v[52:55]
	v_mfma_f32_16x16x32_bf16 v[48:51], v[142:145], v[164:167], v[48:51]
	v_mfma_f32_16x16x32_bf16 v[44:47], v[134:137], v[172:175], v[44:47]
	v_mfma_f32_16x16x32_bf16 v[36:39], v[142:145], v[172:175], v[36:39]
	v_mfma_f32_16x16x32_bf16 v[28:31], v[134:137], v[190:193], v[28:31]
	v_mfma_f32_16x16x32_bf16 v[20:23], v[142:145], v[190:193], v[20:23]
	v_mfma_f32_16x16x32_bf16 v[12:15], v[134:137], v[198:201], v[12:15]
	v_mfma_f32_16x16x32_bf16 v[4:7], v[142:145], v[198:201], v[4:7]
	v_mfma_f32_16x16x32_bf16 v[52:55], v[138:141], v[168:171], v[52:55]
	v_mfma_f32_16x16x32_bf16 v[48:51], v[146:149], v[168:171], v[48:51]
	v_mfma_f32_16x16x32_bf16 v[44:47], v[138:141], v[176:179], v[44:47]
	v_mfma_f32_16x16x32_bf16 v[36:39], v[146:149], v[176:179], v[36:39]
	v_mfma_f32_16x16x32_bf16 v[28:31], v[138:141], v[194:197], v[28:31]
	v_mfma_f32_16x16x32_bf16 v[20:23], v[146:149], v[194:197], v[20:23]
	v_mfma_f32_16x16x32_bf16 v[12:15], v[138:141], v[202:205], v[12:15]
	v_mfma_f32_16x16x32_bf16 v[4:7], v[146:149], v[202:205], v[4:7]
	s_barrier
;     __device__ __forceinline__ void epi(const f32x4 (&acc)[2][2][4][2], const Unit& u, int wr, int wc, int fr, int fq) const {
;     ...
;                 for (int bj = 0; bj < 2; ++bj) xo[m][bj] = *(const u32x4*)(xb + (size_t)(row0 + ai * 128 + m * 16) * D + col0 + bj * 128);
	s_add_u32 s62, s26, 0xb0000
	s_addc_u32 s63, s27, 0
	s_mov_b32 m0, s52
	v_lshl_add_u64 v[134:135], s[62:63], 0, v[154:155]
	global_load_lds_dwordx4 v[134:135], off
	s_mov_b32 m0, s53
	v_lshl_add_u64 v[134:135], s[62:63], 0, v[158:159]
	global_load_lds_dwordx4 v[134:135], off
	s_waitcnt vmcnt(6)
	s_barrier
	v_mfma_f32_16x16x32_bf16 v[60:63], v[206:209], v[164:167], v[60:63]
	v_lshl_or_b32 v248, s30, 8, v184
	v_mfma_f32_16x16x32_bf16 v[56:59], v[214:217], v[164:167], v[56:59]
	v_lshl_add_u32 v250, s2, 8, v182
	v_mfma_f32_16x16x32_bf16 v[40:43], v[206:209], v[172:175], v[40:43]
	v_ashrrev_i32_e32 v249, 31, v248
	v_mfma_f32_16x16x32_bf16 v[32:35], v[214:217], v[172:175], v[32:35]
	v_lshlrev_b64 v[248:249], 1, v[248:249]
	v_mfma_f32_16x16x32_bf16 v[24:27], v[206:209], v[190:193], v[24:27]
	v_ashrrev_i32_e32 v251, 31, v250
	v_mfma_f32_16x16x32_bf16 v[16:19], v[214:217], v[190:193], v[16:19]
	v_lshl_add_u64 v[248:249], s[0:1], 0, v[248:249]
	v_mfma_f32_16x16x32_bf16 v[8:11], v[206:209], v[198:201], v[8:11]
	v_lshlrev_b64 v[250:251], 11, v[250:251]
	v_mfma_f32_16x16x32_bf16 v[0:3], v[214:217], v[198:201], v[0:3]
	v_lshl_add_u64 v[252:253], v[248:249], 0, v[250:251]
	v_mfma_f32_16x16x32_bf16 v[60:63], v[210:213], v[168:171], v[60:63]
	global_load_dwordx4 v[232:235], v[252:253], off
	v_mfma_f32_16x16x32_bf16 v[56:59], v[222:225], v[168:171], v[56:59]
	global_load_dwordx4 v[236:239], v[252:253], off offset:256
	v_mfma_f32_16x16x32_bf16 v[40:43], v[210:213], v[176:179], v[40:43]
	v_mov_b32_e32 v250, 0x8000
	v_mfma_f32_16x16x32_bf16 v[32:35], v[222:225], v[176:179], v[32:35]
	v_mov_b32_e32 v251, 0
	v_mfma_f32_16x16x32_bf16 v[24:27], v[210:213], v[194:197], v[24:27]
	v_lshl_add_u64 v[250:251], v[252:253], 0, v[250:251]
	v_mfma_f32_16x16x32_bf16 v[16:19], v[222:225], v[194:197], v[16:19]
	global_load_dwordx4 v[240:243], v[250:251], off
	v_mfma_f32_16x16x32_bf16 v[8:11], v[210:213], v[202:205], v[8:11]
	global_load_dwordx4 v[244:247], v[250:251], off offset:256
	v_mfma_f32_16x16x32_bf16 v[0:3], v[222:225], v[202:205], v[0:3]
	s_barrier
	ds_read_b128 v[134:137], v132
	ds_read_b128 v[138:141], v132 offset:1024
	ds_read_b128 v[142:145], v132 offset:2048
	ds_read_b128 v[146:149], v132 offset:3072
	s_add_u32 s60, s60, 0xb0000
	s_addc_u32 s61, s61, 0
	s_mov_b32 m0, s39
	v_lshl_add_u64 v[206:207], s[60:61], 0, v[152:153]
	ds_read_b128 v[164:167], v186 offset:32768
	ds_read_b128 v[168:171], v186 offset:33792
	ds_read_b128 v[172:175], v186 offset:34816
	ds_read_b128 v[176:179], v186 offset:35840
	ds_read_b128 v[190:193], v186 offset:36864
	ds_read_b128 v[194:197], v186 offset:37888
	ds_read_b128 v[198:201], v186 offset:38912
	ds_read_b128 v[202:205], v186 offset:39936
	global_load_lds_dwordx4 v[206:207], off
	s_mov_b32 m0, s40
	v_lshl_add_u64 v[206:207], s[60:61], 0, v[156:157]
	global_load_lds_dwordx4 v[206:207], off
	s_waitcnt lgkmcnt(8)
	s_barrier
	s_waitcnt lgkmcnt(0)
	v_mfma_f32_16x16x32_bf16 v[116:119], v[134:137], v[164:167], v[116:119]
	v_mfma_f32_16x16x32_bf16 v[112:115], v[142:145], v[164:167], v[112:115]
	v_mfma_f32_16x16x32_bf16 v[108:111], v[134:137], v[172:175], v[108:111]
	v_mfma_f32_16x16x32_bf16 v[104:107], v[142:145], v[172:175], v[104:107]
	v_mfma_f32_16x16x32_bf16 v[92:95], v[134:137], v[190:193], v[92:95]
	v_mfma_f32_16x16x32_bf16 v[88:91], v[142:145], v[190:193], v[88:91]
	v_mfma_f32_16x16x32_bf16 v[76:79], v[134:137], v[198:201], v[76:79]
	v_mfma_f32_16x16x32_bf16 v[72:75], v[142:145], v[198:201], v[72:75]
	v_mfma_f32_16x16x32_bf16 v[116:119], v[138:141], v[168:171], v[116:119]
	v_mfma_f32_16x16x32_bf16 v[112:115], v[146:149], v[168:171], v[112:115]
	v_mfma_f32_16x16x32_bf16 v[108:111], v[138:141], v[176:179], v[108:111]
	v_mfma_f32_16x16x32_bf16 v[104:107], v[146:149], v[176:179], v[104:107]
	v_mfma_f32_16x16x32_bf16 v[92:95], v[138:141], v[194:197], v[92:95]
	v_mfma_f32_16x16x32_bf16 v[88:91], v[146:149], v[194:197], v[88:91]
	v_mfma_f32_16x16x32_bf16 v[76:79], v[138:141], v[202:205], v[76:79]
	v_mfma_f32_16x16x32_bf16 v[72:75], v[146:149], v[202:205], v[72:75]
	s_barrier
	s_mov_b32 m0, s54
	v_lshl_add_u64 v[150:151], v[150:151], 0, s[10:11]
	ds_read_b128 v[206:209], v133
	ds_read_b128 v[210:213], v133 offset:1024
	ds_read_b128 v[214:217], v133 offset:2048
	ds_read_b128 v[222:225], v133 offset:3072
	global_load_lds_dwordx4 v[150:151], off
	s_mov_b32 m0, s55
	v_lshl_add_u64 v[150:151], v[180:181], 0, s[10:11]
	global_load_lds_dwordx4 v[150:151], off
	s_barrier
	s_waitcnt lgkmcnt(0)
	v_mfma_f32_16x16x32_bf16 v[124:127], v[206:209], v[164:167], v[124:127]
	v_mfma_f32_16x16x32_bf16 v[120:123], v[214:217], v[164:167], v[120:123]
	v_mfma_f32_16x16x32_bf16 v[100:103], v[206:209], v[172:175], v[100:103]
	v_mfma_f32_16x16x32_bf16 v[96:99], v[214:217], v[172:175], v[96:99]
	v_mfma_f32_16x16x32_bf16 v[84:87], v[206:209], v[190:193], v[84:87]
	v_mfma_f32_16x16x32_bf16 v[80:83], v[214:217], v[190:193], v[80:83]
	v_mfma_f32_16x16x32_bf16 v[68:71], v[206:209], v[198:201], v[68:71]
	v_mfma_f32_16x16x32_bf16 v[64:67], v[214:217], v[198:201], v[64:67]
	v_mfma_f32_16x16x32_bf16 v[124:127], v[210:213], v[168:171], v[124:127]
	v_mfma_f32_16x16x32_bf16 v[120:123], v[222:225], v[168:171], v[120:123]
	v_mfma_f32_16x16x32_bf16 v[100:103], v[210:213], v[176:179], v[100:103]
	v_mfma_f32_16x16x32_bf16 v[96:99], v[222:225], v[176:179], v[96:99]
	v_mfma_f32_16x16x32_bf16 v[84:87], v[210:213], v[194:197], v[84:87]
	v_mfma_f32_16x16x32_bf16 v[80:83], v[222:225], v[194:197], v[80:83]
	v_mfma_f32_16x16x32_bf16 v[68:71], v[210:213], v[202:205], v[68:71]
	v_mfma_f32_16x16x32_bf16 v[64:67], v[222:225], v[202:205], v[64:67]
	s_mov_b32 m0, s42
	v_lshl_add_u64 v[150:151], v[218:219], 0, s[10:11]
	s_barrier
	ds_read_b128 v[164:167], v186 offset:49152
	ds_read_b128 v[168:171], v186 offset:50176
	ds_read_b128 v[172:175], v186 offset:51200
	ds_read_b128 v[176:179], v186 offset:52224
	ds_read_b128 v[190:193], v186 offset:53248
	ds_read_b128 v[194:197], v186 offset:54272
	ds_read_b128 v[198:201], v186 offset:55296
	ds_read_b128 v[202:205], v186 offset:56320
	global_load_lds_dwordx4 v[150:151], off
	s_mov_b32 m0, s43
	v_lshl_add_u64 v[150:151], v[226:227], 0, s[10:11]
	global_load_lds_dwordx4 v[150:151], off
	s_barrier
	s_waitcnt lgkmcnt(0)
	v_mfma_f32_16x16x32_bf16 v[52:55], v[134:137], v[164:167], v[52:55]
	v_mfma_f32_16x16x32_bf16 v[48:51], v[142:145], v[164:167], v[48:51]
	v_mfma_f32_16x16x32_bf16 v[44:47], v[134:137], v[172:175], v[44:47]
	v_mfma_f32_16x16x32_bf16 v[36:39], v[142:145], v[172:175], v[36:39]
	v_mfma_f32_16x16x32_bf16 v[28:31], v[134:137], v[190:193], v[28:31]
	v_mfma_f32_16x16x32_bf16 v[20:23], v[142:145], v[190:193], v[20:23]
	v_mfma_f32_16x16x32_bf16 v[12:15], v[134:137], v[198:201], v[12:15]
	v_mfma_f32_16x16x32_bf16 v[4:7], v[142:145], v[198:201], v[4:7]
	v_mfma_f32_16x16x32_bf16 v[52:55], v[138:141], v[168:171], v[52:55]
	v_mfma_f32_16x16x32_bf16 v[48:51], v[146:149], v[168:171], v[48:51]
	v_mfma_f32_16x16x32_bf16 v[44:47], v[138:141], v[176:179], v[44:47]
	v_mfma_f32_16x16x32_bf16 v[36:39], v[146:149], v[176:179], v[36:39]
	v_mfma_f32_16x16x32_bf16 v[28:31], v[138:141], v[194:197], v[28:31]
	v_mfma_f32_16x16x32_bf16 v[20:23], v[146:149], v[194:197], v[20:23]
	v_mfma_f32_16x16x32_bf16 v[12:15], v[138:141], v[202:205], v[12:15]
	v_mfma_f32_16x16x32_bf16 v[4:7], v[146:149], v[202:205], v[4:7]
	s_barrier
	s_add_u32 s26, s26, 0xb0080
	s_addc_u32 s27, s27, 0
	s_mov_b32 m0, s56
	v_lshl_add_u64 v[134:135], s[26:27], 0, v[154:155]
	global_load_lds_dwordx4 v[134:135], off
	s_mov_b32 m0, s57
	v_lshl_add_u64 v[134:135], s[26:27], 0, v[158:159]
	global_load_lds_dwordx4 v[134:135], off
	s_waitcnt vmcnt(6)
	s_barrier
	v_mfma_f32_16x16x32_bf16 v[60:63], v[206:209], v[164:167], v[60:63]
	v_mfma_f32_16x16x32_bf16 v[56:59], v[214:217], v[164:167], v[56:59]
	v_mfma_f32_16x16x32_bf16 v[40:43], v[206:209], v[172:175], v[40:43]
	v_mfma_f32_16x16x32_bf16 v[32:35], v[214:217], v[172:175], v[32:35]
	v_mfma_f32_16x16x32_bf16 v[24:27], v[206:209], v[190:193], v[24:27]
	v_mfma_f32_16x16x32_bf16 v[16:19], v[214:217], v[190:193], v[16:19]
	v_mfma_f32_16x16x32_bf16 v[8:11], v[206:209], v[198:201], v[8:11]
	v_mfma_f32_16x16x32_bf16 v[0:3], v[214:217], v[198:201], v[0:3]
	v_mfma_f32_16x16x32_bf16 v[60:63], v[210:213], v[168:171], v[60:63]
	v_mfma_f32_16x16x32_bf16 v[56:59], v[222:225], v[168:171], v[56:59]
	v_mfma_f32_16x16x32_bf16 v[40:43], v[210:213], v[176:179], v[40:43]
	v_mfma_f32_16x16x32_bf16 v[32:35], v[222:225], v[176:179], v[32:35]
	v_mfma_f32_16x16x32_bf16 v[24:27], v[210:213], v[194:197], v[24:27]
	v_mfma_f32_16x16x32_bf16 v[16:19], v[222:225], v[194:197], v[16:19]
	v_mfma_f32_16x16x32_bf16 v[8:11], v[210:213], v[202:205], v[8:11]
	v_mfma_f32_16x16x32_bf16 v[0:3], v[222:225], v[202:205], v[0:3]
	s_add_i32 s58, s58, 2
	s_add_u32 s24, s24, 0x100
	s_addc_u32 s25, s25, 0
	s_cmp_gt_u32 s58, 41
	s_barrier
; __device__ __forceinline__ unsigned pk2(float lo, float hi) { unsigned r; asm volatile("v_cvt_pk_bf16_f32 %0, %1, %2" : "=v"(r) : "v"(lo), "v"(hi)); return r; }
; __device__ __forceinline__ unsigned pk2(float lo, float hi) { return f2bf(lo) | (f2bf(hi) << 16); }
;     __device__ __forceinline__ void epi(const f32x4 (&acc)[2][2][4][2], const Unit& u, int wr, int wc, int fr, int fq) const {
;     ...
;         const int row0 = u.pm * 256 + wr * 64 + fr, col0 = u.pn * 256 + wc * 32 + 8 * fq;
; #pragma unroll
;         for (int ai = 0; ai < 2; ++ai) {
;             u32x4 xo[4][2];
; #pragma unroll
;             for (int m = 0; m < 4; ++m)
; #pragma unroll
;                 for (int bj = 0; bj < 2; ++bj) xo[m][bj] = *(const u32x4*)(xb + (size_t)(row0 + ai * 128 + m * 16) * D + col0 + bj * 128);
; #pragma unroll
;             for (int m = 0; m < 4; ++m) {
;                 const int row = row0 + ai * 128 + m * 16; const size_t off = (size_t)row * D + col0; float ss = 0.f;
; #pragma unroll
;                 for (int bj = 0; bj < 2; ++bj) {
;                     const u32x4 o = xo[m][bj]; const f32x4 a0v = acc[ai][bj][m][0], a1v = acc[ai][bj][m][1];
;                     const float v0 = bf_lo(o.x) + coef * a0v[0], v1 = bf_hi(o.x) + coef * a0v[1], v2 = bf_lo(o.y) + coef * a0v[2], v3 = bf_hi(o.y) + coef * a0v[3];
;                     const float v4 = bf_lo(o.z) + coef * a1v[0], v5 = bf_hi(o.z) + coef * a1v[1], v6 = bf_lo(o.w) + coef * a1v[2], v7 = bf_hi(o.w) + coef * a1v[3];
;                     u32x4 w; w.x = pk2(v0, v1); w.y = pk2(v2, v3); w.z = pk2(v4, v5); w.w = pk2(v6, v7);
;                     *(u32x4*)(xb + off + bj * 128) = w;
;                     ss += ((v0 * v0 + v1 * v1) + (v2 * v2 + v3 * v3)) + ((v4 * v4 + v5 * v5) + (v6 * v6 + v7 * v7));
;                 }
;                 ss += __shfl_xor(ss, 16); ss += __shfl_xor(ss, 32);
;                 if (fq == 0) rowss[(size_t)row * 32 + u.pn * 4 + wc] = ss;
;             }
	v_lshl_or_b32 v164, s30, 8, v184
	v_lshl_add_u32 v168, s2, 8, v182
	v_ashrrev_i32_e32 v165, 31, v164
	v_lshlrev_b64 v[198:199], 1, v[164:165]
	v_ashrrev_i32_e32 v169, 31, v168
	v_lshl_add_u64 v[166:167], s[0:1], 0, v[198:199]
	v_lshlrev_b64 v[200:201], 11, v[168:169]
	v_lshl_add_u64 v[128:129], v[166:167], 0, v[200:201]
	v_mov_b32_e32 v218, 0x40000
	v_mov_b32_e32 v219, 0
	v_lshl_add_u64 v[216:217], v[128:129], 0, v[218:219]
	v_mov_b32_e32 v218, 0x8000
	s_waitcnt vmcnt(8)
	v_mov_b64_e32 v[190:191], v[232:233]
	v_mov_b64_e32 v[192:193], v[234:235]
	v_mov_b64_e32 v[194:195], v[236:237]
	v_mov_b64_e32 v[196:197], v[238:239]
	v_or_b32_e32 v178, 16, v168
	v_or_b32_e32 v174, 32, v168
	v_or_b32_e32 v170, 48, v168
	v_ashrrev_i32_e32 v179, 31, v178
	v_ashrrev_i32_e32 v175, 31, v174
	v_ashrrev_i32_e32 v171, 31, v170
	v_lshlrev_b64 v[180:181], 11, v[178:179]
	v_lshlrev_b64 v[176:177], 11, v[174:175]
	v_lshlrev_b64 v[172:173], 11, v[170:171]
	v_lshl_add_u64 v[128:129], v[166:167], 0, v[180:181]
	v_lshl_add_u64 v[130:131], v[166:167], 0, v[176:177]
	v_lshl_add_u64 v[202:203], v[166:167], 0, v[172:173]
	v_mov_b64_e32 v[148:149], v[240:241]
	v_mov_b64_e32 v[150:151], v[242:243]
	v_mov_b64_e32 v[144:145], v[244:245]
	v_mov_b64_e32 v[146:147], v[246:247]
	global_load_dwordx4 v[140:143], v[130:131], off
	global_load_dwordx4 v[136:139], v[130:131], off offset:256
	global_load_dwordx4 v[132:135], v[202:203], off
	s_nop 0
	global_load_dwordx4 v[128:131], v[202:203], off offset:256
	global_load_dwordx4 v[222:225], v[216:217], off
	global_load_dwordx4 v[226:229], v[216:217], off offset:256
	v_lshl_add_u64 v[216:217], v[216:217], 0, v[218:219]
	global_load_dwordx4 v[230:233], v[216:217], off
	global_load_dwordx4 v[234:237], v[216:217], off offset:256
	v_lshl_add_u64 v[216:217], v[216:217], 0, v[218:219]
	global_load_dwordx4 v[238:241], v[216:217], off
	global_load_dwordx4 v[242:245], v[216:217], off offset:256
	v_lshl_add_u64 v[216:217], v[216:217], 0, v[218:219]
	global_load_dwordx4 v[246:249], v[216:217], off
	global_load_dwordx4 v[250:253], v[216:217], off offset:256
	v_and_b32_e32 v202, 64, v188
	v_xor_b32_e32 v189, 16, v188
	v_add_u32_e32 v202, 64, v202
	v_cmp_lt_i32_e32 vcc, v189, v202
	v_lshlrev_b32_e32 v203, 16, v190
	v_and_b32_e32 v190, 0xffff0000, v190
	v_lshlrev_b32_e32 v204, 16, v191
	v_and_b32_e32 v191, 0xffff0000, v191
	v_lshlrev_b32_e32 v205, 16, v192
	v_and_b32_e32 v192, 0xffff0000, v192
	v_lshlrev_b32_e32 v206, 16, v193
	v_and_b32_e32 v193, 0xffff0000, v193
	v_lshlrev_b32_e32 v207, 16, v194
	v_and_b32_e32 v194, 0xffff0000, v194
	v_lshlrev_b32_e32 v208, 16, v195
	v_and_b32_e32 v195, 0xffff0000, v195
	v_lshlrev_b32_e32 v209, 16, v196
	v_and_b32_e32 v196, 0xffff0000, v196
	v_lshlrev_b32_e32 v210, 16, v197
	v_and_b32_e32 v197, 0xffff0000, v197
	v_fmac_f32_e32 v190, 0.5, v117
	v_fmac_f32_e32 v191, 0.5, v119
	v_fmac_f32_e32 v192, 0.5, v113
	v_fmac_f32_e32 v193, 0.5, v115
	v_fmac_f32_e32 v194, 0.5, v125
	v_fmac_f32_e32 v195, 0.5, v127
	v_fmac_f32_e32 v196, 0.5, v121
	v_fmac_f32_e32 v197, 0.5, v123
	v_fmac_f32_e32 v203, 0.5, v116
	v_fmac_f32_e32 v204, 0.5, v118
	v_fmac_f32_e32 v205, 0.5, v112
	v_fmac_f32_e32 v206, 0.5, v114
	v_fmac_f32_e32 v207, 0.5, v124
	v_fmac_f32_e32 v208, 0.5, v126
	v_fmac_f32_e32 v209, 0.5, v120
	v_fmac_f32_e32 v210, 0.5, v122
	v_mul_f32_e32 v112, v190, v190
	v_mul_f32_e32 v113, v191, v191
	v_mul_f32_e32 v118, v192, v192
	v_mul_f32_e32 v119, v193, v193
	v_mul_f32_e32 v120, v194, v194
	v_mul_f32_e32 v121, v195, v195
	v_mul_f32_e32 v122, v196, v196
	v_mul_f32_e32 v123, v197, v197
	v_fmac_f32_e32 v112, v203, v203
	v_fmac_f32_e32 v113, v204, v204
	v_fmac_f32_e32 v118, v205, v205
	v_fmac_f32_e32 v119, v206, v206
	v_fmac_f32_e32 v120, v207, v207
	v_fmac_f32_e32 v121, v208, v208
	v_fmac_f32_e32 v122, v209, v209
	v_fmac_f32_e32 v123, v210, v210
	v_add_f32_e32 v112, v112, v113
	v_add_f32_e32 v113, v118, v119
	v_add_f32_e32 v118, v120, v121
	v_add_f32_e32 v119, v122, v123
	v_cndmask_b32_e32 v189, v188, v189, vcc
	v_add_f32_e32 v112, v112, v113
	v_add_f32_e32 v113, v118, v119
	v_add_f32_e32 v113, v112, v113
	v_lshlrev_b32_e32 v112, 2, v189
	ds_bpermute_b32 v122, v112, v113
	v_lshl_add_u64 v[118:119], s[0:1], 0, v[200:201]
	v_cvt_pk_bf16_f32 v114, v203, v190
	v_lshl_add_u64 v[120:121], v[118:119], 0, v[198:199]
	v_cvt_pk_bf16_f32 v115, v204, v191
	v_cvt_pk_bf16_f32 v116, v205, v192
	v_cvt_pk_bf16_f32 v117, v206, v193
	global_store_dwordx4 v[120:121], v[114:117], off
	s_waitcnt lgkmcnt(0)
	s_nop 0
	v_add_f32_e32 v114, v113, v122
	v_xor_b32_e32 v113, 32, v188
	v_cmp_lt_i32_e32 vcc, v113, v202
	v_cvt_pk_bf16_f32 v116, v207, v194
	v_cvt_pk_bf16_f32 v117, v208, v195
	v_cvt_pk_bf16_f32 v118, v209, v196
	v_cvt_pk_bf16_f32 v119, v210, v197
	global_store_dwordx4 v[120:121], v[116:119], off offset:256
	s_nop 0
	v_cndmask_b32_e32 v113, v188, v113, vcc
	v_lshlrev_b32_e32 v113, 2, v113
	ds_bpermute_b32 v115, v113, v114
	s_and_saveexec_b64 s[20:21], s[4:5]
	s_cbranch_execz .LBB0_1909
	s_waitcnt lgkmcnt(0)
	v_add_f32_e32 v116, v114, v115
	s_lshl_b32 s22, s30, 2
	v_lshlrev_b64 v[114:115], 7, v[168:169]
	s_ashr_i32 s23, s22, 31
	v_lshl_add_u64 v[114:115], s[8:9], 0, v[114:115]
	v_lshl_add_u64 v[114:115], s[22:23], 2, v[114:115]
	s_lshl_b32 s2, s41, 2
	v_lshl_add_u64 v[114:115], v[114:115], 0, s[2:3]
	global_store_dword v[114:115], v116, off
